# v37 + GEMM K-loop MFMAs re-ordered within each run of 8 so consecutive MFMAs share an operand register (same per-accumulator k order)
# baseline (speedup 1.0000x reference)
.LBB0_274:
	ds_read_b128 v[146:149], v153
	ds_read_b128 v[156:159], v153 offset:1024
	ds_read_b128 v[160:163], v153 offset:2048
	ds_read_b128 v[164:167], v153 offset:3072
	ds_read_b128 v[168:171], v154
	ds_read_b128 v[172:175], v154 offset:1024
	ds_read_b128 v[176:179], v154 offset:2048
	ds_read_b128 v[180:183], v154 offset:3072
	s_add_u32 s34, s76, 0xfff80080
	s_addc_u32 s35, s77, -1
	s_cmp_eq_u32 s85, 28
	s_cselect_b32 s79, s0, s35
	s_cselect_b32 s78, s1, s34
	s_cselect_b32 s35, s67, s84
	s_cselect_b32 s34, s69, s83
	v_lshl_add_u64 v[218:219], s[76:77], 0, v[138:139]
	s_add_i32 m0, s54, 0xc000
	ds_read_b128 v[184:187], v155
	ds_read_b128 v[188:191], v155 offset:1024
	ds_read_b128 v[192:195], v155 offset:2048
	ds_read_b128 v[196:199], v155 offset:3072
	ds_read_b128 v[200:203], v155 offset:4096
	ds_read_b128 v[204:207], v155 offset:5120
	ds_read_b128 v[208:211], v155 offset:6144
	ds_read_b128 v[212:215], v155 offset:7168
	global_load_lds_dwordx4 v[218:219], off
	v_lshl_add_u64 v[218:219], s[76:77], 0, v[140:141]
	s_add_i32 m0, s54, 0xe000
	s_nop 0
	global_load_lds_dwordx4 v[218:219], off
	s_waitcnt vmcnt(8)
	s_waitcnt lgkmcnt(0)
	s_barrier
	s_setprio 1
	s_waitcnt lgkmcnt(0)
	v_mfma_f32_16x16x32_bf16 v[126:129], v[146:149], v[184:187], v[126:129]
	v_mfma_f32_16x16x32_bf16 v[110:113], v[146:149], v[192:195], v[110:113]
	v_mfma_f32_16x16x32_bf16 v[94:97], v[146:149], v[200:203], v[94:97]
	v_mfma_f32_16x16x32_bf16 v[78:81], v[146:149], v[208:211], v[78:81]
	v_mfma_f32_16x16x32_bf16 v[70:73], v[160:163], v[208:211], v[70:73]
	v_mfma_f32_16x16x32_bf16 v[86:89], v[160:163], v[200:203], v[86:89]
	v_mfma_f32_16x16x32_bf16 v[102:105], v[160:163], v[192:195], v[102:105]
	v_mfma_f32_16x16x32_bf16 v[118:121], v[160:163], v[184:187], v[118:121]
	v_mfma_f32_16x16x32_bf16 v[126:129], v[156:159], v[188:191], v[126:129]
	v_mfma_f32_16x16x32_bf16 v[110:113], v[156:159], v[196:199], v[110:113]
	v_mfma_f32_16x16x32_bf16 v[94:97], v[156:159], v[204:207], v[94:97]
	v_mfma_f32_16x16x32_bf16 v[78:81], v[156:159], v[212:215], v[78:81]
	v_mfma_f32_16x16x32_bf16 v[70:73], v[164:167], v[212:215], v[70:73]
	v_mfma_f32_16x16x32_bf16 v[86:89], v[164:167], v[204:207], v[86:89]
	v_mfma_f32_16x16x32_bf16 v[102:105], v[164:167], v[196:199], v[102:105]
	v_mfma_f32_16x16x32_bf16 v[118:121], v[164:167], v[188:191], v[118:121]
	s_setprio 0
	s_setprio 1
	v_mfma_f32_16x16x32_bf16 v[122:125], v[168:171], v[184:187], v[122:125]
	v_mfma_f32_16x16x32_bf16 v[106:109], v[168:171], v[192:195], v[106:109]
	v_mfma_f32_16x16x32_bf16 v[90:93], v[168:171], v[200:203], v[90:93]
	v_mfma_f32_16x16x32_bf16 v[74:77], v[168:171], v[208:211], v[74:77]
	v_mfma_f32_16x16x32_bf16 v[66:69], v[176:179], v[208:211], v[66:69]
	v_mfma_f32_16x16x32_bf16 v[82:85], v[176:179], v[200:203], v[82:85]
	v_mfma_f32_16x16x32_bf16 v[98:101], v[176:179], v[192:195], v[98:101]
	v_mfma_f32_16x16x32_bf16 v[114:117], v[176:179], v[184:187], v[114:117]
	v_mfma_f32_16x16x32_bf16 v[122:125], v[172:175], v[188:191], v[122:125]
	v_mfma_f32_16x16x32_bf16 v[106:109], v[172:175], v[196:199], v[106:109]
	v_mfma_f32_16x16x32_bf16 v[90:93], v[172:175], v[204:207], v[90:93]
	v_mfma_f32_16x16x32_bf16 v[74:77], v[172:175], v[212:215], v[74:77]
	v_mfma_f32_16x16x32_bf16 v[66:69], v[180:183], v[212:215], v[66:69]
	v_mfma_f32_16x16x32_bf16 v[82:85], v[180:183], v[204:207], v[82:85]
	v_mfma_f32_16x16x32_bf16 v[98:101], v[180:183], v[196:199], v[98:101]
	v_mfma_f32_16x16x32_bf16 v[114:117], v[180:183], v[188:191], v[114:117]
	s_setprio 0
	s_barrier
	s_add_i32 s62, s75, s33
	v_lshl_add_u64 v[218:219], s[34:35], 0, v[134:135]
	s_mov_b32 m0, s62
	ds_read_b128 v[184:187], v155 offset:16384
	ds_read_b128 v[188:191], v155 offset:17408
	ds_read_b128 v[192:195], v155 offset:18432
	ds_read_b128 v[196:199], v155 offset:19456
	ds_read_b128 v[200:203], v155 offset:20480
	ds_read_b128 v[204:207], v155 offset:21504
	ds_read_b128 v[208:211], v155 offset:22528
	ds_read_b128 v[212:215], v155 offset:23552
	global_load_lds_dwordx4 v[218:219], off
	s_add_i32 m0, s62, 0x2000
	s_add_u32 s62, s34, 0x80000
	v_lshl_add_u64 v[220:221], s[34:35], 0, v[130:131]
	s_addc_u32 s63, s35, 0
	s_add_i32 s86, s80, s33
	global_load_lds_dwordx4 v[220:221], off
	v_lshl_add_u64 v[222:223], s[62:63], 0, v[134:135]
	s_mov_b32 m0, s86
	v_lshl_add_u64 v[224:225], s[78:79], 0, v[132:133]
	global_load_lds_dwordx4 v[222:223], off
	v_lshl_add_u64 v[222:223], s[62:63], 0, v[130:131]
	s_add_i32 m0, s86, 0x2000
	s_nop 0
	global_load_lds_dwordx4 v[222:223], off
	v_lshl_add_u64 v[222:223], s[78:79], 0, v[136:137]
	s_mov_b32 m0, s54
	s_nop 0
	global_load_lds_dwordx4 v[222:223], off
	s_mov_b32 m0, s55
	s_nop 0
	global_load_lds_dwordx4 v[224:225], off
	s_waitcnt vmcnt(8)
	s_waitcnt lgkmcnt(0)
	s_barrier
	s_setprio 1
	s_waitcnt lgkmcnt(0)
	v_mfma_f32_16x16x32_bf16 v[62:65], v[146:149], v[184:187], v[62:65]
	v_mfma_f32_16x16x32_bf16 v[46:49], v[146:149], v[192:195], v[46:49]
	v_mfma_f32_16x16x32_bf16 v[30:33], v[146:149], v[200:203], v[30:33]
	v_mfma_f32_16x16x32_bf16 v[14:17], v[146:149], v[208:211], v[14:17]
	v_mfma_f32_16x16x32_bf16 v[6:9], v[160:163], v[208:211], v[6:9]
	v_mfma_f32_16x16x32_bf16 v[22:25], v[160:163], v[200:203], v[22:25]
	v_mfma_f32_16x16x32_bf16 v[38:41], v[160:163], v[192:195], v[38:41]
	v_mfma_f32_16x16x32_bf16 v[54:57], v[160:163], v[184:187], v[54:57]
	v_mfma_f32_16x16x32_bf16 v[62:65], v[156:159], v[188:191], v[62:65]
	v_mfma_f32_16x16x32_bf16 v[46:49], v[156:159], v[196:199], v[46:49]
	v_mfma_f32_16x16x32_bf16 v[30:33], v[156:159], v[204:207], v[30:33]
	v_mfma_f32_16x16x32_bf16 v[14:17], v[156:159], v[212:215], v[14:17]
	v_mfma_f32_16x16x32_bf16 v[6:9], v[164:167], v[212:215], v[6:9]
	v_mfma_f32_16x16x32_bf16 v[22:25], v[164:167], v[204:207], v[22:25]
	v_mfma_f32_16x16x32_bf16 v[38:41], v[164:167], v[196:199], v[38:41]
	v_mfma_f32_16x16x32_bf16 v[54:57], v[164:167], v[188:191], v[54:57]
	s_setprio 0
	s_setprio 1
	v_mfma_f32_16x16x32_bf16 v[58:61], v[168:171], v[184:187], v[58:61]
	v_mfma_f32_16x16x32_bf16 v[42:45], v[168:171], v[192:195], v[42:45]
	v_mfma_f32_16x16x32_bf16 v[26:29], v[168:171], v[200:203], v[26:29]
	v_mfma_f32_16x16x32_bf16 v[10:13], v[168:171], v[208:211], v[10:13]
	v_mfma_f32_16x16x32_bf16 v[2:5], v[176:179], v[208:211], v[2:5]
	v_mfma_f32_16x16x32_bf16 v[18:21], v[176:179], v[200:203], v[18:21]
	v_mfma_f32_16x16x32_bf16 v[34:37], v[176:179], v[192:195], v[34:37]
	v_mfma_f32_16x16x32_bf16 v[50:53], v[176:179], v[184:187], v[50:53]
	v_mfma_f32_16x16x32_bf16 v[58:61], v[172:175], v[188:191], v[58:61]
	v_mfma_f32_16x16x32_bf16 v[42:45], v[172:175], v[196:199], v[42:45]
	v_mfma_f32_16x16x32_bf16 v[26:29], v[172:175], v[204:207], v[26:29]
	v_mfma_f32_16x16x32_bf16 v[10:13], v[172:175], v[212:215], v[10:13]
	v_mfma_f32_16x16x32_bf16 v[2:5], v[180:183], v[212:215], v[2:5]
	v_mfma_f32_16x16x32_bf16 v[18:21], v[180:183], v[204:207], v[18:21]
	v_mfma_f32_16x16x32_bf16 v[34:37], v[180:183], v[196:199], v[34:37]
	v_mfma_f32_16x16x32_bf16 v[50:53], v[180:183], v[188:191], v[50:53]
	s_setprio 0
	s_barrier
	s_add_i32 s86, 0, 0x18000
	s_add_i32 s87, 0, 0x1c000
	v_add_u32_e32 v164, s86, v151
	v_add_u32_e32 v180, s87, v151
	ds_read_b128 v[146:149], v164
	ds_read_b128 v[156:159], v164 offset:1024
	ds_read_b128 v[160:163], v164 offset:2048
	ds_read_b128 v[164:167], v164 offset:3072
	ds_read_b128 v[168:171], v180
	ds_read_b128 v[172:175], v180 offset:1024
	ds_read_b128 v[176:179], v180 offset:2048
	ds_read_b128 v[180:183], v180 offset:3072
	s_add_u32 s62, s78, 0x80000
	s_addc_u32 s63, s79, 0
	s_mov_b32 m0, s56
	v_lshl_add_u64 v[226:227], s[62:63], 0, v[136:137]
	ds_read_b128 v[184:187], v155 offset:32768
	ds_read_b128 v[188:191], v155 offset:33792
	ds_read_b128 v[192:195], v155 offset:34816
	ds_read_b128 v[196:199], v155 offset:35840
	ds_read_b128 v[200:203], v155 offset:36864
	ds_read_b128 v[204:207], v155 offset:37888
	ds_read_b128 v[208:211], v155 offset:38912
	ds_read_b128 v[212:215], v155 offset:39936
	global_load_lds_dwordx4 v[226:227], off
	v_lshl_add_u64 v[226:227], s[62:63], 0, v[132:133]
	s_mov_b32 m0, s57
	s_nop 0
	global_load_lds_dwordx4 v[226:227], off
	s_waitcnt vmcnt(8)
	s_waitcnt lgkmcnt(0)
	s_barrier
	s_setprio 1
	s_waitcnt lgkmcnt(0)
	v_mfma_f32_16x16x32_bf16 v[126:129], v[146:149], v[184:187], v[126:129]
	v_mfma_f32_16x16x32_bf16 v[110:113], v[146:149], v[192:195], v[110:113]
	v_mfma_f32_16x16x32_bf16 v[94:97], v[146:149], v[200:203], v[94:97]
	v_mfma_f32_16x16x32_bf16 v[78:81], v[146:149], v[208:211], v[78:81]
	v_mfma_f32_16x16x32_bf16 v[70:73], v[160:163], v[208:211], v[70:73]
	v_mfma_f32_16x16x32_bf16 v[86:89], v[160:163], v[200:203], v[86:89]
	v_mfma_f32_16x16x32_bf16 v[102:105], v[160:163], v[192:195], v[102:105]
	v_mfma_f32_16x16x32_bf16 v[118:121], v[160:163], v[184:187], v[118:121]
	v_mfma_f32_16x16x32_bf16 v[126:129], v[156:159], v[188:191], v[126:129]
	v_mfma_f32_16x16x32_bf16 v[110:113], v[156:159], v[196:199], v[110:113]
	v_mfma_f32_16x16x32_bf16 v[94:97], v[156:159], v[204:207], v[94:97]
	v_mfma_f32_16x16x32_bf16 v[78:81], v[156:159], v[212:215], v[78:81]
	v_mfma_f32_16x16x32_bf16 v[70:73], v[164:167], v[212:215], v[70:73]
	v_mfma_f32_16x16x32_bf16 v[86:89], v[164:167], v[204:207], v[86:89]
	v_mfma_f32_16x16x32_bf16 v[102:105], v[164:167], v[196:199], v[102:105]
	v_mfma_f32_16x16x32_bf16 v[118:121], v[164:167], v[188:191], v[118:121]
	s_setprio 0
	s_setprio 1
	v_mfma_f32_16x16x32_bf16 v[122:125], v[168:171], v[184:187], v[122:125]
	v_mfma_f32_16x16x32_bf16 v[106:109], v[168:171], v[192:195], v[106:109]
	v_mfma_f32_16x16x32_bf16 v[90:93], v[168:171], v[200:203], v[90:93]
	v_mfma_f32_16x16x32_bf16 v[74:77], v[168:171], v[208:211], v[74:77]
	v_mfma_f32_16x16x32_bf16 v[66:69], v[176:179], v[208:211], v[66:69]
	v_mfma_f32_16x16x32_bf16 v[82:85], v[176:179], v[200:203], v[82:85]
	v_mfma_f32_16x16x32_bf16 v[98:101], v[176:179], v[192:195], v[98:101]
	v_mfma_f32_16x16x32_bf16 v[114:117], v[176:179], v[184:187], v[114:117]
	v_mfma_f32_16x16x32_bf16 v[122:125], v[172:175], v[188:191], v[122:125]
	v_mfma_f32_16x16x32_bf16 v[106:109], v[172:175], v[196:199], v[106:109]
	v_mfma_f32_16x16x32_bf16 v[90:93], v[172:175], v[204:207], v[90:93]
	v_mfma_f32_16x16x32_bf16 v[74:77], v[172:175], v[212:215], v[74:77]
	v_mfma_f32_16x16x32_bf16 v[66:69], v[180:183], v[212:215], v[66:69]
	v_mfma_f32_16x16x32_bf16 v[82:85], v[180:183], v[204:207], v[82:85]
	v_mfma_f32_16x16x32_bf16 v[98:101], v[180:183], v[196:199], v[98:101]
	v_mfma_f32_16x16x32_bf16 v[114:117], v[180:183], v[188:191], v[114:117]
	s_setprio 0
	s_barrier
	s_add_i32 s62, s86, s33
	v_lshl_add_u64 v[218:219], v[218:219], 0, s[8:9]
	s_mov_b32 m0, s62
	ds_read_b128 v[184:187], v155 offset:49152
	ds_read_b128 v[188:191], v155 offset:50176
	ds_read_b128 v[192:195], v155 offset:51200
	ds_read_b128 v[196:199], v155 offset:52224
	ds_read_b128 v[200:203], v155 offset:53248
	ds_read_b128 v[204:207], v155 offset:54272
	ds_read_b128 v[208:211], v155 offset:55296
	ds_read_b128 v[212:215], v155 offset:56320
	global_load_lds_dwordx4 v[218:219], off
	s_add_i32 m0, s62, 0x2000
	s_add_u32 s34, s34, 0x80080
	v_lshl_add_u64 v[218:219], v[220:221], 0, s[8:9]
	s_addc_u32 s35, s35, 0
	s_add_i32 s62, s87, s33
	global_load_lds_dwordx4 v[218:219], off
	v_lshl_add_u64 v[218:219], s[34:35], 0, v[134:135]
	s_mov_b32 m0, s62
	s_nop 0
	global_load_lds_dwordx4 v[218:219], off
	v_lshl_add_u64 v[218:219], s[34:35], 0, v[130:131]
	s_add_i32 m0, s62, 0x2000
	s_nop 0
	global_load_lds_dwordx4 v[218:219], off
	v_lshl_add_u64 v[218:219], v[222:223], 0, s[8:9]
	s_mov_b32 m0, s59
	s_nop 0
	global_load_lds_dwordx4 v[218:219], off
	v_lshl_add_u64 v[218:219], v[224:225], 0, s[8:9]
	s_mov_b32 m0, s60
	s_nop 0
	global_load_lds_dwordx4 v[218:219], off
	s_waitcnt vmcnt(8)
	s_waitcnt lgkmcnt(0)
	s_barrier
	s_setprio 1
	s_waitcnt lgkmcnt(0)
	v_mfma_f32_16x16x32_bf16 v[62:65], v[146:149], v[184:187], v[62:65]
	v_mfma_f32_16x16x32_bf16 v[46:49], v[146:149], v[192:195], v[46:49]
	v_mfma_f32_16x16x32_bf16 v[30:33], v[146:149], v[200:203], v[30:33]
	v_mfma_f32_16x16x32_bf16 v[14:17], v[146:149], v[208:211], v[14:17]
	v_mfma_f32_16x16x32_bf16 v[6:9], v[160:163], v[208:211], v[6:9]
	v_mfma_f32_16x16x32_bf16 v[22:25], v[160:163], v[200:203], v[22:25]
	v_mfma_f32_16x16x32_bf16 v[38:41], v[160:163], v[192:195], v[38:41]
	v_mfma_f32_16x16x32_bf16 v[54:57], v[160:163], v[184:187], v[54:57]
	v_mfma_f32_16x16x32_bf16 v[62:65], v[156:159], v[188:191], v[62:65]
	v_mfma_f32_16x16x32_bf16 v[46:49], v[156:159], v[196:199], v[46:49]
	v_mfma_f32_16x16x32_bf16 v[30:33], v[156:159], v[204:207], v[30:33]
	v_mfma_f32_16x16x32_bf16 v[14:17], v[156:159], v[212:215], v[14:17]
	v_mfma_f32_16x16x32_bf16 v[6:9], v[164:167], v[212:215], v[6:9]
	v_mfma_f32_16x16x32_bf16 v[22:25], v[164:167], v[204:207], v[22:25]
	v_mfma_f32_16x16x32_bf16 v[38:41], v[164:167], v[196:199], v[38:41]
	v_mfma_f32_16x16x32_bf16 v[54:57], v[164:167], v[188:191], v[54:57]
	s_setprio 0
	s_setprio 1
	v_mfma_f32_16x16x32_bf16 v[58:61], v[168:171], v[184:187], v[58:61]
	v_mfma_f32_16x16x32_bf16 v[42:45], v[168:171], v[192:195], v[42:45]
	v_mfma_f32_16x16x32_bf16 v[26:29], v[168:171], v[200:203], v[26:29]
	v_mfma_f32_16x16x32_bf16 v[10:13], v[168:171], v[208:211], v[10:13]
	v_mfma_f32_16x16x32_bf16 v[2:5], v[176:179], v[208:211], v[2:5]
	v_mfma_f32_16x16x32_bf16 v[18:21], v[176:179], v[200:203], v[18:21]
	v_mfma_f32_16x16x32_bf16 v[34:37], v[176:179], v[192:195], v[34:37]
	v_mfma_f32_16x16x32_bf16 v[50:53], v[176:179], v[184:187], v[50:53]
	v_mfma_f32_16x16x32_bf16 v[58:61], v[172:175], v[188:191], v[58:61]
	v_mfma_f32_16x16x32_bf16 v[42:45], v[172:175], v[196:199], v[42:45]
	v_mfma_f32_16x16x32_bf16 v[26:29], v[172:175], v[204:207], v[26:29]
	v_mfma_f32_16x16x32_bf16 v[10:13], v[172:175], v[212:215], v[10:13]
	v_mfma_f32_16x16x32_bf16 v[2:5], v[180:183], v[212:215], v[2:5]
	v_mfma_f32_16x16x32_bf16 v[18:21], v[180:183], v[204:207], v[18:21]
	v_mfma_f32_16x16x32_bf16 v[34:37], v[180:183], v[196:199], v[34:37]
	v_mfma_f32_16x16x32_bf16 v[50:53], v[180:183], v[188:191], v[50:53]
	s_setprio 0
	s_barrier
	s_add_i32 s85, s85, 2
	s_add_u32 s76, s76, 0x100
	s_addc_u32 s77, s77, 0
	s_add_u32 s83, s83, 0x100
	s_addc_u32 s84, s84, 0
	s_cmp_gt_u32 s85, 29
	s_cbranch_scc0 .LBB0_274
	v_mov_b32_e32 v160, 0xbfb8aa3b
	s_and_b64 vcc, exec, s[64:65]
	s_cbranch_vccz .LBB0_277
	s_barrier

.LBB0_387:
	ds_read_b128 v[146:149], v154
	ds_read_b128 v[158:161], v154 offset:1024
	ds_read_b128 v[162:165], v154 offset:2048
	ds_read_b128 v[166:169], v154 offset:3072
	ds_read_b128 v[170:173], v155
	ds_read_b128 v[174:177], v155 offset:1024
	ds_read_b128 v[178:181], v155 offset:2048
	ds_read_b128 v[182:185], v155 offset:3072
	s_add_u32 s34, s72, 0xffea0080
	s_addc_u32 s35, s73, -1
	s_cmpk_eq_i32 s81, 0x54
	s_cselect_b32 s75, s5, s35
	s_cselect_b32 s74, s4, s34
	s_cselect_b32 s35, s71, s1
	s_cselect_b32 s34, s70, s0
	v_lshl_add_u64 v[150:151], s[72:73], 0, v[138:139]
	s_add_i32 m0, s53, 0xc000
	ds_read_b128 v[186:189], v156
	ds_read_b128 v[190:193], v156 offset:1024
	ds_read_b128 v[194:197], v156 offset:2048
	ds_read_b128 v[198:201], v156 offset:3072
	ds_read_b128 v[202:205], v156 offset:4096
	ds_read_b128 v[206:209], v156 offset:5120
	ds_read_b128 v[210:213], v156 offset:6144
	ds_read_b128 v[218:221], v156 offset:7168
	global_load_lds_dwordx4 v[150:151], off
	v_lshl_add_u64 v[150:151], s[72:73], 0, v[140:141]
	s_add_i32 m0, s53, 0xe000
	s_nop 0
	global_load_lds_dwordx4 v[150:151], off
	s_waitcnt vmcnt(8)
	s_waitcnt lgkmcnt(0)
	s_barrier
	s_setprio 1
	s_waitcnt lgkmcnt(0)
	v_mfma_f32_16x16x32_bf16 v[126:129], v[146:149], v[186:189], v[126:129]
	v_mfma_f32_16x16x32_bf16 v[118:121], v[146:149], v[194:197], v[118:121]
	v_mfma_f32_16x16x32_bf16 v[94:97], v[146:149], v[202:205], v[94:97]
	v_mfma_f32_16x16x32_bf16 v[86:89], v[146:149], v[210:213], v[86:89]
	v_mfma_f32_16x16x32_bf16 v[82:85], v[162:165], v[210:213], v[82:85]
	v_mfma_f32_16x16x32_bf16 v[90:93], v[162:165], v[202:205], v[90:93]
	v_mfma_f32_16x16x32_bf16 v[114:117], v[162:165], v[194:197], v[114:117]
	v_mfma_f32_16x16x32_bf16 v[122:125], v[162:165], v[186:189], v[122:125]
	v_mfma_f32_16x16x32_bf16 v[126:129], v[158:161], v[190:193], v[126:129]
	v_mfma_f32_16x16x32_bf16 v[118:121], v[158:161], v[198:201], v[118:121]
	v_mfma_f32_16x16x32_bf16 v[94:97], v[158:161], v[206:209], v[94:97]
	v_mfma_f32_16x16x32_bf16 v[86:89], v[158:161], v[218:221], v[86:89]
	v_mfma_f32_16x16x32_bf16 v[82:85], v[166:169], v[218:221], v[82:85]
	v_mfma_f32_16x16x32_bf16 v[90:93], v[166:169], v[206:209], v[90:93]
	v_mfma_f32_16x16x32_bf16 v[114:117], v[166:169], v[198:201], v[114:117]
	v_mfma_f32_16x16x32_bf16 v[122:125], v[166:169], v[190:193], v[122:125]
	s_setprio 0
	s_setprio 1
	v_mfma_f32_16x16x32_bf16 v[110:113], v[170:173], v[186:189], v[110:113]
	v_mfma_f32_16x16x32_bf16 v[102:105], v[170:173], v[194:197], v[102:105]
	v_mfma_f32_16x16x32_bf16 v[78:81], v[170:173], v[202:205], v[78:81]
	v_mfma_f32_16x16x32_bf16 v[70:73], v[170:173], v[210:213], v[70:73]
	v_mfma_f32_16x16x32_bf16 v[66:69], v[178:181], v[210:213], v[66:69]
	v_mfma_f32_16x16x32_bf16 v[74:77], v[178:181], v[202:205], v[74:77]
	v_mfma_f32_16x16x32_bf16 v[98:101], v[178:181], v[194:197], v[98:101]
	v_mfma_f32_16x16x32_bf16 v[106:109], v[178:181], v[186:189], v[106:109]
	v_mfma_f32_16x16x32_bf16 v[110:113], v[174:177], v[190:193], v[110:113]
	v_mfma_f32_16x16x32_bf16 v[102:105], v[174:177], v[198:201], v[102:105]
	v_mfma_f32_16x16x32_bf16 v[78:81], v[174:177], v[206:209], v[78:81]
	v_mfma_f32_16x16x32_bf16 v[70:73], v[174:177], v[218:221], v[70:73]
	v_mfma_f32_16x16x32_bf16 v[66:69], v[182:185], v[218:221], v[66:69]
	v_mfma_f32_16x16x32_bf16 v[74:77], v[182:185], v[206:209], v[74:77]
	v_mfma_f32_16x16x32_bf16 v[98:101], v[182:185], v[198:201], v[98:101]
	v_mfma_f32_16x16x32_bf16 v[106:109], v[182:185], v[190:193], v[106:109]
	s_setprio 0
	s_barrier
	s_add_i32 s62, s61, s52
	v_lshl_add_u64 v[150:151], s[34:35], 0, v[132:133]
	s_mov_b32 m0, s62
	ds_read_b128 v[186:189], v156 offset:16384
	ds_read_b128 v[190:193], v156 offset:17408
	ds_read_b128 v[194:197], v156 offset:18432
	ds_read_b128 v[198:201], v156 offset:19456
	ds_read_b128 v[202:205], v156 offset:20480
	ds_read_b128 v[206:209], v156 offset:21504
	ds_read_b128 v[210:213], v156 offset:22528
	ds_read_b128 v[218:221], v156 offset:23552
	global_load_lds_dwordx4 v[150:151], off
	s_add_i32 m0, s62, 0x2000
	s_add_u32 s62, s34, 0x160000
	v_lshl_add_u64 v[214:215], s[34:35], 0, v[136:137]
	s_addc_u32 s63, s35, 0
	s_add_i32 s82, s76, s52
	global_load_lds_dwordx4 v[214:215], off
	v_lshl_add_u64 v[222:223], s[62:63], 0, v[132:133]
	s_mov_b32 m0, s82
	v_lshl_add_u64 v[224:225], s[74:75], 0, v[134:135]
	global_load_lds_dwordx4 v[222:223], off
	v_lshl_add_u64 v[222:223], s[62:63], 0, v[136:137]
	s_add_i32 m0, s82, 0x2000
	s_nop 0
	global_load_lds_dwordx4 v[222:223], off
	v_lshl_add_u64 v[222:223], s[74:75], 0, v[130:131]
	s_mov_b32 m0, s53
	s_nop 0
	global_load_lds_dwordx4 v[222:223], off
	s_mov_b32 m0, s54
	s_nop 0
	global_load_lds_dwordx4 v[224:225], off
	s_waitcnt vmcnt(8)
	s_waitcnt lgkmcnt(0)
	s_barrier
	s_setprio 1
	s_waitcnt lgkmcnt(0)
	v_mfma_f32_16x16x32_bf16 v[62:65], v[146:149], v[186:189], v[62:65]
	v_mfma_f32_16x16x32_bf16 v[54:57], v[146:149], v[194:197], v[54:57]
	v_mfma_f32_16x16x32_bf16 v[30:33], v[146:149], v[202:205], v[30:33]
	v_mfma_f32_16x16x32_bf16 v[22:25], v[146:149], v[210:213], v[22:25]
	v_mfma_f32_16x16x32_bf16 v[18:21], v[162:165], v[210:213], v[18:21]
	v_mfma_f32_16x16x32_bf16 v[26:29], v[162:165], v[202:205], v[26:29]
	v_mfma_f32_16x16x32_bf16 v[50:53], v[162:165], v[194:197], v[50:53]
	v_mfma_f32_16x16x32_bf16 v[58:61], v[162:165], v[186:189], v[58:61]
	v_mfma_f32_16x16x32_bf16 v[62:65], v[158:161], v[190:193], v[62:65]
	v_mfma_f32_16x16x32_bf16 v[54:57], v[158:161], v[198:201], v[54:57]
	v_mfma_f32_16x16x32_bf16 v[30:33], v[158:161], v[206:209], v[30:33]
	v_mfma_f32_16x16x32_bf16 v[22:25], v[158:161], v[218:221], v[22:25]
	v_mfma_f32_16x16x32_bf16 v[18:21], v[166:169], v[218:221], v[18:21]
	v_mfma_f32_16x16x32_bf16 v[26:29], v[166:169], v[206:209], v[26:29]
	v_mfma_f32_16x16x32_bf16 v[50:53], v[166:169], v[198:201], v[50:53]
	v_mfma_f32_16x16x32_bf16 v[58:61], v[166:169], v[190:193], v[58:61]
	s_setprio 0
	s_setprio 1
	v_mfma_f32_16x16x32_bf16 v[46:49], v[170:173], v[186:189], v[46:49]
	v_mfma_f32_16x16x32_bf16 v[38:41], v[170:173], v[194:197], v[38:41]
	v_mfma_f32_16x16x32_bf16 v[14:17], v[170:173], v[202:205], v[14:17]
	v_mfma_f32_16x16x32_bf16 v[6:9], v[170:173], v[210:213], v[6:9]
	v_mfma_f32_16x16x32_bf16 v[2:5], v[178:181], v[210:213], v[2:5]
	v_mfma_f32_16x16x32_bf16 v[10:13], v[178:181], v[202:205], v[10:13]
	v_mfma_f32_16x16x32_bf16 v[34:37], v[178:181], v[194:197], v[34:37]
	v_mfma_f32_16x16x32_bf16 v[42:45], v[178:181], v[186:189], v[42:45]
	v_mfma_f32_16x16x32_bf16 v[46:49], v[174:177], v[190:193], v[46:49]
	v_mfma_f32_16x16x32_bf16 v[38:41], v[174:177], v[198:201], v[38:41]
	v_mfma_f32_16x16x32_bf16 v[14:17], v[174:177], v[206:209], v[14:17]
	v_mfma_f32_16x16x32_bf16 v[6:9], v[174:177], v[218:221], v[6:9]
	v_mfma_f32_16x16x32_bf16 v[2:5], v[182:185], v[218:221], v[2:5]
	v_mfma_f32_16x16x32_bf16 v[10:13], v[182:185], v[206:209], v[10:13]
	v_mfma_f32_16x16x32_bf16 v[34:37], v[182:185], v[198:201], v[34:37]
	v_mfma_f32_16x16x32_bf16 v[42:45], v[182:185], v[190:193], v[42:45]
	s_setprio 0
	s_barrier
	s_add_i32 s82, 0, 0x18000
	v_add_u32_e32 v157, s82, v152
	s_add_i32 s83, 0, 0x1c000
	ds_read_b128 v[146:149], v157
	ds_read_b128 v[158:161], v157 offset:1024
	ds_read_b128 v[162:165], v157 offset:2048
	ds_read_b128 v[166:169], v157 offset:3072
	v_add_u32_e32 v157, s83, v152
	ds_read_b128 v[170:173], v157
	ds_read_b128 v[174:177], v157 offset:1024
	ds_read_b128 v[178:181], v157 offset:2048
	ds_read_b128 v[182:185], v157 offset:3072
	s_add_u32 s62, s74, 0x160000
	s_addc_u32 s63, s75, 0
	s_mov_b32 m0, s55
	v_lshl_add_u64 v[226:227], s[62:63], 0, v[130:131]
	ds_read_b128 v[186:189], v156 offset:32768
	ds_read_b128 v[190:193], v156 offset:33792
	ds_read_b128 v[194:197], v156 offset:34816
	ds_read_b128 v[198:201], v156 offset:35840
	ds_read_b128 v[202:205], v156 offset:36864
	ds_read_b128 v[206:209], v156 offset:37888
	ds_read_b128 v[210:213], v156 offset:38912
	ds_read_b128 v[218:221], v156 offset:39936
	global_load_lds_dwordx4 v[226:227], off
	v_lshl_add_u64 v[226:227], s[62:63], 0, v[134:135]
	s_mov_b32 m0, s56
	s_nop 0
	global_load_lds_dwordx4 v[226:227], off
	s_waitcnt vmcnt(8)
	s_waitcnt lgkmcnt(0)
	s_barrier
	s_setprio 1
	s_waitcnt lgkmcnt(0)
	v_mfma_f32_16x16x32_bf16 v[126:129], v[146:149], v[186:189], v[126:129]
	v_mfma_f32_16x16x32_bf16 v[118:121], v[146:149], v[194:197], v[118:121]
	v_mfma_f32_16x16x32_bf16 v[94:97], v[146:149], v[202:205], v[94:97]
	v_mfma_f32_16x16x32_bf16 v[86:89], v[146:149], v[210:213], v[86:89]
	v_mfma_f32_16x16x32_bf16 v[82:85], v[162:165], v[210:213], v[82:85]
	v_mfma_f32_16x16x32_bf16 v[90:93], v[162:165], v[202:205], v[90:93]
	v_mfma_f32_16x16x32_bf16 v[114:117], v[162:165], v[194:197], v[114:117]
	v_mfma_f32_16x16x32_bf16 v[122:125], v[162:165], v[186:189], v[122:125]
	v_mfma_f32_16x16x32_bf16 v[126:129], v[158:161], v[190:193], v[126:129]
	v_mfma_f32_16x16x32_bf16 v[118:121], v[158:161], v[198:201], v[118:121]
	v_mfma_f32_16x16x32_bf16 v[94:97], v[158:161], v[206:209], v[94:97]
	v_mfma_f32_16x16x32_bf16 v[86:89], v[158:161], v[218:221], v[86:89]
	v_mfma_f32_16x16x32_bf16 v[82:85], v[166:169], v[218:221], v[82:85]
	v_mfma_f32_16x16x32_bf16 v[90:93], v[166:169], v[206:209], v[90:93]
	v_mfma_f32_16x16x32_bf16 v[114:117], v[166:169], v[198:201], v[114:117]
	v_mfma_f32_16x16x32_bf16 v[122:125], v[166:169], v[190:193], v[122:125]
	s_setprio 0
	s_setprio 1
	v_mfma_f32_16x16x32_bf16 v[110:113], v[170:173], v[186:189], v[110:113]
	v_mfma_f32_16x16x32_bf16 v[102:105], v[170:173], v[194:197], v[102:105]
	v_mfma_f32_16x16x32_bf16 v[78:81], v[170:173], v[202:205], v[78:81]
	v_mfma_f32_16x16x32_bf16 v[70:73], v[170:173], v[210:213], v[70:73]
	v_mfma_f32_16x16x32_bf16 v[66:69], v[178:181], v[210:213], v[66:69]
	v_mfma_f32_16x16x32_bf16 v[74:77], v[178:181], v[202:205], v[74:77]
	v_mfma_f32_16x16x32_bf16 v[98:101], v[178:181], v[194:197], v[98:101]
	v_mfma_f32_16x16x32_bf16 v[106:109], v[178:181], v[186:189], v[106:109]
	v_mfma_f32_16x16x32_bf16 v[110:113], v[174:177], v[190:193], v[110:113]
	v_mfma_f32_16x16x32_bf16 v[102:105], v[174:177], v[198:201], v[102:105]
	v_mfma_f32_16x16x32_bf16 v[78:81], v[174:177], v[206:209], v[78:81]
	v_mfma_f32_16x16x32_bf16 v[70:73], v[174:177], v[218:221], v[70:73]
	v_mfma_f32_16x16x32_bf16 v[66:69], v[182:185], v[218:221], v[66:69]
	v_mfma_f32_16x16x32_bf16 v[74:77], v[182:185], v[206:209], v[74:77]
	v_mfma_f32_16x16x32_bf16 v[98:101], v[182:185], v[198:201], v[98:101]
	v_mfma_f32_16x16x32_bf16 v[106:109], v[182:185], v[190:193], v[106:109]
	s_setprio 0
	s_barrier
	s_add_i32 s62, s82, s52
	v_lshl_add_u64 v[150:151], v[150:151], 0, s[66:67]
	s_mov_b32 m0, s62
	ds_read_b128 v[186:189], v156 offset:49152
	ds_read_b128 v[190:193], v156 offset:50176
	ds_read_b128 v[194:197], v156 offset:51200
	ds_read_b128 v[198:201], v156 offset:52224
	ds_read_b128 v[202:205], v156 offset:53248
	ds_read_b128 v[206:209], v156 offset:54272
	ds_read_b128 v[210:213], v156 offset:55296
	ds_read_b128 v[218:221], v156 offset:56320
	global_load_lds_dwordx4 v[150:151], off
	s_add_i32 m0, s62, 0x2000
	s_add_u32 s34, s34, 0x160080
	v_lshl_add_u64 v[150:151], v[214:215], 0, s[66:67]
	s_addc_u32 s35, s35, 0
	s_add_i32 s62, s83, s52
	global_load_lds_dwordx4 v[150:151], off
	v_lshl_add_u64 v[150:151], s[34:35], 0, v[132:133]
	s_mov_b32 m0, s62
	s_nop 0
	global_load_lds_dwordx4 v[150:151], off
	v_lshl_add_u64 v[150:151], s[34:35], 0, v[136:137]
	s_add_i32 m0, s62, 0x2000
	s_nop 0
	global_load_lds_dwordx4 v[150:151], off
	v_lshl_add_u64 v[150:151], v[222:223], 0, s[66:67]
	s_mov_b32 m0, s58
	s_nop 0
	global_load_lds_dwordx4 v[150:151], off
	v_lshl_add_u64 v[150:151], v[224:225], 0, s[66:67]
	s_mov_b32 m0, s59
	s_nop 0
	global_load_lds_dwordx4 v[150:151], off
	s_waitcnt vmcnt(8)
	s_waitcnt lgkmcnt(0)
	s_barrier
	s_setprio 1
	s_waitcnt lgkmcnt(0)
	v_mfma_f32_16x16x32_bf16 v[62:65], v[146:149], v[186:189], v[62:65]
	v_mfma_f32_16x16x32_bf16 v[54:57], v[146:149], v[194:197], v[54:57]
	v_mfma_f32_16x16x32_bf16 v[30:33], v[146:149], v[202:205], v[30:33]
	v_mfma_f32_16x16x32_bf16 v[22:25], v[146:149], v[210:213], v[22:25]
	v_mfma_f32_16x16x32_bf16 v[18:21], v[162:165], v[210:213], v[18:21]
	v_mfma_f32_16x16x32_bf16 v[26:29], v[162:165], v[202:205], v[26:29]
	v_mfma_f32_16x16x32_bf16 v[50:53], v[162:165], v[194:197], v[50:53]
	v_mfma_f32_16x16x32_bf16 v[58:61], v[162:165], v[186:189], v[58:61]
	v_mfma_f32_16x16x32_bf16 v[62:65], v[158:161], v[190:193], v[62:65]
	v_mfma_f32_16x16x32_bf16 v[54:57], v[158:161], v[198:201], v[54:57]
	v_mfma_f32_16x16x32_bf16 v[30:33], v[158:161], v[206:209], v[30:33]
	v_mfma_f32_16x16x32_bf16 v[22:25], v[158:161], v[218:221], v[22:25]
	v_mfma_f32_16x16x32_bf16 v[18:21], v[166:169], v[218:221], v[18:21]
	v_mfma_f32_16x16x32_bf16 v[26:29], v[166:169], v[206:209], v[26:29]
	v_mfma_f32_16x16x32_bf16 v[50:53], v[166:169], v[198:201], v[50:53]
	v_mfma_f32_16x16x32_bf16 v[58:61], v[166:169], v[190:193], v[58:61]
	s_setprio 0
	s_setprio 1
	v_mfma_f32_16x16x32_bf16 v[46:49], v[170:173], v[186:189], v[46:49]
	v_mfma_f32_16x16x32_bf16 v[38:41], v[170:173], v[194:197], v[38:41]
	v_mfma_f32_16x16x32_bf16 v[14:17], v[170:173], v[202:205], v[14:17]
	v_mfma_f32_16x16x32_bf16 v[6:9], v[170:173], v[210:213], v[6:9]
	v_mfma_f32_16x16x32_bf16 v[2:5], v[178:181], v[210:213], v[2:5]
	v_mfma_f32_16x16x32_bf16 v[10:13], v[178:181], v[202:205], v[10:13]
	v_mfma_f32_16x16x32_bf16 v[34:37], v[178:181], v[194:197], v[34:37]
	v_mfma_f32_16x16x32_bf16 v[42:45], v[178:181], v[186:189], v[42:45]
	v_mfma_f32_16x16x32_bf16 v[46:49], v[174:177], v[190:193], v[46:49]
	v_mfma_f32_16x16x32_bf16 v[38:41], v[174:177], v[198:201], v[38:41]
	v_mfma_f32_16x16x32_bf16 v[14:17], v[174:177], v[206:209], v[14:17]
	v_mfma_f32_16x16x32_bf16 v[6:9], v[174:177], v[218:221], v[6:9]
	v_mfma_f32_16x16x32_bf16 v[2:5], v[182:185], v[218:221], v[2:5]
	v_mfma_f32_16x16x32_bf16 v[10:13], v[182:185], v[206:209], v[10:13]
	v_mfma_f32_16x16x32_bf16 v[34:37], v[182:185], v[198:201], v[34:37]
	v_mfma_f32_16x16x32_bf16 v[42:45], v[182:185], v[190:193], v[42:45]
	s_setprio 0
	s_barrier
	s_add_i32 s81, s81, 2
	s_add_u32 s72, s72, 0x100
	s_addc_u32 s73, s73, 0
	s_add_u32 s0, s0, 0x100
	s_addc_u32 s1, s1, 0
	s_cmpk_gt_u32 s81, 0x55
	s_cbranch_scc0 .LBB0_387
	s_and_b64 vcc, exec, s[68:69]
	s_cbranch_vccz .LBB0_390
	s_barrier

.LBB0_518:
	ds_read_b128 v[160:163], v155
	ds_read_b128 v[164:167], v155 offset:1024
	ds_read_b128 v[168:171], v155 offset:2048
	ds_read_b128 v[172:175], v155 offset:3072
	ds_read_b128 v[176:179], v156
	ds_read_b128 v[180:183], v156 offset:1024
	ds_read_b128 v[184:187], v156 offset:2048
	ds_read_b128 v[188:191], v156 offset:3072
	s_add_u32 s34, s90, 0xfff80080
	s_addc_u32 s35, s91, -1
	s_cmp_eq_u32 s83, 28
	s_cselect_b32 s93, s0, s35
	s_cselect_b32 s92, s1, s34
	s_cselect_b32 s35, s7, s68
	s_cselect_b32 s34, s9, s52
	v_lshl_add_u64 v[152:153], s[90:91], 0, v[144:145]
	s_add_i32 m0, s56, 0xc000
	ds_read_b128 v[192:195], v157
	ds_read_b128 v[196:199], v157 offset:1024
	ds_read_b128 v[200:203], v157 offset:2048
	ds_read_b128 v[204:207], v157 offset:3072
	ds_read_b128 v[208:211], v157 offset:4096
	ds_read_b128 v[212:215], v157 offset:5120
	ds_read_b128 v[218:221], v157 offset:6144
	ds_read_b128 v[222:225], v157 offset:7168
	global_load_lds_dwordx4 v[152:153], off
	v_lshl_add_u64 v[152:153], s[90:91], 0, v[146:147]
	s_add_i32 m0, s56, 0xe000
	s_nop 0
	global_load_lds_dwordx4 v[152:153], off
	s_waitcnt vmcnt(8)
	s_waitcnt lgkmcnt(0)
	s_barrier
	s_setprio 1
	s_waitcnt lgkmcnt(0)
	v_mfma_f32_16x16x32_bf16 v[126:129], v[160:163], v[192:195], v[126:129]
	v_mfma_f32_16x16x32_bf16 v[110:113], v[160:163], v[200:203], v[110:113]
	v_mfma_f32_16x16x32_bf16 v[94:97], v[160:163], v[208:211], v[94:97]
	v_mfma_f32_16x16x32_bf16 v[78:81], v[160:163], v[218:221], v[78:81]
	v_mfma_f32_16x16x32_bf16 v[74:77], v[168:171], v[218:221], v[74:77]
	v_mfma_f32_16x16x32_bf16 v[90:93], v[168:171], v[208:211], v[90:93]
	v_mfma_f32_16x16x32_bf16 v[106:109], v[168:171], v[200:203], v[106:109]
	v_mfma_f32_16x16x32_bf16 v[122:125], v[168:171], v[192:195], v[122:125]
	v_mfma_f32_16x16x32_bf16 v[126:129], v[164:167], v[196:199], v[126:129]
	v_mfma_f32_16x16x32_bf16 v[110:113], v[164:167], v[204:207], v[110:113]
	v_mfma_f32_16x16x32_bf16 v[94:97], v[164:167], v[212:215], v[94:97]
	v_mfma_f32_16x16x32_bf16 v[78:81], v[164:167], v[222:225], v[78:81]
	v_mfma_f32_16x16x32_bf16 v[74:77], v[172:175], v[222:225], v[74:77]
	v_mfma_f32_16x16x32_bf16 v[90:93], v[172:175], v[212:215], v[90:93]
	v_mfma_f32_16x16x32_bf16 v[106:109], v[172:175], v[204:207], v[106:109]
	v_mfma_f32_16x16x32_bf16 v[122:125], v[172:175], v[196:199], v[122:125]
	s_setprio 0
	s_setprio 1
	v_mfma_f32_16x16x32_bf16 v[118:121], v[176:179], v[192:195], v[118:121]
	v_mfma_f32_16x16x32_bf16 v[102:105], v[176:179], v[200:203], v[102:105]
	v_mfma_f32_16x16x32_bf16 v[86:89], v[176:179], v[208:211], v[86:89]
	v_mfma_f32_16x16x32_bf16 v[70:73], v[176:179], v[218:221], v[70:73]
	v_mfma_f32_16x16x32_bf16 v[66:69], v[184:187], v[218:221], v[66:69]
	v_mfma_f32_16x16x32_bf16 v[82:85], v[184:187], v[208:211], v[82:85]
	v_mfma_f32_16x16x32_bf16 v[98:101], v[184:187], v[200:203], v[98:101]
	v_mfma_f32_16x16x32_bf16 v[114:117], v[184:187], v[192:195], v[114:117]
	v_mfma_f32_16x16x32_bf16 v[118:121], v[180:183], v[196:199], v[118:121]
	v_mfma_f32_16x16x32_bf16 v[102:105], v[180:183], v[204:207], v[102:105]
	v_mfma_f32_16x16x32_bf16 v[86:89], v[180:183], v[212:215], v[86:89]
	v_mfma_f32_16x16x32_bf16 v[70:73], v[180:183], v[222:225], v[70:73]
	v_mfma_f32_16x16x32_bf16 v[66:69], v[188:191], v[222:225], v[66:69]
	v_mfma_f32_16x16x32_bf16 v[82:85], v[188:191], v[212:215], v[82:85]
	v_mfma_f32_16x16x32_bf16 v[98:101], v[188:191], v[204:207], v[98:101]
	v_mfma_f32_16x16x32_bf16 v[114:117], v[188:191], v[196:199], v[114:117]
	s_setprio 0
	s_barrier
	s_add_i32 s53, s75, s30
	v_lshl_add_u64 v[152:153], s[34:35], 0, v[132:133]
	s_mov_b32 m0, s53
	ds_read_b128 v[192:195], v157 offset:16384
	ds_read_b128 v[196:199], v157 offset:17408
	ds_read_b128 v[200:203], v157 offset:18432
	ds_read_b128 v[204:207], v157 offset:19456
	ds_read_b128 v[208:211], v157 offset:20480
	ds_read_b128 v[212:215], v157 offset:21504
	ds_read_b128 v[218:221], v157 offset:22528
	ds_read_b128 v[222:225], v157 offset:23552
	global_load_lds_dwordx4 v[152:153], off
	s_add_i32 m0, s53, 0x2000
	s_add_u32 s54, s34, 0x80000
	v_lshl_add_u64 v[226:227], s[34:35], 0, v[136:137]
	s_addc_u32 s55, s35, 0
	s_add_i32 s53, s94, s30
	global_load_lds_dwordx4 v[226:227], off
	v_lshl_add_u64 v[228:229], s[54:55], 0, v[132:133]
	s_mov_b32 m0, s53
	v_lshl_add_u64 v[230:231], s[92:93], 0, v[134:135]
	global_load_lds_dwordx4 v[228:229], off
	v_lshl_add_u64 v[228:229], s[54:55], 0, v[136:137]
	s_add_i32 m0, s53, 0x2000
	s_nop 0
	global_load_lds_dwordx4 v[228:229], off
	v_lshl_add_u64 v[228:229], s[92:93], 0, v[130:131]
	s_mov_b32 m0, s56
	s_nop 0
	global_load_lds_dwordx4 v[228:229], off
	s_mov_b32 m0, s57
	s_nop 0
	global_load_lds_dwordx4 v[230:231], off
	s_waitcnt vmcnt(8)
	s_waitcnt lgkmcnt(0)
	s_barrier
	s_setprio 1
	s_waitcnt lgkmcnt(0)
	v_mfma_f32_16x16x32_bf16 v[62:65], v[160:163], v[192:195], v[62:65]
	v_mfma_f32_16x16x32_bf16 v[46:49], v[160:163], v[200:203], v[46:49]
	v_mfma_f32_16x16x32_bf16 v[30:33], v[160:163], v[208:211], v[30:33]
	v_mfma_f32_16x16x32_bf16 v[14:17], v[160:163], v[218:221], v[14:17]
	v_mfma_f32_16x16x32_bf16 v[10:13], v[168:171], v[218:221], v[10:13]
	v_mfma_f32_16x16x32_bf16 v[26:29], v[168:171], v[208:211], v[26:29]
	v_mfma_f32_16x16x32_bf16 v[42:45], v[168:171], v[200:203], v[42:45]
	v_mfma_f32_16x16x32_bf16 v[58:61], v[168:171], v[192:195], v[58:61]
	v_mfma_f32_16x16x32_bf16 v[62:65], v[164:167], v[196:199], v[62:65]
	v_mfma_f32_16x16x32_bf16 v[46:49], v[164:167], v[204:207], v[46:49]
	v_mfma_f32_16x16x32_bf16 v[30:33], v[164:167], v[212:215], v[30:33]
	v_mfma_f32_16x16x32_bf16 v[14:17], v[164:167], v[222:225], v[14:17]
	v_mfma_f32_16x16x32_bf16 v[10:13], v[172:175], v[222:225], v[10:13]
	v_mfma_f32_16x16x32_bf16 v[26:29], v[172:175], v[212:215], v[26:29]
	v_mfma_f32_16x16x32_bf16 v[42:45], v[172:175], v[204:207], v[42:45]
	v_mfma_f32_16x16x32_bf16 v[58:61], v[172:175], v[196:199], v[58:61]
	s_setprio 0
	s_setprio 1
	v_mfma_f32_16x16x32_bf16 v[54:57], v[176:179], v[192:195], v[54:57]
	v_mfma_f32_16x16x32_bf16 v[38:41], v[176:179], v[200:203], v[38:41]
	v_mfma_f32_16x16x32_bf16 v[22:25], v[176:179], v[208:211], v[22:25]
	v_mfma_f32_16x16x32_bf16 v[6:9], v[176:179], v[218:221], v[6:9]
	v_mfma_f32_16x16x32_bf16 v[2:5], v[184:187], v[218:221], v[2:5]
	v_mfma_f32_16x16x32_bf16 v[18:21], v[184:187], v[208:211], v[18:21]
	v_mfma_f32_16x16x32_bf16 v[34:37], v[184:187], v[200:203], v[34:37]
	v_mfma_f32_16x16x32_bf16 v[50:53], v[184:187], v[192:195], v[50:53]
	v_mfma_f32_16x16x32_bf16 v[54:57], v[180:183], v[196:199], v[54:57]
	v_mfma_f32_16x16x32_bf16 v[38:41], v[180:183], v[204:207], v[38:41]
	v_mfma_f32_16x16x32_bf16 v[22:25], v[180:183], v[212:215], v[22:25]
	v_mfma_f32_16x16x32_bf16 v[6:9], v[180:183], v[222:225], v[6:9]
	v_mfma_f32_16x16x32_bf16 v[2:5], v[188:191], v[222:225], v[2:5]
	v_mfma_f32_16x16x32_bf16 v[18:21], v[188:191], v[212:215], v[18:21]
	v_mfma_f32_16x16x32_bf16 v[34:37], v[188:191], v[204:207], v[34:37]
	v_mfma_f32_16x16x32_bf16 v[50:53], v[188:191], v[196:199], v[50:53]
	s_setprio 0
	s_barrier
	s_add_i32 s53, 0, 0x18000
	v_add_u32_e32 v138, s53, v154
	s_add_i32 s62, 0, 0x1c000
	ds_read_b128 v[160:163], v138
	ds_read_b128 v[164:167], v138 offset:1024
	ds_read_b128 v[168:171], v138 offset:2048
	ds_read_b128 v[172:175], v138 offset:3072
	v_add_u32_e32 v138, s62, v154
	ds_read_b128 v[176:179], v138
	ds_read_b128 v[180:183], v138 offset:1024
	ds_read_b128 v[184:187], v138 offset:2048
	ds_read_b128 v[188:191], v138 offset:3072
	s_add_u32 s54, s92, 0x80000
	s_addc_u32 s55, s93, 0
	s_mov_b32 m0, s58
	v_lshl_add_u64 v[232:233], s[54:55], 0, v[130:131]
	ds_read_b128 v[192:195], v157 offset:32768
	ds_read_b128 v[196:199], v157 offset:33792
	ds_read_b128 v[200:203], v157 offset:34816
	ds_read_b128 v[204:207], v157 offset:35840
	ds_read_b128 v[208:211], v157 offset:36864
	ds_read_b128 v[212:215], v157 offset:37888
	ds_read_b128 v[218:221], v157 offset:38912
	ds_read_b128 v[222:225], v157 offset:39936
	global_load_lds_dwordx4 v[232:233], off
	v_lshl_add_u64 v[232:233], s[54:55], 0, v[134:135]
	s_mov_b32 m0, s59
	s_nop 0
	global_load_lds_dwordx4 v[232:233], off
	s_waitcnt vmcnt(8)
	s_waitcnt lgkmcnt(0)
	s_barrier
	s_setprio 1
	s_waitcnt lgkmcnt(0)
	v_mfma_f32_16x16x32_bf16 v[126:129], v[160:163], v[192:195], v[126:129]
	v_mfma_f32_16x16x32_bf16 v[110:113], v[160:163], v[200:203], v[110:113]
	v_mfma_f32_16x16x32_bf16 v[94:97], v[160:163], v[208:211], v[94:97]
	v_mfma_f32_16x16x32_bf16 v[78:81], v[160:163], v[218:221], v[78:81]
	v_mfma_f32_16x16x32_bf16 v[74:77], v[168:171], v[218:221], v[74:77]
	v_mfma_f32_16x16x32_bf16 v[90:93], v[168:171], v[208:211], v[90:93]
	v_mfma_f32_16x16x32_bf16 v[106:109], v[168:171], v[200:203], v[106:109]
	v_mfma_f32_16x16x32_bf16 v[122:125], v[168:171], v[192:195], v[122:125]
	v_mfma_f32_16x16x32_bf16 v[126:129], v[164:167], v[196:199], v[126:129]
	v_mfma_f32_16x16x32_bf16 v[110:113], v[164:167], v[204:207], v[110:113]
	v_mfma_f32_16x16x32_bf16 v[94:97], v[164:167], v[212:215], v[94:97]
	v_mfma_f32_16x16x32_bf16 v[78:81], v[164:167], v[222:225], v[78:81]
	v_mfma_f32_16x16x32_bf16 v[74:77], v[172:175], v[222:225], v[74:77]
	v_mfma_f32_16x16x32_bf16 v[90:93], v[172:175], v[212:215], v[90:93]
	v_mfma_f32_16x16x32_bf16 v[106:109], v[172:175], v[204:207], v[106:109]
	v_mfma_f32_16x16x32_bf16 v[122:125], v[172:175], v[196:199], v[122:125]
	s_setprio 0
	s_setprio 1
	v_mfma_f32_16x16x32_bf16 v[118:121], v[176:179], v[192:195], v[118:121]
	v_mfma_f32_16x16x32_bf16 v[102:105], v[176:179], v[200:203], v[102:105]
	v_mfma_f32_16x16x32_bf16 v[86:89], v[176:179], v[208:211], v[86:89]
	v_mfma_f32_16x16x32_bf16 v[70:73], v[176:179], v[218:221], v[70:73]
	v_mfma_f32_16x16x32_bf16 v[66:69], v[184:187], v[218:221], v[66:69]
	v_mfma_f32_16x16x32_bf16 v[82:85], v[184:187], v[208:211], v[82:85]
	v_mfma_f32_16x16x32_bf16 v[98:101], v[184:187], v[200:203], v[98:101]
	v_mfma_f32_16x16x32_bf16 v[114:117], v[184:187], v[192:195], v[114:117]
	v_mfma_f32_16x16x32_bf16 v[118:121], v[180:183], v[196:199], v[118:121]
	v_mfma_f32_16x16x32_bf16 v[102:105], v[180:183], v[204:207], v[102:105]
	v_mfma_f32_16x16x32_bf16 v[86:89], v[180:183], v[212:215], v[86:89]
	v_mfma_f32_16x16x32_bf16 v[70:73], v[180:183], v[222:225], v[70:73]
	v_mfma_f32_16x16x32_bf16 v[66:69], v[188:191], v[222:225], v[66:69]
	v_mfma_f32_16x16x32_bf16 v[82:85], v[188:191], v[212:215], v[82:85]
	v_mfma_f32_16x16x32_bf16 v[98:101], v[188:191], v[204:207], v[98:101]
	v_mfma_f32_16x16x32_bf16 v[114:117], v[188:191], v[196:199], v[114:117]
	s_setprio 0
	s_barrier
	s_add_i32 s53, s53, s30
	v_lshl_add_u64 v[152:153], v[152:153], 0, s[76:77]
	s_mov_b32 m0, s53
	ds_read_b128 v[192:195], v157 offset:49152
	ds_read_b128 v[196:199], v157 offset:50176
	ds_read_b128 v[200:203], v157 offset:51200
	ds_read_b128 v[204:207], v157 offset:52224
	ds_read_b128 v[208:211], v157 offset:53248
	ds_read_b128 v[212:215], v157 offset:54272
	ds_read_b128 v[218:221], v157 offset:55296
	ds_read_b128 v[222:225], v157 offset:56320
	global_load_lds_dwordx4 v[152:153], off
	s_add_i32 m0, s53, 0x2000
	s_add_u32 s34, s34, 0x80080
	v_lshl_add_u64 v[152:153], v[226:227], 0, s[76:77]
	s_addc_u32 s35, s35, 0
	s_add_i32 s53, s62, s30
	global_load_lds_dwordx4 v[152:153], off
	v_lshl_add_u64 v[152:153], s[34:35], 0, v[132:133]
	s_mov_b32 m0, s53
	s_nop 0
	global_load_lds_dwordx4 v[152:153], off
	v_lshl_add_u64 v[152:153], s[34:35], 0, v[136:137]
	s_add_i32 m0, s53, 0x2000
	s_nop 0
	global_load_lds_dwordx4 v[152:153], off
	v_lshl_add_u64 v[152:153], v[228:229], 0, s[76:77]
	s_mov_b32 m0, s61
	s_nop 0
	global_load_lds_dwordx4 v[152:153], off
	v_lshl_add_u64 v[152:153], v[230:231], 0, s[76:77]
	s_mov_b32 m0, s72
	s_nop 0
	global_load_lds_dwordx4 v[152:153], off
	s_waitcnt vmcnt(8)
	s_waitcnt lgkmcnt(0)
	s_barrier
	s_setprio 1
	s_waitcnt lgkmcnt(0)
	v_mfma_f32_16x16x32_bf16 v[62:65], v[160:163], v[192:195], v[62:65]
	v_mfma_f32_16x16x32_bf16 v[46:49], v[160:163], v[200:203], v[46:49]
	v_mfma_f32_16x16x32_bf16 v[30:33], v[160:163], v[208:211], v[30:33]
	v_mfma_f32_16x16x32_bf16 v[14:17], v[160:163], v[218:221], v[14:17]
	v_mfma_f32_16x16x32_bf16 v[10:13], v[168:171], v[218:221], v[10:13]
	v_mfma_f32_16x16x32_bf16 v[26:29], v[168:171], v[208:211], v[26:29]
	v_mfma_f32_16x16x32_bf16 v[42:45], v[168:171], v[200:203], v[42:45]
	v_mfma_f32_16x16x32_bf16 v[58:61], v[168:171], v[192:195], v[58:61]
	v_mfma_f32_16x16x32_bf16 v[62:65], v[164:167], v[196:199], v[62:65]
	v_mfma_f32_16x16x32_bf16 v[46:49], v[164:167], v[204:207], v[46:49]
	v_mfma_f32_16x16x32_bf16 v[30:33], v[164:167], v[212:215], v[30:33]
	v_mfma_f32_16x16x32_bf16 v[14:17], v[164:167], v[222:225], v[14:17]
	v_mfma_f32_16x16x32_bf16 v[10:13], v[172:175], v[222:225], v[10:13]
	v_mfma_f32_16x16x32_bf16 v[26:29], v[172:175], v[212:215], v[26:29]
	v_mfma_f32_16x16x32_bf16 v[42:45], v[172:175], v[204:207], v[42:45]
	v_mfma_f32_16x16x32_bf16 v[58:61], v[172:175], v[196:199], v[58:61]
	s_setprio 0
	s_setprio 1
	v_mfma_f32_16x16x32_bf16 v[54:57], v[176:179], v[192:195], v[54:57]
	v_mfma_f32_16x16x32_bf16 v[38:41], v[176:179], v[200:203], v[38:41]
	v_mfma_f32_16x16x32_bf16 v[22:25], v[176:179], v[208:211], v[22:25]
	v_mfma_f32_16x16x32_bf16 v[6:9], v[176:179], v[218:221], v[6:9]
	v_mfma_f32_16x16x32_bf16 v[2:5], v[184:187], v[218:221], v[2:5]
	v_mfma_f32_16x16x32_bf16 v[18:21], v[184:187], v[208:211], v[18:21]
	v_mfma_f32_16x16x32_bf16 v[34:37], v[184:187], v[200:203], v[34:37]
	v_mfma_f32_16x16x32_bf16 v[50:53], v[184:187], v[192:195], v[50:53]
	v_mfma_f32_16x16x32_bf16 v[54:57], v[180:183], v[196:199], v[54:57]
	v_mfma_f32_16x16x32_bf16 v[38:41], v[180:183], v[204:207], v[38:41]
	v_mfma_f32_16x16x32_bf16 v[22:25], v[180:183], v[212:215], v[22:25]
	v_mfma_f32_16x16x32_bf16 v[6:9], v[180:183], v[222:225], v[6:9]
	v_mfma_f32_16x16x32_bf16 v[2:5], v[188:191], v[222:225], v[2:5]
	v_mfma_f32_16x16x32_bf16 v[18:21], v[188:191], v[212:215], v[18:21]
	v_mfma_f32_16x16x32_bf16 v[34:37], v[188:191], v[204:207], v[34:37]
	v_mfma_f32_16x16x32_bf16 v[50:53], v[188:191], v[196:199], v[50:53]
	s_setprio 0
	s_barrier
	s_add_i32 s83, s83, 2
	s_add_u32 s90, s90, 0x100
	s_addc_u32 s91, s91, 0
	s_add_u32 s52, s52, 0x100
	s_addc_u32 s68, s68, 0
	s_cmp_gt_u32 s83, 29
	s_cbranch_scc0 .LBB0_518
	s_and_b64 vcc, exec, s[78:79]
	s_cbranch_vccz .LBB0_521
	s_barrier

.LBB0_685:
	ds_read_b128 v[146:149], v165
	ds_read_b128 v[150:153], v165 offset:1024
	ds_read_b128 v[168:171], v165 offset:2048
	ds_read_b128 v[172:175], v165 offset:3072
	ds_read_b128 v[176:179], v166
	ds_read_b128 v[180:183], v166 offset:1024
	ds_read_b128 v[184:187], v166 offset:2048
	ds_read_b128 v[188:191], v166 offset:3072
	s_add_u32 s34, s84, 0xfffe0080
	s_addc_u32 s35, s85, -1
	s_cmp_eq_u32 s89, 4
	s_cselect_b32 s87, s0, s35
	s_cselect_b32 s86, s1, s34
	s_cselect_b32 s35, s52, s88
	s_cselect_b32 s34, s71, s77
	v_lshl_add_u64 v[226:227], s[84:85], 0, v[138:139]
	s_add_i32 m0, s33, 0xc000
	ds_read_b128 v[192:195], v167
	ds_read_b128 v[196:199], v167 offset:1024
	ds_read_b128 v[200:203], v167 offset:2048
	ds_read_b128 v[204:207], v167 offset:3072
	ds_read_b128 v[208:211], v167 offset:4096
	ds_read_b128 v[212:215], v167 offset:5120
	ds_read_b128 v[218:221], v167 offset:6144
	ds_read_b128 v[222:225], v167 offset:7168
	global_load_lds_dwordx4 v[226:227], off
	v_lshl_add_u64 v[226:227], s[84:85], 0, v[140:141]
	s_add_i32 m0, s33, 0xe000
	s_nop 0
	global_load_lds_dwordx4 v[226:227], off
	s_waitcnt vmcnt(8)
	s_waitcnt lgkmcnt(0)
	s_barrier
	s_setprio 1
	s_waitcnt lgkmcnt(0)
	v_mfma_f32_16x16x32_bf16 v[126:129], v[146:149], v[192:195], v[126:129]
	v_mfma_f32_16x16x32_bf16 v[114:117], v[146:149], v[200:203], v[114:117]
	v_mfma_f32_16x16x32_bf16 v[98:101], v[146:149], v[208:211], v[98:101]
	v_mfma_f32_16x16x32_bf16 v[82:85], v[146:149], v[218:221], v[82:85]
	v_mfma_f32_16x16x32_bf16 v[74:77], v[168:171], v[218:221], v[74:77]
	v_mfma_f32_16x16x32_bf16 v[90:93], v[168:171], v[208:211], v[90:93]
	v_mfma_f32_16x16x32_bf16 v[106:109], v[168:171], v[200:203], v[106:109]
	v_mfma_f32_16x16x32_bf16 v[122:125], v[168:171], v[192:195], v[122:125]
	v_mfma_f32_16x16x32_bf16 v[126:129], v[150:153], v[196:199], v[126:129]
	v_mfma_f32_16x16x32_bf16 v[114:117], v[150:153], v[204:207], v[114:117]
	v_mfma_f32_16x16x32_bf16 v[98:101], v[150:153], v[212:215], v[98:101]
	v_mfma_f32_16x16x32_bf16 v[82:85], v[150:153], v[222:225], v[82:85]
	v_mfma_f32_16x16x32_bf16 v[74:77], v[172:175], v[222:225], v[74:77]
	v_mfma_f32_16x16x32_bf16 v[90:93], v[172:175], v[212:215], v[90:93]
	v_mfma_f32_16x16x32_bf16 v[106:109], v[172:175], v[204:207], v[106:109]
	v_mfma_f32_16x16x32_bf16 v[122:125], v[172:175], v[196:199], v[122:125]
	s_setprio 0
	s_setprio 1
	v_mfma_f32_16x16x32_bf16 v[118:121], v[176:179], v[192:195], v[118:121]
	v_mfma_f32_16x16x32_bf16 v[102:105], v[176:179], v[200:203], v[102:105]
	v_mfma_f32_16x16x32_bf16 v[86:89], v[176:179], v[208:211], v[86:89]
	v_mfma_f32_16x16x32_bf16 v[70:73], v[176:179], v[218:221], v[70:73]
	v_mfma_f32_16x16x32_bf16 v[66:69], v[184:187], v[218:221], v[66:69]
	v_mfma_f32_16x16x32_bf16 v[78:81], v[184:187], v[208:211], v[78:81]
	v_mfma_f32_16x16x32_bf16 v[94:97], v[184:187], v[200:203], v[94:97]
	v_mfma_f32_16x16x32_bf16 v[110:113], v[184:187], v[192:195], v[110:113]
	v_mfma_f32_16x16x32_bf16 v[118:121], v[180:183], v[196:199], v[118:121]
	v_mfma_f32_16x16x32_bf16 v[102:105], v[180:183], v[204:207], v[102:105]
	v_mfma_f32_16x16x32_bf16 v[86:89], v[180:183], v[212:215], v[86:89]
	v_mfma_f32_16x16x32_bf16 v[70:73], v[180:183], v[222:225], v[70:73]
	v_mfma_f32_16x16x32_bf16 v[66:69], v[188:191], v[222:225], v[66:69]
	v_mfma_f32_16x16x32_bf16 v[78:81], v[188:191], v[212:215], v[78:81]
	v_mfma_f32_16x16x32_bf16 v[94:97], v[188:191], v[204:207], v[94:97]
	v_mfma_f32_16x16x32_bf16 v[110:113], v[188:191], v[196:199], v[110:113]
	s_setprio 0
	s_barrier
	s_add_i32 s53, s73, s12
	v_lshl_add_u64 v[226:227], s[34:35], 0, v[132:133]
	s_mov_b32 m0, s53
	ds_read_b128 v[192:195], v167 offset:16384
	ds_read_b128 v[196:199], v167 offset:17408
	ds_read_b128 v[200:203], v167 offset:18432
	ds_read_b128 v[204:207], v167 offset:19456
	ds_read_b128 v[208:211], v167 offset:20480
	ds_read_b128 v[212:215], v167 offset:21504
	ds_read_b128 v[218:221], v167 offset:22528
	ds_read_b128 v[222:225], v167 offset:23552
	global_load_lds_dwordx4 v[226:227], off
	s_add_i32 m0, s53, 0x2000
	s_add_u32 s54, s34, 0x20000
	v_lshl_add_u64 v[228:229], s[34:35], 0, v[136:137]
	s_addc_u32 s55, s35, 0
	s_add_i32 s53, s74, s12
	global_load_lds_dwordx4 v[228:229], off
	v_lshl_add_u64 v[230:231], s[54:55], 0, v[132:133]
	s_mov_b32 m0, s53
	v_lshl_add_u64 v[232:233], s[86:87], 0, v[134:135]
	global_load_lds_dwordx4 v[230:231], off
	v_lshl_add_u64 v[230:231], s[54:55], 0, v[136:137]
	s_add_i32 m0, s53, 0x2000
	s_nop 0
	global_load_lds_dwordx4 v[230:231], off
	v_lshl_add_u64 v[230:231], s[86:87], 0, v[130:131]
	s_mov_b32 m0, s33
	s_nop 0
	global_load_lds_dwordx4 v[230:231], off
	s_mov_b32 m0, s56
	s_nop 0
	global_load_lds_dwordx4 v[232:233], off
	s_waitcnt vmcnt(8)
	s_waitcnt lgkmcnt(0)
	s_barrier
	s_setprio 1
	s_waitcnt lgkmcnt(0)
	v_mfma_f32_16x16x32_bf16 v[62:65], v[146:149], v[192:195], v[62:65]
	v_mfma_f32_16x16x32_bf16 v[50:53], v[146:149], v[200:203], v[50:53]
	v_mfma_f32_16x16x32_bf16 v[34:37], v[146:149], v[208:211], v[34:37]
	v_mfma_f32_16x16x32_bf16 v[18:21], v[146:149], v[218:221], v[18:21]
	v_mfma_f32_16x16x32_bf16 v[10:13], v[168:171], v[218:221], v[10:13]
	v_mfma_f32_16x16x32_bf16 v[26:29], v[168:171], v[208:211], v[26:29]
	v_mfma_f32_16x16x32_bf16 v[42:45], v[168:171], v[200:203], v[42:45]
	v_mfma_f32_16x16x32_bf16 v[58:61], v[168:171], v[192:195], v[58:61]
	v_mfma_f32_16x16x32_bf16 v[62:65], v[150:153], v[196:199], v[62:65]
	v_mfma_f32_16x16x32_bf16 v[50:53], v[150:153], v[204:207], v[50:53]
	v_mfma_f32_16x16x32_bf16 v[34:37], v[150:153], v[212:215], v[34:37]
	v_mfma_f32_16x16x32_bf16 v[18:21], v[150:153], v[222:225], v[18:21]
	v_mfma_f32_16x16x32_bf16 v[10:13], v[172:175], v[222:225], v[10:13]
	v_mfma_f32_16x16x32_bf16 v[26:29], v[172:175], v[212:215], v[26:29]
	v_mfma_f32_16x16x32_bf16 v[42:45], v[172:175], v[204:207], v[42:45]
	v_mfma_f32_16x16x32_bf16 v[58:61], v[172:175], v[196:199], v[58:61]
	s_setprio 0
	s_setprio 1
	v_mfma_f32_16x16x32_bf16 v[54:57], v[176:179], v[192:195], v[54:57]
	v_mfma_f32_16x16x32_bf16 v[38:41], v[176:179], v[200:203], v[38:41]
	v_mfma_f32_16x16x32_bf16 v[22:25], v[176:179], v[208:211], v[22:25]
	v_mfma_f32_16x16x32_bf16 v[6:9], v[176:179], v[218:221], v[6:9]
	v_mfma_f32_16x16x32_bf16 v[2:5], v[184:187], v[218:221], v[2:5]
	v_mfma_f32_16x16x32_bf16 v[14:17], v[184:187], v[208:211], v[14:17]
	v_mfma_f32_16x16x32_bf16 v[30:33], v[184:187], v[200:203], v[30:33]
	v_mfma_f32_16x16x32_bf16 v[46:49], v[184:187], v[192:195], v[46:49]
	v_mfma_f32_16x16x32_bf16 v[54:57], v[180:183], v[196:199], v[54:57]
	v_mfma_f32_16x16x32_bf16 v[38:41], v[180:183], v[204:207], v[38:41]
	v_mfma_f32_16x16x32_bf16 v[22:25], v[180:183], v[212:215], v[22:25]
	v_mfma_f32_16x16x32_bf16 v[6:9], v[180:183], v[222:225], v[6:9]
	v_mfma_f32_16x16x32_bf16 v[2:5], v[188:191], v[222:225], v[2:5]
	v_mfma_f32_16x16x32_bf16 v[14:17], v[188:191], v[212:215], v[14:17]
	v_mfma_f32_16x16x32_bf16 v[30:33], v[188:191], v[204:207], v[30:33]
	v_mfma_f32_16x16x32_bf16 v[46:49], v[188:191], v[196:199], v[46:49]
	s_setprio 0
	s_barrier
	s_add_i32 s53, 0, 0x18000
	s_add_i32 s62, 0, 0x1c000
	v_add_u32_e32 v172, s53, v162
	v_add_u32_e32 v188, s62, v162
	ds_read_b128 v[146:149], v172
	ds_read_b128 v[150:153], v172 offset:1024
	ds_read_b128 v[168:171], v172 offset:2048
	ds_read_b128 v[172:175], v172 offset:3072
	ds_read_b128 v[176:179], v188
	ds_read_b128 v[180:183], v188 offset:1024
	ds_read_b128 v[184:187], v188 offset:2048
	ds_read_b128 v[188:191], v188 offset:3072
	s_add_u32 s54, s86, 0x20000
	s_addc_u32 s55, s87, 0
	s_mov_b32 m0, s57
	v_lshl_add_u64 v[234:235], s[54:55], 0, v[130:131]
	ds_read_b128 v[192:195], v167 offset:32768
	ds_read_b128 v[196:199], v167 offset:33792
	ds_read_b128 v[200:203], v167 offset:34816
	ds_read_b128 v[204:207], v167 offset:35840
	ds_read_b128 v[208:211], v167 offset:36864
	ds_read_b128 v[212:215], v167 offset:37888
	ds_read_b128 v[218:221], v167 offset:38912
	ds_read_b128 v[222:225], v167 offset:39936
	global_load_lds_dwordx4 v[234:235], off
	v_lshl_add_u64 v[234:235], s[54:55], 0, v[134:135]
	s_mov_b32 m0, s58
	s_nop 0
	global_load_lds_dwordx4 v[234:235], off
	s_waitcnt vmcnt(8)
	s_waitcnt lgkmcnt(0)
	s_barrier
	s_setprio 1
	s_waitcnt lgkmcnt(0)
	v_mfma_f32_16x16x32_bf16 v[126:129], v[146:149], v[192:195], v[126:129]
	v_mfma_f32_16x16x32_bf16 v[114:117], v[146:149], v[200:203], v[114:117]
	v_mfma_f32_16x16x32_bf16 v[98:101], v[146:149], v[208:211], v[98:101]
	v_mfma_f32_16x16x32_bf16 v[82:85], v[146:149], v[218:221], v[82:85]
	v_mfma_f32_16x16x32_bf16 v[74:77], v[168:171], v[218:221], v[74:77]
	v_mfma_f32_16x16x32_bf16 v[90:93], v[168:171], v[208:211], v[90:93]
	v_mfma_f32_16x16x32_bf16 v[106:109], v[168:171], v[200:203], v[106:109]
	v_mfma_f32_16x16x32_bf16 v[122:125], v[168:171], v[192:195], v[122:125]
	v_mfma_f32_16x16x32_bf16 v[126:129], v[150:153], v[196:199], v[126:129]
	v_mfma_f32_16x16x32_bf16 v[114:117], v[150:153], v[204:207], v[114:117]
	v_mfma_f32_16x16x32_bf16 v[98:101], v[150:153], v[212:215], v[98:101]
	v_mfma_f32_16x16x32_bf16 v[82:85], v[150:153], v[222:225], v[82:85]
	v_mfma_f32_16x16x32_bf16 v[74:77], v[172:175], v[222:225], v[74:77]
	v_mfma_f32_16x16x32_bf16 v[90:93], v[172:175], v[212:215], v[90:93]
	v_mfma_f32_16x16x32_bf16 v[106:109], v[172:175], v[204:207], v[106:109]
	v_mfma_f32_16x16x32_bf16 v[122:125], v[172:175], v[196:199], v[122:125]
	s_setprio 0
	s_setprio 1
	v_mfma_f32_16x16x32_bf16 v[118:121], v[176:179], v[192:195], v[118:121]
	v_mfma_f32_16x16x32_bf16 v[102:105], v[176:179], v[200:203], v[102:105]
	v_mfma_f32_16x16x32_bf16 v[86:89], v[176:179], v[208:211], v[86:89]
	v_mfma_f32_16x16x32_bf16 v[70:73], v[176:179], v[218:221], v[70:73]
	v_mfma_f32_16x16x32_bf16 v[66:69], v[184:187], v[218:221], v[66:69]
	v_mfma_f32_16x16x32_bf16 v[78:81], v[184:187], v[208:211], v[78:81]
	v_mfma_f32_16x16x32_bf16 v[94:97], v[184:187], v[200:203], v[94:97]
	v_mfma_f32_16x16x32_bf16 v[110:113], v[184:187], v[192:195], v[110:113]
	v_mfma_f32_16x16x32_bf16 v[118:121], v[180:183], v[196:199], v[118:121]
	v_mfma_f32_16x16x32_bf16 v[102:105], v[180:183], v[204:207], v[102:105]
	v_mfma_f32_16x16x32_bf16 v[86:89], v[180:183], v[212:215], v[86:89]
	v_mfma_f32_16x16x32_bf16 v[70:73], v[180:183], v[222:225], v[70:73]
	v_mfma_f32_16x16x32_bf16 v[66:69], v[188:191], v[222:225], v[66:69]
	v_mfma_f32_16x16x32_bf16 v[78:81], v[188:191], v[212:215], v[78:81]
	v_mfma_f32_16x16x32_bf16 v[94:97], v[188:191], v[204:207], v[94:97]
	v_mfma_f32_16x16x32_bf16 v[110:113], v[188:191], v[196:199], v[110:113]
	s_setprio 0
	s_barrier
	s_add_i32 s53, s53, s12
	v_lshl_add_u64 v[226:227], v[226:227], 0, s[8:9]
	s_mov_b32 m0, s53
	ds_read_b128 v[192:195], v167 offset:49152
	ds_read_b128 v[196:199], v167 offset:50176
	ds_read_b128 v[200:203], v167 offset:51200
	ds_read_b128 v[204:207], v167 offset:52224
	ds_read_b128 v[208:211], v167 offset:53248
	ds_read_b128 v[212:215], v167 offset:54272
	ds_read_b128 v[218:221], v167 offset:55296
	ds_read_b128 v[222:225], v167 offset:56320
	global_load_lds_dwordx4 v[226:227], off
	s_add_i32 m0, s53, 0x2000
	s_add_u32 s34, s34, 0x20080
	v_lshl_add_u64 v[226:227], v[228:229], 0, s[8:9]
	s_addc_u32 s35, s35, 0
	s_add_i32 s53, s62, s12
	global_load_lds_dwordx4 v[226:227], off
	v_lshl_add_u64 v[226:227], s[34:35], 0, v[132:133]
	s_mov_b32 m0, s53
	s_nop 0
	global_load_lds_dwordx4 v[226:227], off
	v_lshl_add_u64 v[226:227], s[34:35], 0, v[136:137]
	s_add_i32 m0, s53, 0x2000
	s_nop 0
	global_load_lds_dwordx4 v[226:227], off
	v_lshl_add_u64 v[226:227], v[230:231], 0, s[8:9]
	s_mov_b32 m0, s60
	s_nop 0
	global_load_lds_dwordx4 v[226:227], off
	v_lshl_add_u64 v[226:227], v[232:233], 0, s[8:9]
	s_mov_b32 m0, s61
	s_nop 0
	global_load_lds_dwordx4 v[226:227], off
	s_waitcnt vmcnt(8)
	s_waitcnt lgkmcnt(0)
	s_barrier
	s_setprio 1
	s_waitcnt lgkmcnt(0)
	v_mfma_f32_16x16x32_bf16 v[62:65], v[146:149], v[192:195], v[62:65]
	v_mfma_f32_16x16x32_bf16 v[50:53], v[146:149], v[200:203], v[50:53]
	v_mfma_f32_16x16x32_bf16 v[34:37], v[146:149], v[208:211], v[34:37]
	v_mfma_f32_16x16x32_bf16 v[18:21], v[146:149], v[218:221], v[18:21]
	v_mfma_f32_16x16x32_bf16 v[10:13], v[168:171], v[218:221], v[10:13]
	v_mfma_f32_16x16x32_bf16 v[26:29], v[168:171], v[208:211], v[26:29]
	v_mfma_f32_16x16x32_bf16 v[42:45], v[168:171], v[200:203], v[42:45]
	v_mfma_f32_16x16x32_bf16 v[58:61], v[168:171], v[192:195], v[58:61]
	v_mfma_f32_16x16x32_bf16 v[62:65], v[150:153], v[196:199], v[62:65]
	v_mfma_f32_16x16x32_bf16 v[50:53], v[150:153], v[204:207], v[50:53]
	v_mfma_f32_16x16x32_bf16 v[34:37], v[150:153], v[212:215], v[34:37]
	v_mfma_f32_16x16x32_bf16 v[18:21], v[150:153], v[222:225], v[18:21]
	v_mfma_f32_16x16x32_bf16 v[10:13], v[172:175], v[222:225], v[10:13]
	v_mfma_f32_16x16x32_bf16 v[26:29], v[172:175], v[212:215], v[26:29]
	v_mfma_f32_16x16x32_bf16 v[42:45], v[172:175], v[204:207], v[42:45]
	v_mfma_f32_16x16x32_bf16 v[58:61], v[172:175], v[196:199], v[58:61]
	s_setprio 0
	s_setprio 1
	v_mfma_f32_16x16x32_bf16 v[54:57], v[176:179], v[192:195], v[54:57]
	v_mfma_f32_16x16x32_bf16 v[38:41], v[176:179], v[200:203], v[38:41]
	v_mfma_f32_16x16x32_bf16 v[22:25], v[176:179], v[208:211], v[22:25]
	v_mfma_f32_16x16x32_bf16 v[6:9], v[176:179], v[218:221], v[6:9]
	v_mfma_f32_16x16x32_bf16 v[2:5], v[184:187], v[218:221], v[2:5]
	v_mfma_f32_16x16x32_bf16 v[14:17], v[184:187], v[208:211], v[14:17]
	v_mfma_f32_16x16x32_bf16 v[30:33], v[184:187], v[200:203], v[30:33]
	v_mfma_f32_16x16x32_bf16 v[46:49], v[184:187], v[192:195], v[46:49]
	v_mfma_f32_16x16x32_bf16 v[54:57], v[180:183], v[196:199], v[54:57]
	v_mfma_f32_16x16x32_bf16 v[38:41], v[180:183], v[204:207], v[38:41]
	v_mfma_f32_16x16x32_bf16 v[22:25], v[180:183], v[212:215], v[22:25]
	v_mfma_f32_16x16x32_bf16 v[6:9], v[180:183], v[222:225], v[6:9]
	v_mfma_f32_16x16x32_bf16 v[2:5], v[188:191], v[222:225], v[2:5]
	v_mfma_f32_16x16x32_bf16 v[14:17], v[188:191], v[212:215], v[14:17]
	v_mfma_f32_16x16x32_bf16 v[30:33], v[188:191], v[204:207], v[30:33]
	v_mfma_f32_16x16x32_bf16 v[46:49], v[188:191], v[196:199], v[46:49]
	s_setprio 0
	s_barrier
	s_add_i32 s89, s89, 2
	s_add_u32 s84, s84, 0x100
	s_addc_u32 s85, s85, 0
	s_add_u32 s77, s77, 0x100
	s_addc_u32 s88, s88, 0
	s_cmp_gt_u32 s89, 5
	s_cbranch_scc0 .LBB0_685
	s_and_b64 vcc, exec, s[66:67]
	s_cbranch_vccz .LBB0_688
	s_barrier

.LBB0_715:
	ds_read_b128 v[146:149], v1
	ds_read_b128 v[160:163], v1 offset:1024
	ds_read_b128 v[164:167], v1 offset:2048
	ds_read_b128 v[168:171], v1 offset:3072
	ds_read_b128 v[172:175], v154
	ds_read_b128 v[176:179], v154 offset:1024
	ds_read_b128 v[180:183], v154 offset:2048
	ds_read_b128 v[184:187], v154 offset:3072
	s_add_u32 s34, s84, 0xfffe0080
	s_addc_u32 s35, s85, -1
	s_cmp_eq_u32 s88, 4
	s_cselect_b32 s87, s0, s35
	s_cselect_b32 s86, s1, s34
	s_cselect_b32 s35, s52, s83
	s_cselect_b32 s34, s71, s77
	v_lshl_add_u64 v[150:151], s[84:85], 0, v[138:139]
	s_add_i32 m0, s33, 0xc000
	ds_read_b128 v[188:191], v155
	ds_read_b128 v[192:195], v155 offset:1024
	ds_read_b128 v[196:199], v155 offset:2048
	ds_read_b128 v[200:203], v155 offset:3072
	ds_read_b128 v[204:207], v155 offset:4096
	ds_read_b128 v[208:211], v155 offset:5120
	ds_read_b128 v[212:215], v155 offset:6144
	ds_read_b128 v[218:221], v155 offset:7168
	global_load_lds_dwordx4 v[150:151], off
	v_lshl_add_u64 v[150:151], s[84:85], 0, v[140:141]
	s_add_i32 m0, s33, 0xe000
	s_nop 0
	global_load_lds_dwordx4 v[150:151], off
	s_waitcnt vmcnt(8)
	s_waitcnt lgkmcnt(0)
	s_barrier
	s_setprio 1
	s_waitcnt lgkmcnt(0)
	v_mfma_f32_16x16x32_bf16 v[126:129], v[146:149], v[188:191], v[126:129]
	v_mfma_f32_16x16x32_bf16 v[110:113], v[146:149], v[196:199], v[110:113]
	v_mfma_f32_16x16x32_bf16 v[94:97], v[146:149], v[204:207], v[94:97]
	v_mfma_f32_16x16x32_bf16 v[78:81], v[146:149], v[212:215], v[78:81]
	v_mfma_f32_16x16x32_bf16 v[74:77], v[164:167], v[212:215], v[74:77]
	v_mfma_f32_16x16x32_bf16 v[90:93], v[164:167], v[204:207], v[90:93]
	v_mfma_f32_16x16x32_bf16 v[106:109], v[164:167], v[196:199], v[106:109]
	v_mfma_f32_16x16x32_bf16 v[122:125], v[164:167], v[188:191], v[122:125]
	v_mfma_f32_16x16x32_bf16 v[126:129], v[160:163], v[192:195], v[126:129]
	v_mfma_f32_16x16x32_bf16 v[110:113], v[160:163], v[200:203], v[110:113]
	v_mfma_f32_16x16x32_bf16 v[94:97], v[160:163], v[208:211], v[94:97]
	v_mfma_f32_16x16x32_bf16 v[78:81], v[160:163], v[218:221], v[78:81]
	v_mfma_f32_16x16x32_bf16 v[74:77], v[168:171], v[218:221], v[74:77]
	v_mfma_f32_16x16x32_bf16 v[90:93], v[168:171], v[208:211], v[90:93]
	v_mfma_f32_16x16x32_bf16 v[106:109], v[168:171], v[200:203], v[106:109]
	v_mfma_f32_16x16x32_bf16 v[122:125], v[168:171], v[192:195], v[122:125]
	s_setprio 0
	s_setprio 1
	v_mfma_f32_16x16x32_bf16 v[118:121], v[172:175], v[188:191], v[118:121]
	v_mfma_f32_16x16x32_bf16 v[102:105], v[172:175], v[196:199], v[102:105]
	v_mfma_f32_16x16x32_bf16 v[86:89], v[172:175], v[204:207], v[86:89]
	v_mfma_f32_16x16x32_bf16 v[70:73], v[172:175], v[212:215], v[70:73]
	v_mfma_f32_16x16x32_bf16 v[66:69], v[180:183], v[212:215], v[66:69]
	v_mfma_f32_16x16x32_bf16 v[82:85], v[180:183], v[204:207], v[82:85]
	v_mfma_f32_16x16x32_bf16 v[98:101], v[180:183], v[196:199], v[98:101]
	v_mfma_f32_16x16x32_bf16 v[114:117], v[180:183], v[188:191], v[114:117]
	v_mfma_f32_16x16x32_bf16 v[118:121], v[176:179], v[192:195], v[118:121]
	v_mfma_f32_16x16x32_bf16 v[102:105], v[176:179], v[200:203], v[102:105]
	v_mfma_f32_16x16x32_bf16 v[86:89], v[176:179], v[208:211], v[86:89]
	v_mfma_f32_16x16x32_bf16 v[70:73], v[176:179], v[218:221], v[70:73]
	v_mfma_f32_16x16x32_bf16 v[66:69], v[184:187], v[218:221], v[66:69]
	v_mfma_f32_16x16x32_bf16 v[82:85], v[184:187], v[208:211], v[82:85]
	v_mfma_f32_16x16x32_bf16 v[98:101], v[184:187], v[200:203], v[98:101]
	v_mfma_f32_16x16x32_bf16 v[114:117], v[184:187], v[192:195], v[114:117]
	s_setprio 0
	s_barrier
	s_add_i32 s53, s73, s13
	v_lshl_add_u64 v[150:151], s[34:35], 0, v[132:133]
	s_mov_b32 m0, s53
	ds_read_b128 v[188:191], v155 offset:16384
	ds_read_b128 v[192:195], v155 offset:17408
	ds_read_b128 v[196:199], v155 offset:18432
	ds_read_b128 v[200:203], v155 offset:19456
	ds_read_b128 v[204:207], v155 offset:20480
	ds_read_b128 v[208:211], v155 offset:21504
	ds_read_b128 v[212:215], v155 offset:22528
	ds_read_b128 v[218:221], v155 offset:23552
	global_load_lds_dwordx4 v[150:151], off
	s_add_i32 m0, s53, 0x2000
	s_add_u32 s54, s34, 0x20000
	v_lshl_add_u64 v[222:223], s[34:35], 0, v[136:137]
	s_addc_u32 s55, s35, 0
	s_add_i32 s53, s74, s13
	global_load_lds_dwordx4 v[222:223], off
	v_lshl_add_u64 v[224:225], s[54:55], 0, v[132:133]
	s_mov_b32 m0, s53
	v_lshl_add_u64 v[226:227], s[86:87], 0, v[134:135]
	global_load_lds_dwordx4 v[224:225], off
	v_lshl_add_u64 v[224:225], s[54:55], 0, v[136:137]
	s_add_i32 m0, s53, 0x2000
	s_nop 0
	global_load_lds_dwordx4 v[224:225], off
	v_lshl_add_u64 v[224:225], s[86:87], 0, v[130:131]
	s_mov_b32 m0, s33
	s_nop 0
	global_load_lds_dwordx4 v[224:225], off
	s_mov_b32 m0, s56
	s_nop 0
	global_load_lds_dwordx4 v[226:227], off
	s_waitcnt vmcnt(8)
	s_waitcnt lgkmcnt(0)
	s_barrier
	s_setprio 1
	s_waitcnt lgkmcnt(0)
	v_mfma_f32_16x16x32_bf16 v[62:65], v[146:149], v[188:191], v[62:65]
	v_mfma_f32_16x16x32_bf16 v[50:53], v[146:149], v[196:199], v[50:53]
	v_mfma_f32_16x16x32_bf16 v[34:37], v[146:149], v[204:207], v[34:37]
	v_mfma_f32_16x16x32_bf16 v[18:21], v[146:149], v[212:215], v[18:21]
	v_mfma_f32_16x16x32_bf16 v[10:13], v[164:167], v[212:215], v[10:13]
	v_mfma_f32_16x16x32_bf16 v[26:29], v[164:167], v[204:207], v[26:29]
	v_mfma_f32_16x16x32_bf16 v[42:45], v[164:167], v[196:199], v[42:45]
	v_mfma_f32_16x16x32_bf16 v[58:61], v[164:167], v[188:191], v[58:61]
	v_mfma_f32_16x16x32_bf16 v[62:65], v[160:163], v[192:195], v[62:65]
	v_mfma_f32_16x16x32_bf16 v[50:53], v[160:163], v[200:203], v[50:53]
	v_mfma_f32_16x16x32_bf16 v[34:37], v[160:163], v[208:211], v[34:37]
	v_mfma_f32_16x16x32_bf16 v[18:21], v[160:163], v[218:221], v[18:21]
	v_mfma_f32_16x16x32_bf16 v[10:13], v[168:171], v[218:221], v[10:13]
	v_mfma_f32_16x16x32_bf16 v[26:29], v[168:171], v[208:211], v[26:29]
	v_mfma_f32_16x16x32_bf16 v[42:45], v[168:171], v[200:203], v[42:45]
	v_mfma_f32_16x16x32_bf16 v[58:61], v[168:171], v[192:195], v[58:61]
	s_setprio 0
	s_setprio 1
	v_mfma_f32_16x16x32_bf16 v[54:57], v[172:175], v[188:191], v[54:57]
	v_mfma_f32_16x16x32_bf16 v[38:41], v[172:175], v[196:199], v[38:41]
	v_mfma_f32_16x16x32_bf16 v[22:25], v[172:175], v[204:207], v[22:25]
	v_mfma_f32_16x16x32_bf16 v[6:9], v[172:175], v[212:215], v[6:9]
	v_mfma_f32_16x16x32_bf16 v[2:5], v[180:183], v[212:215], v[2:5]
	v_mfma_f32_16x16x32_bf16 v[14:17], v[180:183], v[204:207], v[14:17]
	v_mfma_f32_16x16x32_bf16 v[30:33], v[180:183], v[196:199], v[30:33]
	v_mfma_f32_16x16x32_bf16 v[46:49], v[180:183], v[188:191], v[46:49]
	v_mfma_f32_16x16x32_bf16 v[54:57], v[176:179], v[192:195], v[54:57]
	v_mfma_f32_16x16x32_bf16 v[38:41], v[176:179], v[200:203], v[38:41]
	v_mfma_f32_16x16x32_bf16 v[22:25], v[176:179], v[208:211], v[22:25]
	v_mfma_f32_16x16x32_bf16 v[6:9], v[176:179], v[218:221], v[6:9]
	v_mfma_f32_16x16x32_bf16 v[2:5], v[184:187], v[218:221], v[2:5]
	v_mfma_f32_16x16x32_bf16 v[14:17], v[184:187], v[208:211], v[14:17]
	v_mfma_f32_16x16x32_bf16 v[30:33], v[184:187], v[200:203], v[30:33]
	v_mfma_f32_16x16x32_bf16 v[46:49], v[184:187], v[192:195], v[46:49]
	s_setprio 0
	s_barrier
	s_add_i32 s53, 0, 0x18000
	v_add_u32_e32 v156, s53, v153
	s_add_i32 s62, 0, 0x1c000
	ds_read_b128 v[146:149], v156
	ds_read_b128 v[160:163], v156 offset:1024
	ds_read_b128 v[164:167], v156 offset:2048
	ds_read_b128 v[168:171], v156 offset:3072
	v_add_u32_e32 v156, s62, v153
	ds_read_b128 v[172:175], v156
	ds_read_b128 v[176:179], v156 offset:1024
	ds_read_b128 v[180:183], v156 offset:2048
	ds_read_b128 v[184:187], v156 offset:3072
	s_add_u32 s54, s86, 0x20000
	s_addc_u32 s55, s87, 0
	s_mov_b32 m0, s57
	v_lshl_add_u64 v[228:229], s[54:55], 0, v[130:131]
	ds_read_b128 v[188:191], v155 offset:32768
	ds_read_b128 v[192:195], v155 offset:33792
	ds_read_b128 v[196:199], v155 offset:34816
	ds_read_b128 v[200:203], v155 offset:35840
	ds_read_b128 v[204:207], v155 offset:36864
	ds_read_b128 v[208:211], v155 offset:37888
	ds_read_b128 v[212:215], v155 offset:38912
	ds_read_b128 v[218:221], v155 offset:39936
	global_load_lds_dwordx4 v[228:229], off
	v_lshl_add_u64 v[228:229], s[54:55], 0, v[134:135]
	s_mov_b32 m0, s58
	s_nop 0
	global_load_lds_dwordx4 v[228:229], off
	s_waitcnt vmcnt(8)
	s_waitcnt lgkmcnt(0)
	s_barrier
	s_setprio 1
	s_waitcnt lgkmcnt(0)
	v_mfma_f32_16x16x32_bf16 v[126:129], v[146:149], v[188:191], v[126:129]
	v_mfma_f32_16x16x32_bf16 v[110:113], v[146:149], v[196:199], v[110:113]
	v_mfma_f32_16x16x32_bf16 v[94:97], v[146:149], v[204:207], v[94:97]
	v_mfma_f32_16x16x32_bf16 v[78:81], v[146:149], v[212:215], v[78:81]
	v_mfma_f32_16x16x32_bf16 v[74:77], v[164:167], v[212:215], v[74:77]
	v_mfma_f32_16x16x32_bf16 v[90:93], v[164:167], v[204:207], v[90:93]
	v_mfma_f32_16x16x32_bf16 v[106:109], v[164:167], v[196:199], v[106:109]
	v_mfma_f32_16x16x32_bf16 v[122:125], v[164:167], v[188:191], v[122:125]
	v_mfma_f32_16x16x32_bf16 v[126:129], v[160:163], v[192:195], v[126:129]
	v_mfma_f32_16x16x32_bf16 v[110:113], v[160:163], v[200:203], v[110:113]
	v_mfma_f32_16x16x32_bf16 v[94:97], v[160:163], v[208:211], v[94:97]
	v_mfma_f32_16x16x32_bf16 v[78:81], v[160:163], v[218:221], v[78:81]
	v_mfma_f32_16x16x32_bf16 v[74:77], v[168:171], v[218:221], v[74:77]
	v_mfma_f32_16x16x32_bf16 v[90:93], v[168:171], v[208:211], v[90:93]
	v_mfma_f32_16x16x32_bf16 v[106:109], v[168:171], v[200:203], v[106:109]
	v_mfma_f32_16x16x32_bf16 v[122:125], v[168:171], v[192:195], v[122:125]
	s_setprio 0
	s_setprio 1
	v_mfma_f32_16x16x32_bf16 v[118:121], v[172:175], v[188:191], v[118:121]
	v_mfma_f32_16x16x32_bf16 v[102:105], v[172:175], v[196:199], v[102:105]
	v_mfma_f32_16x16x32_bf16 v[86:89], v[172:175], v[204:207], v[86:89]
	v_mfma_f32_16x16x32_bf16 v[70:73], v[172:175], v[212:215], v[70:73]
	v_mfma_f32_16x16x32_bf16 v[66:69], v[180:183], v[212:215], v[66:69]
	v_mfma_f32_16x16x32_bf16 v[82:85], v[180:183], v[204:207], v[82:85]
	v_mfma_f32_16x16x32_bf16 v[98:101], v[180:183], v[196:199], v[98:101]
	v_mfma_f32_16x16x32_bf16 v[114:117], v[180:183], v[188:191], v[114:117]
	v_mfma_f32_16x16x32_bf16 v[118:121], v[176:179], v[192:195], v[118:121]
	v_mfma_f32_16x16x32_bf16 v[102:105], v[176:179], v[200:203], v[102:105]
	v_mfma_f32_16x16x32_bf16 v[86:89], v[176:179], v[208:211], v[86:89]
	v_mfma_f32_16x16x32_bf16 v[70:73], v[176:179], v[218:221], v[70:73]
	v_mfma_f32_16x16x32_bf16 v[66:69], v[184:187], v[218:221], v[66:69]
	v_mfma_f32_16x16x32_bf16 v[82:85], v[184:187], v[208:211], v[82:85]
	v_mfma_f32_16x16x32_bf16 v[98:101], v[184:187], v[200:203], v[98:101]
	v_mfma_f32_16x16x32_bf16 v[114:117], v[184:187], v[192:195], v[114:117]
	s_setprio 0
	s_barrier
	s_add_i32 s53, s53, s13
	v_lshl_add_u64 v[150:151], v[150:151], 0, s[8:9]
	s_mov_b32 m0, s53
	ds_read_b128 v[188:191], v155 offset:49152
	ds_read_b128 v[192:195], v155 offset:50176
	ds_read_b128 v[196:199], v155 offset:51200
	ds_read_b128 v[200:203], v155 offset:52224
	ds_read_b128 v[204:207], v155 offset:53248
	ds_read_b128 v[208:211], v155 offset:54272
	ds_read_b128 v[212:215], v155 offset:55296
	ds_read_b128 v[218:221], v155 offset:56320
	global_load_lds_dwordx4 v[150:151], off
	s_add_i32 m0, s53, 0x2000
	s_add_u32 s34, s34, 0x20080
	v_lshl_add_u64 v[150:151], v[222:223], 0, s[8:9]
	s_addc_u32 s35, s35, 0
	s_add_i32 s53, s62, s13
	global_load_lds_dwordx4 v[150:151], off
	v_lshl_add_u64 v[150:151], s[34:35], 0, v[132:133]
	s_mov_b32 m0, s53
	s_nop 0
	global_load_lds_dwordx4 v[150:151], off
	v_lshl_add_u64 v[150:151], s[34:35], 0, v[136:137]
	s_add_i32 m0, s53, 0x2000
	s_nop 0
	global_load_lds_dwordx4 v[150:151], off
	v_lshl_add_u64 v[150:151], v[224:225], 0, s[8:9]
	s_mov_b32 m0, s60
	s_nop 0
	global_load_lds_dwordx4 v[150:151], off
	v_lshl_add_u64 v[150:151], v[226:227], 0, s[8:9]
	s_mov_b32 m0, s61
	s_nop 0
	global_load_lds_dwordx4 v[150:151], off
	s_waitcnt vmcnt(8)
	s_waitcnt lgkmcnt(0)
	s_barrier
	s_setprio 1
	s_waitcnt lgkmcnt(0)
	v_mfma_f32_16x16x32_bf16 v[62:65], v[146:149], v[188:191], v[62:65]
	v_mfma_f32_16x16x32_bf16 v[50:53], v[146:149], v[196:199], v[50:53]
	v_mfma_f32_16x16x32_bf16 v[34:37], v[146:149], v[204:207], v[34:37]
	v_mfma_f32_16x16x32_bf16 v[18:21], v[146:149], v[212:215], v[18:21]
	v_mfma_f32_16x16x32_bf16 v[10:13], v[164:167], v[212:215], v[10:13]
	v_mfma_f32_16x16x32_bf16 v[26:29], v[164:167], v[204:207], v[26:29]
	v_mfma_f32_16x16x32_bf16 v[42:45], v[164:167], v[196:199], v[42:45]
	v_mfma_f32_16x16x32_bf16 v[58:61], v[164:167], v[188:191], v[58:61]
	v_mfma_f32_16x16x32_bf16 v[62:65], v[160:163], v[192:195], v[62:65]
	v_mfma_f32_16x16x32_bf16 v[50:53], v[160:163], v[200:203], v[50:53]
	v_mfma_f32_16x16x32_bf16 v[34:37], v[160:163], v[208:211], v[34:37]
	v_mfma_f32_16x16x32_bf16 v[18:21], v[160:163], v[218:221], v[18:21]
	v_mfma_f32_16x16x32_bf16 v[10:13], v[168:171], v[218:221], v[10:13]
	v_mfma_f32_16x16x32_bf16 v[26:29], v[168:171], v[208:211], v[26:29]
	v_mfma_f32_16x16x32_bf16 v[42:45], v[168:171], v[200:203], v[42:45]
	v_mfma_f32_16x16x32_bf16 v[58:61], v[168:171], v[192:195], v[58:61]
	s_setprio 0
	s_setprio 1
	v_mfma_f32_16x16x32_bf16 v[54:57], v[172:175], v[188:191], v[54:57]
	v_mfma_f32_16x16x32_bf16 v[38:41], v[172:175], v[196:199], v[38:41]
	v_mfma_f32_16x16x32_bf16 v[22:25], v[172:175], v[204:207], v[22:25]
	v_mfma_f32_16x16x32_bf16 v[6:9], v[172:175], v[212:215], v[6:9]
	v_mfma_f32_16x16x32_bf16 v[2:5], v[180:183], v[212:215], v[2:5]
	v_mfma_f32_16x16x32_bf16 v[14:17], v[180:183], v[204:207], v[14:17]
	v_mfma_f32_16x16x32_bf16 v[30:33], v[180:183], v[196:199], v[30:33]
	v_mfma_f32_16x16x32_bf16 v[46:49], v[180:183], v[188:191], v[46:49]
	v_mfma_f32_16x16x32_bf16 v[54:57], v[176:179], v[192:195], v[54:57]
	v_mfma_f32_16x16x32_bf16 v[38:41], v[176:179], v[200:203], v[38:41]
	v_mfma_f32_16x16x32_bf16 v[22:25], v[176:179], v[208:211], v[22:25]
	v_mfma_f32_16x16x32_bf16 v[6:9], v[176:179], v[218:221], v[6:9]
	v_mfma_f32_16x16x32_bf16 v[2:5], v[184:187], v[218:221], v[2:5]
	v_mfma_f32_16x16x32_bf16 v[14:17], v[184:187], v[208:211], v[14:17]
	v_mfma_f32_16x16x32_bf16 v[30:33], v[184:187], v[200:203], v[30:33]
	v_mfma_f32_16x16x32_bf16 v[46:49], v[184:187], v[192:195], v[46:49]
	s_setprio 0
	s_barrier
	s_add_i32 s88, s88, 2
	s_add_u32 s84, s84, 0x100
	s_addc_u32 s85, s85, 0
	s_add_u32 s77, s77, 0x100
	s_addc_u32 s83, s83, 0
	s_cmp_gt_u32 s88, 5
	s_cbranch_scc0 .LBB0_715
	s_and_b64 vcc, exec, s[66:67]
	s_cbranch_vccz .LBB0_718
	s_barrier

.LBB0_995:
	ds_read_b128 v[146:149], v164
	ds_read_b128 v[150:153], v164 offset:1024
	ds_read_b128 v[154:157], v164 offset:2048
	ds_read_b128 v[158:161], v164 offset:3072
	ds_read_b128 v[168:171], v165
	ds_read_b128 v[172:175], v165 offset:1024
	ds_read_b128 v[176:179], v165 offset:2048
	ds_read_b128 v[180:183], v165 offset:3072
	s_add_u32 s34, s88, 0xfff80080
	s_addc_u32 s35, s89, -1
	s_cmp_eq_u32 s81, 28
	s_cselect_b32 s91, s0, s35
	s_cselect_b32 s90, s1, s34
	s_cselect_b32 s35, s52, s77
	s_cselect_b32 s34, s74, s75
	v_lshl_add_u64 v[218:219], s[88:89], 0, v[138:139]
	s_add_i32 m0, s33, 0xc000
	ds_read_b128 v[184:187], v166
	ds_read_b128 v[188:191], v166 offset:1024
	ds_read_b128 v[192:195], v166 offset:2048
	ds_read_b128 v[196:199], v166 offset:3072
	ds_read_b128 v[200:203], v166 offset:4096
	ds_read_b128 v[204:207], v166 offset:5120
	ds_read_b128 v[208:211], v166 offset:6144
	ds_read_b128 v[212:215], v166 offset:7168
	global_load_lds_dwordx4 v[218:219], off
	v_lshl_add_u64 v[218:219], s[88:89], 0, v[140:141]
	s_add_i32 m0, s33, 0xe000
	s_nop 0
	global_load_lds_dwordx4 v[218:219], off
	s_waitcnt vmcnt(8)
	s_waitcnt lgkmcnt(0)
	s_barrier
	s_setprio 1
	s_waitcnt lgkmcnt(0)
	v_mfma_f32_16x16x32_bf16 v[126:129], v[146:149], v[184:187], v[126:129]
	v_mfma_f32_16x16x32_bf16 v[110:113], v[146:149], v[192:195], v[110:113]
	v_mfma_f32_16x16x32_bf16 v[94:97], v[146:149], v[200:203], v[94:97]
	v_mfma_f32_16x16x32_bf16 v[78:81], v[146:149], v[208:211], v[78:81]
	v_mfma_f32_16x16x32_bf16 v[74:77], v[154:157], v[208:211], v[74:77]
	v_mfma_f32_16x16x32_bf16 v[90:93], v[154:157], v[200:203], v[90:93]
	v_mfma_f32_16x16x32_bf16 v[106:109], v[154:157], v[192:195], v[106:109]
	v_mfma_f32_16x16x32_bf16 v[122:125], v[154:157], v[184:187], v[122:125]
	v_mfma_f32_16x16x32_bf16 v[126:129], v[150:153], v[188:191], v[126:129]
	v_mfma_f32_16x16x32_bf16 v[110:113], v[150:153], v[196:199], v[110:113]
	v_mfma_f32_16x16x32_bf16 v[94:97], v[150:153], v[204:207], v[94:97]
	v_mfma_f32_16x16x32_bf16 v[78:81], v[150:153], v[212:215], v[78:81]
	v_mfma_f32_16x16x32_bf16 v[74:77], v[158:161], v[212:215], v[74:77]
	v_mfma_f32_16x16x32_bf16 v[90:93], v[158:161], v[204:207], v[90:93]
	v_mfma_f32_16x16x32_bf16 v[106:109], v[158:161], v[196:199], v[106:109]
	v_mfma_f32_16x16x32_bf16 v[122:125], v[158:161], v[188:191], v[122:125]
	s_setprio 0
	s_setprio 1
	v_mfma_f32_16x16x32_bf16 v[118:121], v[168:171], v[184:187], v[118:121]
	v_mfma_f32_16x16x32_bf16 v[102:105], v[168:171], v[192:195], v[102:105]
	v_mfma_f32_16x16x32_bf16 v[86:89], v[168:171], v[200:203], v[86:89]
	v_mfma_f32_16x16x32_bf16 v[70:73], v[168:171], v[208:211], v[70:73]
	v_mfma_f32_16x16x32_bf16 v[66:69], v[176:179], v[208:211], v[66:69]
	v_mfma_f32_16x16x32_bf16 v[82:85], v[176:179], v[200:203], v[82:85]
	v_mfma_f32_16x16x32_bf16 v[98:101], v[176:179], v[192:195], v[98:101]
	v_mfma_f32_16x16x32_bf16 v[114:117], v[176:179], v[184:187], v[114:117]
	v_mfma_f32_16x16x32_bf16 v[118:121], v[172:175], v[188:191], v[118:121]
	v_mfma_f32_16x16x32_bf16 v[102:105], v[172:175], v[196:199], v[102:105]
	v_mfma_f32_16x16x32_bf16 v[86:89], v[172:175], v[204:207], v[86:89]
	v_mfma_f32_16x16x32_bf16 v[70:73], v[172:175], v[212:215], v[70:73]
	v_mfma_f32_16x16x32_bf16 v[66:69], v[180:183], v[212:215], v[66:69]
	v_mfma_f32_16x16x32_bf16 v[82:85], v[180:183], v[204:207], v[82:85]
	v_mfma_f32_16x16x32_bf16 v[98:101], v[180:183], v[196:199], v[98:101]
	v_mfma_f32_16x16x32_bf16 v[114:117], v[180:183], v[188:191], v[114:117]
	s_setprio 0
	s_barrier
	s_add_i32 s53, s71, s31
	v_lshl_add_u64 v[218:219], s[34:35], 0, v[132:133]
	s_mov_b32 m0, s53
	ds_read_b128 v[184:187], v166 offset:16384
	ds_read_b128 v[188:191], v166 offset:17408
	ds_read_b128 v[192:195], v166 offset:18432
	ds_read_b128 v[196:199], v166 offset:19456
	ds_read_b128 v[200:203], v166 offset:20480
	ds_read_b128 v[204:207], v166 offset:21504
	ds_read_b128 v[208:211], v166 offset:22528
	ds_read_b128 v[212:215], v166 offset:23552
	global_load_lds_dwordx4 v[218:219], off
	s_add_i32 m0, s53, 0x2000
	s_add_u32 s54, s34, 0x80000
	v_lshl_add_u64 v[220:221], s[34:35], 0, v[136:137]
	s_addc_u32 s55, s35, 0
	s_add_i32 s53, s72, s31
	global_load_lds_dwordx4 v[220:221], off
	v_lshl_add_u64 v[222:223], s[54:55], 0, v[132:133]
	s_mov_b32 m0, s53
	v_lshl_add_u64 v[224:225], s[90:91], 0, v[134:135]
	global_load_lds_dwordx4 v[222:223], off
	v_lshl_add_u64 v[222:223], s[54:55], 0, v[136:137]
	s_add_i32 m0, s53, 0x2000
	s_nop 0
	global_load_lds_dwordx4 v[222:223], off
	v_lshl_add_u64 v[222:223], s[90:91], 0, v[130:131]
	s_mov_b32 m0, s33
	s_nop 0
	global_load_lds_dwordx4 v[222:223], off
	s_mov_b32 m0, s56
	s_nop 0
	global_load_lds_dwordx4 v[224:225], off
	s_waitcnt vmcnt(8)
	s_waitcnt lgkmcnt(0)
	s_barrier
	s_setprio 1
	s_waitcnt lgkmcnt(0)
	v_mfma_f32_16x16x32_bf16 v[62:65], v[146:149], v[184:187], v[62:65]
	v_mfma_f32_16x16x32_bf16 v[46:49], v[146:149], v[192:195], v[46:49]
	v_mfma_f32_16x16x32_bf16 v[30:33], v[146:149], v[200:203], v[30:33]
	v_mfma_f32_16x16x32_bf16 v[14:17], v[146:149], v[208:211], v[14:17]
	v_mfma_f32_16x16x32_bf16 v[10:13], v[154:157], v[208:211], v[10:13]
	v_mfma_f32_16x16x32_bf16 v[26:29], v[154:157], v[200:203], v[26:29]
	v_mfma_f32_16x16x32_bf16 v[42:45], v[154:157], v[192:195], v[42:45]
	v_mfma_f32_16x16x32_bf16 v[58:61], v[154:157], v[184:187], v[58:61]
	v_mfma_f32_16x16x32_bf16 v[62:65], v[150:153], v[188:191], v[62:65]
	v_mfma_f32_16x16x32_bf16 v[46:49], v[150:153], v[196:199], v[46:49]
	v_mfma_f32_16x16x32_bf16 v[30:33], v[150:153], v[204:207], v[30:33]
	v_mfma_f32_16x16x32_bf16 v[14:17], v[150:153], v[212:215], v[14:17]
	v_mfma_f32_16x16x32_bf16 v[10:13], v[158:161], v[212:215], v[10:13]
	v_mfma_f32_16x16x32_bf16 v[26:29], v[158:161], v[204:207], v[26:29]
	v_mfma_f32_16x16x32_bf16 v[42:45], v[158:161], v[196:199], v[42:45]
	v_mfma_f32_16x16x32_bf16 v[58:61], v[158:161], v[188:191], v[58:61]
	s_setprio 0
	s_setprio 1
	v_mfma_f32_16x16x32_bf16 v[54:57], v[168:171], v[184:187], v[54:57]
	v_mfma_f32_16x16x32_bf16 v[38:41], v[168:171], v[192:195], v[38:41]
	v_mfma_f32_16x16x32_bf16 v[22:25], v[168:171], v[200:203], v[22:25]
	v_mfma_f32_16x16x32_bf16 v[6:9], v[168:171], v[208:211], v[6:9]
	v_mfma_f32_16x16x32_bf16 v[2:5], v[176:179], v[208:211], v[2:5]
	v_mfma_f32_16x16x32_bf16 v[18:21], v[176:179], v[200:203], v[18:21]
	v_mfma_f32_16x16x32_bf16 v[34:37], v[176:179], v[192:195], v[34:37]
	v_mfma_f32_16x16x32_bf16 v[50:53], v[176:179], v[184:187], v[50:53]
	v_mfma_f32_16x16x32_bf16 v[54:57], v[172:175], v[188:191], v[54:57]
	v_mfma_f32_16x16x32_bf16 v[38:41], v[172:175], v[196:199], v[38:41]
	v_mfma_f32_16x16x32_bf16 v[22:25], v[172:175], v[204:207], v[22:25]
	v_mfma_f32_16x16x32_bf16 v[6:9], v[172:175], v[212:215], v[6:9]
	v_mfma_f32_16x16x32_bf16 v[2:5], v[180:183], v[212:215], v[2:5]
	v_mfma_f32_16x16x32_bf16 v[18:21], v[180:183], v[204:207], v[18:21]
	v_mfma_f32_16x16x32_bf16 v[34:37], v[180:183], v[196:199], v[34:37]
	v_mfma_f32_16x16x32_bf16 v[50:53], v[180:183], v[188:191], v[50:53]
	s_setprio 0
	s_barrier
	s_add_i32 s53, 0, 0x18000
	s_add_i32 s62, 0, 0x1c000
	v_add_u32_e32 v158, s53, v162
	v_add_u32_e32 v167, s62, v162
	ds_read_b128 v[146:149], v158
	ds_read_b128 v[150:153], v158 offset:1024
	ds_read_b128 v[154:157], v158 offset:2048
	ds_read_b128 v[158:161], v158 offset:3072
	ds_read_b128 v[168:171], v167
	ds_read_b128 v[172:175], v167 offset:1024
	ds_read_b128 v[176:179], v167 offset:2048
	ds_read_b128 v[180:183], v167 offset:3072
	s_add_u32 s54, s90, 0x80000
	s_addc_u32 s55, s91, 0
	s_mov_b32 m0, s57
	v_lshl_add_u64 v[226:227], s[54:55], 0, v[130:131]
	ds_read_b128 v[184:187], v166 offset:32768
	ds_read_b128 v[188:191], v166 offset:33792
	ds_read_b128 v[192:195], v166 offset:34816
	ds_read_b128 v[196:199], v166 offset:35840
	ds_read_b128 v[200:203], v166 offset:36864
	ds_read_b128 v[204:207], v166 offset:37888
	ds_read_b128 v[208:211], v166 offset:38912
	ds_read_b128 v[212:215], v166 offset:39936
	global_load_lds_dwordx4 v[226:227], off
	v_lshl_add_u64 v[226:227], s[54:55], 0, v[134:135]
	s_mov_b32 m0, s58
	s_nop 0
	global_load_lds_dwordx4 v[226:227], off
	s_waitcnt vmcnt(8)
	s_waitcnt lgkmcnt(0)
	s_barrier
	s_setprio 1
	s_waitcnt lgkmcnt(0)
	v_mfma_f32_16x16x32_bf16 v[126:129], v[146:149], v[184:187], v[126:129]
	v_mfma_f32_16x16x32_bf16 v[110:113], v[146:149], v[192:195], v[110:113]
	v_mfma_f32_16x16x32_bf16 v[94:97], v[146:149], v[200:203], v[94:97]
	v_mfma_f32_16x16x32_bf16 v[78:81], v[146:149], v[208:211], v[78:81]
	v_mfma_f32_16x16x32_bf16 v[74:77], v[154:157], v[208:211], v[74:77]
	v_mfma_f32_16x16x32_bf16 v[90:93], v[154:157], v[200:203], v[90:93]
	v_mfma_f32_16x16x32_bf16 v[106:109], v[154:157], v[192:195], v[106:109]
	v_mfma_f32_16x16x32_bf16 v[122:125], v[154:157], v[184:187], v[122:125]
	v_mfma_f32_16x16x32_bf16 v[126:129], v[150:153], v[188:191], v[126:129]
	v_mfma_f32_16x16x32_bf16 v[110:113], v[150:153], v[196:199], v[110:113]
	v_mfma_f32_16x16x32_bf16 v[94:97], v[150:153], v[204:207], v[94:97]
	v_mfma_f32_16x16x32_bf16 v[78:81], v[150:153], v[212:215], v[78:81]
	v_mfma_f32_16x16x32_bf16 v[74:77], v[158:161], v[212:215], v[74:77]
	v_mfma_f32_16x16x32_bf16 v[90:93], v[158:161], v[204:207], v[90:93]
	v_mfma_f32_16x16x32_bf16 v[106:109], v[158:161], v[196:199], v[106:109]
	v_mfma_f32_16x16x32_bf16 v[122:125], v[158:161], v[188:191], v[122:125]
	s_setprio 0
	s_setprio 1
	v_mfma_f32_16x16x32_bf16 v[118:121], v[168:171], v[184:187], v[118:121]
	v_mfma_f32_16x16x32_bf16 v[102:105], v[168:171], v[192:195], v[102:105]
	v_mfma_f32_16x16x32_bf16 v[86:89], v[168:171], v[200:203], v[86:89]
	v_mfma_f32_16x16x32_bf16 v[70:73], v[168:171], v[208:211], v[70:73]
	v_mfma_f32_16x16x32_bf16 v[66:69], v[176:179], v[208:211], v[66:69]
	v_mfma_f32_16x16x32_bf16 v[82:85], v[176:179], v[200:203], v[82:85]
	v_mfma_f32_16x16x32_bf16 v[98:101], v[176:179], v[192:195], v[98:101]
	v_mfma_f32_16x16x32_bf16 v[114:117], v[176:179], v[184:187], v[114:117]
	v_mfma_f32_16x16x32_bf16 v[118:121], v[172:175], v[188:191], v[118:121]
	v_mfma_f32_16x16x32_bf16 v[102:105], v[172:175], v[196:199], v[102:105]
	v_mfma_f32_16x16x32_bf16 v[86:89], v[172:175], v[204:207], v[86:89]
	v_mfma_f32_16x16x32_bf16 v[70:73], v[172:175], v[212:215], v[70:73]
	v_mfma_f32_16x16x32_bf16 v[66:69], v[180:183], v[212:215], v[66:69]
	v_mfma_f32_16x16x32_bf16 v[82:85], v[180:183], v[204:207], v[82:85]
	v_mfma_f32_16x16x32_bf16 v[98:101], v[180:183], v[196:199], v[98:101]
	v_mfma_f32_16x16x32_bf16 v[114:117], v[180:183], v[188:191], v[114:117]
	s_setprio 0
	s_barrier
	s_add_i32 s53, s53, s31
	v_lshl_add_u64 v[218:219], v[218:219], 0, s[8:9]
	s_mov_b32 m0, s53
	ds_read_b128 v[184:187], v166 offset:49152
	ds_read_b128 v[188:191], v166 offset:50176
	ds_read_b128 v[192:195], v166 offset:51200
	ds_read_b128 v[196:199], v166 offset:52224
	ds_read_b128 v[200:203], v166 offset:53248
	ds_read_b128 v[204:207], v166 offset:54272
	ds_read_b128 v[208:211], v166 offset:55296
	ds_read_b128 v[212:215], v166 offset:56320
	global_load_lds_dwordx4 v[218:219], off
	s_add_i32 m0, s53, 0x2000
	s_add_u32 s34, s34, 0x80080
	v_lshl_add_u64 v[218:219], v[220:221], 0, s[8:9]
	s_addc_u32 s35, s35, 0
	s_add_i32 s53, s62, s31
	global_load_lds_dwordx4 v[218:219], off
	v_lshl_add_u64 v[218:219], s[34:35], 0, v[132:133]
	s_mov_b32 m0, s53
	s_nop 0
	global_load_lds_dwordx4 v[218:219], off
	v_lshl_add_u64 v[218:219], s[34:35], 0, v[136:137]
	s_add_i32 m0, s53, 0x2000
	s_nop 0
	global_load_lds_dwordx4 v[218:219], off
	v_lshl_add_u64 v[218:219], v[222:223], 0, s[8:9]
	s_mov_b32 m0, s60
	s_nop 0
	global_load_lds_dwordx4 v[218:219], off
	v_lshl_add_u64 v[218:219], v[224:225], 0, s[8:9]
	s_mov_b32 m0, s61
	s_nop 0
	global_load_lds_dwordx4 v[218:219], off
	s_waitcnt vmcnt(8)
	s_waitcnt lgkmcnt(0)
	s_barrier
	s_setprio 1
	s_waitcnt lgkmcnt(0)
	v_mfma_f32_16x16x32_bf16 v[62:65], v[146:149], v[184:187], v[62:65]
	v_mfma_f32_16x16x32_bf16 v[46:49], v[146:149], v[192:195], v[46:49]
	v_mfma_f32_16x16x32_bf16 v[30:33], v[146:149], v[200:203], v[30:33]
	v_mfma_f32_16x16x32_bf16 v[14:17], v[146:149], v[208:211], v[14:17]
	v_mfma_f32_16x16x32_bf16 v[10:13], v[154:157], v[208:211], v[10:13]
	v_mfma_f32_16x16x32_bf16 v[26:29], v[154:157], v[200:203], v[26:29]
	v_mfma_f32_16x16x32_bf16 v[42:45], v[154:157], v[192:195], v[42:45]
	v_mfma_f32_16x16x32_bf16 v[58:61], v[154:157], v[184:187], v[58:61]
	v_mfma_f32_16x16x32_bf16 v[62:65], v[150:153], v[188:191], v[62:65]
	v_mfma_f32_16x16x32_bf16 v[46:49], v[150:153], v[196:199], v[46:49]
	v_mfma_f32_16x16x32_bf16 v[30:33], v[150:153], v[204:207], v[30:33]
	v_mfma_f32_16x16x32_bf16 v[14:17], v[150:153], v[212:215], v[14:17]
	v_mfma_f32_16x16x32_bf16 v[10:13], v[158:161], v[212:215], v[10:13]
	v_mfma_f32_16x16x32_bf16 v[26:29], v[158:161], v[204:207], v[26:29]
	v_mfma_f32_16x16x32_bf16 v[42:45], v[158:161], v[196:199], v[42:45]
	v_mfma_f32_16x16x32_bf16 v[58:61], v[158:161], v[188:191], v[58:61]
	s_setprio 0
	s_setprio 1
	v_mfma_f32_16x16x32_bf16 v[54:57], v[168:171], v[184:187], v[54:57]
	v_mfma_f32_16x16x32_bf16 v[38:41], v[168:171], v[192:195], v[38:41]
	v_mfma_f32_16x16x32_bf16 v[22:25], v[168:171], v[200:203], v[22:25]
	v_mfma_f32_16x16x32_bf16 v[6:9], v[168:171], v[208:211], v[6:9]
	v_mfma_f32_16x16x32_bf16 v[2:5], v[176:179], v[208:211], v[2:5]
	v_mfma_f32_16x16x32_bf16 v[18:21], v[176:179], v[200:203], v[18:21]
	v_mfma_f32_16x16x32_bf16 v[34:37], v[176:179], v[192:195], v[34:37]
	v_mfma_f32_16x16x32_bf16 v[50:53], v[176:179], v[184:187], v[50:53]
	v_mfma_f32_16x16x32_bf16 v[54:57], v[172:175], v[188:191], v[54:57]
	v_mfma_f32_16x16x32_bf16 v[38:41], v[172:175], v[196:199], v[38:41]
	v_mfma_f32_16x16x32_bf16 v[22:25], v[172:175], v[204:207], v[22:25]
	v_mfma_f32_16x16x32_bf16 v[6:9], v[172:175], v[212:215], v[6:9]
	v_mfma_f32_16x16x32_bf16 v[2:5], v[180:183], v[212:215], v[2:5]
	v_mfma_f32_16x16x32_bf16 v[18:21], v[180:183], v[204:207], v[18:21]
	v_mfma_f32_16x16x32_bf16 v[34:37], v[180:183], v[196:199], v[34:37]
	v_mfma_f32_16x16x32_bf16 v[50:53], v[180:183], v[188:191], v[50:53]
	s_setprio 0
	s_barrier
	s_add_i32 s81, s81, 2
	s_add_u32 s88, s88, 0x100
	s_addc_u32 s89, s89, 0
	s_add_u32 s75, s75, 0x100
	s_addc_u32 s77, s77, 0
	s_cmp_gt_u32 s81, 29
	s_cbranch_scc0 .LBB0_995
	s_and_b64 vcc, exec, s[78:79]
	s_cbranch_vccz .LBB0_998
	s_barrier

.LBB0_1124:
	ds_read_b128 v[146:149], v153
	ds_read_b128 v[156:159], v153 offset:1024
	ds_read_b128 v[160:163], v153 offset:2048
	ds_read_b128 v[164:167], v153 offset:3072
	ds_read_b128 v[168:171], v154
	ds_read_b128 v[172:175], v154 offset:1024
	ds_read_b128 v[176:179], v154 offset:2048
	ds_read_b128 v[180:183], v154 offset:3072
	s_add_u32 s34, s88, 0xfff80080
	s_addc_u32 s35, s89, -1
	s_cmp_eq_u32 s92, 28
	s_cselect_b32 s91, s0, s35
	s_cselect_b32 s90, s1, s34
	s_cselect_b32 s35, s52, s83
	s_cselect_b32 s34, s77, s81
	v_lshl_add_u64 v[218:219], s[88:89], 0, v[138:139]
	s_add_i32 m0, s56, 0xc000
	ds_read_b128 v[184:187], v155
	ds_read_b128 v[188:191], v155 offset:1024
	ds_read_b128 v[192:195], v155 offset:2048
	ds_read_b128 v[196:199], v155 offset:3072
	ds_read_b128 v[200:203], v155 offset:4096
	ds_read_b128 v[204:207], v155 offset:5120
	ds_read_b128 v[208:211], v155 offset:6144
	ds_read_b128 v[212:215], v155 offset:7168
	global_load_lds_dwordx4 v[218:219], off
	v_lshl_add_u64 v[218:219], s[88:89], 0, v[140:141]
	s_add_i32 m0, s56, 0xe000
	s_nop 0
	global_load_lds_dwordx4 v[218:219], off
	s_waitcnt vmcnt(8)
	s_waitcnt lgkmcnt(0)
	s_barrier
	s_setprio 1
	s_waitcnt lgkmcnt(0)
	v_mfma_f32_16x16x32_bf16 v[126:129], v[146:149], v[184:187], v[126:129]
	v_mfma_f32_16x16x32_bf16 v[110:113], v[146:149], v[192:195], v[110:113]
	v_mfma_f32_16x16x32_bf16 v[94:97], v[146:149], v[200:203], v[94:97]
	v_mfma_f32_16x16x32_bf16 v[78:81], v[146:149], v[208:211], v[78:81]
	v_mfma_f32_16x16x32_bf16 v[70:73], v[160:163], v[208:211], v[70:73]
	v_mfma_f32_16x16x32_bf16 v[86:89], v[160:163], v[200:203], v[86:89]
	v_mfma_f32_16x16x32_bf16 v[102:105], v[160:163], v[192:195], v[102:105]
	v_mfma_f32_16x16x32_bf16 v[118:121], v[160:163], v[184:187], v[118:121]
	v_mfma_f32_16x16x32_bf16 v[126:129], v[156:159], v[188:191], v[126:129]
	v_mfma_f32_16x16x32_bf16 v[110:113], v[156:159], v[196:199], v[110:113]
	v_mfma_f32_16x16x32_bf16 v[94:97], v[156:159], v[204:207], v[94:97]
	v_mfma_f32_16x16x32_bf16 v[78:81], v[156:159], v[212:215], v[78:81]
	v_mfma_f32_16x16x32_bf16 v[70:73], v[164:167], v[212:215], v[70:73]
	v_mfma_f32_16x16x32_bf16 v[86:89], v[164:167], v[204:207], v[86:89]
	v_mfma_f32_16x16x32_bf16 v[102:105], v[164:167], v[196:199], v[102:105]
	v_mfma_f32_16x16x32_bf16 v[118:121], v[164:167], v[188:191], v[118:121]
	s_setprio 0
	s_setprio 1
	v_mfma_f32_16x16x32_bf16 v[122:125], v[168:171], v[184:187], v[122:125]
	v_mfma_f32_16x16x32_bf16 v[106:109], v[168:171], v[192:195], v[106:109]
	v_mfma_f32_16x16x32_bf16 v[90:93], v[168:171], v[200:203], v[90:93]
	v_mfma_f32_16x16x32_bf16 v[74:77], v[168:171], v[208:211], v[74:77]
	v_mfma_f32_16x16x32_bf16 v[66:69], v[176:179], v[208:211], v[66:69]
	v_mfma_f32_16x16x32_bf16 v[82:85], v[176:179], v[200:203], v[82:85]
	v_mfma_f32_16x16x32_bf16 v[98:101], v[176:179], v[192:195], v[98:101]
	v_mfma_f32_16x16x32_bf16 v[114:117], v[176:179], v[184:187], v[114:117]
	v_mfma_f32_16x16x32_bf16 v[122:125], v[172:175], v[188:191], v[122:125]
	v_mfma_f32_16x16x32_bf16 v[106:109], v[172:175], v[196:199], v[106:109]
	v_mfma_f32_16x16x32_bf16 v[90:93], v[172:175], v[204:207], v[90:93]
	v_mfma_f32_16x16x32_bf16 v[74:77], v[172:175], v[212:215], v[74:77]
	v_mfma_f32_16x16x32_bf16 v[66:69], v[180:183], v[212:215], v[66:69]
	v_mfma_f32_16x16x32_bf16 v[82:85], v[180:183], v[204:207], v[82:85]
	v_mfma_f32_16x16x32_bf16 v[98:101], v[180:183], v[196:199], v[98:101]
	v_mfma_f32_16x16x32_bf16 v[114:117], v[180:183], v[188:191], v[114:117]
	s_setprio 0
	s_barrier
	s_add_i32 s53, s72, s30
	v_lshl_add_u64 v[218:219], s[34:35], 0, v[134:135]
	s_mov_b32 m0, s53
	ds_read_b128 v[184:187], v155 offset:16384
	ds_read_b128 v[188:191], v155 offset:17408
	ds_read_b128 v[192:195], v155 offset:18432
	ds_read_b128 v[196:199], v155 offset:19456
	ds_read_b128 v[200:203], v155 offset:20480
	ds_read_b128 v[204:207], v155 offset:21504
	ds_read_b128 v[208:211], v155 offset:22528
	ds_read_b128 v[212:215], v155 offset:23552
	global_load_lds_dwordx4 v[218:219], off
	s_add_i32 m0, s53, 0x2000
	s_add_u32 s54, s34, 0x80000
	v_lshl_add_u64 v[220:221], s[34:35], 0, v[130:131]
	s_addc_u32 s55, s35, 0
	s_add_i32 s53, s73, s30
	global_load_lds_dwordx4 v[220:221], off
	v_lshl_add_u64 v[222:223], s[54:55], 0, v[134:135]
	s_mov_b32 m0, s53
	v_lshl_add_u64 v[224:225], s[90:91], 0, v[132:133]
	global_load_lds_dwordx4 v[222:223], off
	v_lshl_add_u64 v[222:223], s[54:55], 0, v[130:131]
	s_add_i32 m0, s53, 0x2000
	s_nop 0
	global_load_lds_dwordx4 v[222:223], off
	v_lshl_add_u64 v[222:223], s[90:91], 0, v[136:137]
	s_mov_b32 m0, s56
	s_nop 0
	global_load_lds_dwordx4 v[222:223], off
	s_mov_b32 m0, s57
	s_nop 0
	global_load_lds_dwordx4 v[224:225], off
	s_waitcnt vmcnt(8)
	s_waitcnt lgkmcnt(0)
	s_barrier
	s_setprio 1
	s_waitcnt lgkmcnt(0)
	v_mfma_f32_16x16x32_bf16 v[62:65], v[146:149], v[184:187], v[62:65]
	v_mfma_f32_16x16x32_bf16 v[46:49], v[146:149], v[192:195], v[46:49]
	v_mfma_f32_16x16x32_bf16 v[30:33], v[146:149], v[200:203], v[30:33]
	v_mfma_f32_16x16x32_bf16 v[14:17], v[146:149], v[208:211], v[14:17]
	v_mfma_f32_16x16x32_bf16 v[6:9], v[160:163], v[208:211], v[6:9]
	v_mfma_f32_16x16x32_bf16 v[22:25], v[160:163], v[200:203], v[22:25]
	v_mfma_f32_16x16x32_bf16 v[38:41], v[160:163], v[192:195], v[38:41]
	v_mfma_f32_16x16x32_bf16 v[54:57], v[160:163], v[184:187], v[54:57]
	v_mfma_f32_16x16x32_bf16 v[62:65], v[156:159], v[188:191], v[62:65]
	v_mfma_f32_16x16x32_bf16 v[46:49], v[156:159], v[196:199], v[46:49]
	v_mfma_f32_16x16x32_bf16 v[30:33], v[156:159], v[204:207], v[30:33]
	v_mfma_f32_16x16x32_bf16 v[14:17], v[156:159], v[212:215], v[14:17]
	v_mfma_f32_16x16x32_bf16 v[6:9], v[164:167], v[212:215], v[6:9]
	v_mfma_f32_16x16x32_bf16 v[22:25], v[164:167], v[204:207], v[22:25]
	v_mfma_f32_16x16x32_bf16 v[38:41], v[164:167], v[196:199], v[38:41]
	v_mfma_f32_16x16x32_bf16 v[54:57], v[164:167], v[188:191], v[54:57]
	s_setprio 0
	s_setprio 1
	v_mfma_f32_16x16x32_bf16 v[58:61], v[168:171], v[184:187], v[58:61]
	v_mfma_f32_16x16x32_bf16 v[42:45], v[168:171], v[192:195], v[42:45]
	v_mfma_f32_16x16x32_bf16 v[26:29], v[168:171], v[200:203], v[26:29]
	v_mfma_f32_16x16x32_bf16 v[10:13], v[168:171], v[208:211], v[10:13]
	v_mfma_f32_16x16x32_bf16 v[2:5], v[176:179], v[208:211], v[2:5]
	v_mfma_f32_16x16x32_bf16 v[18:21], v[176:179], v[200:203], v[18:21]
	v_mfma_f32_16x16x32_bf16 v[34:37], v[176:179], v[192:195], v[34:37]
	v_mfma_f32_16x16x32_bf16 v[50:53], v[176:179], v[184:187], v[50:53]
	v_mfma_f32_16x16x32_bf16 v[58:61], v[172:175], v[188:191], v[58:61]
	v_mfma_f32_16x16x32_bf16 v[42:45], v[172:175], v[196:199], v[42:45]
	v_mfma_f32_16x16x32_bf16 v[26:29], v[172:175], v[204:207], v[26:29]
	v_mfma_f32_16x16x32_bf16 v[10:13], v[172:175], v[212:215], v[10:13]
	v_mfma_f32_16x16x32_bf16 v[2:5], v[180:183], v[212:215], v[2:5]
	v_mfma_f32_16x16x32_bf16 v[18:21], v[180:183], v[204:207], v[18:21]
	v_mfma_f32_16x16x32_bf16 v[34:37], v[180:183], v[196:199], v[34:37]
	v_mfma_f32_16x16x32_bf16 v[50:53], v[180:183], v[188:191], v[50:53]
	s_setprio 0
	s_barrier
	s_add_i32 s53, 0, 0x18000
	s_add_i32 s62, 0, 0x1c000
	v_add_u32_e32 v164, s53, v151
	v_add_u32_e32 v180, s62, v151
	ds_read_b128 v[146:149], v164
	ds_read_b128 v[156:159], v164 offset:1024
	ds_read_b128 v[160:163], v164 offset:2048
	ds_read_b128 v[164:167], v164 offset:3072
	ds_read_b128 v[168:171], v180
	ds_read_b128 v[172:175], v180 offset:1024
	ds_read_b128 v[176:179], v180 offset:2048
	ds_read_b128 v[180:183], v180 offset:3072
	s_add_u32 s54, s90, 0x80000
	s_addc_u32 s55, s91, 0
	s_mov_b32 m0, s58
	v_lshl_add_u64 v[226:227], s[54:55], 0, v[136:137]
	ds_read_b128 v[184:187], v155 offset:32768
	ds_read_b128 v[188:191], v155 offset:33792
	ds_read_b128 v[192:195], v155 offset:34816
	ds_read_b128 v[196:199], v155 offset:35840
	ds_read_b128 v[200:203], v155 offset:36864
	ds_read_b128 v[204:207], v155 offset:37888
	ds_read_b128 v[208:211], v155 offset:38912
	ds_read_b128 v[212:215], v155 offset:39936
	global_load_lds_dwordx4 v[226:227], off
	v_lshl_add_u64 v[226:227], s[54:55], 0, v[132:133]
	s_mov_b32 m0, s59
	s_nop 0
	global_load_lds_dwordx4 v[226:227], off
	s_waitcnt vmcnt(8)
	s_waitcnt lgkmcnt(0)
	s_barrier
	s_setprio 1
	s_waitcnt lgkmcnt(0)
	v_mfma_f32_16x16x32_bf16 v[126:129], v[146:149], v[184:187], v[126:129]
	v_mfma_f32_16x16x32_bf16 v[110:113], v[146:149], v[192:195], v[110:113]
	v_mfma_f32_16x16x32_bf16 v[94:97], v[146:149], v[200:203], v[94:97]
	v_mfma_f32_16x16x32_bf16 v[78:81], v[146:149], v[208:211], v[78:81]
	v_mfma_f32_16x16x32_bf16 v[70:73], v[160:163], v[208:211], v[70:73]
	v_mfma_f32_16x16x32_bf16 v[86:89], v[160:163], v[200:203], v[86:89]
	v_mfma_f32_16x16x32_bf16 v[102:105], v[160:163], v[192:195], v[102:105]
	v_mfma_f32_16x16x32_bf16 v[118:121], v[160:163], v[184:187], v[118:121]
	v_mfma_f32_16x16x32_bf16 v[126:129], v[156:159], v[188:191], v[126:129]
	v_mfma_f32_16x16x32_bf16 v[110:113], v[156:159], v[196:199], v[110:113]
	v_mfma_f32_16x16x32_bf16 v[94:97], v[156:159], v[204:207], v[94:97]
	v_mfma_f32_16x16x32_bf16 v[78:81], v[156:159], v[212:215], v[78:81]
	v_mfma_f32_16x16x32_bf16 v[70:73], v[164:167], v[212:215], v[70:73]
	v_mfma_f32_16x16x32_bf16 v[86:89], v[164:167], v[204:207], v[86:89]
	v_mfma_f32_16x16x32_bf16 v[102:105], v[164:167], v[196:199], v[102:105]
	v_mfma_f32_16x16x32_bf16 v[118:121], v[164:167], v[188:191], v[118:121]
	s_setprio 0
	s_setprio 1
	v_mfma_f32_16x16x32_bf16 v[122:125], v[168:171], v[184:187], v[122:125]
	v_mfma_f32_16x16x32_bf16 v[106:109], v[168:171], v[192:195], v[106:109]
	v_mfma_f32_16x16x32_bf16 v[90:93], v[168:171], v[200:203], v[90:93]
	v_mfma_f32_16x16x32_bf16 v[74:77], v[168:171], v[208:211], v[74:77]
	v_mfma_f32_16x16x32_bf16 v[66:69], v[176:179], v[208:211], v[66:69]
	v_mfma_f32_16x16x32_bf16 v[82:85], v[176:179], v[200:203], v[82:85]
	v_mfma_f32_16x16x32_bf16 v[98:101], v[176:179], v[192:195], v[98:101]
	v_mfma_f32_16x16x32_bf16 v[114:117], v[176:179], v[184:187], v[114:117]
	v_mfma_f32_16x16x32_bf16 v[122:125], v[172:175], v[188:191], v[122:125]
	v_mfma_f32_16x16x32_bf16 v[106:109], v[172:175], v[196:199], v[106:109]
	v_mfma_f32_16x16x32_bf16 v[90:93], v[172:175], v[204:207], v[90:93]
	v_mfma_f32_16x16x32_bf16 v[74:77], v[172:175], v[212:215], v[74:77]
	v_mfma_f32_16x16x32_bf16 v[66:69], v[180:183], v[212:215], v[66:69]
	v_mfma_f32_16x16x32_bf16 v[82:85], v[180:183], v[204:207], v[82:85]
	v_mfma_f32_16x16x32_bf16 v[98:101], v[180:183], v[196:199], v[98:101]
	v_mfma_f32_16x16x32_bf16 v[114:117], v[180:183], v[188:191], v[114:117]
	s_setprio 0
	s_barrier
	s_add_i32 s53, s53, s30
	v_lshl_add_u64 v[218:219], v[218:219], 0, s[8:9]
	s_mov_b32 m0, s53
	ds_read_b128 v[184:187], v155 offset:49152
	ds_read_b128 v[188:191], v155 offset:50176
	ds_read_b128 v[192:195], v155 offset:51200
	ds_read_b128 v[196:199], v155 offset:52224
	ds_read_b128 v[200:203], v155 offset:53248
	ds_read_b128 v[204:207], v155 offset:54272
	ds_read_b128 v[208:211], v155 offset:55296
	ds_read_b128 v[212:215], v155 offset:56320
	global_load_lds_dwordx4 v[218:219], off
	s_add_i32 m0, s53, 0x2000
	s_add_u32 s34, s34, 0x80080
	v_lshl_add_u64 v[218:219], v[220:221], 0, s[8:9]
	s_addc_u32 s35, s35, 0
	s_add_i32 s53, s62, s30
	global_load_lds_dwordx4 v[218:219], off
	v_lshl_add_u64 v[218:219], s[34:35], 0, v[134:135]
	s_mov_b32 m0, s53
	s_nop 0
	global_load_lds_dwordx4 v[218:219], off
	v_lshl_add_u64 v[218:219], s[34:35], 0, v[130:131]
	s_add_i32 m0, s53, 0x2000
	s_nop 0
	global_load_lds_dwordx4 v[218:219], off
	v_lshl_add_u64 v[218:219], v[222:223], 0, s[8:9]
	s_mov_b32 m0, s61
	s_nop 0
	global_load_lds_dwordx4 v[218:219], off
	v_lshl_add_u64 v[218:219], v[224:225], 0, s[8:9]
	s_mov_b32 m0, s70
	s_nop 0
	global_load_lds_dwordx4 v[218:219], off
	s_waitcnt vmcnt(8)
	s_waitcnt lgkmcnt(0)
	s_barrier
	s_setprio 1
	s_waitcnt lgkmcnt(0)
	v_mfma_f32_16x16x32_bf16 v[62:65], v[146:149], v[184:187], v[62:65]
	v_mfma_f32_16x16x32_bf16 v[46:49], v[146:149], v[192:195], v[46:49]
	v_mfma_f32_16x16x32_bf16 v[30:33], v[146:149], v[200:203], v[30:33]
	v_mfma_f32_16x16x32_bf16 v[14:17], v[146:149], v[208:211], v[14:17]
	v_mfma_f32_16x16x32_bf16 v[6:9], v[160:163], v[208:211], v[6:9]
	v_mfma_f32_16x16x32_bf16 v[22:25], v[160:163], v[200:203], v[22:25]
	v_mfma_f32_16x16x32_bf16 v[38:41], v[160:163], v[192:195], v[38:41]
	v_mfma_f32_16x16x32_bf16 v[54:57], v[160:163], v[184:187], v[54:57]
	v_mfma_f32_16x16x32_bf16 v[62:65], v[156:159], v[188:191], v[62:65]
	v_mfma_f32_16x16x32_bf16 v[46:49], v[156:159], v[196:199], v[46:49]
	v_mfma_f32_16x16x32_bf16 v[30:33], v[156:159], v[204:207], v[30:33]
	v_mfma_f32_16x16x32_bf16 v[14:17], v[156:159], v[212:215], v[14:17]
	v_mfma_f32_16x16x32_bf16 v[6:9], v[164:167], v[212:215], v[6:9]
	v_mfma_f32_16x16x32_bf16 v[22:25], v[164:167], v[204:207], v[22:25]
	v_mfma_f32_16x16x32_bf16 v[38:41], v[164:167], v[196:199], v[38:41]
	v_mfma_f32_16x16x32_bf16 v[54:57], v[164:167], v[188:191], v[54:57]
	s_setprio 0
	s_setprio 1
	v_mfma_f32_16x16x32_bf16 v[58:61], v[168:171], v[184:187], v[58:61]
	v_mfma_f32_16x16x32_bf16 v[42:45], v[168:171], v[192:195], v[42:45]
	v_mfma_f32_16x16x32_bf16 v[26:29], v[168:171], v[200:203], v[26:29]
	v_mfma_f32_16x16x32_bf16 v[10:13], v[168:171], v[208:211], v[10:13]
	v_mfma_f32_16x16x32_bf16 v[2:5], v[176:179], v[208:211], v[2:5]
	v_mfma_f32_16x16x32_bf16 v[18:21], v[176:179], v[200:203], v[18:21]
	v_mfma_f32_16x16x32_bf16 v[34:37], v[176:179], v[192:195], v[34:37]
	v_mfma_f32_16x16x32_bf16 v[50:53], v[176:179], v[184:187], v[50:53]
	v_mfma_f32_16x16x32_bf16 v[58:61], v[172:175], v[188:191], v[58:61]
	v_mfma_f32_16x16x32_bf16 v[42:45], v[172:175], v[196:199], v[42:45]
	v_mfma_f32_16x16x32_bf16 v[26:29], v[172:175], v[204:207], v[26:29]
	v_mfma_f32_16x16x32_bf16 v[10:13], v[172:175], v[212:215], v[10:13]
	v_mfma_f32_16x16x32_bf16 v[2:5], v[180:183], v[212:215], v[2:5]
	v_mfma_f32_16x16x32_bf16 v[18:21], v[180:183], v[204:207], v[18:21]
	v_mfma_f32_16x16x32_bf16 v[34:37], v[180:183], v[196:199], v[34:37]
	v_mfma_f32_16x16x32_bf16 v[50:53], v[180:183], v[188:191], v[50:53]
	s_setprio 0
	s_barrier
	s_add_i32 s92, s92, 2
	s_add_u32 s88, s88, 0x100
	s_addc_u32 s89, s89, 0
	s_add_u32 s81, s81, 0x100
	s_addc_u32 s83, s83, 0
	s_cmp_gt_u32 s92, 29
	s_cbranch_scc0 .LBB0_1124
	v_mov_b32_e32 v157, 0xbfb8aa3b
	s_and_b64 vcc, exec, s[78:79]
	s_cbranch_vccz .LBB0_1127
	s_barrier

.LBB0_1237:
	ds_read_b128 v[146:149], v164
	ds_read_b128 v[150:153], v164 offset:1024
	ds_read_b128 v[154:157], v164 offset:2048
	ds_read_b128 v[158:161], v164 offset:3072
	ds_read_b128 v[168:171], v165
	ds_read_b128 v[172:175], v165 offset:1024
	ds_read_b128 v[176:179], v165 offset:2048
	ds_read_b128 v[180:183], v165 offset:3072
	s_add_u32 s34, s76, 0xffea0080
	s_addc_u32 s35, s77, -1
	s_cmpk_eq_i32 s52, 0x54
	s_cselect_b32 s85, s5, s35
	s_cselect_b32 s84, s4, s34
	s_cselect_b32 s35, s83, s1
	s_cselect_b32 s34, s82, s0
	v_lshl_add_u64 v[218:219], s[76:77], 0, v[138:139]
	s_add_i32 m0, s33, 0xc000
	ds_read_b128 v[184:187], v166
	ds_read_b128 v[188:191], v166 offset:1024
	ds_read_b128 v[192:195], v166 offset:2048
	ds_read_b128 v[196:199], v166 offset:3072
	ds_read_b128 v[200:203], v166 offset:4096
	ds_read_b128 v[204:207], v166 offset:5120
	ds_read_b128 v[208:211], v166 offset:6144
	ds_read_b128 v[212:215], v166 offset:7168
	global_load_lds_dwordx4 v[218:219], off
	v_lshl_add_u64 v[218:219], s[76:77], 0, v[140:141]
	s_add_i32 m0, s33, 0xe000
	s_nop 0
	global_load_lds_dwordx4 v[218:219], off
	s_waitcnt vmcnt(8)
	s_waitcnt lgkmcnt(0)
	s_barrier
	s_setprio 1
	s_waitcnt lgkmcnt(0)
	v_mfma_f32_16x16x32_bf16 v[126:129], v[146:149], v[184:187], v[126:129]
	v_mfma_f32_16x16x32_bf16 v[110:113], v[146:149], v[192:195], v[110:113]
	v_mfma_f32_16x16x32_bf16 v[94:97], v[146:149], v[200:203], v[94:97]
	v_mfma_f32_16x16x32_bf16 v[78:81], v[146:149], v[208:211], v[78:81]
	v_mfma_f32_16x16x32_bf16 v[74:77], v[154:157], v[208:211], v[74:77]
	v_mfma_f32_16x16x32_bf16 v[90:93], v[154:157], v[200:203], v[90:93]
	v_mfma_f32_16x16x32_bf16 v[106:109], v[154:157], v[192:195], v[106:109]
	v_mfma_f32_16x16x32_bf16 v[122:125], v[154:157], v[184:187], v[122:125]
	v_mfma_f32_16x16x32_bf16 v[126:129], v[150:153], v[188:191], v[126:129]
	v_mfma_f32_16x16x32_bf16 v[110:113], v[150:153], v[196:199], v[110:113]
	v_mfma_f32_16x16x32_bf16 v[94:97], v[150:153], v[204:207], v[94:97]
	v_mfma_f32_16x16x32_bf16 v[78:81], v[150:153], v[212:215], v[78:81]
	v_mfma_f32_16x16x32_bf16 v[74:77], v[158:161], v[212:215], v[74:77]
	v_mfma_f32_16x16x32_bf16 v[90:93], v[158:161], v[204:207], v[90:93]
	v_mfma_f32_16x16x32_bf16 v[106:109], v[158:161], v[196:199], v[106:109]
	v_mfma_f32_16x16x32_bf16 v[122:125], v[158:161], v[188:191], v[122:125]
	s_setprio 0
	s_setprio 1
	v_mfma_f32_16x16x32_bf16 v[118:121], v[168:171], v[184:187], v[118:121]
	v_mfma_f32_16x16x32_bf16 v[102:105], v[168:171], v[192:195], v[102:105]
	v_mfma_f32_16x16x32_bf16 v[86:89], v[168:171], v[200:203], v[86:89]
	v_mfma_f32_16x16x32_bf16 v[70:73], v[168:171], v[208:211], v[70:73]
	v_mfma_f32_16x16x32_bf16 v[66:69], v[176:179], v[208:211], v[66:69]
	v_mfma_f32_16x16x32_bf16 v[82:85], v[176:179], v[200:203], v[82:85]
	v_mfma_f32_16x16x32_bf16 v[98:101], v[176:179], v[192:195], v[98:101]
	v_mfma_f32_16x16x32_bf16 v[114:117], v[176:179], v[184:187], v[114:117]
	v_mfma_f32_16x16x32_bf16 v[118:121], v[172:175], v[188:191], v[118:121]
	v_mfma_f32_16x16x32_bf16 v[102:105], v[172:175], v[196:199], v[102:105]
	v_mfma_f32_16x16x32_bf16 v[86:89], v[172:175], v[204:207], v[86:89]
	v_mfma_f32_16x16x32_bf16 v[70:73], v[172:175], v[212:215], v[70:73]
	v_mfma_f32_16x16x32_bf16 v[66:69], v[180:183], v[212:215], v[66:69]
	v_mfma_f32_16x16x32_bf16 v[82:85], v[180:183], v[204:207], v[82:85]
	v_mfma_f32_16x16x32_bf16 v[98:101], v[180:183], v[196:199], v[98:101]
	v_mfma_f32_16x16x32_bf16 v[114:117], v[180:183], v[188:191], v[114:117]
	s_setprio 0
	s_barrier
	s_add_i32 s53, s71, s31
	v_lshl_add_u64 v[218:219], s[34:35], 0, v[132:133]
	s_mov_b32 m0, s53
	ds_read_b128 v[184:187], v166 offset:16384
	ds_read_b128 v[188:191], v166 offset:17408
	ds_read_b128 v[192:195], v166 offset:18432
	ds_read_b128 v[196:199], v166 offset:19456
	ds_read_b128 v[200:203], v166 offset:20480
	ds_read_b128 v[204:207], v166 offset:21504
	ds_read_b128 v[208:211], v166 offset:22528
	ds_read_b128 v[212:215], v166 offset:23552
	global_load_lds_dwordx4 v[218:219], off
	s_add_i32 m0, s53, 0x2000
	s_add_u32 s54, s34, 0x160000
	v_lshl_add_u64 v[220:221], s[34:35], 0, v[136:137]
	s_addc_u32 s55, s35, 0
	s_add_i32 s53, s72, s31
	global_load_lds_dwordx4 v[220:221], off
	v_lshl_add_u64 v[222:223], s[54:55], 0, v[132:133]
	s_mov_b32 m0, s53
	v_lshl_add_u64 v[224:225], s[84:85], 0, v[134:135]
	global_load_lds_dwordx4 v[222:223], off
	v_lshl_add_u64 v[222:223], s[54:55], 0, v[136:137]
	s_add_i32 m0, s53, 0x2000
	s_nop 0
	global_load_lds_dwordx4 v[222:223], off
	v_lshl_add_u64 v[222:223], s[84:85], 0, v[130:131]
	s_mov_b32 m0, s33
	s_nop 0
	global_load_lds_dwordx4 v[222:223], off
	s_mov_b32 m0, s56
	s_nop 0
	global_load_lds_dwordx4 v[224:225], off
	s_waitcnt vmcnt(8)
	s_waitcnt lgkmcnt(0)
	s_barrier
	s_setprio 1
	s_waitcnt lgkmcnt(0)
	v_mfma_f32_16x16x32_bf16 v[62:65], v[146:149], v[184:187], v[62:65]
	v_mfma_f32_16x16x32_bf16 v[46:49], v[146:149], v[192:195], v[46:49]
	v_mfma_f32_16x16x32_bf16 v[30:33], v[146:149], v[200:203], v[30:33]
	v_mfma_f32_16x16x32_bf16 v[14:17], v[146:149], v[208:211], v[14:17]
	v_mfma_f32_16x16x32_bf16 v[10:13], v[154:157], v[208:211], v[10:13]
	v_mfma_f32_16x16x32_bf16 v[26:29], v[154:157], v[200:203], v[26:29]
	v_mfma_f32_16x16x32_bf16 v[42:45], v[154:157], v[192:195], v[42:45]
	v_mfma_f32_16x16x32_bf16 v[58:61], v[154:157], v[184:187], v[58:61]
	v_mfma_f32_16x16x32_bf16 v[62:65], v[150:153], v[188:191], v[62:65]
	v_mfma_f32_16x16x32_bf16 v[46:49], v[150:153], v[196:199], v[46:49]
	v_mfma_f32_16x16x32_bf16 v[30:33], v[150:153], v[204:207], v[30:33]
	v_mfma_f32_16x16x32_bf16 v[14:17], v[150:153], v[212:215], v[14:17]
	v_mfma_f32_16x16x32_bf16 v[10:13], v[158:161], v[212:215], v[10:13]
	v_mfma_f32_16x16x32_bf16 v[26:29], v[158:161], v[204:207], v[26:29]
	v_mfma_f32_16x16x32_bf16 v[42:45], v[158:161], v[196:199], v[42:45]
	v_mfma_f32_16x16x32_bf16 v[58:61], v[158:161], v[188:191], v[58:61]
	s_setprio 0
	s_setprio 1
	v_mfma_f32_16x16x32_bf16 v[54:57], v[168:171], v[184:187], v[54:57]
	v_mfma_f32_16x16x32_bf16 v[38:41], v[168:171], v[192:195], v[38:41]
	v_mfma_f32_16x16x32_bf16 v[22:25], v[168:171], v[200:203], v[22:25]
	v_mfma_f32_16x16x32_bf16 v[6:9], v[168:171], v[208:211], v[6:9]
	v_mfma_f32_16x16x32_bf16 v[2:5], v[176:179], v[208:211], v[2:5]
	v_mfma_f32_16x16x32_bf16 v[18:21], v[176:179], v[200:203], v[18:21]
	v_mfma_f32_16x16x32_bf16 v[34:37], v[176:179], v[192:195], v[34:37]
	v_mfma_f32_16x16x32_bf16 v[50:53], v[176:179], v[184:187], v[50:53]
	v_mfma_f32_16x16x32_bf16 v[54:57], v[172:175], v[188:191], v[54:57]
	v_mfma_f32_16x16x32_bf16 v[38:41], v[172:175], v[196:199], v[38:41]
	v_mfma_f32_16x16x32_bf16 v[22:25], v[172:175], v[204:207], v[22:25]
	v_mfma_f32_16x16x32_bf16 v[6:9], v[172:175], v[212:215], v[6:9]
	v_mfma_f32_16x16x32_bf16 v[2:5], v[180:183], v[212:215], v[2:5]
	v_mfma_f32_16x16x32_bf16 v[18:21], v[180:183], v[204:207], v[18:21]
	v_mfma_f32_16x16x32_bf16 v[34:37], v[180:183], v[196:199], v[34:37]
	v_mfma_f32_16x16x32_bf16 v[50:53], v[180:183], v[188:191], v[50:53]
	s_setprio 0
	s_barrier
	s_add_i32 s53, 0, 0x18000
	s_add_i32 s62, 0, 0x1c000
	v_add_u32_e32 v158, s53, v162
	v_add_u32_e32 v167, s62, v162
	ds_read_b128 v[146:149], v158
	ds_read_b128 v[150:153], v158 offset:1024
	ds_read_b128 v[154:157], v158 offset:2048
	ds_read_b128 v[158:161], v158 offset:3072
	ds_read_b128 v[168:171], v167
	ds_read_b128 v[172:175], v167 offset:1024
	ds_read_b128 v[176:179], v167 offset:2048
	ds_read_b128 v[180:183], v167 offset:3072
	s_add_u32 s54, s84, 0x160000
	s_addc_u32 s55, s85, 0
	s_mov_b32 m0, s57
	v_lshl_add_u64 v[226:227], s[54:55], 0, v[130:131]
	ds_read_b128 v[184:187], v166 offset:32768
	ds_read_b128 v[188:191], v166 offset:33792
	ds_read_b128 v[192:195], v166 offset:34816
	ds_read_b128 v[196:199], v166 offset:35840
	ds_read_b128 v[200:203], v166 offset:36864
	ds_read_b128 v[204:207], v166 offset:37888
	ds_read_b128 v[208:211], v166 offset:38912
	ds_read_b128 v[212:215], v166 offset:39936
	global_load_lds_dwordx4 v[226:227], off
	v_lshl_add_u64 v[226:227], s[54:55], 0, v[134:135]
	s_mov_b32 m0, s58
	s_nop 0
	global_load_lds_dwordx4 v[226:227], off
	s_waitcnt vmcnt(8)
	s_waitcnt lgkmcnt(0)
	s_barrier
	s_setprio 1
	s_waitcnt lgkmcnt(0)
	v_mfma_f32_16x16x32_bf16 v[126:129], v[146:149], v[184:187], v[126:129]
	v_mfma_f32_16x16x32_bf16 v[110:113], v[146:149], v[192:195], v[110:113]
	v_mfma_f32_16x16x32_bf16 v[94:97], v[146:149], v[200:203], v[94:97]
	v_mfma_f32_16x16x32_bf16 v[78:81], v[146:149], v[208:211], v[78:81]
	v_mfma_f32_16x16x32_bf16 v[74:77], v[154:157], v[208:211], v[74:77]
	v_mfma_f32_16x16x32_bf16 v[90:93], v[154:157], v[200:203], v[90:93]
	v_mfma_f32_16x16x32_bf16 v[106:109], v[154:157], v[192:195], v[106:109]
	v_mfma_f32_16x16x32_bf16 v[122:125], v[154:157], v[184:187], v[122:125]
	v_mfma_f32_16x16x32_bf16 v[126:129], v[150:153], v[188:191], v[126:129]
	v_mfma_f32_16x16x32_bf16 v[110:113], v[150:153], v[196:199], v[110:113]
	v_mfma_f32_16x16x32_bf16 v[94:97], v[150:153], v[204:207], v[94:97]
	v_mfma_f32_16x16x32_bf16 v[78:81], v[150:153], v[212:215], v[78:81]
	v_mfma_f32_16x16x32_bf16 v[74:77], v[158:161], v[212:215], v[74:77]
	v_mfma_f32_16x16x32_bf16 v[90:93], v[158:161], v[204:207], v[90:93]
	v_mfma_f32_16x16x32_bf16 v[106:109], v[158:161], v[196:199], v[106:109]
	v_mfma_f32_16x16x32_bf16 v[122:125], v[158:161], v[188:191], v[122:125]
	s_setprio 0
	s_setprio 1
	v_mfma_f32_16x16x32_bf16 v[118:121], v[168:171], v[184:187], v[118:121]
	v_mfma_f32_16x16x32_bf16 v[102:105], v[168:171], v[192:195], v[102:105]
	v_mfma_f32_16x16x32_bf16 v[86:89], v[168:171], v[200:203], v[86:89]
	v_mfma_f32_16x16x32_bf16 v[70:73], v[168:171], v[208:211], v[70:73]
	v_mfma_f32_16x16x32_bf16 v[66:69], v[176:179], v[208:211], v[66:69]
	v_mfma_f32_16x16x32_bf16 v[82:85], v[176:179], v[200:203], v[82:85]
	v_mfma_f32_16x16x32_bf16 v[98:101], v[176:179], v[192:195], v[98:101]
	v_mfma_f32_16x16x32_bf16 v[114:117], v[176:179], v[184:187], v[114:117]
	v_mfma_f32_16x16x32_bf16 v[118:121], v[172:175], v[188:191], v[118:121]
	v_mfma_f32_16x16x32_bf16 v[102:105], v[172:175], v[196:199], v[102:105]
	v_mfma_f32_16x16x32_bf16 v[86:89], v[172:175], v[204:207], v[86:89]
	v_mfma_f32_16x16x32_bf16 v[70:73], v[172:175], v[212:215], v[70:73]
	v_mfma_f32_16x16x32_bf16 v[66:69], v[180:183], v[212:215], v[66:69]
	v_mfma_f32_16x16x32_bf16 v[82:85], v[180:183], v[204:207], v[82:85]
	v_mfma_f32_16x16x32_bf16 v[98:101], v[180:183], v[196:199], v[98:101]
	v_mfma_f32_16x16x32_bf16 v[114:117], v[180:183], v[188:191], v[114:117]
	s_setprio 0
	s_barrier
	s_add_i32 s53, s53, s31
	v_lshl_add_u64 v[218:219], v[218:219], 0, s[78:79]
	s_mov_b32 m0, s53
	ds_read_b128 v[184:187], v166 offset:49152
	ds_read_b128 v[188:191], v166 offset:50176
	ds_read_b128 v[192:195], v166 offset:51200
	ds_read_b128 v[196:199], v166 offset:52224
	ds_read_b128 v[200:203], v166 offset:53248
	ds_read_b128 v[204:207], v166 offset:54272
	ds_read_b128 v[208:211], v166 offset:55296
	ds_read_b128 v[212:215], v166 offset:56320
	global_load_lds_dwordx4 v[218:219], off
	s_add_i32 m0, s53, 0x2000
	s_add_u32 s34, s34, 0x160080
	v_lshl_add_u64 v[218:219], v[220:221], 0, s[78:79]
	s_addc_u32 s35, s35, 0
	s_add_i32 s53, s62, s31
	global_load_lds_dwordx4 v[218:219], off
	v_lshl_add_u64 v[218:219], s[34:35], 0, v[132:133]
	s_mov_b32 m0, s53
	s_nop 0
	global_load_lds_dwordx4 v[218:219], off
	v_lshl_add_u64 v[218:219], s[34:35], 0, v[136:137]
	s_add_i32 m0, s53, 0x2000
	s_nop 0
	global_load_lds_dwordx4 v[218:219], off
	v_lshl_add_u64 v[218:219], v[222:223], 0, s[78:79]
	s_mov_b32 m0, s60
	s_nop 0
	global_load_lds_dwordx4 v[218:219], off
	v_lshl_add_u64 v[218:219], v[224:225], 0, s[78:79]
	s_mov_b32 m0, s61
	s_nop 0
	global_load_lds_dwordx4 v[218:219], off
	s_waitcnt vmcnt(8)
	s_waitcnt lgkmcnt(0)
	s_barrier
	s_setprio 1
	s_waitcnt lgkmcnt(0)
	v_mfma_f32_16x16x32_bf16 v[62:65], v[146:149], v[184:187], v[62:65]
	v_mfma_f32_16x16x32_bf16 v[46:49], v[146:149], v[192:195], v[46:49]
	v_mfma_f32_16x16x32_bf16 v[30:33], v[146:149], v[200:203], v[30:33]
	v_mfma_f32_16x16x32_bf16 v[14:17], v[146:149], v[208:211], v[14:17]
	v_mfma_f32_16x16x32_bf16 v[10:13], v[154:157], v[208:211], v[10:13]
	v_mfma_f32_16x16x32_bf16 v[26:29], v[154:157], v[200:203], v[26:29]
	v_mfma_f32_16x16x32_bf16 v[42:45], v[154:157], v[192:195], v[42:45]
	v_mfma_f32_16x16x32_bf16 v[58:61], v[154:157], v[184:187], v[58:61]
	v_mfma_f32_16x16x32_bf16 v[62:65], v[150:153], v[188:191], v[62:65]
	v_mfma_f32_16x16x32_bf16 v[46:49], v[150:153], v[196:199], v[46:49]
	v_mfma_f32_16x16x32_bf16 v[30:33], v[150:153], v[204:207], v[30:33]
	v_mfma_f32_16x16x32_bf16 v[14:17], v[150:153], v[212:215], v[14:17]
	v_mfma_f32_16x16x32_bf16 v[10:13], v[158:161], v[212:215], v[10:13]
	v_mfma_f32_16x16x32_bf16 v[26:29], v[158:161], v[204:207], v[26:29]
	v_mfma_f32_16x16x32_bf16 v[42:45], v[158:161], v[196:199], v[42:45]
	v_mfma_f32_16x16x32_bf16 v[58:61], v[158:161], v[188:191], v[58:61]
	s_setprio 0
	s_setprio 1
	v_mfma_f32_16x16x32_bf16 v[54:57], v[168:171], v[184:187], v[54:57]
	v_mfma_f32_16x16x32_bf16 v[38:41], v[168:171], v[192:195], v[38:41]
	v_mfma_f32_16x16x32_bf16 v[22:25], v[168:171], v[200:203], v[22:25]
	v_mfma_f32_16x16x32_bf16 v[6:9], v[168:171], v[208:211], v[6:9]
	v_mfma_f32_16x16x32_bf16 v[2:5], v[176:179], v[208:211], v[2:5]
	v_mfma_f32_16x16x32_bf16 v[18:21], v[176:179], v[200:203], v[18:21]
	v_mfma_f32_16x16x32_bf16 v[34:37], v[176:179], v[192:195], v[34:37]
	v_mfma_f32_16x16x32_bf16 v[50:53], v[176:179], v[184:187], v[50:53]
	v_mfma_f32_16x16x32_bf16 v[54:57], v[172:175], v[188:191], v[54:57]
	v_mfma_f32_16x16x32_bf16 v[38:41], v[172:175], v[196:199], v[38:41]
	v_mfma_f32_16x16x32_bf16 v[22:25], v[172:175], v[204:207], v[22:25]
	v_mfma_f32_16x16x32_bf16 v[6:9], v[172:175], v[212:215], v[6:9]
	v_mfma_f32_16x16x32_bf16 v[2:5], v[180:183], v[212:215], v[2:5]
	v_mfma_f32_16x16x32_bf16 v[18:21], v[180:183], v[204:207], v[18:21]
	v_mfma_f32_16x16x32_bf16 v[34:37], v[180:183], v[196:199], v[34:37]
	v_mfma_f32_16x16x32_bf16 v[50:53], v[180:183], v[188:191], v[50:53]
	s_setprio 0
	s_barrier
	s_add_i32 s52, s52, 2
	s_add_u32 s76, s76, 0x100
	s_addc_u32 s77, s77, 0
	s_add_u32 s0, s0, 0x100
	s_addc_u32 s1, s1, 0
	s_cmpk_gt_u32 s52, 0x55
	s_cbranch_scc0 .LBB0_1237
	s_and_b64 vcc, exec, s[80:81]
	s_cbranch_vccz .LBB0_1240
	s_barrier

.LBB0_1624:
	ds_read_b128 v[154:157], v151
	ds_read_b128 v[158:161], v151 offset:1024
	ds_read_b128 v[162:165], v151 offset:2048
	ds_read_b128 v[166:169], v151 offset:3072
	ds_read_b128 v[170:173], v152
	ds_read_b128 v[174:177], v152 offset:1024
	ds_read_b128 v[178:181], v152 offset:2048
	ds_read_b128 v[182:185], v152 offset:3072
	s_add_u32 s34, s88, 0xfff80080
	s_addc_u32 s35, s89, -1
	s_cmp_eq_u32 s83, 28
	s_cselect_b32 s91, s0, s35
	s_cselect_b32 s90, s1, s34
	s_cselect_b32 s35, s52, s81
	s_cselect_b32 s34, s75, s77
	v_lshl_add_u64 v[146:147], s[88:89], 0, v[138:139]
	s_add_i32 m0, s33, 0xc000
	ds_read_b128 v[186:189], v153
	ds_read_b128 v[190:193], v153 offset:1024
	ds_read_b128 v[194:197], v153 offset:2048
	ds_read_b128 v[198:201], v153 offset:3072
	ds_read_b128 v[202:205], v153 offset:4096
	ds_read_b128 v[206:209], v153 offset:5120
	ds_read_b128 v[210:213], v153 offset:6144
	ds_read_b128 v[218:221], v153 offset:7168
	global_load_lds_dwordx4 v[146:147], off
	v_lshl_add_u64 v[146:147], s[88:89], 0, v[140:141]
	s_add_i32 m0, s33, 0xe000
	s_nop 0
	global_load_lds_dwordx4 v[146:147], off
	s_waitcnt vmcnt(8)
	s_waitcnt lgkmcnt(0)
	s_barrier
	s_setprio 1
	s_waitcnt lgkmcnt(0)
	v_mfma_f32_16x16x32_bf16 v[126:129], v[154:157], v[186:189], v[126:129]
	v_mfma_f32_16x16x32_bf16 v[114:117], v[154:157], v[194:197], v[114:117]
	v_mfma_f32_16x16x32_bf16 v[98:101], v[154:157], v[202:205], v[98:101]
	v_mfma_f32_16x16x32_bf16 v[82:85], v[154:157], v[210:213], v[82:85]
	v_mfma_f32_16x16x32_bf16 v[74:77], v[162:165], v[210:213], v[74:77]
	v_mfma_f32_16x16x32_bf16 v[90:93], v[162:165], v[202:205], v[90:93]
	v_mfma_f32_16x16x32_bf16 v[106:109], v[162:165], v[194:197], v[106:109]
	v_mfma_f32_16x16x32_bf16 v[122:125], v[162:165], v[186:189], v[122:125]
	v_mfma_f32_16x16x32_bf16 v[126:129], v[158:161], v[190:193], v[126:129]
	v_mfma_f32_16x16x32_bf16 v[114:117], v[158:161], v[198:201], v[114:117]
	v_mfma_f32_16x16x32_bf16 v[98:101], v[158:161], v[206:209], v[98:101]
	v_mfma_f32_16x16x32_bf16 v[82:85], v[158:161], v[218:221], v[82:85]
	v_mfma_f32_16x16x32_bf16 v[74:77], v[166:169], v[218:221], v[74:77]
	v_mfma_f32_16x16x32_bf16 v[90:93], v[166:169], v[206:209], v[90:93]
	v_mfma_f32_16x16x32_bf16 v[106:109], v[166:169], v[198:201], v[106:109]
	v_mfma_f32_16x16x32_bf16 v[122:125], v[166:169], v[190:193], v[122:125]
	s_setprio 0
	s_setprio 1
	v_mfma_f32_16x16x32_bf16 v[118:121], v[170:173], v[186:189], v[118:121]
	v_mfma_f32_16x16x32_bf16 v[102:105], v[170:173], v[194:197], v[102:105]
	v_mfma_f32_16x16x32_bf16 v[86:89], v[170:173], v[202:205], v[86:89]
	v_mfma_f32_16x16x32_bf16 v[70:73], v[170:173], v[210:213], v[70:73]
	v_mfma_f32_16x16x32_bf16 v[66:69], v[178:181], v[210:213], v[66:69]
	v_mfma_f32_16x16x32_bf16 v[78:81], v[178:181], v[202:205], v[78:81]
	v_mfma_f32_16x16x32_bf16 v[94:97], v[178:181], v[194:197], v[94:97]
	v_mfma_f32_16x16x32_bf16 v[110:113], v[178:181], v[186:189], v[110:113]
	v_mfma_f32_16x16x32_bf16 v[118:121], v[174:177], v[190:193], v[118:121]
	v_mfma_f32_16x16x32_bf16 v[102:105], v[174:177], v[198:201], v[102:105]
	v_mfma_f32_16x16x32_bf16 v[86:89], v[174:177], v[206:209], v[86:89]
	v_mfma_f32_16x16x32_bf16 v[70:73], v[174:177], v[218:221], v[70:73]
	v_mfma_f32_16x16x32_bf16 v[66:69], v[182:185], v[218:221], v[66:69]
	v_mfma_f32_16x16x32_bf16 v[78:81], v[182:185], v[206:209], v[78:81]
	v_mfma_f32_16x16x32_bf16 v[94:97], v[182:185], v[198:201], v[94:97]
	v_mfma_f32_16x16x32_bf16 v[110:113], v[182:185], v[190:193], v[110:113]
	s_setprio 0
	s_barrier
	s_add_i32 s53, s71, s12
	v_lshl_add_u64 v[146:147], s[34:35], 0, v[134:135]
	s_mov_b32 m0, s53
	ds_read_b128 v[186:189], v153 offset:16384
	ds_read_b128 v[190:193], v153 offset:17408
	ds_read_b128 v[194:197], v153 offset:18432
	ds_read_b128 v[198:201], v153 offset:19456
	ds_read_b128 v[202:205], v153 offset:20480
	ds_read_b128 v[206:209], v153 offset:21504
	ds_read_b128 v[210:213], v153 offset:22528
	ds_read_b128 v[218:221], v153 offset:23552
	global_load_lds_dwordx4 v[146:147], off
	s_add_i32 m0, s53, 0x2000
	s_add_u32 s54, s34, 0x80000
	v_lshl_add_u64 v[214:215], s[34:35], 0, v[130:131]
	s_addc_u32 s55, s35, 0
	s_add_i32 s53, s72, s12
	global_load_lds_dwordx4 v[214:215], off
	v_lshl_add_u64 v[222:223], s[54:55], 0, v[134:135]
	s_mov_b32 m0, s53
	v_lshl_add_u64 v[224:225], s[90:91], 0, v[132:133]
	global_load_lds_dwordx4 v[222:223], off
	v_lshl_add_u64 v[222:223], s[54:55], 0, v[130:131]
	s_add_i32 m0, s53, 0x2000
	s_nop 0
	global_load_lds_dwordx4 v[222:223], off
	v_lshl_add_u64 v[222:223], s[90:91], 0, v[136:137]
	s_mov_b32 m0, s33
	s_nop 0
	global_load_lds_dwordx4 v[222:223], off
	s_mov_b32 m0, s56
	s_nop 0
	global_load_lds_dwordx4 v[224:225], off
	s_waitcnt vmcnt(8)
	s_waitcnt lgkmcnt(0)
	s_barrier
	s_setprio 1
	s_waitcnt lgkmcnt(0)
	v_mfma_f32_16x16x32_bf16 v[62:65], v[154:157], v[186:189], v[62:65]
	v_mfma_f32_16x16x32_bf16 v[50:53], v[154:157], v[194:197], v[50:53]
	v_mfma_f32_16x16x32_bf16 v[34:37], v[154:157], v[202:205], v[34:37]
	v_mfma_f32_16x16x32_bf16 v[18:21], v[154:157], v[210:213], v[18:21]
	v_mfma_f32_16x16x32_bf16 v[10:13], v[162:165], v[210:213], v[10:13]
	v_mfma_f32_16x16x32_bf16 v[26:29], v[162:165], v[202:205], v[26:29]
	v_mfma_f32_16x16x32_bf16 v[42:45], v[162:165], v[194:197], v[42:45]
	v_mfma_f32_16x16x32_bf16 v[58:61], v[162:165], v[186:189], v[58:61]
	v_mfma_f32_16x16x32_bf16 v[62:65], v[158:161], v[190:193], v[62:65]
	v_mfma_f32_16x16x32_bf16 v[50:53], v[158:161], v[198:201], v[50:53]
	v_mfma_f32_16x16x32_bf16 v[34:37], v[158:161], v[206:209], v[34:37]
	v_mfma_f32_16x16x32_bf16 v[18:21], v[158:161], v[218:221], v[18:21]
	v_mfma_f32_16x16x32_bf16 v[10:13], v[166:169], v[218:221], v[10:13]
	v_mfma_f32_16x16x32_bf16 v[26:29], v[166:169], v[206:209], v[26:29]
	v_mfma_f32_16x16x32_bf16 v[42:45], v[166:169], v[198:201], v[42:45]
	v_mfma_f32_16x16x32_bf16 v[58:61], v[166:169], v[190:193], v[58:61]
	s_setprio 0
	s_setprio 1
	v_mfma_f32_16x16x32_bf16 v[54:57], v[170:173], v[186:189], v[54:57]
	v_mfma_f32_16x16x32_bf16 v[38:41], v[170:173], v[194:197], v[38:41]
	v_mfma_f32_16x16x32_bf16 v[22:25], v[170:173], v[202:205], v[22:25]
	v_mfma_f32_16x16x32_bf16 v[6:9], v[170:173], v[210:213], v[6:9]
	v_mfma_f32_16x16x32_bf16 v[2:5], v[178:181], v[210:213], v[2:5]
	v_mfma_f32_16x16x32_bf16 v[14:17], v[178:181], v[202:205], v[14:17]
	v_mfma_f32_16x16x32_bf16 v[30:33], v[178:181], v[194:197], v[30:33]
	v_mfma_f32_16x16x32_bf16 v[46:49], v[178:181], v[186:189], v[46:49]
	v_mfma_f32_16x16x32_bf16 v[54:57], v[174:177], v[190:193], v[54:57]
	v_mfma_f32_16x16x32_bf16 v[38:41], v[174:177], v[198:201], v[38:41]
	v_mfma_f32_16x16x32_bf16 v[22:25], v[174:177], v[206:209], v[22:25]
	v_mfma_f32_16x16x32_bf16 v[6:9], v[174:177], v[218:221], v[6:9]
	v_mfma_f32_16x16x32_bf16 v[2:5], v[182:185], v[218:221], v[2:5]
	v_mfma_f32_16x16x32_bf16 v[14:17], v[182:185], v[206:209], v[14:17]
	v_mfma_f32_16x16x32_bf16 v[30:33], v[182:185], v[198:201], v[30:33]
	v_mfma_f32_16x16x32_bf16 v[46:49], v[182:185], v[190:193], v[46:49]
	s_setprio 0
	s_barrier
	s_add_i32 s53, 0, 0x18000
	s_add_i32 s62, 0, 0x1c000
	v_add_u32_e32 v166, s53, v149
	v_add_u32_e32 v182, s62, v149
	ds_read_b128 v[154:157], v166
	ds_read_b128 v[158:161], v166 offset:1024
	ds_read_b128 v[162:165], v166 offset:2048
	ds_read_b128 v[166:169], v166 offset:3072
	ds_read_b128 v[170:173], v182
	ds_read_b128 v[174:177], v182 offset:1024
	ds_read_b128 v[178:181], v182 offset:2048
	ds_read_b128 v[182:185], v182 offset:3072
	s_add_u32 s54, s90, 0x80000
	s_addc_u32 s55, s91, 0
	s_mov_b32 m0, s57
	v_lshl_add_u64 v[226:227], s[54:55], 0, v[136:137]
	ds_read_b128 v[186:189], v153 offset:32768
	ds_read_b128 v[190:193], v153 offset:33792
	ds_read_b128 v[194:197], v153 offset:34816
	ds_read_b128 v[198:201], v153 offset:35840
	ds_read_b128 v[202:205], v153 offset:36864
	ds_read_b128 v[206:209], v153 offset:37888
	ds_read_b128 v[210:213], v153 offset:38912
	ds_read_b128 v[218:221], v153 offset:39936
	global_load_lds_dwordx4 v[226:227], off
	v_lshl_add_u64 v[226:227], s[54:55], 0, v[132:133]
	s_mov_b32 m0, s58
	s_nop 0
	global_load_lds_dwordx4 v[226:227], off
	s_waitcnt vmcnt(8)
	s_waitcnt lgkmcnt(0)
	s_barrier
	s_setprio 1
	s_waitcnt lgkmcnt(0)
	v_mfma_f32_16x16x32_bf16 v[126:129], v[154:157], v[186:189], v[126:129]
	v_mfma_f32_16x16x32_bf16 v[114:117], v[154:157], v[194:197], v[114:117]
	v_mfma_f32_16x16x32_bf16 v[98:101], v[154:157], v[202:205], v[98:101]
	v_mfma_f32_16x16x32_bf16 v[82:85], v[154:157], v[210:213], v[82:85]
	v_mfma_f32_16x16x32_bf16 v[74:77], v[162:165], v[210:213], v[74:77]
	v_mfma_f32_16x16x32_bf16 v[90:93], v[162:165], v[202:205], v[90:93]
	v_mfma_f32_16x16x32_bf16 v[106:109], v[162:165], v[194:197], v[106:109]
	v_mfma_f32_16x16x32_bf16 v[122:125], v[162:165], v[186:189], v[122:125]
	v_mfma_f32_16x16x32_bf16 v[126:129], v[158:161], v[190:193], v[126:129]
	v_mfma_f32_16x16x32_bf16 v[114:117], v[158:161], v[198:201], v[114:117]
	v_mfma_f32_16x16x32_bf16 v[98:101], v[158:161], v[206:209], v[98:101]
	v_mfma_f32_16x16x32_bf16 v[82:85], v[158:161], v[218:221], v[82:85]
	v_mfma_f32_16x16x32_bf16 v[74:77], v[166:169], v[218:221], v[74:77]
	v_mfma_f32_16x16x32_bf16 v[90:93], v[166:169], v[206:209], v[90:93]
	v_mfma_f32_16x16x32_bf16 v[106:109], v[166:169], v[198:201], v[106:109]
	v_mfma_f32_16x16x32_bf16 v[122:125], v[166:169], v[190:193], v[122:125]
	s_setprio 0
	s_setprio 1
	v_mfma_f32_16x16x32_bf16 v[118:121], v[170:173], v[186:189], v[118:121]
	v_mfma_f32_16x16x32_bf16 v[102:105], v[170:173], v[194:197], v[102:105]
	v_mfma_f32_16x16x32_bf16 v[86:89], v[170:173], v[202:205], v[86:89]
	v_mfma_f32_16x16x32_bf16 v[70:73], v[170:173], v[210:213], v[70:73]
	v_mfma_f32_16x16x32_bf16 v[66:69], v[178:181], v[210:213], v[66:69]
	v_mfma_f32_16x16x32_bf16 v[78:81], v[178:181], v[202:205], v[78:81]
	v_mfma_f32_16x16x32_bf16 v[94:97], v[178:181], v[194:197], v[94:97]
	v_mfma_f32_16x16x32_bf16 v[110:113], v[178:181], v[186:189], v[110:113]
	v_mfma_f32_16x16x32_bf16 v[118:121], v[174:177], v[190:193], v[118:121]
	v_mfma_f32_16x16x32_bf16 v[102:105], v[174:177], v[198:201], v[102:105]
	v_mfma_f32_16x16x32_bf16 v[86:89], v[174:177], v[206:209], v[86:89]
	v_mfma_f32_16x16x32_bf16 v[70:73], v[174:177], v[218:221], v[70:73]
	v_mfma_f32_16x16x32_bf16 v[66:69], v[182:185], v[218:221], v[66:69]
	v_mfma_f32_16x16x32_bf16 v[78:81], v[182:185], v[206:209], v[78:81]
	v_mfma_f32_16x16x32_bf16 v[94:97], v[182:185], v[198:201], v[94:97]
	v_mfma_f32_16x16x32_bf16 v[110:113], v[182:185], v[190:193], v[110:113]
	s_setprio 0
	s_barrier
	s_add_i32 s53, s53, s12
	v_lshl_add_u64 v[146:147], v[146:147], 0, s[8:9]
	s_mov_b32 m0, s53
	ds_read_b128 v[186:189], v153 offset:49152
	ds_read_b128 v[190:193], v153 offset:50176
	ds_read_b128 v[194:197], v153 offset:51200
	ds_read_b128 v[198:201], v153 offset:52224
	ds_read_b128 v[202:205], v153 offset:53248
	ds_read_b128 v[206:209], v153 offset:54272
	ds_read_b128 v[210:213], v153 offset:55296
	ds_read_b128 v[218:221], v153 offset:56320
	global_load_lds_dwordx4 v[146:147], off
	s_add_i32 m0, s53, 0x2000
	s_add_u32 s34, s34, 0x80080
	v_lshl_add_u64 v[146:147], v[214:215], 0, s[8:9]
	s_addc_u32 s35, s35, 0
	s_add_i32 s53, s62, s12
	global_load_lds_dwordx4 v[146:147], off
	v_lshl_add_u64 v[146:147], s[34:35], 0, v[134:135]
	s_mov_b32 m0, s53
	s_nop 0
	global_load_lds_dwordx4 v[146:147], off
	v_lshl_add_u64 v[146:147], s[34:35], 0, v[130:131]
	s_add_i32 m0, s53, 0x2000
	s_nop 0
	global_load_lds_dwordx4 v[146:147], off
	v_lshl_add_u64 v[146:147], v[222:223], 0, s[8:9]
	s_mov_b32 m0, s60
	s_nop 0
	global_load_lds_dwordx4 v[146:147], off
	v_lshl_add_u64 v[146:147], v[224:225], 0, s[8:9]
	s_mov_b32 m0, s61
	s_nop 0
	global_load_lds_dwordx4 v[146:147], off
	s_waitcnt vmcnt(8)
	s_waitcnt lgkmcnt(0)
	s_barrier
	s_setprio 1
	s_waitcnt lgkmcnt(0)
	v_mfma_f32_16x16x32_bf16 v[62:65], v[154:157], v[186:189], v[62:65]
	v_mfma_f32_16x16x32_bf16 v[50:53], v[154:157], v[194:197], v[50:53]
	v_mfma_f32_16x16x32_bf16 v[34:37], v[154:157], v[202:205], v[34:37]
	v_mfma_f32_16x16x32_bf16 v[18:21], v[154:157], v[210:213], v[18:21]
	v_mfma_f32_16x16x32_bf16 v[10:13], v[162:165], v[210:213], v[10:13]
	v_mfma_f32_16x16x32_bf16 v[26:29], v[162:165], v[202:205], v[26:29]
	v_mfma_f32_16x16x32_bf16 v[42:45], v[162:165], v[194:197], v[42:45]
	v_mfma_f32_16x16x32_bf16 v[58:61], v[162:165], v[186:189], v[58:61]
	v_mfma_f32_16x16x32_bf16 v[62:65], v[158:161], v[190:193], v[62:65]
	v_mfma_f32_16x16x32_bf16 v[50:53], v[158:161], v[198:201], v[50:53]
	v_mfma_f32_16x16x32_bf16 v[34:37], v[158:161], v[206:209], v[34:37]
	v_mfma_f32_16x16x32_bf16 v[18:21], v[158:161], v[218:221], v[18:21]
	v_mfma_f32_16x16x32_bf16 v[10:13], v[166:169], v[218:221], v[10:13]
	v_mfma_f32_16x16x32_bf16 v[26:29], v[166:169], v[206:209], v[26:29]
	v_mfma_f32_16x16x32_bf16 v[42:45], v[166:169], v[198:201], v[42:45]
	v_mfma_f32_16x16x32_bf16 v[58:61], v[166:169], v[190:193], v[58:61]
	s_setprio 0
	s_setprio 1
	v_mfma_f32_16x16x32_bf16 v[54:57], v[170:173], v[186:189], v[54:57]
	v_mfma_f32_16x16x32_bf16 v[38:41], v[170:173], v[194:197], v[38:41]
	v_mfma_f32_16x16x32_bf16 v[22:25], v[170:173], v[202:205], v[22:25]
	v_mfma_f32_16x16x32_bf16 v[6:9], v[170:173], v[210:213], v[6:9]
	v_mfma_f32_16x16x32_bf16 v[2:5], v[178:181], v[210:213], v[2:5]
	v_mfma_f32_16x16x32_bf16 v[14:17], v[178:181], v[202:205], v[14:17]
	v_mfma_f32_16x16x32_bf16 v[30:33], v[178:181], v[194:197], v[30:33]
	v_mfma_f32_16x16x32_bf16 v[46:49], v[178:181], v[186:189], v[46:49]
	v_mfma_f32_16x16x32_bf16 v[54:57], v[174:177], v[190:193], v[54:57]
	v_mfma_f32_16x16x32_bf16 v[38:41], v[174:177], v[198:201], v[38:41]
	v_mfma_f32_16x16x32_bf16 v[22:25], v[174:177], v[206:209], v[22:25]
	v_mfma_f32_16x16x32_bf16 v[6:9], v[174:177], v[218:221], v[6:9]
	v_mfma_f32_16x16x32_bf16 v[2:5], v[182:185], v[218:221], v[2:5]
	v_mfma_f32_16x16x32_bf16 v[14:17], v[182:185], v[206:209], v[14:17]
	v_mfma_f32_16x16x32_bf16 v[30:33], v[182:185], v[198:201], v[30:33]
	v_mfma_f32_16x16x32_bf16 v[46:49], v[182:185], v[190:193], v[46:49]
	s_setprio 0
	s_barrier
	s_add_i32 s83, s83, 2
	s_add_u32 s88, s88, 0x100
	s_addc_u32 s89, s89, 0
	s_add_u32 s77, s77, 0x100
	s_addc_u32 s81, s81, 0
	s_cmp_gt_u32 s83, 29
	s_cbranch_scc0 .LBB0_1624
	s_and_b64 vcc, exec, s[78:79]
	s_cbranch_vccz .LBB0_1627
	s_barrier

.LBB0_2089:
	ds_read_b128 v[130:133], v178
	ds_read_b128 v[134:137], v178 offset:1024
	ds_read_b128 v[138:141], v178 offset:2048
	ds_read_b128 v[142:145], v178 offset:3072
	ds_read_b128 v[162:165], v179
	ds_read_b128 v[166:169], v179 offset:1024
	ds_read_b128 v[170:173], v179 offset:2048
	ds_read_b128 v[182:185], v179 offset:3072
	s_add_u32 s34, s38, 0xffea0080
	s_addc_u32 s35, s39, -1
	s_cmpk_eq_i32 s52, 0x54
	s_cselect_b32 s41, s5, s35
	s_cselect_b32 s40, s4, s34
	s_cselect_b32 s35, s37, s1
	s_cselect_b32 s34, s36, s0
	v_lshl_add_u64 v[174:175], s[38:39], 0, v[154:155]
	s_add_i32 m0, s33, 0xc000
	ds_read_b128 v[186:189], v180
	ds_read_b128 v[190:193], v180 offset:1024
	ds_read_b128 v[194:197], v180 offset:2048
	ds_read_b128 v[198:201], v180 offset:3072
	ds_read_b128 v[202:205], v180 offset:4096
	ds_read_b128 v[206:209], v180 offset:5120
	ds_read_b128 v[210:213], v180 offset:6144
	ds_read_b128 v[218:221], v180 offset:7168
	global_load_lds_dwordx4 v[174:175], off
	v_lshl_add_u64 v[174:175], s[38:39], 0, v[156:157]
	s_add_i32 m0, s33, 0xe000
	s_nop 0
	global_load_lds_dwordx4 v[174:175], off
	s_waitcnt vmcnt(8)
	s_waitcnt lgkmcnt(0)
	s_barrier
	s_setprio 1
	s_waitcnt lgkmcnt(0)
	v_mfma_f32_16x16x32_bf16 v[126:129], v[130:133], v[186:189], v[126:129]
	v_mfma_f32_16x16x32_bf16 v[110:113], v[130:133], v[194:197], v[110:113]
	v_mfma_f32_16x16x32_bf16 v[94:97], v[130:133], v[202:205], v[94:97]
	v_mfma_f32_16x16x32_bf16 v[78:81], v[130:133], v[210:213], v[78:81]
	v_mfma_f32_16x16x32_bf16 v[74:77], v[138:141], v[210:213], v[74:77]
	v_mfma_f32_16x16x32_bf16 v[90:93], v[138:141], v[202:205], v[90:93]
	v_mfma_f32_16x16x32_bf16 v[106:109], v[138:141], v[194:197], v[106:109]
	v_mfma_f32_16x16x32_bf16 v[122:125], v[138:141], v[186:189], v[122:125]
	v_mfma_f32_16x16x32_bf16 v[126:129], v[134:137], v[190:193], v[126:129]
	v_mfma_f32_16x16x32_bf16 v[110:113], v[134:137], v[198:201], v[110:113]
	v_mfma_f32_16x16x32_bf16 v[94:97], v[134:137], v[206:209], v[94:97]
	v_mfma_f32_16x16x32_bf16 v[78:81], v[134:137], v[218:221], v[78:81]
	v_mfma_f32_16x16x32_bf16 v[74:77], v[142:145], v[218:221], v[74:77]
	v_mfma_f32_16x16x32_bf16 v[90:93], v[142:145], v[206:209], v[90:93]
	v_mfma_f32_16x16x32_bf16 v[106:109], v[142:145], v[198:201], v[106:109]
	v_mfma_f32_16x16x32_bf16 v[122:125], v[142:145], v[190:193], v[122:125]
	s_setprio 0
	s_setprio 1
	v_mfma_f32_16x16x32_bf16 v[118:121], v[162:165], v[186:189], v[118:121]
	v_mfma_f32_16x16x32_bf16 v[102:105], v[162:165], v[194:197], v[102:105]
	v_mfma_f32_16x16x32_bf16 v[86:89], v[162:165], v[202:205], v[86:89]
	v_mfma_f32_16x16x32_bf16 v[70:73], v[162:165], v[210:213], v[70:73]
	v_mfma_f32_16x16x32_bf16 v[66:69], v[170:173], v[210:213], v[66:69]
	v_mfma_f32_16x16x32_bf16 v[82:85], v[170:173], v[202:205], v[82:85]
	v_mfma_f32_16x16x32_bf16 v[98:101], v[170:173], v[194:197], v[98:101]
	v_mfma_f32_16x16x32_bf16 v[114:117], v[170:173], v[186:189], v[114:117]
	v_mfma_f32_16x16x32_bf16 v[118:121], v[166:169], v[190:193], v[118:121]
	v_mfma_f32_16x16x32_bf16 v[102:105], v[166:169], v[198:201], v[102:105]
	v_mfma_f32_16x16x32_bf16 v[86:89], v[166:169], v[206:209], v[86:89]
	v_mfma_f32_16x16x32_bf16 v[70:73], v[166:169], v[218:221], v[70:73]
	v_mfma_f32_16x16x32_bf16 v[66:69], v[182:185], v[218:221], v[66:69]
	v_mfma_f32_16x16x32_bf16 v[82:85], v[182:185], v[206:209], v[82:85]
	v_mfma_f32_16x16x32_bf16 v[98:101], v[182:185], v[198:201], v[98:101]
	v_mfma_f32_16x16x32_bf16 v[114:117], v[182:185], v[190:193], v[114:117]
	s_setprio 0
	s_barrier
	s_add_i32 s53, s61, s31
	v_lshl_add_u64 v[174:175], s[34:35], 0, v[148:149]
	s_mov_b32 m0, s53
	ds_read_b128 v[186:189], v180 offset:16384
	ds_read_b128 v[190:193], v180 offset:17408
	ds_read_b128 v[194:197], v180 offset:18432
	ds_read_b128 v[198:201], v180 offset:19456
	ds_read_b128 v[202:205], v180 offset:20480
	ds_read_b128 v[206:209], v180 offset:21504
	ds_read_b128 v[210:213], v180 offset:22528
	ds_read_b128 v[218:221], v180 offset:23552
	global_load_lds_dwordx4 v[174:175], off
	s_add_i32 m0, s53, 0x2000
	s_add_u32 s54, s34, 0x160000
	v_lshl_add_u64 v[214:215], s[34:35], 0, v[152:153]
	s_addc_u32 s55, s35, 0
	s_add_i32 s53, s70, s31
	global_load_lds_dwordx4 v[214:215], off
	v_lshl_add_u64 v[222:223], s[54:55], 0, v[148:149]
	s_mov_b32 m0, s53
	v_lshl_add_u64 v[224:225], s[40:41], 0, v[150:151]
	global_load_lds_dwordx4 v[222:223], off
	v_lshl_add_u64 v[222:223], s[54:55], 0, v[152:153]
	s_add_i32 m0, s53, 0x2000
	s_nop 0
	global_load_lds_dwordx4 v[222:223], off
	v_lshl_add_u64 v[222:223], s[40:41], 0, v[146:147]
	s_mov_b32 m0, s33
	s_nop 0
	global_load_lds_dwordx4 v[222:223], off
	s_mov_b32 m0, s46
	s_nop 0
	global_load_lds_dwordx4 v[224:225], off
	s_waitcnt vmcnt(8)
	s_waitcnt lgkmcnt(0)
	s_barrier
	s_setprio 1
	s_waitcnt lgkmcnt(0)
	v_mfma_f32_16x16x32_bf16 v[62:65], v[130:133], v[186:189], v[62:65]
	v_mfma_f32_16x16x32_bf16 v[50:53], v[130:133], v[194:197], v[50:53]
	v_mfma_f32_16x16x32_bf16 v[38:41], v[130:133], v[202:205], v[38:41]
	v_mfma_f32_16x16x32_bf16 v[14:17], v[130:133], v[210:213], v[14:17]
	v_mfma_f32_16x16x32_bf16 v[10:13], v[138:141], v[210:213], v[10:13]
	v_mfma_f32_16x16x32_bf16 v[34:37], v[138:141], v[202:205], v[34:37]
	v_mfma_f32_16x16x32_bf16 v[42:45], v[138:141], v[194:197], v[42:45]
	v_mfma_f32_16x16x32_bf16 v[58:61], v[138:141], v[186:189], v[58:61]
	v_mfma_f32_16x16x32_bf16 v[62:65], v[134:137], v[190:193], v[62:65]
	v_mfma_f32_16x16x32_bf16 v[50:53], v[134:137], v[198:201], v[50:53]
	v_mfma_f32_16x16x32_bf16 v[38:41], v[134:137], v[206:209], v[38:41]
	v_mfma_f32_16x16x32_bf16 v[14:17], v[134:137], v[218:221], v[14:17]
	v_mfma_f32_16x16x32_bf16 v[10:13], v[142:145], v[218:221], v[10:13]
	v_mfma_f32_16x16x32_bf16 v[34:37], v[142:145], v[206:209], v[34:37]
	v_mfma_f32_16x16x32_bf16 v[42:45], v[142:145], v[198:201], v[42:45]
	v_mfma_f32_16x16x32_bf16 v[58:61], v[142:145], v[190:193], v[58:61]
	s_setprio 0
	s_setprio 1
	v_mfma_f32_16x16x32_bf16 v[54:57], v[162:165], v[186:189], v[54:57]
	v_mfma_f32_16x16x32_bf16 v[30:33], v[162:165], v[194:197], v[30:33]
	v_mfma_f32_16x16x32_bf16 v[22:25], v[162:165], v[202:205], v[22:25]
	v_mfma_f32_16x16x32_bf16 v[6:9], v[162:165], v[210:213], v[6:9]
	v_mfma_f32_16x16x32_bf16 v[2:5], v[170:173], v[210:213], v[2:5]
	v_mfma_f32_16x16x32_bf16 v[18:21], v[170:173], v[202:205], v[18:21]
	v_mfma_f32_16x16x32_bf16 v[26:29], v[170:173], v[194:197], v[26:29]
	v_mfma_f32_16x16x32_bf16 v[46:49], v[170:173], v[186:189], v[46:49]
	v_mfma_f32_16x16x32_bf16 v[54:57], v[166:169], v[190:193], v[54:57]
	v_mfma_f32_16x16x32_bf16 v[30:33], v[166:169], v[198:201], v[30:33]
	v_mfma_f32_16x16x32_bf16 v[22:25], v[166:169], v[206:209], v[22:25]
	v_mfma_f32_16x16x32_bf16 v[6:9], v[166:169], v[218:221], v[6:9]
	v_mfma_f32_16x16x32_bf16 v[2:5], v[182:185], v[218:221], v[2:5]
	v_mfma_f32_16x16x32_bf16 v[18:21], v[182:185], v[206:209], v[18:21]
	v_mfma_f32_16x16x32_bf16 v[26:29], v[182:185], v[198:201], v[26:29]
	v_mfma_f32_16x16x32_bf16 v[46:49], v[182:185], v[190:193], v[46:49]
	s_setprio 0
	s_barrier
	s_add_i32 s53, 0, 0x18000
	s_add_i32 s54, 0, 0x1c000
	v_add_u32_e32 v142, s53, v176
	v_add_u32_e32 v181, s54, v176
	ds_read_b128 v[130:133], v142
	ds_read_b128 v[134:137], v142 offset:1024
	ds_read_b128 v[138:141], v142 offset:2048
	ds_read_b128 v[142:145], v142 offset:3072
	ds_read_b128 v[162:165], v181
	ds_read_b128 v[166:169], v181 offset:1024
	ds_read_b128 v[170:173], v181 offset:2048
	ds_read_b128 v[182:185], v181 offset:3072
	s_add_u32 s40, s40, 0x160000
	s_addc_u32 s41, s41, 0
	s_mov_b32 m0, s47
	v_lshl_add_u64 v[226:227], s[40:41], 0, v[146:147]
	ds_read_b128 v[186:189], v180 offset:32768
	ds_read_b128 v[190:193], v180 offset:33792
	ds_read_b128 v[194:197], v180 offset:34816
	ds_read_b128 v[198:201], v180 offset:35840
	ds_read_b128 v[202:205], v180 offset:36864
	ds_read_b128 v[206:209], v180 offset:37888
	ds_read_b128 v[210:213], v180 offset:38912
	ds_read_b128 v[218:221], v180 offset:39936
	global_load_lds_dwordx4 v[226:227], off
	v_lshl_add_u64 v[226:227], s[40:41], 0, v[150:151]
	s_mov_b32 m0, s56
	s_nop 0
	global_load_lds_dwordx4 v[226:227], off
	s_waitcnt vmcnt(8)
	s_waitcnt lgkmcnt(0)
	s_barrier
	s_setprio 1
	s_waitcnt lgkmcnt(0)
	v_mfma_f32_16x16x32_bf16 v[126:129], v[130:133], v[186:189], v[126:129]
	v_mfma_f32_16x16x32_bf16 v[110:113], v[130:133], v[194:197], v[110:113]
	v_mfma_f32_16x16x32_bf16 v[94:97], v[130:133], v[202:205], v[94:97]
	v_mfma_f32_16x16x32_bf16 v[78:81], v[130:133], v[210:213], v[78:81]
	v_mfma_f32_16x16x32_bf16 v[74:77], v[138:141], v[210:213], v[74:77]
	v_mfma_f32_16x16x32_bf16 v[90:93], v[138:141], v[202:205], v[90:93]
	v_mfma_f32_16x16x32_bf16 v[106:109], v[138:141], v[194:197], v[106:109]
	v_mfma_f32_16x16x32_bf16 v[122:125], v[138:141], v[186:189], v[122:125]
	v_mfma_f32_16x16x32_bf16 v[126:129], v[134:137], v[190:193], v[126:129]
	v_mfma_f32_16x16x32_bf16 v[110:113], v[134:137], v[198:201], v[110:113]
	v_mfma_f32_16x16x32_bf16 v[94:97], v[134:137], v[206:209], v[94:97]
	v_mfma_f32_16x16x32_bf16 v[78:81], v[134:137], v[218:221], v[78:81]
	v_mfma_f32_16x16x32_bf16 v[74:77], v[142:145], v[218:221], v[74:77]
	v_mfma_f32_16x16x32_bf16 v[90:93], v[142:145], v[206:209], v[90:93]
	v_mfma_f32_16x16x32_bf16 v[106:109], v[142:145], v[198:201], v[106:109]
	v_mfma_f32_16x16x32_bf16 v[122:125], v[142:145], v[190:193], v[122:125]
	s_setprio 0
	s_setprio 1
	v_mfma_f32_16x16x32_bf16 v[118:121], v[162:165], v[186:189], v[118:121]
	v_mfma_f32_16x16x32_bf16 v[102:105], v[162:165], v[194:197], v[102:105]
	v_mfma_f32_16x16x32_bf16 v[86:89], v[162:165], v[202:205], v[86:89]
	v_mfma_f32_16x16x32_bf16 v[70:73], v[162:165], v[210:213], v[70:73]
	v_mfma_f32_16x16x32_bf16 v[66:69], v[170:173], v[210:213], v[66:69]
	v_mfma_f32_16x16x32_bf16 v[82:85], v[170:173], v[202:205], v[82:85]
	v_mfma_f32_16x16x32_bf16 v[98:101], v[170:173], v[194:197], v[98:101]
	v_mfma_f32_16x16x32_bf16 v[114:117], v[170:173], v[186:189], v[114:117]
	v_mfma_f32_16x16x32_bf16 v[118:121], v[166:169], v[190:193], v[118:121]
	v_mfma_f32_16x16x32_bf16 v[102:105], v[166:169], v[198:201], v[102:105]
	v_mfma_f32_16x16x32_bf16 v[86:89], v[166:169], v[206:209], v[86:89]
	v_mfma_f32_16x16x32_bf16 v[70:73], v[166:169], v[218:221], v[70:73]
	v_mfma_f32_16x16x32_bf16 v[66:69], v[182:185], v[218:221], v[66:69]
	v_mfma_f32_16x16x32_bf16 v[82:85], v[182:185], v[206:209], v[82:85]
	v_mfma_f32_16x16x32_bf16 v[98:101], v[182:185], v[198:201], v[98:101]
	v_mfma_f32_16x16x32_bf16 v[114:117], v[182:185], v[190:193], v[114:117]
	s_setprio 0
	s_barrier
	s_add_i32 s40, s53, s31
	v_lshl_add_u64 v[174:175], v[174:175], 0, s[24:25]
	s_mov_b32 m0, s40
	ds_read_b128 v[186:189], v180 offset:49152
	ds_read_b128 v[190:193], v180 offset:50176
	ds_read_b128 v[194:197], v180 offset:51200
	ds_read_b128 v[198:201], v180 offset:52224
	ds_read_b128 v[202:205], v180 offset:53248
	ds_read_b128 v[206:209], v180 offset:54272
	ds_read_b128 v[210:213], v180 offset:55296
	ds_read_b128 v[218:221], v180 offset:56320
	global_load_lds_dwordx4 v[174:175], off
	s_add_i32 m0, s40, 0x2000
	s_add_u32 s34, s34, 0x160080
	v_lshl_add_u64 v[174:175], v[214:215], 0, s[24:25]
	s_addc_u32 s35, s35, 0
	s_add_i32 s40, s54, s31
	global_load_lds_dwordx4 v[174:175], off
	v_lshl_add_u64 v[174:175], s[34:35], 0, v[148:149]
	s_mov_b32 m0, s40
	s_nop 0
	global_load_lds_dwordx4 v[174:175], off
	v_lshl_add_u64 v[174:175], s[34:35], 0, v[152:153]
	s_add_i32 m0, s40, 0x2000
	s_nop 0
	global_load_lds_dwordx4 v[174:175], off
	v_lshl_add_u64 v[174:175], v[222:223], 0, s[24:25]
	s_mov_b32 m0, s58
	s_nop 0
	global_load_lds_dwordx4 v[174:175], off
	v_lshl_add_u64 v[174:175], v[224:225], 0, s[24:25]
	s_mov_b32 m0, s59
	s_nop 0
	global_load_lds_dwordx4 v[174:175], off
	s_waitcnt vmcnt(8)
	s_waitcnt lgkmcnt(0)
	s_barrier
	s_setprio 1
	s_waitcnt lgkmcnt(0)
	v_mfma_f32_16x16x32_bf16 v[62:65], v[130:133], v[186:189], v[62:65]
	v_mfma_f32_16x16x32_bf16 v[50:53], v[130:133], v[194:197], v[50:53]
	v_mfma_f32_16x16x32_bf16 v[38:41], v[130:133], v[202:205], v[38:41]
	v_mfma_f32_16x16x32_bf16 v[14:17], v[130:133], v[210:213], v[14:17]
	v_mfma_f32_16x16x32_bf16 v[10:13], v[138:141], v[210:213], v[10:13]
	v_mfma_f32_16x16x32_bf16 v[34:37], v[138:141], v[202:205], v[34:37]
	v_mfma_f32_16x16x32_bf16 v[42:45], v[138:141], v[194:197], v[42:45]
	v_mfma_f32_16x16x32_bf16 v[58:61], v[138:141], v[186:189], v[58:61]
	v_mfma_f32_16x16x32_bf16 v[62:65], v[134:137], v[190:193], v[62:65]
	v_mfma_f32_16x16x32_bf16 v[50:53], v[134:137], v[198:201], v[50:53]
	v_mfma_f32_16x16x32_bf16 v[38:41], v[134:137], v[206:209], v[38:41]
	v_mfma_f32_16x16x32_bf16 v[14:17], v[134:137], v[218:221], v[14:17]
	v_mfma_f32_16x16x32_bf16 v[10:13], v[142:145], v[218:221], v[10:13]
	v_mfma_f32_16x16x32_bf16 v[34:37], v[142:145], v[206:209], v[34:37]
	v_mfma_f32_16x16x32_bf16 v[42:45], v[142:145], v[198:201], v[42:45]
	v_mfma_f32_16x16x32_bf16 v[58:61], v[142:145], v[190:193], v[58:61]
	s_setprio 0
	s_setprio 1
	v_mfma_f32_16x16x32_bf16 v[54:57], v[162:165], v[186:189], v[54:57]
	v_mfma_f32_16x16x32_bf16 v[30:33], v[162:165], v[194:197], v[30:33]
	v_mfma_f32_16x16x32_bf16 v[22:25], v[162:165], v[202:205], v[22:25]
	v_mfma_f32_16x16x32_bf16 v[6:9], v[162:165], v[210:213], v[6:9]
	v_mfma_f32_16x16x32_bf16 v[2:5], v[170:173], v[210:213], v[2:5]
	v_mfma_f32_16x16x32_bf16 v[18:21], v[170:173], v[202:205], v[18:21]
	v_mfma_f32_16x16x32_bf16 v[26:29], v[170:173], v[194:197], v[26:29]
	v_mfma_f32_16x16x32_bf16 v[46:49], v[170:173], v[186:189], v[46:49]
	v_mfma_f32_16x16x32_bf16 v[54:57], v[166:169], v[190:193], v[54:57]
	v_mfma_f32_16x16x32_bf16 v[30:33], v[166:169], v[198:201], v[30:33]
	v_mfma_f32_16x16x32_bf16 v[22:25], v[166:169], v[206:209], v[22:25]
	v_mfma_f32_16x16x32_bf16 v[6:9], v[166:169], v[218:221], v[6:9]
	v_mfma_f32_16x16x32_bf16 v[2:5], v[182:185], v[218:221], v[2:5]
	v_mfma_f32_16x16x32_bf16 v[18:21], v[182:185], v[206:209], v[18:21]
	v_mfma_f32_16x16x32_bf16 v[26:29], v[182:185], v[198:201], v[26:29]
	v_mfma_f32_16x16x32_bf16 v[46:49], v[182:185], v[190:193], v[46:49]
	s_setprio 0
	s_barrier
	s_add_i32 s52, s52, 2
	s_add_u32 s38, s38, 0x100
	s_addc_u32 s39, s39, 0
	s_add_u32 s0, s0, 0x100
	s_addc_u32 s1, s1, 0
	s_cmpk_gt_u32 s52, 0x55
	s_cbranch_scc0 .LBB0_2089
	s_and_b64 vcc, exec, s[26:27]
	s_cbranch_vccz .LBB0_2092
	s_barrier

.LBB0_2218:
	ds_read_b128 v[146:149], v153
	ds_read_b128 v[156:159], v153 offset:1024
	ds_read_b128 v[160:163], v153 offset:2048
	ds_read_b128 v[164:167], v153 offset:3072
	ds_read_b128 v[168:171], v154
	ds_read_b128 v[172:175], v154 offset:1024
	ds_read_b128 v[176:179], v154 offset:2048
	ds_read_b128 v[180:183], v154 offset:3072
	s_add_u32 s34, s76, 0xfff80080
	s_addc_u32 s35, s77, -1
	s_cmp_eq_u32 s80, 28
	s_cselect_b32 s79, s0, s35
	s_cselect_b32 s78, s1, s34
	s_cselect_b32 s35, s27, s75
	s_cselect_b32 s34, s37, s52
	v_lshl_add_u64 v[218:219], s[76:77], 0, v[138:139]
	s_add_i32 m0, s47, 0xc000
	ds_read_b128 v[184:187], v155
	ds_read_b128 v[188:191], v155 offset:1024
	ds_read_b128 v[192:195], v155 offset:2048
	ds_read_b128 v[196:199], v155 offset:3072
	ds_read_b128 v[200:203], v155 offset:4096
	ds_read_b128 v[204:207], v155 offset:5120
	ds_read_b128 v[208:211], v155 offset:6144
	ds_read_b128 v[212:215], v155 offset:7168
	global_load_lds_dwordx4 v[218:219], off
	v_lshl_add_u64 v[218:219], s[76:77], 0, v[140:141]
	s_add_i32 m0, s47, 0xe000
	s_nop 0
	global_load_lds_dwordx4 v[218:219], off
	s_waitcnt vmcnt(8)
	s_waitcnt lgkmcnt(0)
	s_barrier
	s_setprio 1
	s_waitcnt lgkmcnt(0)
	v_mfma_f32_16x16x32_bf16 v[126:129], v[146:149], v[184:187], v[126:129]
	v_mfma_f32_16x16x32_bf16 v[110:113], v[146:149], v[192:195], v[110:113]
	v_mfma_f32_16x16x32_bf16 v[94:97], v[146:149], v[200:203], v[94:97]
	v_mfma_f32_16x16x32_bf16 v[78:81], v[146:149], v[208:211], v[78:81]
	v_mfma_f32_16x16x32_bf16 v[70:73], v[160:163], v[208:211], v[70:73]
	v_mfma_f32_16x16x32_bf16 v[86:89], v[160:163], v[200:203], v[86:89]
	v_mfma_f32_16x16x32_bf16 v[102:105], v[160:163], v[192:195], v[102:105]
	v_mfma_f32_16x16x32_bf16 v[118:121], v[160:163], v[184:187], v[118:121]
	v_mfma_f32_16x16x32_bf16 v[126:129], v[156:159], v[188:191], v[126:129]
	v_mfma_f32_16x16x32_bf16 v[110:113], v[156:159], v[196:199], v[110:113]
	v_mfma_f32_16x16x32_bf16 v[94:97], v[156:159], v[204:207], v[94:97]
	v_mfma_f32_16x16x32_bf16 v[78:81], v[156:159], v[212:215], v[78:81]
	v_mfma_f32_16x16x32_bf16 v[70:73], v[164:167], v[212:215], v[70:73]
	v_mfma_f32_16x16x32_bf16 v[86:89], v[164:167], v[204:207], v[86:89]
	v_mfma_f32_16x16x32_bf16 v[102:105], v[164:167], v[196:199], v[102:105]
	v_mfma_f32_16x16x32_bf16 v[118:121], v[164:167], v[188:191], v[118:121]
	s_setprio 0
	s_setprio 1
	v_mfma_f32_16x16x32_bf16 v[122:125], v[168:171], v[184:187], v[122:125]
	v_mfma_f32_16x16x32_bf16 v[106:109], v[168:171], v[192:195], v[106:109]
	v_mfma_f32_16x16x32_bf16 v[90:93], v[168:171], v[200:203], v[90:93]
	v_mfma_f32_16x16x32_bf16 v[74:77], v[168:171], v[208:211], v[74:77]
	v_mfma_f32_16x16x32_bf16 v[66:69], v[176:179], v[208:211], v[66:69]
	v_mfma_f32_16x16x32_bf16 v[82:85], v[176:179], v[200:203], v[82:85]
	v_mfma_f32_16x16x32_bf16 v[98:101], v[176:179], v[192:195], v[98:101]
	v_mfma_f32_16x16x32_bf16 v[114:117], v[176:179], v[184:187], v[114:117]
	v_mfma_f32_16x16x32_bf16 v[122:125], v[172:175], v[188:191], v[122:125]
	v_mfma_f32_16x16x32_bf16 v[106:109], v[172:175], v[196:199], v[106:109]
	v_mfma_f32_16x16x32_bf16 v[90:93], v[172:175], v[204:207], v[90:93]
	v_mfma_f32_16x16x32_bf16 v[74:77], v[172:175], v[212:215], v[74:77]
	v_mfma_f32_16x16x32_bf16 v[66:69], v[180:183], v[212:215], v[66:69]
	v_mfma_f32_16x16x32_bf16 v[82:85], v[180:183], v[204:207], v[82:85]
	v_mfma_f32_16x16x32_bf16 v[98:101], v[180:183], v[196:199], v[98:101]
	v_mfma_f32_16x16x32_bf16 v[114:117], v[180:183], v[188:191], v[114:117]
	s_setprio 0
	s_barrier
	s_add_i32 s53, s71, s30
	v_lshl_add_u64 v[218:219], s[34:35], 0, v[134:135]
	s_mov_b32 m0, s53
	ds_read_b128 v[184:187], v155 offset:16384
	ds_read_b128 v[188:191], v155 offset:17408
	ds_read_b128 v[192:195], v155 offset:18432
	ds_read_b128 v[196:199], v155 offset:19456
	ds_read_b128 v[200:203], v155 offset:20480
	ds_read_b128 v[204:207], v155 offset:21504
	ds_read_b128 v[208:211], v155 offset:22528
	ds_read_b128 v[212:215], v155 offset:23552
	global_load_lds_dwordx4 v[218:219], off
	s_add_i32 m0, s53, 0x2000
	s_add_u32 s54, s34, 0x80000
	v_lshl_add_u64 v[220:221], s[34:35], 0, v[130:131]
	s_addc_u32 s55, s35, 0
	s_add_i32 s53, s72, s30
	global_load_lds_dwordx4 v[220:221], off
	v_lshl_add_u64 v[222:223], s[54:55], 0, v[134:135]
	s_mov_b32 m0, s53
	v_lshl_add_u64 v[224:225], s[78:79], 0, v[132:133]
	global_load_lds_dwordx4 v[222:223], off
	v_lshl_add_u64 v[222:223], s[54:55], 0, v[130:131]
	s_add_i32 m0, s53, 0x2000
	s_nop 0
	global_load_lds_dwordx4 v[222:223], off
	v_lshl_add_u64 v[222:223], s[78:79], 0, v[136:137]
	s_mov_b32 m0, s47
	s_nop 0
	global_load_lds_dwordx4 v[222:223], off
	s_mov_b32 m0, s56
	s_nop 0
	global_load_lds_dwordx4 v[224:225], off
	s_waitcnt vmcnt(8)
	s_waitcnt lgkmcnt(0)
	s_barrier
	s_setprio 1
	s_waitcnt lgkmcnt(0)
	v_mfma_f32_16x16x32_bf16 v[62:65], v[146:149], v[184:187], v[62:65]
	v_mfma_f32_16x16x32_bf16 v[46:49], v[146:149], v[192:195], v[46:49]
	v_mfma_f32_16x16x32_bf16 v[30:33], v[146:149], v[200:203], v[30:33]
	v_mfma_f32_16x16x32_bf16 v[14:17], v[146:149], v[208:211], v[14:17]
	v_mfma_f32_16x16x32_bf16 v[6:9], v[160:163], v[208:211], v[6:9]
	v_mfma_f32_16x16x32_bf16 v[22:25], v[160:163], v[200:203], v[22:25]
	v_mfma_f32_16x16x32_bf16 v[38:41], v[160:163], v[192:195], v[38:41]
	v_mfma_f32_16x16x32_bf16 v[54:57], v[160:163], v[184:187], v[54:57]
	v_mfma_f32_16x16x32_bf16 v[62:65], v[156:159], v[188:191], v[62:65]
	v_mfma_f32_16x16x32_bf16 v[46:49], v[156:159], v[196:199], v[46:49]
	v_mfma_f32_16x16x32_bf16 v[30:33], v[156:159], v[204:207], v[30:33]
	v_mfma_f32_16x16x32_bf16 v[14:17], v[156:159], v[212:215], v[14:17]
	v_mfma_f32_16x16x32_bf16 v[6:9], v[164:167], v[212:215], v[6:9]
	v_mfma_f32_16x16x32_bf16 v[22:25], v[164:167], v[204:207], v[22:25]
	v_mfma_f32_16x16x32_bf16 v[38:41], v[164:167], v[196:199], v[38:41]
	v_mfma_f32_16x16x32_bf16 v[54:57], v[164:167], v[188:191], v[54:57]
	s_setprio 0
	s_setprio 1
	v_mfma_f32_16x16x32_bf16 v[58:61], v[168:171], v[184:187], v[58:61]
	v_mfma_f32_16x16x32_bf16 v[42:45], v[168:171], v[192:195], v[42:45]
	v_mfma_f32_16x16x32_bf16 v[26:29], v[168:171], v[200:203], v[26:29]
	v_mfma_f32_16x16x32_bf16 v[10:13], v[168:171], v[208:211], v[10:13]
	v_mfma_f32_16x16x32_bf16 v[2:5], v[176:179], v[208:211], v[2:5]
	v_mfma_f32_16x16x32_bf16 v[18:21], v[176:179], v[200:203], v[18:21]
	v_mfma_f32_16x16x32_bf16 v[34:37], v[176:179], v[192:195], v[34:37]
	v_mfma_f32_16x16x32_bf16 v[50:53], v[176:179], v[184:187], v[50:53]
	v_mfma_f32_16x16x32_bf16 v[58:61], v[172:175], v[188:191], v[58:61]
	v_mfma_f32_16x16x32_bf16 v[42:45], v[172:175], v[196:199], v[42:45]
	v_mfma_f32_16x16x32_bf16 v[26:29], v[172:175], v[204:207], v[26:29]
	v_mfma_f32_16x16x32_bf16 v[10:13], v[172:175], v[212:215], v[10:13]
	v_mfma_f32_16x16x32_bf16 v[2:5], v[180:183], v[212:215], v[2:5]
	v_mfma_f32_16x16x32_bf16 v[18:21], v[180:183], v[204:207], v[18:21]
	v_mfma_f32_16x16x32_bf16 v[34:37], v[180:183], v[196:199], v[34:37]
	v_mfma_f32_16x16x32_bf16 v[50:53], v[180:183], v[188:191], v[50:53]
	s_setprio 0
	s_barrier
	s_add_i32 s53, 0, 0x18000
	s_add_i32 s62, 0, 0x1c000
	v_add_u32_e32 v164, s53, v151
	v_add_u32_e32 v180, s62, v151
	ds_read_b128 v[146:149], v164
	ds_read_b128 v[156:159], v164 offset:1024
	ds_read_b128 v[160:163], v164 offset:2048
	ds_read_b128 v[164:167], v164 offset:3072
	ds_read_b128 v[168:171], v180
	ds_read_b128 v[172:175], v180 offset:1024
	ds_read_b128 v[176:179], v180 offset:2048
	ds_read_b128 v[180:183], v180 offset:3072
	s_add_u32 s54, s78, 0x80000
	s_addc_u32 s55, s79, 0
	s_mov_b32 m0, s57
	v_lshl_add_u64 v[226:227], s[54:55], 0, v[136:137]
	ds_read_b128 v[184:187], v155 offset:32768
	ds_read_b128 v[188:191], v155 offset:33792
	ds_read_b128 v[192:195], v155 offset:34816
	ds_read_b128 v[196:199], v155 offset:35840
	ds_read_b128 v[200:203], v155 offset:36864
	ds_read_b128 v[204:207], v155 offset:37888
	ds_read_b128 v[208:211], v155 offset:38912
	ds_read_b128 v[212:215], v155 offset:39936
	global_load_lds_dwordx4 v[226:227], off
	v_lshl_add_u64 v[226:227], s[54:55], 0, v[132:133]
	s_mov_b32 m0, s58
	s_nop 0
	global_load_lds_dwordx4 v[226:227], off
	s_waitcnt vmcnt(8)
	s_waitcnt lgkmcnt(0)
	s_barrier
	s_setprio 1
	s_waitcnt lgkmcnt(0)
	v_mfma_f32_16x16x32_bf16 v[126:129], v[146:149], v[184:187], v[126:129]
	v_mfma_f32_16x16x32_bf16 v[110:113], v[146:149], v[192:195], v[110:113]
	v_mfma_f32_16x16x32_bf16 v[94:97], v[146:149], v[200:203], v[94:97]
	v_mfma_f32_16x16x32_bf16 v[78:81], v[146:149], v[208:211], v[78:81]
	v_mfma_f32_16x16x32_bf16 v[70:73], v[160:163], v[208:211], v[70:73]
	v_mfma_f32_16x16x32_bf16 v[86:89], v[160:163], v[200:203], v[86:89]
	v_mfma_f32_16x16x32_bf16 v[102:105], v[160:163], v[192:195], v[102:105]
	v_mfma_f32_16x16x32_bf16 v[118:121], v[160:163], v[184:187], v[118:121]
	v_mfma_f32_16x16x32_bf16 v[126:129], v[156:159], v[188:191], v[126:129]
	v_mfma_f32_16x16x32_bf16 v[110:113], v[156:159], v[196:199], v[110:113]
	v_mfma_f32_16x16x32_bf16 v[94:97], v[156:159], v[204:207], v[94:97]
	v_mfma_f32_16x16x32_bf16 v[78:81], v[156:159], v[212:215], v[78:81]
	v_mfma_f32_16x16x32_bf16 v[70:73], v[164:167], v[212:215], v[70:73]
	v_mfma_f32_16x16x32_bf16 v[86:89], v[164:167], v[204:207], v[86:89]
	v_mfma_f32_16x16x32_bf16 v[102:105], v[164:167], v[196:199], v[102:105]
	v_mfma_f32_16x16x32_bf16 v[118:121], v[164:167], v[188:191], v[118:121]
	s_setprio 0
	s_setprio 1
	v_mfma_f32_16x16x32_bf16 v[122:125], v[168:171], v[184:187], v[122:125]
	v_mfma_f32_16x16x32_bf16 v[106:109], v[168:171], v[192:195], v[106:109]
	v_mfma_f32_16x16x32_bf16 v[90:93], v[168:171], v[200:203], v[90:93]
	v_mfma_f32_16x16x32_bf16 v[74:77], v[168:171], v[208:211], v[74:77]
	v_mfma_f32_16x16x32_bf16 v[66:69], v[176:179], v[208:211], v[66:69]
	v_mfma_f32_16x16x32_bf16 v[82:85], v[176:179], v[200:203], v[82:85]
	v_mfma_f32_16x16x32_bf16 v[98:101], v[176:179], v[192:195], v[98:101]
	v_mfma_f32_16x16x32_bf16 v[114:117], v[176:179], v[184:187], v[114:117]
	v_mfma_f32_16x16x32_bf16 v[122:125], v[172:175], v[188:191], v[122:125]
	v_mfma_f32_16x16x32_bf16 v[106:109], v[172:175], v[196:199], v[106:109]
	v_mfma_f32_16x16x32_bf16 v[90:93], v[172:175], v[204:207], v[90:93]
	v_mfma_f32_16x16x32_bf16 v[74:77], v[172:175], v[212:215], v[74:77]
	v_mfma_f32_16x16x32_bf16 v[66:69], v[180:183], v[212:215], v[66:69]
	v_mfma_f32_16x16x32_bf16 v[82:85], v[180:183], v[204:207], v[82:85]
	v_mfma_f32_16x16x32_bf16 v[98:101], v[180:183], v[196:199], v[98:101]
	v_mfma_f32_16x16x32_bf16 v[114:117], v[180:183], v[188:191], v[114:117]
	s_setprio 0
	s_barrier
	s_add_i32 s53, s53, s30
	v_lshl_add_u64 v[218:219], v[218:219], 0, s[8:9]
	s_mov_b32 m0, s53
	ds_read_b128 v[184:187], v155 offset:49152
	ds_read_b128 v[188:191], v155 offset:50176
	ds_read_b128 v[192:195], v155 offset:51200
	ds_read_b128 v[196:199], v155 offset:52224
	ds_read_b128 v[200:203], v155 offset:53248
	ds_read_b128 v[204:207], v155 offset:54272
	ds_read_b128 v[208:211], v155 offset:55296
	ds_read_b128 v[212:215], v155 offset:56320
	global_load_lds_dwordx4 v[218:219], off
	s_add_i32 m0, s53, 0x2000
	s_add_u32 s34, s34, 0x80080
	v_lshl_add_u64 v[218:219], v[220:221], 0, s[8:9]
	s_addc_u32 s35, s35, 0
	s_add_i32 s53, s62, s30
	global_load_lds_dwordx4 v[218:219], off
	v_lshl_add_u64 v[218:219], s[34:35], 0, v[134:135]
	s_mov_b32 m0, s53
	s_nop 0
	global_load_lds_dwordx4 v[218:219], off
	v_lshl_add_u64 v[218:219], s[34:35], 0, v[130:131]
	s_add_i32 m0, s53, 0x2000
	s_nop 0
	global_load_lds_dwordx4 v[218:219], off
	v_lshl_add_u64 v[218:219], v[222:223], 0, s[8:9]
	s_mov_b32 m0, s60
	s_nop 0
	global_load_lds_dwordx4 v[218:219], off
	v_lshl_add_u64 v[218:219], v[224:225], 0, s[8:9]
	s_mov_b32 m0, s61
	s_nop 0
	global_load_lds_dwordx4 v[218:219], off
	s_waitcnt vmcnt(8)
	s_waitcnt lgkmcnt(0)
	s_barrier
	s_setprio 1
	s_waitcnt lgkmcnt(0)
	v_mfma_f32_16x16x32_bf16 v[62:65], v[146:149], v[184:187], v[62:65]
	v_mfma_f32_16x16x32_bf16 v[46:49], v[146:149], v[192:195], v[46:49]
	v_mfma_f32_16x16x32_bf16 v[30:33], v[146:149], v[200:203], v[30:33]
	v_mfma_f32_16x16x32_bf16 v[14:17], v[146:149], v[208:211], v[14:17]
	v_mfma_f32_16x16x32_bf16 v[6:9], v[160:163], v[208:211], v[6:9]
	v_mfma_f32_16x16x32_bf16 v[22:25], v[160:163], v[200:203], v[22:25]
	v_mfma_f32_16x16x32_bf16 v[38:41], v[160:163], v[192:195], v[38:41]
	v_mfma_f32_16x16x32_bf16 v[54:57], v[160:163], v[184:187], v[54:57]
	v_mfma_f32_16x16x32_bf16 v[62:65], v[156:159], v[188:191], v[62:65]
	v_mfma_f32_16x16x32_bf16 v[46:49], v[156:159], v[196:199], v[46:49]
	v_mfma_f32_16x16x32_bf16 v[30:33], v[156:159], v[204:207], v[30:33]
	v_mfma_f32_16x16x32_bf16 v[14:17], v[156:159], v[212:215], v[14:17]
	v_mfma_f32_16x16x32_bf16 v[6:9], v[164:167], v[212:215], v[6:9]
	v_mfma_f32_16x16x32_bf16 v[22:25], v[164:167], v[204:207], v[22:25]
	v_mfma_f32_16x16x32_bf16 v[38:41], v[164:167], v[196:199], v[38:41]
	v_mfma_f32_16x16x32_bf16 v[54:57], v[164:167], v[188:191], v[54:57]
	s_setprio 0
	s_setprio 1
	v_mfma_f32_16x16x32_bf16 v[58:61], v[168:171], v[184:187], v[58:61]
	v_mfma_f32_16x16x32_bf16 v[42:45], v[168:171], v[192:195], v[42:45]
	v_mfma_f32_16x16x32_bf16 v[26:29], v[168:171], v[200:203], v[26:29]
	v_mfma_f32_16x16x32_bf16 v[10:13], v[168:171], v[208:211], v[10:13]
	v_mfma_f32_16x16x32_bf16 v[2:5], v[176:179], v[208:211], v[2:5]
	v_mfma_f32_16x16x32_bf16 v[18:21], v[176:179], v[200:203], v[18:21]
	v_mfma_f32_16x16x32_bf16 v[34:37], v[176:179], v[192:195], v[34:37]
	v_mfma_f32_16x16x32_bf16 v[50:53], v[176:179], v[184:187], v[50:53]
	v_mfma_f32_16x16x32_bf16 v[58:61], v[172:175], v[188:191], v[58:61]
	v_mfma_f32_16x16x32_bf16 v[42:45], v[172:175], v[196:199], v[42:45]
	v_mfma_f32_16x16x32_bf16 v[26:29], v[172:175], v[204:207], v[26:29]
	v_mfma_f32_16x16x32_bf16 v[10:13], v[172:175], v[212:215], v[10:13]
	v_mfma_f32_16x16x32_bf16 v[2:5], v[180:183], v[212:215], v[2:5]
	v_mfma_f32_16x16x32_bf16 v[18:21], v[180:183], v[204:207], v[18:21]
	v_mfma_f32_16x16x32_bf16 v[34:37], v[180:183], v[196:199], v[34:37]
	v_mfma_f32_16x16x32_bf16 v[50:53], v[180:183], v[188:191], v[50:53]
	s_setprio 0
	s_barrier
	s_add_i32 s80, s80, 2
	s_add_u32 s76, s76, 0x100
	s_addc_u32 s77, s77, 0
	s_add_u32 s52, s52, 0x100
	s_addc_u32 s75, s75, 0
	s_cmp_gt_u32 s80, 29
	s_cbranch_scc0 .LBB0_2218
	v_mov_b32_e32 v160, 0xbfb8aa3b
	s_and_b64 vcc, exec, s[24:25]
	s_cbranch_vccz .LBB0_2221
	s_barrier

.LBB0_2462:
	ds_read_b128 v[160:163], v155
	ds_read_b128 v[164:167], v155 offset:1024
	ds_read_b128 v[168:171], v155 offset:2048
	ds_read_b128 v[172:175], v155 offset:3072
	ds_read_b128 v[176:179], v156
	ds_read_b128 v[180:183], v156 offset:1024
	ds_read_b128 v[184:187], v156 offset:2048
	ds_read_b128 v[188:191], v156 offset:3072
	s_add_u32 s34, s76, 0xfff80080
	s_addc_u32 s35, s77, -1
	s_cmp_eq_u32 s74, 28
	s_cselect_b32 s89, s0, s35
	s_cselect_b32 s88, s1, s34
	s_cselect_b32 s35, s7, s52
	s_cselect_b32 s34, s9, s36
	v_lshl_add_u64 v[152:153], s[76:77], 0, v[144:145]
	s_add_i32 m0, s31, 0xc000
	ds_read_b128 v[192:195], v157
	ds_read_b128 v[196:199], v157 offset:1024
	ds_read_b128 v[200:203], v157 offset:2048
	ds_read_b128 v[204:207], v157 offset:3072
	ds_read_b128 v[208:211], v157 offset:4096
	ds_read_b128 v[212:215], v157 offset:5120
	ds_read_b128 v[218:221], v157 offset:6144
	ds_read_b128 v[222:225], v157 offset:7168
	global_load_lds_dwordx4 v[152:153], off
	v_lshl_add_u64 v[152:153], s[76:77], 0, v[146:147]
	s_add_i32 m0, s31, 0xe000
	s_nop 0
	global_load_lds_dwordx4 v[152:153], off
	s_waitcnt vmcnt(8)
	s_waitcnt lgkmcnt(0)
	s_barrier
	s_setprio 1
	s_waitcnt lgkmcnt(0)
	v_mfma_f32_16x16x32_bf16 v[126:129], v[160:163], v[192:195], v[126:129]
	v_mfma_f32_16x16x32_bf16 v[110:113], v[160:163], v[200:203], v[110:113]
	v_mfma_f32_16x16x32_bf16 v[94:97], v[160:163], v[208:211], v[94:97]
	v_mfma_f32_16x16x32_bf16 v[78:81], v[160:163], v[218:221], v[78:81]
	v_mfma_f32_16x16x32_bf16 v[74:77], v[168:171], v[218:221], v[74:77]
	v_mfma_f32_16x16x32_bf16 v[90:93], v[168:171], v[208:211], v[90:93]
	v_mfma_f32_16x16x32_bf16 v[106:109], v[168:171], v[200:203], v[106:109]
	v_mfma_f32_16x16x32_bf16 v[122:125], v[168:171], v[192:195], v[122:125]
	v_mfma_f32_16x16x32_bf16 v[126:129], v[164:167], v[196:199], v[126:129]
	v_mfma_f32_16x16x32_bf16 v[110:113], v[164:167], v[204:207], v[110:113]
	v_mfma_f32_16x16x32_bf16 v[94:97], v[164:167], v[212:215], v[94:97]
	v_mfma_f32_16x16x32_bf16 v[78:81], v[164:167], v[222:225], v[78:81]
	v_mfma_f32_16x16x32_bf16 v[74:77], v[172:175], v[222:225], v[74:77]
	v_mfma_f32_16x16x32_bf16 v[90:93], v[172:175], v[212:215], v[90:93]
	v_mfma_f32_16x16x32_bf16 v[106:109], v[172:175], v[204:207], v[106:109]
	v_mfma_f32_16x16x32_bf16 v[122:125], v[172:175], v[196:199], v[122:125]
	s_setprio 0
	s_setprio 1
	v_mfma_f32_16x16x32_bf16 v[118:121], v[176:179], v[192:195], v[118:121]
	v_mfma_f32_16x16x32_bf16 v[102:105], v[176:179], v[200:203], v[102:105]
	v_mfma_f32_16x16x32_bf16 v[86:89], v[176:179], v[208:211], v[86:89]
	v_mfma_f32_16x16x32_bf16 v[70:73], v[176:179], v[218:221], v[70:73]
	v_mfma_f32_16x16x32_bf16 v[66:69], v[184:187], v[218:221], v[66:69]
	v_mfma_f32_16x16x32_bf16 v[82:85], v[184:187], v[208:211], v[82:85]
	v_mfma_f32_16x16x32_bf16 v[98:101], v[184:187], v[200:203], v[98:101]
	v_mfma_f32_16x16x32_bf16 v[114:117], v[184:187], v[192:195], v[114:117]
	v_mfma_f32_16x16x32_bf16 v[118:121], v[180:183], v[196:199], v[118:121]
	v_mfma_f32_16x16x32_bf16 v[102:105], v[180:183], v[204:207], v[102:105]
	v_mfma_f32_16x16x32_bf16 v[86:89], v[180:183], v[212:215], v[86:89]
	v_mfma_f32_16x16x32_bf16 v[70:73], v[180:183], v[222:225], v[70:73]
	v_mfma_f32_16x16x32_bf16 v[66:69], v[188:191], v[222:225], v[66:69]
	v_mfma_f32_16x16x32_bf16 v[82:85], v[188:191], v[212:215], v[82:85]
	v_mfma_f32_16x16x32_bf16 v[98:101], v[188:191], v[204:207], v[98:101]
	v_mfma_f32_16x16x32_bf16 v[114:117], v[188:191], v[196:199], v[114:117]
	s_setprio 0
	s_barrier
	s_add_i32 s53, s71, s12
	v_lshl_add_u64 v[152:153], s[34:35], 0, v[132:133]
	s_mov_b32 m0, s53
	ds_read_b128 v[192:195], v157 offset:16384
	ds_read_b128 v[196:199], v157 offset:17408
	ds_read_b128 v[200:203], v157 offset:18432
	ds_read_b128 v[204:207], v157 offset:19456
	ds_read_b128 v[208:211], v157 offset:20480
	ds_read_b128 v[212:215], v157 offset:21504
	ds_read_b128 v[218:221], v157 offset:22528
	ds_read_b128 v[222:225], v157 offset:23552
	global_load_lds_dwordx4 v[152:153], off
	s_add_i32 m0, s53, 0x2000
	s_add_u32 s54, s34, 0x80000
	v_lshl_add_u64 v[226:227], s[34:35], 0, v[136:137]
	s_addc_u32 s55, s35, 0
	s_add_i32 s53, s72, s12
	global_load_lds_dwordx4 v[226:227], off
	v_lshl_add_u64 v[228:229], s[54:55], 0, v[132:133]
	s_mov_b32 m0, s53
	v_lshl_add_u64 v[230:231], s[88:89], 0, v[134:135]
	global_load_lds_dwordx4 v[228:229], off
	v_lshl_add_u64 v[228:229], s[54:55], 0, v[136:137]
	s_add_i32 m0, s53, 0x2000
	s_nop 0
	global_load_lds_dwordx4 v[228:229], off
	v_lshl_add_u64 v[228:229], s[88:89], 0, v[130:131]
	s_mov_b32 m0, s31
	s_nop 0
	global_load_lds_dwordx4 v[228:229], off
	s_mov_b32 m0, s33
	s_nop 0
	global_load_lds_dwordx4 v[230:231], off
	s_waitcnt vmcnt(8)
	s_waitcnt lgkmcnt(0)
	s_barrier
	s_setprio 1
	s_waitcnt lgkmcnt(0)
	v_mfma_f32_16x16x32_bf16 v[62:65], v[160:163], v[192:195], v[62:65]
	v_mfma_f32_16x16x32_bf16 v[46:49], v[160:163], v[200:203], v[46:49]
	v_mfma_f32_16x16x32_bf16 v[30:33], v[160:163], v[208:211], v[30:33]
	v_mfma_f32_16x16x32_bf16 v[14:17], v[160:163], v[218:221], v[14:17]
	v_mfma_f32_16x16x32_bf16 v[10:13], v[168:171], v[218:221], v[10:13]
	v_mfma_f32_16x16x32_bf16 v[26:29], v[168:171], v[208:211], v[26:29]
	v_mfma_f32_16x16x32_bf16 v[42:45], v[168:171], v[200:203], v[42:45]
	v_mfma_f32_16x16x32_bf16 v[58:61], v[168:171], v[192:195], v[58:61]
	v_mfma_f32_16x16x32_bf16 v[62:65], v[164:167], v[196:199], v[62:65]
	v_mfma_f32_16x16x32_bf16 v[46:49], v[164:167], v[204:207], v[46:49]
	v_mfma_f32_16x16x32_bf16 v[30:33], v[164:167], v[212:215], v[30:33]
	v_mfma_f32_16x16x32_bf16 v[14:17], v[164:167], v[222:225], v[14:17]
	v_mfma_f32_16x16x32_bf16 v[10:13], v[172:175], v[222:225], v[10:13]
	v_mfma_f32_16x16x32_bf16 v[26:29], v[172:175], v[212:215], v[26:29]
	v_mfma_f32_16x16x32_bf16 v[42:45], v[172:175], v[204:207], v[42:45]
	v_mfma_f32_16x16x32_bf16 v[58:61], v[172:175], v[196:199], v[58:61]
	s_setprio 0
	s_setprio 1
	v_mfma_f32_16x16x32_bf16 v[54:57], v[176:179], v[192:195], v[54:57]
	v_mfma_f32_16x16x32_bf16 v[38:41], v[176:179], v[200:203], v[38:41]
	v_mfma_f32_16x16x32_bf16 v[22:25], v[176:179], v[208:211], v[22:25]
	v_mfma_f32_16x16x32_bf16 v[6:9], v[176:179], v[218:221], v[6:9]
	v_mfma_f32_16x16x32_bf16 v[2:5], v[184:187], v[218:221], v[2:5]
	v_mfma_f32_16x16x32_bf16 v[18:21], v[184:187], v[208:211], v[18:21]
	v_mfma_f32_16x16x32_bf16 v[34:37], v[184:187], v[200:203], v[34:37]
	v_mfma_f32_16x16x32_bf16 v[50:53], v[184:187], v[192:195], v[50:53]
	v_mfma_f32_16x16x32_bf16 v[54:57], v[180:183], v[196:199], v[54:57]
	v_mfma_f32_16x16x32_bf16 v[38:41], v[180:183], v[204:207], v[38:41]
	v_mfma_f32_16x16x32_bf16 v[22:25], v[180:183], v[212:215], v[22:25]
	v_mfma_f32_16x16x32_bf16 v[6:9], v[180:183], v[222:225], v[6:9]
	v_mfma_f32_16x16x32_bf16 v[2:5], v[188:191], v[222:225], v[2:5]
	v_mfma_f32_16x16x32_bf16 v[18:21], v[188:191], v[212:215], v[18:21]
	v_mfma_f32_16x16x32_bf16 v[34:37], v[188:191], v[204:207], v[34:37]
	v_mfma_f32_16x16x32_bf16 v[50:53], v[188:191], v[196:199], v[50:53]
	s_setprio 0
	s_barrier
	s_add_i32 s53, 0, 0x18000
	v_add_u32_e32 v138, s53, v154
	s_add_i32 s62, 0, 0x1c000
	ds_read_b128 v[160:163], v138
	ds_read_b128 v[164:167], v138 offset:1024
	ds_read_b128 v[168:171], v138 offset:2048
	ds_read_b128 v[172:175], v138 offset:3072
	v_add_u32_e32 v138, s62, v154
	ds_read_b128 v[176:179], v138
	ds_read_b128 v[180:183], v138 offset:1024
	ds_read_b128 v[184:187], v138 offset:2048
	ds_read_b128 v[188:191], v138 offset:3072
	s_add_u32 s54, s88, 0x80000
	s_addc_u32 s55, s89, 0
	s_mov_b32 m0, s56
	v_lshl_add_u64 v[232:233], s[54:55], 0, v[130:131]
	ds_read_b128 v[192:195], v157 offset:32768
	ds_read_b128 v[196:199], v157 offset:33792
	ds_read_b128 v[200:203], v157 offset:34816
	ds_read_b128 v[204:207], v157 offset:35840
	ds_read_b128 v[208:211], v157 offset:36864
	ds_read_b128 v[212:215], v157 offset:37888
	ds_read_b128 v[218:221], v157 offset:38912
	ds_read_b128 v[222:225], v157 offset:39936
	global_load_lds_dwordx4 v[232:233], off
	v_lshl_add_u64 v[232:233], s[54:55], 0, v[134:135]
	s_mov_b32 m0, s57
	s_nop 0
	global_load_lds_dwordx4 v[232:233], off
	s_waitcnt vmcnt(8)
	s_waitcnt lgkmcnt(0)
	s_barrier
	s_setprio 1
	s_waitcnt lgkmcnt(0)
	v_mfma_f32_16x16x32_bf16 v[126:129], v[160:163], v[192:195], v[126:129]
	v_mfma_f32_16x16x32_bf16 v[110:113], v[160:163], v[200:203], v[110:113]
	v_mfma_f32_16x16x32_bf16 v[94:97], v[160:163], v[208:211], v[94:97]
	v_mfma_f32_16x16x32_bf16 v[78:81], v[160:163], v[218:221], v[78:81]
	v_mfma_f32_16x16x32_bf16 v[74:77], v[168:171], v[218:221], v[74:77]
	v_mfma_f32_16x16x32_bf16 v[90:93], v[168:171], v[208:211], v[90:93]
	v_mfma_f32_16x16x32_bf16 v[106:109], v[168:171], v[200:203], v[106:109]
	v_mfma_f32_16x16x32_bf16 v[122:125], v[168:171], v[192:195], v[122:125]
	v_mfma_f32_16x16x32_bf16 v[126:129], v[164:167], v[196:199], v[126:129]
	v_mfma_f32_16x16x32_bf16 v[110:113], v[164:167], v[204:207], v[110:113]
	v_mfma_f32_16x16x32_bf16 v[94:97], v[164:167], v[212:215], v[94:97]
	v_mfma_f32_16x16x32_bf16 v[78:81], v[164:167], v[222:225], v[78:81]
	v_mfma_f32_16x16x32_bf16 v[74:77], v[172:175], v[222:225], v[74:77]
	v_mfma_f32_16x16x32_bf16 v[90:93], v[172:175], v[212:215], v[90:93]
	v_mfma_f32_16x16x32_bf16 v[106:109], v[172:175], v[204:207], v[106:109]
	v_mfma_f32_16x16x32_bf16 v[122:125], v[172:175], v[196:199], v[122:125]
	s_setprio 0
	s_setprio 1
	v_mfma_f32_16x16x32_bf16 v[118:121], v[176:179], v[192:195], v[118:121]
	v_mfma_f32_16x16x32_bf16 v[102:105], v[176:179], v[200:203], v[102:105]
	v_mfma_f32_16x16x32_bf16 v[86:89], v[176:179], v[208:211], v[86:89]
	v_mfma_f32_16x16x32_bf16 v[70:73], v[176:179], v[218:221], v[70:73]
	v_mfma_f32_16x16x32_bf16 v[66:69], v[184:187], v[218:221], v[66:69]
	v_mfma_f32_16x16x32_bf16 v[82:85], v[184:187], v[208:211], v[82:85]
	v_mfma_f32_16x16x32_bf16 v[98:101], v[184:187], v[200:203], v[98:101]
	v_mfma_f32_16x16x32_bf16 v[114:117], v[184:187], v[192:195], v[114:117]
	v_mfma_f32_16x16x32_bf16 v[118:121], v[180:183], v[196:199], v[118:121]
	v_mfma_f32_16x16x32_bf16 v[102:105], v[180:183], v[204:207], v[102:105]
	v_mfma_f32_16x16x32_bf16 v[86:89], v[180:183], v[212:215], v[86:89]
	v_mfma_f32_16x16x32_bf16 v[70:73], v[180:183], v[222:225], v[70:73]
	v_mfma_f32_16x16x32_bf16 v[66:69], v[188:191], v[222:225], v[66:69]
	v_mfma_f32_16x16x32_bf16 v[82:85], v[188:191], v[212:215], v[82:85]
	v_mfma_f32_16x16x32_bf16 v[98:101], v[188:191], v[204:207], v[98:101]
	v_mfma_f32_16x16x32_bf16 v[114:117], v[188:191], v[196:199], v[114:117]
	s_setprio 0
	s_barrier
	s_add_i32 s53, s53, s12
	v_lshl_add_u64 v[152:153], v[152:153], 0, s[40:41]
	s_mov_b32 m0, s53
	ds_read_b128 v[192:195], v157 offset:49152
	ds_read_b128 v[196:199], v157 offset:50176
	ds_read_b128 v[200:203], v157 offset:51200
	ds_read_b128 v[204:207], v157 offset:52224
	ds_read_b128 v[208:211], v157 offset:53248
	ds_read_b128 v[212:215], v157 offset:54272
	ds_read_b128 v[218:221], v157 offset:55296
	ds_read_b128 v[222:225], v157 offset:56320
	global_load_lds_dwordx4 v[152:153], off
	s_add_i32 m0, s53, 0x2000
	s_add_u32 s34, s34, 0x80080
	v_lshl_add_u64 v[152:153], v[226:227], 0, s[40:41]
	s_addc_u32 s35, s35, 0
	s_add_i32 s53, s62, s12
	global_load_lds_dwordx4 v[152:153], off
	v_lshl_add_u64 v[152:153], s[34:35], 0, v[132:133]
	s_mov_b32 m0, s53
	s_nop 0
	global_load_lds_dwordx4 v[152:153], off
	v_lshl_add_u64 v[152:153], s[34:35], 0, v[136:137]
	s_add_i32 m0, s53, 0x2000
	s_nop 0
	global_load_lds_dwordx4 v[152:153], off
	v_lshl_add_u64 v[152:153], v[228:229], 0, s[40:41]
	s_mov_b32 m0, s59
	s_nop 0
	global_load_lds_dwordx4 v[152:153], off
	v_lshl_add_u64 v[152:153], v[230:231], 0, s[40:41]
	s_mov_b32 m0, s60
	s_nop 0
	global_load_lds_dwordx4 v[152:153], off
	s_waitcnt vmcnt(8)
	s_waitcnt lgkmcnt(0)
	s_barrier
	s_setprio 1
	s_waitcnt lgkmcnt(0)
	v_mfma_f32_16x16x32_bf16 v[62:65], v[160:163], v[192:195], v[62:65]
	v_mfma_f32_16x16x32_bf16 v[46:49], v[160:163], v[200:203], v[46:49]
	v_mfma_f32_16x16x32_bf16 v[30:33], v[160:163], v[208:211], v[30:33]
	v_mfma_f32_16x16x32_bf16 v[14:17], v[160:163], v[218:221], v[14:17]
	v_mfma_f32_16x16x32_bf16 v[10:13], v[168:171], v[218:221], v[10:13]
	v_mfma_f32_16x16x32_bf16 v[26:29], v[168:171], v[208:211], v[26:29]
	v_mfma_f32_16x16x32_bf16 v[42:45], v[168:171], v[200:203], v[42:45]
	v_mfma_f32_16x16x32_bf16 v[58:61], v[168:171], v[192:195], v[58:61]
	v_mfma_f32_16x16x32_bf16 v[62:65], v[164:167], v[196:199], v[62:65]
	v_mfma_f32_16x16x32_bf16 v[46:49], v[164:167], v[204:207], v[46:49]
	v_mfma_f32_16x16x32_bf16 v[30:33], v[164:167], v[212:215], v[30:33]
	v_mfma_f32_16x16x32_bf16 v[14:17], v[164:167], v[222:225], v[14:17]
	v_mfma_f32_16x16x32_bf16 v[10:13], v[172:175], v[222:225], v[10:13]
	v_mfma_f32_16x16x32_bf16 v[26:29], v[172:175], v[212:215], v[26:29]
	v_mfma_f32_16x16x32_bf16 v[42:45], v[172:175], v[204:207], v[42:45]
	v_mfma_f32_16x16x32_bf16 v[58:61], v[172:175], v[196:199], v[58:61]
	s_setprio 0
	s_setprio 1
	v_mfma_f32_16x16x32_bf16 v[54:57], v[176:179], v[192:195], v[54:57]
	v_mfma_f32_16x16x32_bf16 v[38:41], v[176:179], v[200:203], v[38:41]
	v_mfma_f32_16x16x32_bf16 v[22:25], v[176:179], v[208:211], v[22:25]
	v_mfma_f32_16x16x32_bf16 v[6:9], v[176:179], v[218:221], v[6:9]
	v_mfma_f32_16x16x32_bf16 v[2:5], v[184:187], v[218:221], v[2:5]
	v_mfma_f32_16x16x32_bf16 v[18:21], v[184:187], v[208:211], v[18:21]
	v_mfma_f32_16x16x32_bf16 v[34:37], v[184:187], v[200:203], v[34:37]
	v_mfma_f32_16x16x32_bf16 v[50:53], v[184:187], v[192:195], v[50:53]
	v_mfma_f32_16x16x32_bf16 v[54:57], v[180:183], v[196:199], v[54:57]
	v_mfma_f32_16x16x32_bf16 v[38:41], v[180:183], v[204:207], v[38:41]
	v_mfma_f32_16x16x32_bf16 v[22:25], v[180:183], v[212:215], v[22:25]
	v_mfma_f32_16x16x32_bf16 v[6:9], v[180:183], v[222:225], v[6:9]
	v_mfma_f32_16x16x32_bf16 v[2:5], v[188:191], v[222:225], v[2:5]
	v_mfma_f32_16x16x32_bf16 v[18:21], v[188:191], v[212:215], v[18:21]
	v_mfma_f32_16x16x32_bf16 v[34:37], v[188:191], v[204:207], v[34:37]
	v_mfma_f32_16x16x32_bf16 v[50:53], v[188:191], v[196:199], v[50:53]
	s_setprio 0
	s_barrier
	s_add_i32 s74, s74, 2
	s_add_u32 s76, s76, 0x100
	s_addc_u32 s77, s77, 0
	s_add_u32 s36, s36, 0x100
	s_addc_u32 s52, s52, 0
	s_cmp_gt_u32 s74, 29
	s_cbranch_scc0 .LBB0_2462
	s_and_b64 vcc, exec, s[46:47]
	s_cbranch_vccz .LBB0_2465
	s_barrier

.LBB0_2629:
	ds_read_b128 v[146:149], v165
	ds_read_b128 v[150:153], v165 offset:1024
	ds_read_b128 v[168:171], v165 offset:2048
	ds_read_b128 v[172:175], v165 offset:3072
	ds_read_b128 v[176:179], v166
	ds_read_b128 v[180:183], v166 offset:1024
	ds_read_b128 v[184:187], v166 offset:2048
	ds_read_b128 v[188:191], v166 offset:3072
	s_add_u32 s34, s74, 0xfffe0080
	s_addc_u32 s35, s75, -1
	s_cmp_eq_u32 s79, 4
	s_cselect_b32 s77, s0, s35
	s_cselect_b32 s76, s1, s34
	s_cselect_b32 s35, s27, s78
	s_cselect_b32 s34, s37, s52
	v_lshl_add_u64 v[226:227], s[74:75], 0, v[138:139]
	s_add_i32 m0, s33, 0xc000
	ds_read_b128 v[192:195], v167
	ds_read_b128 v[196:199], v167 offset:1024
	ds_read_b128 v[200:203], v167 offset:2048
	ds_read_b128 v[204:207], v167 offset:3072
	ds_read_b128 v[208:211], v167 offset:4096
	ds_read_b128 v[212:215], v167 offset:5120
	ds_read_b128 v[218:221], v167 offset:6144
	ds_read_b128 v[222:225], v167 offset:7168
	global_load_lds_dwordx4 v[226:227], off
	v_lshl_add_u64 v[226:227], s[74:75], 0, v[140:141]
	s_add_i32 m0, s33, 0xe000
	s_nop 0
	global_load_lds_dwordx4 v[226:227], off
	s_waitcnt vmcnt(8)
	s_waitcnt lgkmcnt(0)
	s_barrier
	s_setprio 1
	s_waitcnt lgkmcnt(0)
	v_mfma_f32_16x16x32_bf16 v[126:129], v[146:149], v[192:195], v[126:129]
	v_mfma_f32_16x16x32_bf16 v[114:117], v[146:149], v[200:203], v[114:117]
	v_mfma_f32_16x16x32_bf16 v[98:101], v[146:149], v[208:211], v[98:101]
	v_mfma_f32_16x16x32_bf16 v[82:85], v[146:149], v[218:221], v[82:85]
	v_mfma_f32_16x16x32_bf16 v[74:77], v[168:171], v[218:221], v[74:77]
	v_mfma_f32_16x16x32_bf16 v[90:93], v[168:171], v[208:211], v[90:93]
	v_mfma_f32_16x16x32_bf16 v[106:109], v[168:171], v[200:203], v[106:109]
	v_mfma_f32_16x16x32_bf16 v[122:125], v[168:171], v[192:195], v[122:125]
	v_mfma_f32_16x16x32_bf16 v[126:129], v[150:153], v[196:199], v[126:129]
	v_mfma_f32_16x16x32_bf16 v[114:117], v[150:153], v[204:207], v[114:117]
	v_mfma_f32_16x16x32_bf16 v[98:101], v[150:153], v[212:215], v[98:101]
	v_mfma_f32_16x16x32_bf16 v[82:85], v[150:153], v[222:225], v[82:85]
	v_mfma_f32_16x16x32_bf16 v[74:77], v[172:175], v[222:225], v[74:77]
	v_mfma_f32_16x16x32_bf16 v[90:93], v[172:175], v[212:215], v[90:93]
	v_mfma_f32_16x16x32_bf16 v[106:109], v[172:175], v[204:207], v[106:109]
	v_mfma_f32_16x16x32_bf16 v[122:125], v[172:175], v[196:199], v[122:125]
	s_setprio 0
	s_setprio 1
	v_mfma_f32_16x16x32_bf16 v[118:121], v[176:179], v[192:195], v[118:121]
	v_mfma_f32_16x16x32_bf16 v[102:105], v[176:179], v[200:203], v[102:105]
	v_mfma_f32_16x16x32_bf16 v[86:89], v[176:179], v[208:211], v[86:89]
	v_mfma_f32_16x16x32_bf16 v[70:73], v[176:179], v[218:221], v[70:73]
	v_mfma_f32_16x16x32_bf16 v[66:69], v[184:187], v[218:221], v[66:69]
	v_mfma_f32_16x16x32_bf16 v[78:81], v[184:187], v[208:211], v[78:81]
	v_mfma_f32_16x16x32_bf16 v[94:97], v[184:187], v[200:203], v[94:97]
	v_mfma_f32_16x16x32_bf16 v[110:113], v[184:187], v[192:195], v[110:113]
	v_mfma_f32_16x16x32_bf16 v[118:121], v[180:183], v[196:199], v[118:121]
	v_mfma_f32_16x16x32_bf16 v[102:105], v[180:183], v[204:207], v[102:105]
	v_mfma_f32_16x16x32_bf16 v[86:89], v[180:183], v[212:215], v[86:89]
	v_mfma_f32_16x16x32_bf16 v[70:73], v[180:183], v[222:225], v[70:73]
	v_mfma_f32_16x16x32_bf16 v[66:69], v[188:191], v[222:225], v[66:69]
	v_mfma_f32_16x16x32_bf16 v[78:81], v[188:191], v[212:215], v[78:81]
	v_mfma_f32_16x16x32_bf16 v[94:97], v[188:191], v[204:207], v[94:97]
	v_mfma_f32_16x16x32_bf16 v[110:113], v[188:191], v[196:199], v[110:113]
	s_setprio 0
	s_barrier
	s_add_i32 s53, s70, s12
	v_lshl_add_u64 v[226:227], s[34:35], 0, v[132:133]
	s_mov_b32 m0, s53
	ds_read_b128 v[192:195], v167 offset:16384
	ds_read_b128 v[196:199], v167 offset:17408
	ds_read_b128 v[200:203], v167 offset:18432
	ds_read_b128 v[204:207], v167 offset:19456
	ds_read_b128 v[208:211], v167 offset:20480
	ds_read_b128 v[212:215], v167 offset:21504
	ds_read_b128 v[218:221], v167 offset:22528
	ds_read_b128 v[222:225], v167 offset:23552
	global_load_lds_dwordx4 v[226:227], off
	s_add_i32 m0, s53, 0x2000
	s_add_u32 s54, s34, 0x20000
	v_lshl_add_u64 v[228:229], s[34:35], 0, v[136:137]
	s_addc_u32 s55, s35, 0
	s_add_i32 s53, s71, s12
	global_load_lds_dwordx4 v[228:229], off
	v_lshl_add_u64 v[230:231], s[54:55], 0, v[132:133]
	s_mov_b32 m0, s53
	v_lshl_add_u64 v[232:233], s[76:77], 0, v[134:135]
	global_load_lds_dwordx4 v[230:231], off
	v_lshl_add_u64 v[230:231], s[54:55], 0, v[136:137]
	s_add_i32 m0, s53, 0x2000
	s_nop 0
	global_load_lds_dwordx4 v[230:231], off
	v_lshl_add_u64 v[230:231], s[76:77], 0, v[130:131]
	s_mov_b32 m0, s33
	s_nop 0
	global_load_lds_dwordx4 v[230:231], off
	s_mov_b32 m0, s47
	s_nop 0
	global_load_lds_dwordx4 v[232:233], off
	s_waitcnt vmcnt(8)
	s_waitcnt lgkmcnt(0)
	s_barrier
	s_setprio 1
	s_waitcnt lgkmcnt(0)
	v_mfma_f32_16x16x32_bf16 v[62:65], v[146:149], v[192:195], v[62:65]
	v_mfma_f32_16x16x32_bf16 v[50:53], v[146:149], v[200:203], v[50:53]
	v_mfma_f32_16x16x32_bf16 v[34:37], v[146:149], v[208:211], v[34:37]
	v_mfma_f32_16x16x32_bf16 v[18:21], v[146:149], v[218:221], v[18:21]
	v_mfma_f32_16x16x32_bf16 v[10:13], v[168:171], v[218:221], v[10:13]
	v_mfma_f32_16x16x32_bf16 v[26:29], v[168:171], v[208:211], v[26:29]
	v_mfma_f32_16x16x32_bf16 v[42:45], v[168:171], v[200:203], v[42:45]
	v_mfma_f32_16x16x32_bf16 v[58:61], v[168:171], v[192:195], v[58:61]
	v_mfma_f32_16x16x32_bf16 v[62:65], v[150:153], v[196:199], v[62:65]
	v_mfma_f32_16x16x32_bf16 v[50:53], v[150:153], v[204:207], v[50:53]
	v_mfma_f32_16x16x32_bf16 v[34:37], v[150:153], v[212:215], v[34:37]
	v_mfma_f32_16x16x32_bf16 v[18:21], v[150:153], v[222:225], v[18:21]
	v_mfma_f32_16x16x32_bf16 v[10:13], v[172:175], v[222:225], v[10:13]
	v_mfma_f32_16x16x32_bf16 v[26:29], v[172:175], v[212:215], v[26:29]
	v_mfma_f32_16x16x32_bf16 v[42:45], v[172:175], v[204:207], v[42:45]
	v_mfma_f32_16x16x32_bf16 v[58:61], v[172:175], v[196:199], v[58:61]
	s_setprio 0
	s_setprio 1
	v_mfma_f32_16x16x32_bf16 v[54:57], v[176:179], v[192:195], v[54:57]
	v_mfma_f32_16x16x32_bf16 v[38:41], v[176:179], v[200:203], v[38:41]
	v_mfma_f32_16x16x32_bf16 v[22:25], v[176:179], v[208:211], v[22:25]
	v_mfma_f32_16x16x32_bf16 v[6:9], v[176:179], v[218:221], v[6:9]
	v_mfma_f32_16x16x32_bf16 v[2:5], v[184:187], v[218:221], v[2:5]
	v_mfma_f32_16x16x32_bf16 v[14:17], v[184:187], v[208:211], v[14:17]
	v_mfma_f32_16x16x32_bf16 v[30:33], v[184:187], v[200:203], v[30:33]
	v_mfma_f32_16x16x32_bf16 v[46:49], v[184:187], v[192:195], v[46:49]
	v_mfma_f32_16x16x32_bf16 v[54:57], v[180:183], v[196:199], v[54:57]
	v_mfma_f32_16x16x32_bf16 v[38:41], v[180:183], v[204:207], v[38:41]
	v_mfma_f32_16x16x32_bf16 v[22:25], v[180:183], v[212:215], v[22:25]
	v_mfma_f32_16x16x32_bf16 v[6:9], v[180:183], v[222:225], v[6:9]
	v_mfma_f32_16x16x32_bf16 v[2:5], v[188:191], v[222:225], v[2:5]
	v_mfma_f32_16x16x32_bf16 v[14:17], v[188:191], v[212:215], v[14:17]
	v_mfma_f32_16x16x32_bf16 v[30:33], v[188:191], v[204:207], v[30:33]
	v_mfma_f32_16x16x32_bf16 v[46:49], v[188:191], v[196:199], v[46:49]
	s_setprio 0
	s_barrier
	s_add_i32 s53, 0, 0x18000
	s_add_i32 s62, 0, 0x1c000
	v_add_u32_e32 v172, s53, v162
	v_add_u32_e32 v188, s62, v162
	ds_read_b128 v[146:149], v172
	ds_read_b128 v[150:153], v172 offset:1024
	ds_read_b128 v[168:171], v172 offset:2048
	ds_read_b128 v[172:175], v172 offset:3072
	ds_read_b128 v[176:179], v188
	ds_read_b128 v[180:183], v188 offset:1024
	ds_read_b128 v[184:187], v188 offset:2048
	ds_read_b128 v[188:191], v188 offset:3072
	s_add_u32 s54, s76, 0x20000
	s_addc_u32 s55, s77, 0
	s_mov_b32 m0, s56
	v_lshl_add_u64 v[234:235], s[54:55], 0, v[130:131]
	ds_read_b128 v[192:195], v167 offset:32768
	ds_read_b128 v[196:199], v167 offset:33792
	ds_read_b128 v[200:203], v167 offset:34816
	ds_read_b128 v[204:207], v167 offset:35840
	ds_read_b128 v[208:211], v167 offset:36864
	ds_read_b128 v[212:215], v167 offset:37888
	ds_read_b128 v[218:221], v167 offset:38912
	ds_read_b128 v[222:225], v167 offset:39936
	global_load_lds_dwordx4 v[234:235], off
	v_lshl_add_u64 v[234:235], s[54:55], 0, v[134:135]
	s_mov_b32 m0, s57
	s_nop 0
	global_load_lds_dwordx4 v[234:235], off
	s_waitcnt vmcnt(8)
	s_waitcnt lgkmcnt(0)
	s_barrier
	s_setprio 1
	s_waitcnt lgkmcnt(0)
	v_mfma_f32_16x16x32_bf16 v[126:129], v[146:149], v[192:195], v[126:129]
	v_mfma_f32_16x16x32_bf16 v[114:117], v[146:149], v[200:203], v[114:117]
	v_mfma_f32_16x16x32_bf16 v[98:101], v[146:149], v[208:211], v[98:101]
	v_mfma_f32_16x16x32_bf16 v[82:85], v[146:149], v[218:221], v[82:85]
	v_mfma_f32_16x16x32_bf16 v[74:77], v[168:171], v[218:221], v[74:77]
	v_mfma_f32_16x16x32_bf16 v[90:93], v[168:171], v[208:211], v[90:93]
	v_mfma_f32_16x16x32_bf16 v[106:109], v[168:171], v[200:203], v[106:109]
	v_mfma_f32_16x16x32_bf16 v[122:125], v[168:171], v[192:195], v[122:125]
	v_mfma_f32_16x16x32_bf16 v[126:129], v[150:153], v[196:199], v[126:129]
	v_mfma_f32_16x16x32_bf16 v[114:117], v[150:153], v[204:207], v[114:117]
	v_mfma_f32_16x16x32_bf16 v[98:101], v[150:153], v[212:215], v[98:101]
	v_mfma_f32_16x16x32_bf16 v[82:85], v[150:153], v[222:225], v[82:85]
	v_mfma_f32_16x16x32_bf16 v[74:77], v[172:175], v[222:225], v[74:77]
	v_mfma_f32_16x16x32_bf16 v[90:93], v[172:175], v[212:215], v[90:93]
	v_mfma_f32_16x16x32_bf16 v[106:109], v[172:175], v[204:207], v[106:109]
	v_mfma_f32_16x16x32_bf16 v[122:125], v[172:175], v[196:199], v[122:125]
	s_setprio 0
	s_setprio 1
	v_mfma_f32_16x16x32_bf16 v[118:121], v[176:179], v[192:195], v[118:121]
	v_mfma_f32_16x16x32_bf16 v[102:105], v[176:179], v[200:203], v[102:105]
	v_mfma_f32_16x16x32_bf16 v[86:89], v[176:179], v[208:211], v[86:89]
	v_mfma_f32_16x16x32_bf16 v[70:73], v[176:179], v[218:221], v[70:73]
	v_mfma_f32_16x16x32_bf16 v[66:69], v[184:187], v[218:221], v[66:69]
	v_mfma_f32_16x16x32_bf16 v[78:81], v[184:187], v[208:211], v[78:81]
	v_mfma_f32_16x16x32_bf16 v[94:97], v[184:187], v[200:203], v[94:97]
	v_mfma_f32_16x16x32_bf16 v[110:113], v[184:187], v[192:195], v[110:113]
	v_mfma_f32_16x16x32_bf16 v[118:121], v[180:183], v[196:199], v[118:121]
	v_mfma_f32_16x16x32_bf16 v[102:105], v[180:183], v[204:207], v[102:105]
	v_mfma_f32_16x16x32_bf16 v[86:89], v[180:183], v[212:215], v[86:89]
	v_mfma_f32_16x16x32_bf16 v[70:73], v[180:183], v[222:225], v[70:73]
	v_mfma_f32_16x16x32_bf16 v[66:69], v[188:191], v[222:225], v[66:69]
	v_mfma_f32_16x16x32_bf16 v[78:81], v[188:191], v[212:215], v[78:81]
	v_mfma_f32_16x16x32_bf16 v[94:97], v[188:191], v[204:207], v[94:97]
	v_mfma_f32_16x16x32_bf16 v[110:113], v[188:191], v[196:199], v[110:113]
	s_setprio 0
	s_barrier
	s_add_i32 s53, s53, s12
	v_lshl_add_u64 v[226:227], v[226:227], 0, s[8:9]
	s_mov_b32 m0, s53
	ds_read_b128 v[192:195], v167 offset:49152
	ds_read_b128 v[196:199], v167 offset:50176
	ds_read_b128 v[200:203], v167 offset:51200
	ds_read_b128 v[204:207], v167 offset:52224
	ds_read_b128 v[208:211], v167 offset:53248
	ds_read_b128 v[212:215], v167 offset:54272
	ds_read_b128 v[218:221], v167 offset:55296
	ds_read_b128 v[222:225], v167 offset:56320
	global_load_lds_dwordx4 v[226:227], off
	s_add_i32 m0, s53, 0x2000
	s_add_u32 s34, s34, 0x20080
	v_lshl_add_u64 v[226:227], v[228:229], 0, s[8:9]
	s_addc_u32 s35, s35, 0
	s_add_i32 s53, s62, s12
	global_load_lds_dwordx4 v[226:227], off
	v_lshl_add_u64 v[226:227], s[34:35], 0, v[132:133]
	s_mov_b32 m0, s53
	s_nop 0
	global_load_lds_dwordx4 v[226:227], off
	v_lshl_add_u64 v[226:227], s[34:35], 0, v[136:137]
	s_add_i32 m0, s53, 0x2000
	s_nop 0
	global_load_lds_dwordx4 v[226:227], off
	v_lshl_add_u64 v[226:227], v[230:231], 0, s[8:9]
	s_mov_b32 m0, s59
	s_nop 0
	global_load_lds_dwordx4 v[226:227], off
	v_lshl_add_u64 v[226:227], v[232:233], 0, s[8:9]
	s_mov_b32 m0, s60
	s_nop 0
	global_load_lds_dwordx4 v[226:227], off
	s_waitcnt vmcnt(8)
	s_waitcnt lgkmcnt(0)
	s_barrier
	s_setprio 1
	s_waitcnt lgkmcnt(0)
	v_mfma_f32_16x16x32_bf16 v[62:65], v[146:149], v[192:195], v[62:65]
	v_mfma_f32_16x16x32_bf16 v[50:53], v[146:149], v[200:203], v[50:53]
	v_mfma_f32_16x16x32_bf16 v[34:37], v[146:149], v[208:211], v[34:37]
	v_mfma_f32_16x16x32_bf16 v[18:21], v[146:149], v[218:221], v[18:21]
	v_mfma_f32_16x16x32_bf16 v[10:13], v[168:171], v[218:221], v[10:13]
	v_mfma_f32_16x16x32_bf16 v[26:29], v[168:171], v[208:211], v[26:29]
	v_mfma_f32_16x16x32_bf16 v[42:45], v[168:171], v[200:203], v[42:45]
	v_mfma_f32_16x16x32_bf16 v[58:61], v[168:171], v[192:195], v[58:61]
	v_mfma_f32_16x16x32_bf16 v[62:65], v[150:153], v[196:199], v[62:65]
	v_mfma_f32_16x16x32_bf16 v[50:53], v[150:153], v[204:207], v[50:53]
	v_mfma_f32_16x16x32_bf16 v[34:37], v[150:153], v[212:215], v[34:37]
	v_mfma_f32_16x16x32_bf16 v[18:21], v[150:153], v[222:225], v[18:21]
	v_mfma_f32_16x16x32_bf16 v[10:13], v[172:175], v[222:225], v[10:13]
	v_mfma_f32_16x16x32_bf16 v[26:29], v[172:175], v[212:215], v[26:29]
	v_mfma_f32_16x16x32_bf16 v[42:45], v[172:175], v[204:207], v[42:45]
	v_mfma_f32_16x16x32_bf16 v[58:61], v[172:175], v[196:199], v[58:61]
	s_setprio 0
	s_setprio 1
	v_mfma_f32_16x16x32_bf16 v[54:57], v[176:179], v[192:195], v[54:57]
	v_mfma_f32_16x16x32_bf16 v[38:41], v[176:179], v[200:203], v[38:41]
	v_mfma_f32_16x16x32_bf16 v[22:25], v[176:179], v[208:211], v[22:25]
	v_mfma_f32_16x16x32_bf16 v[6:9], v[176:179], v[218:221], v[6:9]
	v_mfma_f32_16x16x32_bf16 v[2:5], v[184:187], v[218:221], v[2:5]
	v_mfma_f32_16x16x32_bf16 v[14:17], v[184:187], v[208:211], v[14:17]
	v_mfma_f32_16x16x32_bf16 v[30:33], v[184:187], v[200:203], v[30:33]
	v_mfma_f32_16x16x32_bf16 v[46:49], v[184:187], v[192:195], v[46:49]
	v_mfma_f32_16x16x32_bf16 v[54:57], v[180:183], v[196:199], v[54:57]
	v_mfma_f32_16x16x32_bf16 v[38:41], v[180:183], v[204:207], v[38:41]
	v_mfma_f32_16x16x32_bf16 v[22:25], v[180:183], v[212:215], v[22:25]
	v_mfma_f32_16x16x32_bf16 v[6:9], v[180:183], v[222:225], v[6:9]
	v_mfma_f32_16x16x32_bf16 v[2:5], v[188:191], v[222:225], v[2:5]
	v_mfma_f32_16x16x32_bf16 v[14:17], v[188:191], v[212:215], v[14:17]
	v_mfma_f32_16x16x32_bf16 v[30:33], v[188:191], v[204:207], v[30:33]
	v_mfma_f32_16x16x32_bf16 v[46:49], v[188:191], v[196:199], v[46:49]
	s_setprio 0
	s_barrier
	s_add_i32 s79, s79, 2
	s_add_u32 s74, s74, 0x100
	s_addc_u32 s75, s75, 0
	s_add_u32 s52, s52, 0x100
	s_addc_u32 s78, s78, 0
	s_cmp_gt_u32 s79, 5
	s_cbranch_scc0 .LBB0_2629
	s_and_b64 vcc, exec, s[24:25]
	s_cbranch_vccz .LBB0_2632
	s_barrier

.LBB0_2659:
	ds_read_b128 v[146:149], v1
	ds_read_b128 v[160:163], v1 offset:1024
	ds_read_b128 v[164:167], v1 offset:2048
	ds_read_b128 v[168:171], v1 offset:3072
	ds_read_b128 v[172:175], v154
	ds_read_b128 v[176:179], v154 offset:1024
	ds_read_b128 v[180:183], v154 offset:2048
	ds_read_b128 v[184:187], v154 offset:3072
	s_add_u32 s34, s74, 0xfffe0080
	s_addc_u32 s35, s75, -1
	s_cmp_eq_u32 s72, 4
	s_cselect_b32 s77, s0, s35
	s_cselect_b32 s76, s1, s34
	s_cselect_b32 s35, s27, s71
	s_cselect_b32 s34, s37, s52
	v_lshl_add_u64 v[150:151], s[74:75], 0, v[138:139]
	s_add_i32 m0, s33, 0xc000
	ds_read_b128 v[188:191], v155
	ds_read_b128 v[192:195], v155 offset:1024
	ds_read_b128 v[196:199], v155 offset:2048
	ds_read_b128 v[200:203], v155 offset:3072
	ds_read_b128 v[204:207], v155 offset:4096
	ds_read_b128 v[208:211], v155 offset:5120
	ds_read_b128 v[212:215], v155 offset:6144
	ds_read_b128 v[218:221], v155 offset:7168
	global_load_lds_dwordx4 v[150:151], off
	v_lshl_add_u64 v[150:151], s[74:75], 0, v[140:141]
	s_add_i32 m0, s33, 0xe000
	s_nop 0
	global_load_lds_dwordx4 v[150:151], off
	s_waitcnt vmcnt(8)
	s_waitcnt lgkmcnt(0)
	s_barrier
	s_setprio 1
	s_waitcnt lgkmcnt(0)
	v_mfma_f32_16x16x32_bf16 v[126:129], v[146:149], v[188:191], v[126:129]
	v_mfma_f32_16x16x32_bf16 v[110:113], v[146:149], v[196:199], v[110:113]
	v_mfma_f32_16x16x32_bf16 v[94:97], v[146:149], v[204:207], v[94:97]
	v_mfma_f32_16x16x32_bf16 v[78:81], v[146:149], v[212:215], v[78:81]
	v_mfma_f32_16x16x32_bf16 v[74:77], v[164:167], v[212:215], v[74:77]
	v_mfma_f32_16x16x32_bf16 v[90:93], v[164:167], v[204:207], v[90:93]
	v_mfma_f32_16x16x32_bf16 v[106:109], v[164:167], v[196:199], v[106:109]
	v_mfma_f32_16x16x32_bf16 v[122:125], v[164:167], v[188:191], v[122:125]
	v_mfma_f32_16x16x32_bf16 v[126:129], v[160:163], v[192:195], v[126:129]
	v_mfma_f32_16x16x32_bf16 v[110:113], v[160:163], v[200:203], v[110:113]
	v_mfma_f32_16x16x32_bf16 v[94:97], v[160:163], v[208:211], v[94:97]
	v_mfma_f32_16x16x32_bf16 v[78:81], v[160:163], v[218:221], v[78:81]
	v_mfma_f32_16x16x32_bf16 v[74:77], v[168:171], v[218:221], v[74:77]
	v_mfma_f32_16x16x32_bf16 v[90:93], v[168:171], v[208:211], v[90:93]
	v_mfma_f32_16x16x32_bf16 v[106:109], v[168:171], v[200:203], v[106:109]
	v_mfma_f32_16x16x32_bf16 v[122:125], v[168:171], v[192:195], v[122:125]
	s_setprio 0
	s_setprio 1
	v_mfma_f32_16x16x32_bf16 v[118:121], v[172:175], v[188:191], v[118:121]
	v_mfma_f32_16x16x32_bf16 v[102:105], v[172:175], v[196:199], v[102:105]
	v_mfma_f32_16x16x32_bf16 v[86:89], v[172:175], v[204:207], v[86:89]
	v_mfma_f32_16x16x32_bf16 v[70:73], v[172:175], v[212:215], v[70:73]
	v_mfma_f32_16x16x32_bf16 v[66:69], v[180:183], v[212:215], v[66:69]
	v_mfma_f32_16x16x32_bf16 v[82:85], v[180:183], v[204:207], v[82:85]
	v_mfma_f32_16x16x32_bf16 v[98:101], v[180:183], v[196:199], v[98:101]
	v_mfma_f32_16x16x32_bf16 v[114:117], v[180:183], v[188:191], v[114:117]
	v_mfma_f32_16x16x32_bf16 v[118:121], v[176:179], v[192:195], v[118:121]
	v_mfma_f32_16x16x32_bf16 v[102:105], v[176:179], v[200:203], v[102:105]
	v_mfma_f32_16x16x32_bf16 v[86:89], v[176:179], v[208:211], v[86:89]
	v_mfma_f32_16x16x32_bf16 v[70:73], v[176:179], v[218:221], v[70:73]
	v_mfma_f32_16x16x32_bf16 v[66:69], v[184:187], v[218:221], v[66:69]
	v_mfma_f32_16x16x32_bf16 v[82:85], v[184:187], v[208:211], v[82:85]
	v_mfma_f32_16x16x32_bf16 v[98:101], v[184:187], v[200:203], v[98:101]
	v_mfma_f32_16x16x32_bf16 v[114:117], v[184:187], v[192:195], v[114:117]
	s_setprio 0
	s_barrier
	s_add_i32 s53, s60, s13
	v_lshl_add_u64 v[150:151], s[34:35], 0, v[132:133]
	s_mov_b32 m0, s53
	ds_read_b128 v[188:191], v155 offset:16384
	ds_read_b128 v[192:195], v155 offset:17408
	ds_read_b128 v[196:199], v155 offset:18432
	ds_read_b128 v[200:203], v155 offset:19456
	ds_read_b128 v[204:207], v155 offset:20480
	ds_read_b128 v[208:211], v155 offset:21504
	ds_read_b128 v[212:215], v155 offset:22528
	ds_read_b128 v[218:221], v155 offset:23552
	global_load_lds_dwordx4 v[150:151], off
	s_add_i32 m0, s53, 0x2000
	s_add_u32 s62, s34, 0x20000
	v_lshl_add_u64 v[222:223], s[34:35], 0, v[136:137]
	s_addc_u32 s63, s35, 0
	s_add_i32 s53, s61, s13
	global_load_lds_dwordx4 v[222:223], off
	v_lshl_add_u64 v[224:225], s[62:63], 0, v[132:133]
	s_mov_b32 m0, s53
	v_lshl_add_u64 v[226:227], s[76:77], 0, v[134:135]
	global_load_lds_dwordx4 v[224:225], off
	v_lshl_add_u64 v[224:225], s[62:63], 0, v[136:137]
	s_add_i32 m0, s53, 0x2000
	s_nop 0
	global_load_lds_dwordx4 v[224:225], off
	v_lshl_add_u64 v[224:225], s[76:77], 0, v[130:131]
	s_mov_b32 m0, s33
	s_nop 0
	global_load_lds_dwordx4 v[224:225], off
	s_mov_b32 m0, s47
	s_nop 0
	global_load_lds_dwordx4 v[226:227], off
	s_waitcnt vmcnt(8)
	s_waitcnt lgkmcnt(0)
	s_barrier
	s_setprio 1
	s_waitcnt lgkmcnt(0)
	v_mfma_f32_16x16x32_bf16 v[62:65], v[146:149], v[188:191], v[62:65]
	v_mfma_f32_16x16x32_bf16 v[50:53], v[146:149], v[196:199], v[50:53]
	v_mfma_f32_16x16x32_bf16 v[34:37], v[146:149], v[204:207], v[34:37]
	v_mfma_f32_16x16x32_bf16 v[18:21], v[146:149], v[212:215], v[18:21]
	v_mfma_f32_16x16x32_bf16 v[10:13], v[164:167], v[212:215], v[10:13]
	v_mfma_f32_16x16x32_bf16 v[26:29], v[164:167], v[204:207], v[26:29]
	v_mfma_f32_16x16x32_bf16 v[42:45], v[164:167], v[196:199], v[42:45]
	v_mfma_f32_16x16x32_bf16 v[58:61], v[164:167], v[188:191], v[58:61]
	v_mfma_f32_16x16x32_bf16 v[62:65], v[160:163], v[192:195], v[62:65]
	v_mfma_f32_16x16x32_bf16 v[50:53], v[160:163], v[200:203], v[50:53]
	v_mfma_f32_16x16x32_bf16 v[34:37], v[160:163], v[208:211], v[34:37]
	v_mfma_f32_16x16x32_bf16 v[18:21], v[160:163], v[218:221], v[18:21]
	v_mfma_f32_16x16x32_bf16 v[10:13], v[168:171], v[218:221], v[10:13]
	v_mfma_f32_16x16x32_bf16 v[26:29], v[168:171], v[208:211], v[26:29]
	v_mfma_f32_16x16x32_bf16 v[42:45], v[168:171], v[200:203], v[42:45]
	v_mfma_f32_16x16x32_bf16 v[58:61], v[168:171], v[192:195], v[58:61]
	s_setprio 0
	s_setprio 1
	v_mfma_f32_16x16x32_bf16 v[54:57], v[172:175], v[188:191], v[54:57]
	v_mfma_f32_16x16x32_bf16 v[38:41], v[172:175], v[196:199], v[38:41]
	v_mfma_f32_16x16x32_bf16 v[22:25], v[172:175], v[204:207], v[22:25]
	v_mfma_f32_16x16x32_bf16 v[6:9], v[172:175], v[212:215], v[6:9]
	v_mfma_f32_16x16x32_bf16 v[2:5], v[180:183], v[212:215], v[2:5]
	v_mfma_f32_16x16x32_bf16 v[14:17], v[180:183], v[204:207], v[14:17]
	v_mfma_f32_16x16x32_bf16 v[30:33], v[180:183], v[196:199], v[30:33]
	v_mfma_f32_16x16x32_bf16 v[46:49], v[180:183], v[188:191], v[46:49]
	v_mfma_f32_16x16x32_bf16 v[54:57], v[176:179], v[192:195], v[54:57]
	v_mfma_f32_16x16x32_bf16 v[38:41], v[176:179], v[200:203], v[38:41]
	v_mfma_f32_16x16x32_bf16 v[22:25], v[176:179], v[208:211], v[22:25]
	v_mfma_f32_16x16x32_bf16 v[6:9], v[176:179], v[218:221], v[6:9]
	v_mfma_f32_16x16x32_bf16 v[2:5], v[184:187], v[218:221], v[2:5]
	v_mfma_f32_16x16x32_bf16 v[14:17], v[184:187], v[208:211], v[14:17]
	v_mfma_f32_16x16x32_bf16 v[30:33], v[184:187], v[200:203], v[30:33]
	v_mfma_f32_16x16x32_bf16 v[46:49], v[184:187], v[192:195], v[46:49]
	s_setprio 0
	s_barrier
	s_add_i32 s53, 0, 0x18000
	v_add_u32_e32 v156, s53, v153
	s_add_i32 s66, 0, 0x1c000
	ds_read_b128 v[146:149], v156
	ds_read_b128 v[160:163], v156 offset:1024
	ds_read_b128 v[164:167], v156 offset:2048
	ds_read_b128 v[168:171], v156 offset:3072
	v_add_u32_e32 v156, s66, v153
	ds_read_b128 v[172:175], v156
	ds_read_b128 v[176:179], v156 offset:1024
	ds_read_b128 v[180:183], v156 offset:2048
	ds_read_b128 v[184:187], v156 offset:3072
	s_add_u32 s62, s76, 0x20000
	s_addc_u32 s63, s77, 0
	s_mov_b32 m0, s54
	v_lshl_add_u64 v[228:229], s[62:63], 0, v[130:131]
	ds_read_b128 v[188:191], v155 offset:32768
	ds_read_b128 v[192:195], v155 offset:33792
	ds_read_b128 v[196:199], v155 offset:34816
	ds_read_b128 v[200:203], v155 offset:35840
	ds_read_b128 v[204:207], v155 offset:36864
	ds_read_b128 v[208:211], v155 offset:37888
	ds_read_b128 v[212:215], v155 offset:38912
	ds_read_b128 v[218:221], v155 offset:39936
	global_load_lds_dwordx4 v[228:229], off
	v_lshl_add_u64 v[228:229], s[62:63], 0, v[134:135]
	s_mov_b32 m0, s55
	s_nop 0
	global_load_lds_dwordx4 v[228:229], off
	s_waitcnt vmcnt(8)
	s_waitcnt lgkmcnt(0)
	s_barrier
	s_setprio 1
	s_waitcnt lgkmcnt(0)
	v_mfma_f32_16x16x32_bf16 v[126:129], v[146:149], v[188:191], v[126:129]
	v_mfma_f32_16x16x32_bf16 v[110:113], v[146:149], v[196:199], v[110:113]
	v_mfma_f32_16x16x32_bf16 v[94:97], v[146:149], v[204:207], v[94:97]
	v_mfma_f32_16x16x32_bf16 v[78:81], v[146:149], v[212:215], v[78:81]
	v_mfma_f32_16x16x32_bf16 v[74:77], v[164:167], v[212:215], v[74:77]
	v_mfma_f32_16x16x32_bf16 v[90:93], v[164:167], v[204:207], v[90:93]
	v_mfma_f32_16x16x32_bf16 v[106:109], v[164:167], v[196:199], v[106:109]
	v_mfma_f32_16x16x32_bf16 v[122:125], v[164:167], v[188:191], v[122:125]
	v_mfma_f32_16x16x32_bf16 v[126:129], v[160:163], v[192:195], v[126:129]
	v_mfma_f32_16x16x32_bf16 v[110:113], v[160:163], v[200:203], v[110:113]
	v_mfma_f32_16x16x32_bf16 v[94:97], v[160:163], v[208:211], v[94:97]
	v_mfma_f32_16x16x32_bf16 v[78:81], v[160:163], v[218:221], v[78:81]
	v_mfma_f32_16x16x32_bf16 v[74:77], v[168:171], v[218:221], v[74:77]
	v_mfma_f32_16x16x32_bf16 v[90:93], v[168:171], v[208:211], v[90:93]
	v_mfma_f32_16x16x32_bf16 v[106:109], v[168:171], v[200:203], v[106:109]
	v_mfma_f32_16x16x32_bf16 v[122:125], v[168:171], v[192:195], v[122:125]
	s_setprio 0
	s_setprio 1
	v_mfma_f32_16x16x32_bf16 v[118:121], v[172:175], v[188:191], v[118:121]
	v_mfma_f32_16x16x32_bf16 v[102:105], v[172:175], v[196:199], v[102:105]
	v_mfma_f32_16x16x32_bf16 v[86:89], v[172:175], v[204:207], v[86:89]
	v_mfma_f32_16x16x32_bf16 v[70:73], v[172:175], v[212:215], v[70:73]
	v_mfma_f32_16x16x32_bf16 v[66:69], v[180:183], v[212:215], v[66:69]
	v_mfma_f32_16x16x32_bf16 v[82:85], v[180:183], v[204:207], v[82:85]
	v_mfma_f32_16x16x32_bf16 v[98:101], v[180:183], v[196:199], v[98:101]
	v_mfma_f32_16x16x32_bf16 v[114:117], v[180:183], v[188:191], v[114:117]
	v_mfma_f32_16x16x32_bf16 v[118:121], v[176:179], v[192:195], v[118:121]
	v_mfma_f32_16x16x32_bf16 v[102:105], v[176:179], v[200:203], v[102:105]
	v_mfma_f32_16x16x32_bf16 v[86:89], v[176:179], v[208:211], v[86:89]
	v_mfma_f32_16x16x32_bf16 v[70:73], v[176:179], v[218:221], v[70:73]
	v_mfma_f32_16x16x32_bf16 v[66:69], v[184:187], v[218:221], v[66:69]
	v_mfma_f32_16x16x32_bf16 v[82:85], v[184:187], v[208:211], v[82:85]
	v_mfma_f32_16x16x32_bf16 v[98:101], v[184:187], v[200:203], v[98:101]
	v_mfma_f32_16x16x32_bf16 v[114:117], v[184:187], v[192:195], v[114:117]
	s_setprio 0
	s_barrier
	s_add_i32 s53, s53, s13
	v_lshl_add_u64 v[150:151], v[150:151], 0, s[8:9]
	s_mov_b32 m0, s53
	ds_read_b128 v[188:191], v155 offset:49152
	ds_read_b128 v[192:195], v155 offset:50176
	ds_read_b128 v[196:199], v155 offset:51200
	ds_read_b128 v[200:203], v155 offset:52224
	ds_read_b128 v[204:207], v155 offset:53248
	ds_read_b128 v[208:211], v155 offset:54272
	ds_read_b128 v[212:215], v155 offset:55296
	ds_read_b128 v[218:221], v155 offset:56320
	global_load_lds_dwordx4 v[150:151], off
	s_add_i32 m0, s53, 0x2000
	s_add_u32 s34, s34, 0x20080
	v_lshl_add_u64 v[150:151], v[222:223], 0, s[8:9]
	s_addc_u32 s35, s35, 0
	s_add_i32 s53, s66, s13
	global_load_lds_dwordx4 v[150:151], off
	v_lshl_add_u64 v[150:151], s[34:35], 0, v[132:133]
	s_mov_b32 m0, s53
	s_nop 0
	global_load_lds_dwordx4 v[150:151], off
	v_lshl_add_u64 v[150:151], s[34:35], 0, v[136:137]
	s_add_i32 m0, s53, 0x2000
	s_nop 0
	global_load_lds_dwordx4 v[150:151], off
	v_lshl_add_u64 v[150:151], v[224:225], 0, s[8:9]
	s_mov_b32 m0, s57
	s_nop 0
	global_load_lds_dwordx4 v[150:151], off
	v_lshl_add_u64 v[150:151], v[226:227], 0, s[8:9]
	s_mov_b32 m0, s58
	s_nop 0
	global_load_lds_dwordx4 v[150:151], off
	s_waitcnt vmcnt(8)
	s_waitcnt lgkmcnt(0)
	s_barrier
	s_setprio 1
	s_waitcnt lgkmcnt(0)
	v_mfma_f32_16x16x32_bf16 v[62:65], v[146:149], v[188:191], v[62:65]
	v_mfma_f32_16x16x32_bf16 v[50:53], v[146:149], v[196:199], v[50:53]
	v_mfma_f32_16x16x32_bf16 v[34:37], v[146:149], v[204:207], v[34:37]
	v_mfma_f32_16x16x32_bf16 v[18:21], v[146:149], v[212:215], v[18:21]
	v_mfma_f32_16x16x32_bf16 v[10:13], v[164:167], v[212:215], v[10:13]
	v_mfma_f32_16x16x32_bf16 v[26:29], v[164:167], v[204:207], v[26:29]
	v_mfma_f32_16x16x32_bf16 v[42:45], v[164:167], v[196:199], v[42:45]
	v_mfma_f32_16x16x32_bf16 v[58:61], v[164:167], v[188:191], v[58:61]
	v_mfma_f32_16x16x32_bf16 v[62:65], v[160:163], v[192:195], v[62:65]
	v_mfma_f32_16x16x32_bf16 v[50:53], v[160:163], v[200:203], v[50:53]
	v_mfma_f32_16x16x32_bf16 v[34:37], v[160:163], v[208:211], v[34:37]
	v_mfma_f32_16x16x32_bf16 v[18:21], v[160:163], v[218:221], v[18:21]
	v_mfma_f32_16x16x32_bf16 v[10:13], v[168:171], v[218:221], v[10:13]
	v_mfma_f32_16x16x32_bf16 v[26:29], v[168:171], v[208:211], v[26:29]
	v_mfma_f32_16x16x32_bf16 v[42:45], v[168:171], v[200:203], v[42:45]
	v_mfma_f32_16x16x32_bf16 v[58:61], v[168:171], v[192:195], v[58:61]
	s_setprio 0
	s_setprio 1
	v_mfma_f32_16x16x32_bf16 v[54:57], v[172:175], v[188:191], v[54:57]
	v_mfma_f32_16x16x32_bf16 v[38:41], v[172:175], v[196:199], v[38:41]
	v_mfma_f32_16x16x32_bf16 v[22:25], v[172:175], v[204:207], v[22:25]
	v_mfma_f32_16x16x32_bf16 v[6:9], v[172:175], v[212:215], v[6:9]
	v_mfma_f32_16x16x32_bf16 v[2:5], v[180:183], v[212:215], v[2:5]
	v_mfma_f32_16x16x32_bf16 v[14:17], v[180:183], v[204:207], v[14:17]
	v_mfma_f32_16x16x32_bf16 v[30:33], v[180:183], v[196:199], v[30:33]
	v_mfma_f32_16x16x32_bf16 v[46:49], v[180:183], v[188:191], v[46:49]
	v_mfma_f32_16x16x32_bf16 v[54:57], v[176:179], v[192:195], v[54:57]
	v_mfma_f32_16x16x32_bf16 v[38:41], v[176:179], v[200:203], v[38:41]
	v_mfma_f32_16x16x32_bf16 v[22:25], v[176:179], v[208:211], v[22:25]
	v_mfma_f32_16x16x32_bf16 v[6:9], v[176:179], v[218:221], v[6:9]
	v_mfma_f32_16x16x32_bf16 v[2:5], v[184:187], v[218:221], v[2:5]
	v_mfma_f32_16x16x32_bf16 v[14:17], v[184:187], v[208:211], v[14:17]
	v_mfma_f32_16x16x32_bf16 v[30:33], v[184:187], v[200:203], v[30:33]
	v_mfma_f32_16x16x32_bf16 v[46:49], v[184:187], v[192:195], v[46:49]
	s_setprio 0
	s_barrier
	s_add_i32 s72, s72, 2
	s_add_u32 s74, s74, 0x100
	s_addc_u32 s75, s75, 0
	s_add_u32 s52, s52, 0x100
	s_addc_u32 s71, s71, 0
	s_cmp_gt_u32 s72, 5
	s_cbranch_scc0 .LBB0_2659
	s_and_b64 vcc, exec, s[24:25]
	s_cbranch_vccz .LBB0_2662
	s_barrier

.LBB0_2938:
	ds_read_b128 v[130:133], v174
	ds_read_b128 v[134:137], v174 offset:1024
	ds_read_b128 v[138:141], v174 offset:2048
	ds_read_b128 v[158:161], v174 offset:3072
	ds_read_b128 v[162:165], v175
	ds_read_b128 v[166:169], v175 offset:1024
	ds_read_b128 v[178:181], v175 offset:2048
	ds_read_b128 v[182:185], v175 offset:3072
	s_add_u32 s34, s46, 0xfff80080
	s_addc_u32 s35, s47, -1
	s_cmp_eq_u32 s72, 28
	s_cselect_b32 s69, s0, s35
	s_cselect_b32 s68, s1, s34
	s_cselect_b32 s35, s37, s71
	s_cselect_b32 s34, s39, s70
	v_lshl_add_u64 v[170:171], s[46:47], 0, v[150:151]
	s_add_i32 m0, s33, 0xc000
	ds_read_b128 v[186:189], v176
	ds_read_b128 v[190:193], v176 offset:1024
	ds_read_b128 v[194:197], v176 offset:2048
	ds_read_b128 v[198:201], v176 offset:3072
	ds_read_b128 v[202:205], v176 offset:4096
	ds_read_b128 v[206:209], v176 offset:5120
	ds_read_b128 v[210:213], v176 offset:6144
	ds_read_b128 v[218:221], v176 offset:7168
	global_load_lds_dwordx4 v[170:171], off
	v_lshl_add_u64 v[170:171], s[46:47], 0, v[152:153]
	s_add_i32 m0, s33, 0xe000
	s_nop 0
	global_load_lds_dwordx4 v[170:171], off
	s_waitcnt vmcnt(8)
	s_waitcnt lgkmcnt(0)
	s_barrier
	s_setprio 1
	s_waitcnt lgkmcnt(0)
	v_mfma_f32_16x16x32_bf16 v[126:129], v[130:133], v[186:189], v[126:129]
	v_mfma_f32_16x16x32_bf16 v[110:113], v[130:133], v[194:197], v[110:113]
	v_mfma_f32_16x16x32_bf16 v[94:97], v[130:133], v[202:205], v[94:97]
	v_mfma_f32_16x16x32_bf16 v[78:81], v[130:133], v[210:213], v[78:81]
	v_mfma_f32_16x16x32_bf16 v[74:77], v[138:141], v[210:213], v[74:77]
	v_mfma_f32_16x16x32_bf16 v[90:93], v[138:141], v[202:205], v[90:93]
	v_mfma_f32_16x16x32_bf16 v[106:109], v[138:141], v[194:197], v[106:109]
	v_mfma_f32_16x16x32_bf16 v[122:125], v[138:141], v[186:189], v[122:125]
	v_mfma_f32_16x16x32_bf16 v[126:129], v[134:137], v[190:193], v[126:129]
	v_mfma_f32_16x16x32_bf16 v[110:113], v[134:137], v[198:201], v[110:113]
	v_mfma_f32_16x16x32_bf16 v[94:97], v[134:137], v[206:209], v[94:97]
	v_mfma_f32_16x16x32_bf16 v[78:81], v[134:137], v[218:221], v[78:81]
	v_mfma_f32_16x16x32_bf16 v[74:77], v[158:161], v[218:221], v[74:77]
	v_mfma_f32_16x16x32_bf16 v[90:93], v[158:161], v[206:209], v[90:93]
	v_mfma_f32_16x16x32_bf16 v[106:109], v[158:161], v[198:201], v[106:109]
	v_mfma_f32_16x16x32_bf16 v[122:125], v[158:161], v[190:193], v[122:125]
	s_setprio 0
	s_setprio 1
	v_mfma_f32_16x16x32_bf16 v[118:121], v[162:165], v[186:189], v[118:121]
	v_mfma_f32_16x16x32_bf16 v[102:105], v[162:165], v[194:197], v[102:105]
	v_mfma_f32_16x16x32_bf16 v[86:89], v[162:165], v[202:205], v[86:89]
	v_mfma_f32_16x16x32_bf16 v[70:73], v[162:165], v[210:213], v[70:73]
	v_mfma_f32_16x16x32_bf16 v[66:69], v[178:181], v[210:213], v[66:69]
	v_mfma_f32_16x16x32_bf16 v[82:85], v[178:181], v[202:205], v[82:85]
	v_mfma_f32_16x16x32_bf16 v[98:101], v[178:181], v[194:197], v[98:101]
	v_mfma_f32_16x16x32_bf16 v[114:117], v[178:181], v[186:189], v[114:117]
	v_mfma_f32_16x16x32_bf16 v[118:121], v[166:169], v[190:193], v[118:121]
	v_mfma_f32_16x16x32_bf16 v[102:105], v[166:169], v[198:201], v[102:105]
	v_mfma_f32_16x16x32_bf16 v[86:89], v[166:169], v[206:209], v[86:89]
	v_mfma_f32_16x16x32_bf16 v[70:73], v[166:169], v[218:221], v[70:73]
	v_mfma_f32_16x16x32_bf16 v[66:69], v[182:185], v[218:221], v[66:69]
	v_mfma_f32_16x16x32_bf16 v[82:85], v[182:185], v[206:209], v[82:85]
	v_mfma_f32_16x16x32_bf16 v[98:101], v[182:185], v[198:201], v[98:101]
	v_mfma_f32_16x16x32_bf16 v[114:117], v[182:185], v[190:193], v[114:117]
	s_setprio 0
	s_barrier
	s_add_i32 s62, s58, s31
	v_lshl_add_u64 v[170:171], s[34:35], 0, v[144:145]
	s_mov_b32 m0, s62
	ds_read_b128 v[186:189], v176 offset:16384
	ds_read_b128 v[190:193], v176 offset:17408
	ds_read_b128 v[194:197], v176 offset:18432
	ds_read_b128 v[198:201], v176 offset:19456
	ds_read_b128 v[202:205], v176 offset:20480
	ds_read_b128 v[206:209], v176 offset:21504
	ds_read_b128 v[210:213], v176 offset:22528
	ds_read_b128 v[218:221], v176 offset:23552
	global_load_lds_dwordx4 v[170:171], off
	s_add_i32 m0, s62, 0x2000
	s_add_u32 s62, s34, 0x80000
	v_lshl_add_u64 v[214:215], s[34:35], 0, v[148:149]
	s_addc_u32 s63, s35, 0
	s_add_i32 s66, s59, s31
	global_load_lds_dwordx4 v[214:215], off
	v_lshl_add_u64 v[222:223], s[62:63], 0, v[144:145]
	s_mov_b32 m0, s66
	v_lshl_add_u64 v[224:225], s[68:69], 0, v[146:147]
	global_load_lds_dwordx4 v[222:223], off
	v_lshl_add_u64 v[222:223], s[62:63], 0, v[148:149]
	s_add_i32 m0, s66, 0x2000
	s_nop 0
	global_load_lds_dwordx4 v[222:223], off
	v_lshl_add_u64 v[222:223], s[68:69], 0, v[142:143]
	s_mov_b32 m0, s33
	s_nop 0
	global_load_lds_dwordx4 v[222:223], off
	s_mov_b32 m0, s45
	s_nop 0
	global_load_lds_dwordx4 v[224:225], off
	s_waitcnt vmcnt(8)
	s_waitcnt lgkmcnt(0)
	s_barrier
	s_setprio 1
	s_waitcnt lgkmcnt(0)
	v_mfma_f32_16x16x32_bf16 v[62:65], v[130:133], v[186:189], v[62:65]
	v_mfma_f32_16x16x32_bf16 v[50:53], v[130:133], v[194:197], v[50:53]
	v_mfma_f32_16x16x32_bf16 v[38:41], v[130:133], v[202:205], v[38:41]
	v_mfma_f32_16x16x32_bf16 v[14:17], v[130:133], v[210:213], v[14:17]
	v_mfma_f32_16x16x32_bf16 v[10:13], v[138:141], v[210:213], v[10:13]
	v_mfma_f32_16x16x32_bf16 v[34:37], v[138:141], v[202:205], v[34:37]
	v_mfma_f32_16x16x32_bf16 v[42:45], v[138:141], v[194:197], v[42:45]
	v_mfma_f32_16x16x32_bf16 v[58:61], v[138:141], v[186:189], v[58:61]
	v_mfma_f32_16x16x32_bf16 v[62:65], v[134:137], v[190:193], v[62:65]
	v_mfma_f32_16x16x32_bf16 v[50:53], v[134:137], v[198:201], v[50:53]
	v_mfma_f32_16x16x32_bf16 v[38:41], v[134:137], v[206:209], v[38:41]
	v_mfma_f32_16x16x32_bf16 v[14:17], v[134:137], v[218:221], v[14:17]
	v_mfma_f32_16x16x32_bf16 v[10:13], v[158:161], v[218:221], v[10:13]
	v_mfma_f32_16x16x32_bf16 v[34:37], v[158:161], v[206:209], v[34:37]
	v_mfma_f32_16x16x32_bf16 v[42:45], v[158:161], v[198:201], v[42:45]
	v_mfma_f32_16x16x32_bf16 v[58:61], v[158:161], v[190:193], v[58:61]
	s_setprio 0
	s_setprio 1
	v_mfma_f32_16x16x32_bf16 v[54:57], v[162:165], v[186:189], v[54:57]
	v_mfma_f32_16x16x32_bf16 v[30:33], v[162:165], v[194:197], v[30:33]
	v_mfma_f32_16x16x32_bf16 v[22:25], v[162:165], v[202:205], v[22:25]
	v_mfma_f32_16x16x32_bf16 v[6:9], v[162:165], v[210:213], v[6:9]
	v_mfma_f32_16x16x32_bf16 v[2:5], v[178:181], v[210:213], v[2:5]
	v_mfma_f32_16x16x32_bf16 v[18:21], v[178:181], v[202:205], v[18:21]
	v_mfma_f32_16x16x32_bf16 v[26:29], v[178:181], v[194:197], v[26:29]
	v_mfma_f32_16x16x32_bf16 v[46:49], v[178:181], v[186:189], v[46:49]
	v_mfma_f32_16x16x32_bf16 v[54:57], v[166:169], v[190:193], v[54:57]
	v_mfma_f32_16x16x32_bf16 v[30:33], v[166:169], v[198:201], v[30:33]
	v_mfma_f32_16x16x32_bf16 v[22:25], v[166:169], v[206:209], v[22:25]
	v_mfma_f32_16x16x32_bf16 v[6:9], v[166:169], v[218:221], v[6:9]
	v_mfma_f32_16x16x32_bf16 v[2:5], v[182:185], v[218:221], v[2:5]
	v_mfma_f32_16x16x32_bf16 v[18:21], v[182:185], v[206:209], v[18:21]
	v_mfma_f32_16x16x32_bf16 v[26:29], v[182:185], v[198:201], v[26:29]
	v_mfma_f32_16x16x32_bf16 v[46:49], v[182:185], v[190:193], v[46:49]
	s_setprio 0
	s_barrier
	s_add_i32 s66, 0, 0x18000
	s_add_i32 s67, 0, 0x1c000
	v_add_u32_e32 v158, s66, v172
	v_add_u32_e32 v177, s67, v172
	ds_read_b128 v[130:133], v158
	ds_read_b128 v[134:137], v158 offset:1024
	ds_read_b128 v[138:141], v158 offset:2048
	ds_read_b128 v[158:161], v158 offset:3072
	ds_read_b128 v[162:165], v177
	ds_read_b128 v[166:169], v177 offset:1024
	ds_read_b128 v[178:181], v177 offset:2048
	ds_read_b128 v[182:185], v177 offset:3072
	s_add_u32 s62, s68, 0x80000
	s_addc_u32 s63, s69, 0
	s_mov_b32 m0, s52
	v_lshl_add_u64 v[226:227], s[62:63], 0, v[142:143]
	ds_read_b128 v[186:189], v176 offset:32768
	ds_read_b128 v[190:193], v176 offset:33792
	ds_read_b128 v[194:197], v176 offset:34816
	ds_read_b128 v[198:201], v176 offset:35840
	ds_read_b128 v[202:205], v176 offset:36864
	ds_read_b128 v[206:209], v176 offset:37888
	ds_read_b128 v[210:213], v176 offset:38912
	ds_read_b128 v[218:221], v176 offset:39936
	global_load_lds_dwordx4 v[226:227], off
	v_lshl_add_u64 v[226:227], s[62:63], 0, v[146:147]
	s_mov_b32 m0, s53
	s_nop 0
	global_load_lds_dwordx4 v[226:227], off
	s_waitcnt vmcnt(8)
	s_waitcnt lgkmcnt(0)
	s_barrier
	s_setprio 1
	s_waitcnt lgkmcnt(0)
	v_mfma_f32_16x16x32_bf16 v[126:129], v[130:133], v[186:189], v[126:129]
	v_mfma_f32_16x16x32_bf16 v[110:113], v[130:133], v[194:197], v[110:113]
	v_mfma_f32_16x16x32_bf16 v[94:97], v[130:133], v[202:205], v[94:97]
	v_mfma_f32_16x16x32_bf16 v[78:81], v[130:133], v[210:213], v[78:81]
	v_mfma_f32_16x16x32_bf16 v[74:77], v[138:141], v[210:213], v[74:77]
	v_mfma_f32_16x16x32_bf16 v[90:93], v[138:141], v[202:205], v[90:93]
	v_mfma_f32_16x16x32_bf16 v[106:109], v[138:141], v[194:197], v[106:109]
	v_mfma_f32_16x16x32_bf16 v[122:125], v[138:141], v[186:189], v[122:125]
	v_mfma_f32_16x16x32_bf16 v[126:129], v[134:137], v[190:193], v[126:129]
	v_mfma_f32_16x16x32_bf16 v[110:113], v[134:137], v[198:201], v[110:113]
	v_mfma_f32_16x16x32_bf16 v[94:97], v[134:137], v[206:209], v[94:97]
	v_mfma_f32_16x16x32_bf16 v[78:81], v[134:137], v[218:221], v[78:81]
	v_mfma_f32_16x16x32_bf16 v[74:77], v[158:161], v[218:221], v[74:77]
	v_mfma_f32_16x16x32_bf16 v[90:93], v[158:161], v[206:209], v[90:93]
	v_mfma_f32_16x16x32_bf16 v[106:109], v[158:161], v[198:201], v[106:109]
	v_mfma_f32_16x16x32_bf16 v[122:125], v[158:161], v[190:193], v[122:125]
	s_setprio 0
	s_setprio 1
	v_mfma_f32_16x16x32_bf16 v[118:121], v[162:165], v[186:189], v[118:121]
	v_mfma_f32_16x16x32_bf16 v[102:105], v[162:165], v[194:197], v[102:105]
	v_mfma_f32_16x16x32_bf16 v[86:89], v[162:165], v[202:205], v[86:89]
	v_mfma_f32_16x16x32_bf16 v[70:73], v[162:165], v[210:213], v[70:73]
	v_mfma_f32_16x16x32_bf16 v[66:69], v[178:181], v[210:213], v[66:69]
	v_mfma_f32_16x16x32_bf16 v[82:85], v[178:181], v[202:205], v[82:85]
	v_mfma_f32_16x16x32_bf16 v[98:101], v[178:181], v[194:197], v[98:101]
	v_mfma_f32_16x16x32_bf16 v[114:117], v[178:181], v[186:189], v[114:117]
	v_mfma_f32_16x16x32_bf16 v[118:121], v[166:169], v[190:193], v[118:121]
	v_mfma_f32_16x16x32_bf16 v[102:105], v[166:169], v[198:201], v[102:105]
	v_mfma_f32_16x16x32_bf16 v[86:89], v[166:169], v[206:209], v[86:89]
	v_mfma_f32_16x16x32_bf16 v[70:73], v[166:169], v[218:221], v[70:73]
	v_mfma_f32_16x16x32_bf16 v[66:69], v[182:185], v[218:221], v[66:69]
	v_mfma_f32_16x16x32_bf16 v[82:85], v[182:185], v[206:209], v[82:85]
	v_mfma_f32_16x16x32_bf16 v[98:101], v[182:185], v[198:201], v[98:101]
	v_mfma_f32_16x16x32_bf16 v[114:117], v[182:185], v[190:193], v[114:117]
	s_setprio 0
	s_barrier
	s_add_i32 s62, s66, s31
	v_lshl_add_u64 v[170:171], v[170:171], 0, s[24:25]
	s_mov_b32 m0, s62
	ds_read_b128 v[186:189], v176 offset:49152
	ds_read_b128 v[190:193], v176 offset:50176
	ds_read_b128 v[194:197], v176 offset:51200
	ds_read_b128 v[198:201], v176 offset:52224
	ds_read_b128 v[202:205], v176 offset:53248
	ds_read_b128 v[206:209], v176 offset:54272
	ds_read_b128 v[210:213], v176 offset:55296
	ds_read_b128 v[218:221], v176 offset:56320
	global_load_lds_dwordx4 v[170:171], off
	s_add_i32 m0, s62, 0x2000
	s_add_u32 s34, s34, 0x80080
	v_lshl_add_u64 v[170:171], v[214:215], 0, s[24:25]
	s_addc_u32 s35, s35, 0
	s_add_i32 s62, s67, s31
	global_load_lds_dwordx4 v[170:171], off
	v_lshl_add_u64 v[170:171], s[34:35], 0, v[144:145]
	s_mov_b32 m0, s62
	s_nop 0
	global_load_lds_dwordx4 v[170:171], off
	v_lshl_add_u64 v[170:171], s[34:35], 0, v[148:149]
	s_add_i32 m0, s62, 0x2000
	s_nop 0
	global_load_lds_dwordx4 v[170:171], off
	v_lshl_add_u64 v[170:171], v[222:223], 0, s[24:25]
	s_mov_b32 m0, s55
	s_nop 0
	global_load_lds_dwordx4 v[170:171], off
	v_lshl_add_u64 v[170:171], v[224:225], 0, s[24:25]
	s_mov_b32 m0, s56
	s_nop 0
	global_load_lds_dwordx4 v[170:171], off
	s_waitcnt vmcnt(8)
	s_waitcnt lgkmcnt(0)
	s_barrier
	s_setprio 1
	s_waitcnt lgkmcnt(0)
	v_mfma_f32_16x16x32_bf16 v[62:65], v[130:133], v[186:189], v[62:65]
	v_mfma_f32_16x16x32_bf16 v[50:53], v[130:133], v[194:197], v[50:53]
	v_mfma_f32_16x16x32_bf16 v[38:41], v[130:133], v[202:205], v[38:41]
	v_mfma_f32_16x16x32_bf16 v[14:17], v[130:133], v[210:213], v[14:17]
	v_mfma_f32_16x16x32_bf16 v[10:13], v[138:141], v[210:213], v[10:13]
	v_mfma_f32_16x16x32_bf16 v[34:37], v[138:141], v[202:205], v[34:37]
	v_mfma_f32_16x16x32_bf16 v[42:45], v[138:141], v[194:197], v[42:45]
	v_mfma_f32_16x16x32_bf16 v[58:61], v[138:141], v[186:189], v[58:61]
	v_mfma_f32_16x16x32_bf16 v[62:65], v[134:137], v[190:193], v[62:65]
	v_mfma_f32_16x16x32_bf16 v[50:53], v[134:137], v[198:201], v[50:53]
	v_mfma_f32_16x16x32_bf16 v[38:41], v[134:137], v[206:209], v[38:41]
	v_mfma_f32_16x16x32_bf16 v[14:17], v[134:137], v[218:221], v[14:17]
	v_mfma_f32_16x16x32_bf16 v[10:13], v[158:161], v[218:221], v[10:13]
	v_mfma_f32_16x16x32_bf16 v[34:37], v[158:161], v[206:209], v[34:37]
	v_mfma_f32_16x16x32_bf16 v[42:45], v[158:161], v[198:201], v[42:45]
	v_mfma_f32_16x16x32_bf16 v[58:61], v[158:161], v[190:193], v[58:61]
	s_setprio 0
	s_setprio 1
	v_mfma_f32_16x16x32_bf16 v[54:57], v[162:165], v[186:189], v[54:57]
	v_mfma_f32_16x16x32_bf16 v[30:33], v[162:165], v[194:197], v[30:33]
	v_mfma_f32_16x16x32_bf16 v[22:25], v[162:165], v[202:205], v[22:25]
	v_mfma_f32_16x16x32_bf16 v[6:9], v[162:165], v[210:213], v[6:9]
	v_mfma_f32_16x16x32_bf16 v[2:5], v[178:181], v[210:213], v[2:5]
	v_mfma_f32_16x16x32_bf16 v[18:21], v[178:181], v[202:205], v[18:21]
	v_mfma_f32_16x16x32_bf16 v[26:29], v[178:181], v[194:197], v[26:29]
	v_mfma_f32_16x16x32_bf16 v[46:49], v[178:181], v[186:189], v[46:49]
	v_mfma_f32_16x16x32_bf16 v[54:57], v[166:169], v[190:193], v[54:57]
	v_mfma_f32_16x16x32_bf16 v[30:33], v[166:169], v[198:201], v[30:33]
	v_mfma_f32_16x16x32_bf16 v[22:25], v[166:169], v[206:209], v[22:25]
	v_mfma_f32_16x16x32_bf16 v[6:9], v[166:169], v[218:221], v[6:9]
	v_mfma_f32_16x16x32_bf16 v[2:5], v[182:185], v[218:221], v[2:5]
	v_mfma_f32_16x16x32_bf16 v[18:21], v[182:185], v[206:209], v[18:21]
	v_mfma_f32_16x16x32_bf16 v[26:29], v[182:185], v[198:201], v[26:29]
	v_mfma_f32_16x16x32_bf16 v[46:49], v[182:185], v[190:193], v[46:49]
	s_setprio 0
	s_barrier
	s_add_i32 s72, s72, 2
	s_add_u32 s46, s46, 0x100
	s_addc_u32 s47, s47, 0
	s_add_u32 s70, s70, 0x100
	s_addc_u32 s71, s71, 0
	s_cmp_gt_u32 s72, 29
	s_cbranch_scc0 .LBB0_2938
	s_and_b64 vcc, exec, s[26:27]
	s_cbranch_vccz .LBB0_2941
	s_barrier

.LBB0_3067:
	ds_read_b128 v[146:149], v153
	ds_read_b128 v[156:159], v153 offset:1024
	ds_read_b128 v[160:163], v153 offset:2048
	ds_read_b128 v[164:167], v153 offset:3072
	ds_read_b128 v[168:171], v154
	ds_read_b128 v[172:175], v154 offset:1024
	ds_read_b128 v[176:179], v154 offset:2048
	ds_read_b128 v[180:183], v154 offset:3072
	s_add_u32 s34, s44, 0xfff80080
	s_addc_u32 s35, s45, -1
	s_cmp_eq_u32 s71, 28
	s_cselect_b32 s47, s0, s35
	s_cselect_b32 s46, s1, s34
	s_cselect_b32 s35, s27, s70
	s_cselect_b32 s34, s37, s69
	v_lshl_add_u64 v[218:219], s[44:45], 0, v[138:139]
	s_add_i32 m0, s43, 0xc000
	ds_read_b128 v[184:187], v155
	ds_read_b128 v[188:191], v155 offset:1024
	ds_read_b128 v[192:195], v155 offset:2048
	ds_read_b128 v[196:199], v155 offset:3072
	ds_read_b128 v[200:203], v155 offset:4096
	ds_read_b128 v[204:207], v155 offset:5120
	ds_read_b128 v[208:211], v155 offset:6144
	ds_read_b128 v[212:215], v155 offset:7168
	global_load_lds_dwordx4 v[218:219], off
	v_lshl_add_u64 v[218:219], s[44:45], 0, v[140:141]
	s_add_i32 m0, s43, 0xe000
	s_nop 0
	global_load_lds_dwordx4 v[218:219], off
	s_waitcnt vmcnt(8)
	s_waitcnt lgkmcnt(0)
	s_barrier
	s_setprio 1
	s_waitcnt lgkmcnt(0)
	v_mfma_f32_16x16x32_bf16 v[126:129], v[146:149], v[184:187], v[126:129]
	v_mfma_f32_16x16x32_bf16 v[110:113], v[146:149], v[192:195], v[110:113]
	v_mfma_f32_16x16x32_bf16 v[94:97], v[146:149], v[200:203], v[94:97]
	v_mfma_f32_16x16x32_bf16 v[78:81], v[146:149], v[208:211], v[78:81]
	v_mfma_f32_16x16x32_bf16 v[70:73], v[160:163], v[208:211], v[70:73]
	v_mfma_f32_16x16x32_bf16 v[86:89], v[160:163], v[200:203], v[86:89]
	v_mfma_f32_16x16x32_bf16 v[102:105], v[160:163], v[192:195], v[102:105]
	v_mfma_f32_16x16x32_bf16 v[118:121], v[160:163], v[184:187], v[118:121]
	v_mfma_f32_16x16x32_bf16 v[126:129], v[156:159], v[188:191], v[126:129]
	v_mfma_f32_16x16x32_bf16 v[110:113], v[156:159], v[196:199], v[110:113]
	v_mfma_f32_16x16x32_bf16 v[94:97], v[156:159], v[204:207], v[94:97]
	v_mfma_f32_16x16x32_bf16 v[78:81], v[156:159], v[212:215], v[78:81]
	v_mfma_f32_16x16x32_bf16 v[70:73], v[164:167], v[212:215], v[70:73]
	v_mfma_f32_16x16x32_bf16 v[86:89], v[164:167], v[204:207], v[86:89]
	v_mfma_f32_16x16x32_bf16 v[102:105], v[164:167], v[196:199], v[102:105]
	v_mfma_f32_16x16x32_bf16 v[118:121], v[164:167], v[188:191], v[118:121]
	s_setprio 0
	s_setprio 1
	v_mfma_f32_16x16x32_bf16 v[122:125], v[168:171], v[184:187], v[122:125]
	v_mfma_f32_16x16x32_bf16 v[106:109], v[168:171], v[192:195], v[106:109]
	v_mfma_f32_16x16x32_bf16 v[90:93], v[168:171], v[200:203], v[90:93]
	v_mfma_f32_16x16x32_bf16 v[74:77], v[168:171], v[208:211], v[74:77]
	v_mfma_f32_16x16x32_bf16 v[66:69], v[176:179], v[208:211], v[66:69]
	v_mfma_f32_16x16x32_bf16 v[82:85], v[176:179], v[200:203], v[82:85]
	v_mfma_f32_16x16x32_bf16 v[98:101], v[176:179], v[192:195], v[98:101]
	v_mfma_f32_16x16x32_bf16 v[114:117], v[176:179], v[184:187], v[114:117]
	v_mfma_f32_16x16x32_bf16 v[122:125], v[172:175], v[188:191], v[122:125]
	v_mfma_f32_16x16x32_bf16 v[106:109], v[172:175], v[196:199], v[106:109]
	v_mfma_f32_16x16x32_bf16 v[90:93], v[172:175], v[204:207], v[90:93]
	v_mfma_f32_16x16x32_bf16 v[74:77], v[172:175], v[212:215], v[74:77]
	v_mfma_f32_16x16x32_bf16 v[66:69], v[180:183], v[212:215], v[66:69]
	v_mfma_f32_16x16x32_bf16 v[82:85], v[180:183], v[204:207], v[82:85]
	v_mfma_f32_16x16x32_bf16 v[98:101], v[180:183], v[196:199], v[98:101]
	v_mfma_f32_16x16x32_bf16 v[114:117], v[180:183], v[188:191], v[114:117]
	s_setprio 0
	s_barrier
	s_add_i32 s62, s59, s30
	v_lshl_add_u64 v[218:219], s[34:35], 0, v[134:135]
	s_mov_b32 m0, s62
	ds_read_b128 v[184:187], v155 offset:16384
	ds_read_b128 v[188:191], v155 offset:17408
	ds_read_b128 v[192:195], v155 offset:18432
	ds_read_b128 v[196:199], v155 offset:19456
	ds_read_b128 v[200:203], v155 offset:20480
	ds_read_b128 v[204:207], v155 offset:21504
	ds_read_b128 v[208:211], v155 offset:22528
	ds_read_b128 v[212:215], v155 offset:23552
	global_load_lds_dwordx4 v[218:219], off
	s_add_i32 m0, s62, 0x2000
	s_add_u32 s62, s34, 0x80000
	v_lshl_add_u64 v[220:221], s[34:35], 0, v[130:131]
	s_addc_u32 s63, s35, 0
	s_add_i32 s66, s60, s30
	global_load_lds_dwordx4 v[220:221], off
	v_lshl_add_u64 v[222:223], s[62:63], 0, v[134:135]
	s_mov_b32 m0, s66
	v_lshl_add_u64 v[224:225], s[46:47], 0, v[132:133]
	global_load_lds_dwordx4 v[222:223], off
	v_lshl_add_u64 v[222:223], s[62:63], 0, v[130:131]
	s_add_i32 m0, s66, 0x2000
	s_nop 0
	global_load_lds_dwordx4 v[222:223], off
	v_lshl_add_u64 v[222:223], s[46:47], 0, v[136:137]
	s_mov_b32 m0, s43
	s_nop 0
	global_load_lds_dwordx4 v[222:223], off
	s_mov_b32 m0, s52
	s_nop 0
	global_load_lds_dwordx4 v[224:225], off
	s_waitcnt vmcnt(8)
	s_waitcnt lgkmcnt(0)
	s_barrier
	s_setprio 1
	s_waitcnt lgkmcnt(0)
	v_mfma_f32_16x16x32_bf16 v[62:65], v[146:149], v[184:187], v[62:65]
	v_mfma_f32_16x16x32_bf16 v[46:49], v[146:149], v[192:195], v[46:49]
	v_mfma_f32_16x16x32_bf16 v[30:33], v[146:149], v[200:203], v[30:33]
	v_mfma_f32_16x16x32_bf16 v[14:17], v[146:149], v[208:211], v[14:17]
	v_mfma_f32_16x16x32_bf16 v[6:9], v[160:163], v[208:211], v[6:9]
	v_mfma_f32_16x16x32_bf16 v[22:25], v[160:163], v[200:203], v[22:25]
	v_mfma_f32_16x16x32_bf16 v[38:41], v[160:163], v[192:195], v[38:41]
	v_mfma_f32_16x16x32_bf16 v[54:57], v[160:163], v[184:187], v[54:57]
	v_mfma_f32_16x16x32_bf16 v[62:65], v[156:159], v[188:191], v[62:65]
	v_mfma_f32_16x16x32_bf16 v[46:49], v[156:159], v[196:199], v[46:49]
	v_mfma_f32_16x16x32_bf16 v[30:33], v[156:159], v[204:207], v[30:33]
	v_mfma_f32_16x16x32_bf16 v[14:17], v[156:159], v[212:215], v[14:17]
	v_mfma_f32_16x16x32_bf16 v[6:9], v[164:167], v[212:215], v[6:9]
	v_mfma_f32_16x16x32_bf16 v[22:25], v[164:167], v[204:207], v[22:25]
	v_mfma_f32_16x16x32_bf16 v[38:41], v[164:167], v[196:199], v[38:41]
	v_mfma_f32_16x16x32_bf16 v[54:57], v[164:167], v[188:191], v[54:57]
	s_setprio 0
	s_setprio 1
	v_mfma_f32_16x16x32_bf16 v[58:61], v[168:171], v[184:187], v[58:61]
	v_mfma_f32_16x16x32_bf16 v[42:45], v[168:171], v[192:195], v[42:45]
	v_mfma_f32_16x16x32_bf16 v[26:29], v[168:171], v[200:203], v[26:29]
	v_mfma_f32_16x16x32_bf16 v[10:13], v[168:171], v[208:211], v[10:13]
	v_mfma_f32_16x16x32_bf16 v[2:5], v[176:179], v[208:211], v[2:5]
	v_mfma_f32_16x16x32_bf16 v[18:21], v[176:179], v[200:203], v[18:21]
	v_mfma_f32_16x16x32_bf16 v[34:37], v[176:179], v[192:195], v[34:37]
	v_mfma_f32_16x16x32_bf16 v[50:53], v[176:179], v[184:187], v[50:53]
	v_mfma_f32_16x16x32_bf16 v[58:61], v[172:175], v[188:191], v[58:61]
	v_mfma_f32_16x16x32_bf16 v[42:45], v[172:175], v[196:199], v[42:45]
	v_mfma_f32_16x16x32_bf16 v[26:29], v[172:175], v[204:207], v[26:29]
	v_mfma_f32_16x16x32_bf16 v[10:13], v[172:175], v[212:215], v[10:13]
	v_mfma_f32_16x16x32_bf16 v[2:5], v[180:183], v[212:215], v[2:5]
	v_mfma_f32_16x16x32_bf16 v[18:21], v[180:183], v[204:207], v[18:21]
	v_mfma_f32_16x16x32_bf16 v[34:37], v[180:183], v[196:199], v[34:37]
	v_mfma_f32_16x16x32_bf16 v[50:53], v[180:183], v[188:191], v[50:53]
	s_setprio 0
	s_barrier
	s_add_i32 s62, 0, 0x18000
	s_add_i32 s63, 0, 0x1c000
	v_add_u32_e32 v164, s62, v151
	v_add_u32_e32 v180, s63, v151
	ds_read_b128 v[146:149], v164
	ds_read_b128 v[156:159], v164 offset:1024
	ds_read_b128 v[160:163], v164 offset:2048
	ds_read_b128 v[164:167], v164 offset:3072
	ds_read_b128 v[168:171], v180
	ds_read_b128 v[172:175], v180 offset:1024
	ds_read_b128 v[176:179], v180 offset:2048
	ds_read_b128 v[180:183], v180 offset:3072
	s_add_u32 s46, s46, 0x80000
	s_addc_u32 s47, s47, 0
	s_mov_b32 m0, s53
	v_lshl_add_u64 v[226:227], s[46:47], 0, v[136:137]
	ds_read_b128 v[184:187], v155 offset:32768
	ds_read_b128 v[188:191], v155 offset:33792
	ds_read_b128 v[192:195], v155 offset:34816
	ds_read_b128 v[196:199], v155 offset:35840
	ds_read_b128 v[200:203], v155 offset:36864
	ds_read_b128 v[204:207], v155 offset:37888
	ds_read_b128 v[208:211], v155 offset:38912
	ds_read_b128 v[212:215], v155 offset:39936
	global_load_lds_dwordx4 v[226:227], off
	v_lshl_add_u64 v[226:227], s[46:47], 0, v[132:133]
	s_mov_b32 m0, s54
	s_nop 0
	global_load_lds_dwordx4 v[226:227], off
	s_waitcnt vmcnt(8)
	s_waitcnt lgkmcnt(0)
	s_barrier
	s_setprio 1
	s_waitcnt lgkmcnt(0)
	v_mfma_f32_16x16x32_bf16 v[126:129], v[146:149], v[184:187], v[126:129]
	v_mfma_f32_16x16x32_bf16 v[110:113], v[146:149], v[192:195], v[110:113]
	v_mfma_f32_16x16x32_bf16 v[94:97], v[146:149], v[200:203], v[94:97]
	v_mfma_f32_16x16x32_bf16 v[78:81], v[146:149], v[208:211], v[78:81]
	v_mfma_f32_16x16x32_bf16 v[70:73], v[160:163], v[208:211], v[70:73]
	v_mfma_f32_16x16x32_bf16 v[86:89], v[160:163], v[200:203], v[86:89]
	v_mfma_f32_16x16x32_bf16 v[102:105], v[160:163], v[192:195], v[102:105]
	v_mfma_f32_16x16x32_bf16 v[118:121], v[160:163], v[184:187], v[118:121]
	v_mfma_f32_16x16x32_bf16 v[126:129], v[156:159], v[188:191], v[126:129]
	v_mfma_f32_16x16x32_bf16 v[110:113], v[156:159], v[196:199], v[110:113]
	v_mfma_f32_16x16x32_bf16 v[94:97], v[156:159], v[204:207], v[94:97]
	v_mfma_f32_16x16x32_bf16 v[78:81], v[156:159], v[212:215], v[78:81]
	v_mfma_f32_16x16x32_bf16 v[70:73], v[164:167], v[212:215], v[70:73]
	v_mfma_f32_16x16x32_bf16 v[86:89], v[164:167], v[204:207], v[86:89]
	v_mfma_f32_16x16x32_bf16 v[102:105], v[164:167], v[196:199], v[102:105]
	v_mfma_f32_16x16x32_bf16 v[118:121], v[164:167], v[188:191], v[118:121]
	s_setprio 0
	s_setprio 1
	v_mfma_f32_16x16x32_bf16 v[122:125], v[168:171], v[184:187], v[122:125]
	v_mfma_f32_16x16x32_bf16 v[106:109], v[168:171], v[192:195], v[106:109]
	v_mfma_f32_16x16x32_bf16 v[90:93], v[168:171], v[200:203], v[90:93]
	v_mfma_f32_16x16x32_bf16 v[74:77], v[168:171], v[208:211], v[74:77]
	v_mfma_f32_16x16x32_bf16 v[66:69], v[176:179], v[208:211], v[66:69]
	v_mfma_f32_16x16x32_bf16 v[82:85], v[176:179], v[200:203], v[82:85]
	v_mfma_f32_16x16x32_bf16 v[98:101], v[176:179], v[192:195], v[98:101]
	v_mfma_f32_16x16x32_bf16 v[114:117], v[176:179], v[184:187], v[114:117]
	v_mfma_f32_16x16x32_bf16 v[122:125], v[172:175], v[188:191], v[122:125]
	v_mfma_f32_16x16x32_bf16 v[106:109], v[172:175], v[196:199], v[106:109]
	v_mfma_f32_16x16x32_bf16 v[90:93], v[172:175], v[204:207], v[90:93]
	v_mfma_f32_16x16x32_bf16 v[74:77], v[172:175], v[212:215], v[74:77]
	v_mfma_f32_16x16x32_bf16 v[66:69], v[180:183], v[212:215], v[66:69]
	v_mfma_f32_16x16x32_bf16 v[82:85], v[180:183], v[204:207], v[82:85]
	v_mfma_f32_16x16x32_bf16 v[98:101], v[180:183], v[196:199], v[98:101]
	v_mfma_f32_16x16x32_bf16 v[114:117], v[180:183], v[188:191], v[114:117]
	s_setprio 0
	s_barrier
	s_add_i32 s46, s62, s30
	v_lshl_add_u64 v[218:219], v[218:219], 0, s[8:9]
	s_mov_b32 m0, s46
	ds_read_b128 v[184:187], v155 offset:49152
	ds_read_b128 v[188:191], v155 offset:50176
	ds_read_b128 v[192:195], v155 offset:51200
	ds_read_b128 v[196:199], v155 offset:52224
	ds_read_b128 v[200:203], v155 offset:53248
	ds_read_b128 v[204:207], v155 offset:54272
	ds_read_b128 v[208:211], v155 offset:55296
	ds_read_b128 v[212:215], v155 offset:56320
	global_load_lds_dwordx4 v[218:219], off
	s_add_i32 m0, s46, 0x2000
	s_add_u32 s34, s34, 0x80080
	v_lshl_add_u64 v[218:219], v[220:221], 0, s[8:9]
	s_addc_u32 s35, s35, 0
	s_add_i32 s46, s63, s30
	global_load_lds_dwordx4 v[218:219], off
	v_lshl_add_u64 v[218:219], s[34:35], 0, v[134:135]
	s_mov_b32 m0, s46
	s_nop 0
	global_load_lds_dwordx4 v[218:219], off
	v_lshl_add_u64 v[218:219], s[34:35], 0, v[130:131]
	s_add_i32 m0, s46, 0x2000
	s_nop 0
	global_load_lds_dwordx4 v[218:219], off
	v_lshl_add_u64 v[218:219], v[222:223], 0, s[8:9]
	s_mov_b32 m0, s56
	s_nop 0
	global_load_lds_dwordx4 v[218:219], off
	v_lshl_add_u64 v[218:219], v[224:225], 0, s[8:9]
	s_mov_b32 m0, s57
	s_nop 0
	global_load_lds_dwordx4 v[218:219], off
	s_waitcnt vmcnt(8)
	s_waitcnt lgkmcnt(0)
	s_barrier
	s_setprio 1
	s_waitcnt lgkmcnt(0)
	v_mfma_f32_16x16x32_bf16 v[62:65], v[146:149], v[184:187], v[62:65]
	v_mfma_f32_16x16x32_bf16 v[46:49], v[146:149], v[192:195], v[46:49]
	v_mfma_f32_16x16x32_bf16 v[30:33], v[146:149], v[200:203], v[30:33]
	v_mfma_f32_16x16x32_bf16 v[14:17], v[146:149], v[208:211], v[14:17]
	v_mfma_f32_16x16x32_bf16 v[6:9], v[160:163], v[208:211], v[6:9]
	v_mfma_f32_16x16x32_bf16 v[22:25], v[160:163], v[200:203], v[22:25]
	v_mfma_f32_16x16x32_bf16 v[38:41], v[160:163], v[192:195], v[38:41]
	v_mfma_f32_16x16x32_bf16 v[54:57], v[160:163], v[184:187], v[54:57]
	v_mfma_f32_16x16x32_bf16 v[62:65], v[156:159], v[188:191], v[62:65]
	v_mfma_f32_16x16x32_bf16 v[46:49], v[156:159], v[196:199], v[46:49]
	v_mfma_f32_16x16x32_bf16 v[30:33], v[156:159], v[204:207], v[30:33]
	v_mfma_f32_16x16x32_bf16 v[14:17], v[156:159], v[212:215], v[14:17]
	v_mfma_f32_16x16x32_bf16 v[6:9], v[164:167], v[212:215], v[6:9]
	v_mfma_f32_16x16x32_bf16 v[22:25], v[164:167], v[204:207], v[22:25]
	v_mfma_f32_16x16x32_bf16 v[38:41], v[164:167], v[196:199], v[38:41]
	v_mfma_f32_16x16x32_bf16 v[54:57], v[164:167], v[188:191], v[54:57]
	s_setprio 0
	s_setprio 1
	v_mfma_f32_16x16x32_bf16 v[58:61], v[168:171], v[184:187], v[58:61]
	v_mfma_f32_16x16x32_bf16 v[42:45], v[168:171], v[192:195], v[42:45]
	v_mfma_f32_16x16x32_bf16 v[26:29], v[168:171], v[200:203], v[26:29]
	v_mfma_f32_16x16x32_bf16 v[10:13], v[168:171], v[208:211], v[10:13]
	v_mfma_f32_16x16x32_bf16 v[2:5], v[176:179], v[208:211], v[2:5]
	v_mfma_f32_16x16x32_bf16 v[18:21], v[176:179], v[200:203], v[18:21]
	v_mfma_f32_16x16x32_bf16 v[34:37], v[176:179], v[192:195], v[34:37]
	v_mfma_f32_16x16x32_bf16 v[50:53], v[176:179], v[184:187], v[50:53]
	v_mfma_f32_16x16x32_bf16 v[58:61], v[172:175], v[188:191], v[58:61]
	v_mfma_f32_16x16x32_bf16 v[42:45], v[172:175], v[196:199], v[42:45]
	v_mfma_f32_16x16x32_bf16 v[26:29], v[172:175], v[204:207], v[26:29]
	v_mfma_f32_16x16x32_bf16 v[10:13], v[172:175], v[212:215], v[10:13]
	v_mfma_f32_16x16x32_bf16 v[2:5], v[180:183], v[212:215], v[2:5]
	v_mfma_f32_16x16x32_bf16 v[18:21], v[180:183], v[204:207], v[18:21]
	v_mfma_f32_16x16x32_bf16 v[34:37], v[180:183], v[196:199], v[34:37]
	v_mfma_f32_16x16x32_bf16 v[50:53], v[180:183], v[188:191], v[50:53]
	s_setprio 0
	s_barrier
	s_add_i32 s71, s71, 2
	s_add_u32 s44, s44, 0x100
	s_addc_u32 s45, s45, 0
	s_add_u32 s69, s69, 0x100
	s_addc_u32 s70, s70, 0
	s_cmp_gt_u32 s71, 29
	s_cbranch_scc0 .LBB0_3067
	v_mov_b32_e32 v160, 0xbfb8aa3b
	s_and_b64 vcc, exec, s[24:25]
	s_cbranch_vccz .LBB0_3070
	s_barrier

.LBB0_3180:
	ds_read_b128 v[130:133], v174
	ds_read_b128 v[134:137], v174 offset:1024
	ds_read_b128 v[138:141], v174 offset:2048
	ds_read_b128 v[158:161], v174 offset:3072
	ds_read_b128 v[162:165], v175
	ds_read_b128 v[166:169], v175 offset:1024
	ds_read_b128 v[178:181], v175 offset:2048
	ds_read_b128 v[182:185], v175 offset:3072
	s_add_u32 s34, s40, 0xffea0080
	s_addc_u32 s35, s41, -1
	s_cmpk_eq_i32 s60, 0x54
	s_cselect_b32 s43, s5, s35
	s_cselect_b32 s42, s4, s34
	s_cselect_b32 s35, s39, s1
	s_cselect_b32 s34, s38, s0
	v_lshl_add_u64 v[170:171], s[40:41], 0, v[150:151]
	s_add_i32 m0, s33, 0xc000
	ds_read_b128 v[186:189], v176
	ds_read_b128 v[190:193], v176 offset:1024
	ds_read_b128 v[194:197], v176 offset:2048
	ds_read_b128 v[198:201], v176 offset:3072
	ds_read_b128 v[202:205], v176 offset:4096
	ds_read_b128 v[206:209], v176 offset:5120
	ds_read_b128 v[210:213], v176 offset:6144
	ds_read_b128 v[218:221], v176 offset:7168
	global_load_lds_dwordx4 v[170:171], off
	v_lshl_add_u64 v[170:171], s[40:41], 0, v[152:153]
	s_add_i32 m0, s33, 0xe000
	s_nop 0
	global_load_lds_dwordx4 v[170:171], off
	s_waitcnt vmcnt(8)
	s_waitcnt lgkmcnt(0)
	s_barrier
	s_setprio 1
	s_waitcnt lgkmcnt(0)
	v_mfma_f32_16x16x32_bf16 v[126:129], v[130:133], v[186:189], v[126:129]
	v_mfma_f32_16x16x32_bf16 v[110:113], v[130:133], v[194:197], v[110:113]
	v_mfma_f32_16x16x32_bf16 v[94:97], v[130:133], v[202:205], v[94:97]
	v_mfma_f32_16x16x32_bf16 v[78:81], v[130:133], v[210:213], v[78:81]
	v_mfma_f32_16x16x32_bf16 v[74:77], v[138:141], v[210:213], v[74:77]
	v_mfma_f32_16x16x32_bf16 v[90:93], v[138:141], v[202:205], v[90:93]
	v_mfma_f32_16x16x32_bf16 v[106:109], v[138:141], v[194:197], v[106:109]
	v_mfma_f32_16x16x32_bf16 v[122:125], v[138:141], v[186:189], v[122:125]
	v_mfma_f32_16x16x32_bf16 v[126:129], v[134:137], v[190:193], v[126:129]
	v_mfma_f32_16x16x32_bf16 v[110:113], v[134:137], v[198:201], v[110:113]
	v_mfma_f32_16x16x32_bf16 v[94:97], v[134:137], v[206:209], v[94:97]
	v_mfma_f32_16x16x32_bf16 v[78:81], v[134:137], v[218:221], v[78:81]
	v_mfma_f32_16x16x32_bf16 v[74:77], v[158:161], v[218:221], v[74:77]
	v_mfma_f32_16x16x32_bf16 v[90:93], v[158:161], v[206:209], v[90:93]
	v_mfma_f32_16x16x32_bf16 v[106:109], v[158:161], v[198:201], v[106:109]
	v_mfma_f32_16x16x32_bf16 v[122:125], v[158:161], v[190:193], v[122:125]
	s_setprio 0
	s_setprio 1
	v_mfma_f32_16x16x32_bf16 v[118:121], v[162:165], v[186:189], v[118:121]
	v_mfma_f32_16x16x32_bf16 v[102:105], v[162:165], v[194:197], v[102:105]
	v_mfma_f32_16x16x32_bf16 v[86:89], v[162:165], v[202:205], v[86:89]
	v_mfma_f32_16x16x32_bf16 v[70:73], v[162:165], v[210:213], v[70:73]
	v_mfma_f32_16x16x32_bf16 v[66:69], v[178:181], v[210:213], v[66:69]
	v_mfma_f32_16x16x32_bf16 v[82:85], v[178:181], v[202:205], v[82:85]
	v_mfma_f32_16x16x32_bf16 v[98:101], v[178:181], v[194:197], v[98:101]
	v_mfma_f32_16x16x32_bf16 v[114:117], v[178:181], v[186:189], v[114:117]
	v_mfma_f32_16x16x32_bf16 v[118:121], v[166:169], v[190:193], v[118:121]
	v_mfma_f32_16x16x32_bf16 v[102:105], v[166:169], v[198:201], v[102:105]
	v_mfma_f32_16x16x32_bf16 v[86:89], v[166:169], v[206:209], v[86:89]
	v_mfma_f32_16x16x32_bf16 v[70:73], v[166:169], v[218:221], v[70:73]
	v_mfma_f32_16x16x32_bf16 v[66:69], v[182:185], v[218:221], v[66:69]
	v_mfma_f32_16x16x32_bf16 v[82:85], v[182:185], v[206:209], v[82:85]
	v_mfma_f32_16x16x32_bf16 v[98:101], v[182:185], v[198:201], v[98:101]
	v_mfma_f32_16x16x32_bf16 v[114:117], v[182:185], v[190:193], v[114:117]
	s_setprio 0
	s_barrier
	s_add_i32 s61, s53, s31
	v_lshl_add_u64 v[170:171], s[34:35], 0, v[144:145]
	s_mov_b32 m0, s61
	ds_read_b128 v[186:189], v176 offset:16384
	ds_read_b128 v[190:193], v176 offset:17408
	ds_read_b128 v[194:197], v176 offset:18432
	ds_read_b128 v[198:201], v176 offset:19456
	ds_read_b128 v[202:205], v176 offset:20480
	ds_read_b128 v[206:209], v176 offset:21504
	ds_read_b128 v[210:213], v176 offset:22528
	ds_read_b128 v[218:221], v176 offset:23552
	global_load_lds_dwordx4 v[170:171], off
	s_add_i32 m0, s61, 0x2000
	s_add_u32 s62, s34, 0x160000
	v_lshl_add_u64 v[214:215], s[34:35], 0, v[148:149]
	s_addc_u32 s63, s35, 0
	s_add_i32 s61, s54, s31
	global_load_lds_dwordx4 v[214:215], off
	v_lshl_add_u64 v[222:223], s[62:63], 0, v[144:145]
	s_mov_b32 m0, s61
	v_lshl_add_u64 v[224:225], s[42:43], 0, v[146:147]
	global_load_lds_dwordx4 v[222:223], off
	v_lshl_add_u64 v[222:223], s[62:63], 0, v[148:149]
	s_add_i32 m0, s61, 0x2000
	s_nop 0
	global_load_lds_dwordx4 v[222:223], off
	v_lshl_add_u64 v[222:223], s[42:43], 0, v[142:143]
	s_mov_b32 m0, s33
	s_nop 0
	global_load_lds_dwordx4 v[222:223], off
	s_mov_b32 m0, s44
	s_nop 0
	global_load_lds_dwordx4 v[224:225], off
	s_waitcnt vmcnt(8)
	s_waitcnt lgkmcnt(0)
	s_barrier
	s_setprio 1
	s_waitcnt lgkmcnt(0)
	v_mfma_f32_16x16x32_bf16 v[62:65], v[130:133], v[186:189], v[62:65]
	v_mfma_f32_16x16x32_bf16 v[50:53], v[130:133], v[194:197], v[50:53]
	v_mfma_f32_16x16x32_bf16 v[38:41], v[130:133], v[202:205], v[38:41]
	v_mfma_f32_16x16x32_bf16 v[14:17], v[130:133], v[210:213], v[14:17]
	v_mfma_f32_16x16x32_bf16 v[10:13], v[138:141], v[210:213], v[10:13]
	v_mfma_f32_16x16x32_bf16 v[34:37], v[138:141], v[202:205], v[34:37]
	v_mfma_f32_16x16x32_bf16 v[42:45], v[138:141], v[194:197], v[42:45]
	v_mfma_f32_16x16x32_bf16 v[58:61], v[138:141], v[186:189], v[58:61]
	v_mfma_f32_16x16x32_bf16 v[62:65], v[134:137], v[190:193], v[62:65]
	v_mfma_f32_16x16x32_bf16 v[50:53], v[134:137], v[198:201], v[50:53]
	v_mfma_f32_16x16x32_bf16 v[38:41], v[134:137], v[206:209], v[38:41]
	v_mfma_f32_16x16x32_bf16 v[14:17], v[134:137], v[218:221], v[14:17]
	v_mfma_f32_16x16x32_bf16 v[10:13], v[158:161], v[218:221], v[10:13]
	v_mfma_f32_16x16x32_bf16 v[34:37], v[158:161], v[206:209], v[34:37]
	v_mfma_f32_16x16x32_bf16 v[42:45], v[158:161], v[198:201], v[42:45]
	v_mfma_f32_16x16x32_bf16 v[58:61], v[158:161], v[190:193], v[58:61]
	s_setprio 0
	s_setprio 1
	v_mfma_f32_16x16x32_bf16 v[54:57], v[162:165], v[186:189], v[54:57]
	v_mfma_f32_16x16x32_bf16 v[30:33], v[162:165], v[194:197], v[30:33]
	v_mfma_f32_16x16x32_bf16 v[22:25], v[162:165], v[202:205], v[22:25]
	v_mfma_f32_16x16x32_bf16 v[6:9], v[162:165], v[210:213], v[6:9]
	v_mfma_f32_16x16x32_bf16 v[2:5], v[178:181], v[210:213], v[2:5]
	v_mfma_f32_16x16x32_bf16 v[18:21], v[178:181], v[202:205], v[18:21]
	v_mfma_f32_16x16x32_bf16 v[26:29], v[178:181], v[194:197], v[26:29]
	v_mfma_f32_16x16x32_bf16 v[46:49], v[178:181], v[186:189], v[46:49]
	v_mfma_f32_16x16x32_bf16 v[54:57], v[166:169], v[190:193], v[54:57]
	v_mfma_f32_16x16x32_bf16 v[30:33], v[166:169], v[198:201], v[30:33]
	v_mfma_f32_16x16x32_bf16 v[22:25], v[166:169], v[206:209], v[22:25]
	v_mfma_f32_16x16x32_bf16 v[6:9], v[166:169], v[218:221], v[6:9]
	v_mfma_f32_16x16x32_bf16 v[2:5], v[182:185], v[218:221], v[2:5]
	v_mfma_f32_16x16x32_bf16 v[18:21], v[182:185], v[206:209], v[18:21]
	v_mfma_f32_16x16x32_bf16 v[26:29], v[182:185], v[198:201], v[26:29]
	v_mfma_f32_16x16x32_bf16 v[46:49], v[182:185], v[190:193], v[46:49]
	s_setprio 0
	s_barrier
	s_add_i32 s61, 0, 0x18000
	s_add_i32 s62, 0, 0x1c000
	v_add_u32_e32 v158, s61, v172
	v_add_u32_e32 v177, s62, v172
	ds_read_b128 v[130:133], v158
	ds_read_b128 v[134:137], v158 offset:1024
	ds_read_b128 v[138:141], v158 offset:2048
	ds_read_b128 v[158:161], v158 offset:3072
	ds_read_b128 v[162:165], v177
	ds_read_b128 v[166:169], v177 offset:1024
	ds_read_b128 v[178:181], v177 offset:2048
	ds_read_b128 v[182:185], v177 offset:3072
	s_add_u32 s42, s42, 0x160000
	s_addc_u32 s43, s43, 0
	s_mov_b32 m0, s45
	v_lshl_add_u64 v[226:227], s[42:43], 0, v[142:143]
	ds_read_b128 v[186:189], v176 offset:32768
	ds_read_b128 v[190:193], v176 offset:33792
	ds_read_b128 v[194:197], v176 offset:34816
	ds_read_b128 v[198:201], v176 offset:35840
	ds_read_b128 v[202:205], v176 offset:36864
	ds_read_b128 v[206:209], v176 offset:37888
	ds_read_b128 v[210:213], v176 offset:38912
	ds_read_b128 v[218:221], v176 offset:39936
	global_load_lds_dwordx4 v[226:227], off
	v_lshl_add_u64 v[226:227], s[42:43], 0, v[146:147]
	s_mov_b32 m0, s46
	s_nop 0
	global_load_lds_dwordx4 v[226:227], off
	s_waitcnt vmcnt(8)
	s_waitcnt lgkmcnt(0)
	s_barrier
	s_setprio 1
	s_waitcnt lgkmcnt(0)
	v_mfma_f32_16x16x32_bf16 v[126:129], v[130:133], v[186:189], v[126:129]
	v_mfma_f32_16x16x32_bf16 v[110:113], v[130:133], v[194:197], v[110:113]
	v_mfma_f32_16x16x32_bf16 v[94:97], v[130:133], v[202:205], v[94:97]
	v_mfma_f32_16x16x32_bf16 v[78:81], v[130:133], v[210:213], v[78:81]
	v_mfma_f32_16x16x32_bf16 v[74:77], v[138:141], v[210:213], v[74:77]
	v_mfma_f32_16x16x32_bf16 v[90:93], v[138:141], v[202:205], v[90:93]
	v_mfma_f32_16x16x32_bf16 v[106:109], v[138:141], v[194:197], v[106:109]
	v_mfma_f32_16x16x32_bf16 v[122:125], v[138:141], v[186:189], v[122:125]
	v_mfma_f32_16x16x32_bf16 v[126:129], v[134:137], v[190:193], v[126:129]
	v_mfma_f32_16x16x32_bf16 v[110:113], v[134:137], v[198:201], v[110:113]
	v_mfma_f32_16x16x32_bf16 v[94:97], v[134:137], v[206:209], v[94:97]
	v_mfma_f32_16x16x32_bf16 v[78:81], v[134:137], v[218:221], v[78:81]
	v_mfma_f32_16x16x32_bf16 v[74:77], v[158:161], v[218:221], v[74:77]
	v_mfma_f32_16x16x32_bf16 v[90:93], v[158:161], v[206:209], v[90:93]
	v_mfma_f32_16x16x32_bf16 v[106:109], v[158:161], v[198:201], v[106:109]
	v_mfma_f32_16x16x32_bf16 v[122:125], v[158:161], v[190:193], v[122:125]
	s_setprio 0
	s_setprio 1
	v_mfma_f32_16x16x32_bf16 v[118:121], v[162:165], v[186:189], v[118:121]
	v_mfma_f32_16x16x32_bf16 v[102:105], v[162:165], v[194:197], v[102:105]
	v_mfma_f32_16x16x32_bf16 v[86:89], v[162:165], v[202:205], v[86:89]
	v_mfma_f32_16x16x32_bf16 v[70:73], v[162:165], v[210:213], v[70:73]
	v_mfma_f32_16x16x32_bf16 v[66:69], v[178:181], v[210:213], v[66:69]
	v_mfma_f32_16x16x32_bf16 v[82:85], v[178:181], v[202:205], v[82:85]
	v_mfma_f32_16x16x32_bf16 v[98:101], v[178:181], v[194:197], v[98:101]
	v_mfma_f32_16x16x32_bf16 v[114:117], v[178:181], v[186:189], v[114:117]
	v_mfma_f32_16x16x32_bf16 v[118:121], v[166:169], v[190:193], v[118:121]
	v_mfma_f32_16x16x32_bf16 v[102:105], v[166:169], v[198:201], v[102:105]
	v_mfma_f32_16x16x32_bf16 v[86:89], v[166:169], v[206:209], v[86:89]
	v_mfma_f32_16x16x32_bf16 v[70:73], v[166:169], v[218:221], v[70:73]
	v_mfma_f32_16x16x32_bf16 v[66:69], v[182:185], v[218:221], v[66:69]
	v_mfma_f32_16x16x32_bf16 v[82:85], v[182:185], v[206:209], v[82:85]
	v_mfma_f32_16x16x32_bf16 v[98:101], v[182:185], v[198:201], v[98:101]
	v_mfma_f32_16x16x32_bf16 v[114:117], v[182:185], v[190:193], v[114:117]
	s_setprio 0
	s_barrier
	s_add_i32 s42, s61, s31
	v_lshl_add_u64 v[170:171], v[170:171], 0, s[24:25]
	s_mov_b32 m0, s42
	ds_read_b128 v[186:189], v176 offset:49152
	ds_read_b128 v[190:193], v176 offset:50176
	ds_read_b128 v[194:197], v176 offset:51200
	ds_read_b128 v[198:201], v176 offset:52224
	ds_read_b128 v[202:205], v176 offset:53248
	ds_read_b128 v[206:209], v176 offset:54272
	ds_read_b128 v[210:213], v176 offset:55296
	ds_read_b128 v[218:221], v176 offset:56320
	global_load_lds_dwordx4 v[170:171], off
	s_add_i32 m0, s42, 0x2000
	s_add_u32 s34, s34, 0x160080
	v_lshl_add_u64 v[170:171], v[214:215], 0, s[24:25]
	s_addc_u32 s35, s35, 0
	s_add_i32 s42, s62, s31
	global_load_lds_dwordx4 v[170:171], off
	v_lshl_add_u64 v[170:171], s[34:35], 0, v[144:145]
	s_mov_b32 m0, s42
	s_nop 0
	global_load_lds_dwordx4 v[170:171], off
	v_lshl_add_u64 v[170:171], s[34:35], 0, v[148:149]
	s_add_i32 m0, s42, 0x2000
	s_nop 0
	global_load_lds_dwordx4 v[170:171], off
	v_lshl_add_u64 v[170:171], v[222:223], 0, s[24:25]
	s_mov_b32 m0, s48
	s_nop 0
	global_load_lds_dwordx4 v[170:171], off
	v_lshl_add_u64 v[170:171], v[224:225], 0, s[24:25]
	s_mov_b32 m0, s49
	s_nop 0
	global_load_lds_dwordx4 v[170:171], off
	s_waitcnt vmcnt(8)
	s_waitcnt lgkmcnt(0)
	s_barrier
	s_setprio 1
	s_waitcnt lgkmcnt(0)
	v_mfma_f32_16x16x32_bf16 v[62:65], v[130:133], v[186:189], v[62:65]
	v_mfma_f32_16x16x32_bf16 v[50:53], v[130:133], v[194:197], v[50:53]
	v_mfma_f32_16x16x32_bf16 v[38:41], v[130:133], v[202:205], v[38:41]
	v_mfma_f32_16x16x32_bf16 v[14:17], v[130:133], v[210:213], v[14:17]
	v_mfma_f32_16x16x32_bf16 v[10:13], v[138:141], v[210:213], v[10:13]
	v_mfma_f32_16x16x32_bf16 v[34:37], v[138:141], v[202:205], v[34:37]
	v_mfma_f32_16x16x32_bf16 v[42:45], v[138:141], v[194:197], v[42:45]
	v_mfma_f32_16x16x32_bf16 v[58:61], v[138:141], v[186:189], v[58:61]
	v_mfma_f32_16x16x32_bf16 v[62:65], v[134:137], v[190:193], v[62:65]
	v_mfma_f32_16x16x32_bf16 v[50:53], v[134:137], v[198:201], v[50:53]
	v_mfma_f32_16x16x32_bf16 v[38:41], v[134:137], v[206:209], v[38:41]
	v_mfma_f32_16x16x32_bf16 v[14:17], v[134:137], v[218:221], v[14:17]
	v_mfma_f32_16x16x32_bf16 v[10:13], v[158:161], v[218:221], v[10:13]
	v_mfma_f32_16x16x32_bf16 v[34:37], v[158:161], v[206:209], v[34:37]
	v_mfma_f32_16x16x32_bf16 v[42:45], v[158:161], v[198:201], v[42:45]
	v_mfma_f32_16x16x32_bf16 v[58:61], v[158:161], v[190:193], v[58:61]
	s_setprio 0
	s_setprio 1
	v_mfma_f32_16x16x32_bf16 v[54:57], v[162:165], v[186:189], v[54:57]
	v_mfma_f32_16x16x32_bf16 v[30:33], v[162:165], v[194:197], v[30:33]
	v_mfma_f32_16x16x32_bf16 v[22:25], v[162:165], v[202:205], v[22:25]
	v_mfma_f32_16x16x32_bf16 v[6:9], v[162:165], v[210:213], v[6:9]
	v_mfma_f32_16x16x32_bf16 v[2:5], v[178:181], v[210:213], v[2:5]
	v_mfma_f32_16x16x32_bf16 v[18:21], v[178:181], v[202:205], v[18:21]
	v_mfma_f32_16x16x32_bf16 v[26:29], v[178:181], v[194:197], v[26:29]
	v_mfma_f32_16x16x32_bf16 v[46:49], v[178:181], v[186:189], v[46:49]
	v_mfma_f32_16x16x32_bf16 v[54:57], v[166:169], v[190:193], v[54:57]
	v_mfma_f32_16x16x32_bf16 v[30:33], v[166:169], v[198:201], v[30:33]
	v_mfma_f32_16x16x32_bf16 v[22:25], v[166:169], v[206:209], v[22:25]
	v_mfma_f32_16x16x32_bf16 v[6:9], v[166:169], v[218:221], v[6:9]
	v_mfma_f32_16x16x32_bf16 v[2:5], v[182:185], v[218:221], v[2:5]
	v_mfma_f32_16x16x32_bf16 v[18:21], v[182:185], v[206:209], v[18:21]
	v_mfma_f32_16x16x32_bf16 v[26:29], v[182:185], v[198:201], v[26:29]
	v_mfma_f32_16x16x32_bf16 v[46:49], v[182:185], v[190:193], v[46:49]
	s_setprio 0
	s_barrier
	s_add_i32 s60, s60, 2
	s_add_u32 s40, s40, 0x100
	s_addc_u32 s41, s41, 0
	s_add_u32 s0, s0, 0x100
	s_addc_u32 s1, s1, 0
	s_cmpk_gt_u32 s60, 0x55
	s_cbranch_scc0 .LBB0_3180
	s_and_b64 vcc, exec, s[26:27]
	s_cbranch_vccz .LBB0_3183
	s_barrier

.LBB0_3309:
	ds_read_b128 v[146:149], v153
	ds_read_b128 v[156:159], v153 offset:1024
	ds_read_b128 v[160:163], v153 offset:2048
	ds_read_b128 v[164:167], v153 offset:3072
	ds_read_b128 v[168:171], v154
	ds_read_b128 v[172:175], v154 offset:1024
	ds_read_b128 v[176:179], v154 offset:2048
	ds_read_b128 v[180:183], v154 offset:3072
	s_add_u32 s34, s44, 0xfff80080
	s_addc_u32 s35, s45, -1
	s_cmp_eq_u32 s69, 28
	s_cselect_b32 s47, s0, s35
	s_cselect_b32 s46, s1, s34
	s_cselect_b32 s35, s27, s68
	s_cselect_b32 s34, s37, s61
	v_lshl_add_u64 v[218:219], s[44:45], 0, v[138:139]
	s_add_i32 m0, s43, 0xc000
	ds_read_b128 v[184:187], v155
	ds_read_b128 v[188:191], v155 offset:1024
	ds_read_b128 v[192:195], v155 offset:2048
	ds_read_b128 v[196:199], v155 offset:3072
	ds_read_b128 v[200:203], v155 offset:4096
	ds_read_b128 v[204:207], v155 offset:5120
	ds_read_b128 v[208:211], v155 offset:6144
	ds_read_b128 v[212:215], v155 offset:7168
	global_load_lds_dwordx4 v[218:219], off
	v_lshl_add_u64 v[218:219], s[44:45], 0, v[140:141]
	s_add_i32 m0, s43, 0xe000
	s_nop 0
	global_load_lds_dwordx4 v[218:219], off
	s_waitcnt vmcnt(8)
	s_waitcnt lgkmcnt(0)
	s_barrier
	s_setprio 1
	s_waitcnt lgkmcnt(0)
	v_mfma_f32_16x16x32_bf16 v[126:129], v[146:149], v[184:187], v[126:129]
	v_mfma_f32_16x16x32_bf16 v[110:113], v[146:149], v[192:195], v[110:113]
	v_mfma_f32_16x16x32_bf16 v[94:97], v[146:149], v[200:203], v[94:97]
	v_mfma_f32_16x16x32_bf16 v[78:81], v[146:149], v[208:211], v[78:81]
	v_mfma_f32_16x16x32_bf16 v[70:73], v[160:163], v[208:211], v[70:73]
	v_mfma_f32_16x16x32_bf16 v[86:89], v[160:163], v[200:203], v[86:89]
	v_mfma_f32_16x16x32_bf16 v[102:105], v[160:163], v[192:195], v[102:105]
	v_mfma_f32_16x16x32_bf16 v[118:121], v[160:163], v[184:187], v[118:121]
	v_mfma_f32_16x16x32_bf16 v[126:129], v[156:159], v[188:191], v[126:129]
	v_mfma_f32_16x16x32_bf16 v[110:113], v[156:159], v[196:199], v[110:113]
	v_mfma_f32_16x16x32_bf16 v[94:97], v[156:159], v[204:207], v[94:97]
	v_mfma_f32_16x16x32_bf16 v[78:81], v[156:159], v[212:215], v[78:81]
	v_mfma_f32_16x16x32_bf16 v[70:73], v[164:167], v[212:215], v[70:73]
	v_mfma_f32_16x16x32_bf16 v[86:89], v[164:167], v[204:207], v[86:89]
	v_mfma_f32_16x16x32_bf16 v[102:105], v[164:167], v[196:199], v[102:105]
	v_mfma_f32_16x16x32_bf16 v[118:121], v[164:167], v[188:191], v[118:121]
	s_setprio 0
	s_setprio 1
	v_mfma_f32_16x16x32_bf16 v[122:125], v[168:171], v[184:187], v[122:125]
	v_mfma_f32_16x16x32_bf16 v[106:109], v[168:171], v[192:195], v[106:109]
	v_mfma_f32_16x16x32_bf16 v[90:93], v[168:171], v[200:203], v[90:93]
	v_mfma_f32_16x16x32_bf16 v[74:77], v[168:171], v[208:211], v[74:77]
	v_mfma_f32_16x16x32_bf16 v[66:69], v[176:179], v[208:211], v[66:69]
	v_mfma_f32_16x16x32_bf16 v[82:85], v[176:179], v[200:203], v[82:85]
	v_mfma_f32_16x16x32_bf16 v[98:101], v[176:179], v[192:195], v[98:101]
	v_mfma_f32_16x16x32_bf16 v[114:117], v[176:179], v[184:187], v[114:117]
	v_mfma_f32_16x16x32_bf16 v[122:125], v[172:175], v[188:191], v[122:125]
	v_mfma_f32_16x16x32_bf16 v[106:109], v[172:175], v[196:199], v[106:109]
	v_mfma_f32_16x16x32_bf16 v[90:93], v[172:175], v[204:207], v[90:93]
	v_mfma_f32_16x16x32_bf16 v[74:77], v[172:175], v[212:215], v[74:77]
	v_mfma_f32_16x16x32_bf16 v[66:69], v[180:183], v[212:215], v[66:69]
	v_mfma_f32_16x16x32_bf16 v[82:85], v[180:183], v[204:207], v[82:85]
	v_mfma_f32_16x16x32_bf16 v[98:101], v[180:183], v[196:199], v[98:101]
	v_mfma_f32_16x16x32_bf16 v[114:117], v[180:183], v[188:191], v[114:117]
	s_setprio 0
	s_barrier
	s_add_i32 s62, s57, s30
	v_lshl_add_u64 v[218:219], s[34:35], 0, v[134:135]
	s_mov_b32 m0, s62
	ds_read_b128 v[184:187], v155 offset:16384
	ds_read_b128 v[188:191], v155 offset:17408
	ds_read_b128 v[192:195], v155 offset:18432
	ds_read_b128 v[196:199], v155 offset:19456
	ds_read_b128 v[200:203], v155 offset:20480
	ds_read_b128 v[204:207], v155 offset:21504
	ds_read_b128 v[208:211], v155 offset:22528
	ds_read_b128 v[212:215], v155 offset:23552
	global_load_lds_dwordx4 v[218:219], off
	s_add_i32 m0, s62, 0x2000
	s_add_u32 s62, s34, 0x80000
	v_lshl_add_u64 v[220:221], s[34:35], 0, v[130:131]
	s_addc_u32 s63, s35, 0
	s_add_i32 s66, s58, s30
	global_load_lds_dwordx4 v[220:221], off
	v_lshl_add_u64 v[222:223], s[62:63], 0, v[134:135]
	s_mov_b32 m0, s66
	v_lshl_add_u64 v[224:225], s[46:47], 0, v[132:133]
	global_load_lds_dwordx4 v[222:223], off
	v_lshl_add_u64 v[222:223], s[62:63], 0, v[130:131]
	s_add_i32 m0, s66, 0x2000
	s_nop 0
	global_load_lds_dwordx4 v[222:223], off
	v_lshl_add_u64 v[222:223], s[46:47], 0, v[136:137]
	s_mov_b32 m0, s43
	s_nop 0
	global_load_lds_dwordx4 v[222:223], off
	s_mov_b32 m0, s48
	s_nop 0
	global_load_lds_dwordx4 v[224:225], off
	s_waitcnt vmcnt(8)
	s_waitcnt lgkmcnt(0)
	s_barrier
	s_setprio 1
	s_waitcnt lgkmcnt(0)
	v_mfma_f32_16x16x32_bf16 v[62:65], v[146:149], v[184:187], v[62:65]
	v_mfma_f32_16x16x32_bf16 v[46:49], v[146:149], v[192:195], v[46:49]
	v_mfma_f32_16x16x32_bf16 v[30:33], v[146:149], v[200:203], v[30:33]
	v_mfma_f32_16x16x32_bf16 v[14:17], v[146:149], v[208:211], v[14:17]
	v_mfma_f32_16x16x32_bf16 v[6:9], v[160:163], v[208:211], v[6:9]
	v_mfma_f32_16x16x32_bf16 v[22:25], v[160:163], v[200:203], v[22:25]
	v_mfma_f32_16x16x32_bf16 v[38:41], v[160:163], v[192:195], v[38:41]
	v_mfma_f32_16x16x32_bf16 v[54:57], v[160:163], v[184:187], v[54:57]
	v_mfma_f32_16x16x32_bf16 v[62:65], v[156:159], v[188:191], v[62:65]
	v_mfma_f32_16x16x32_bf16 v[46:49], v[156:159], v[196:199], v[46:49]
	v_mfma_f32_16x16x32_bf16 v[30:33], v[156:159], v[204:207], v[30:33]
	v_mfma_f32_16x16x32_bf16 v[14:17], v[156:159], v[212:215], v[14:17]
	v_mfma_f32_16x16x32_bf16 v[6:9], v[164:167], v[212:215], v[6:9]
	v_mfma_f32_16x16x32_bf16 v[22:25], v[164:167], v[204:207], v[22:25]
	v_mfma_f32_16x16x32_bf16 v[38:41], v[164:167], v[196:199], v[38:41]
	v_mfma_f32_16x16x32_bf16 v[54:57], v[164:167], v[188:191], v[54:57]
	s_setprio 0
	s_setprio 1
	v_mfma_f32_16x16x32_bf16 v[58:61], v[168:171], v[184:187], v[58:61]
	v_mfma_f32_16x16x32_bf16 v[42:45], v[168:171], v[192:195], v[42:45]
	v_mfma_f32_16x16x32_bf16 v[26:29], v[168:171], v[200:203], v[26:29]
	v_mfma_f32_16x16x32_bf16 v[10:13], v[168:171], v[208:211], v[10:13]
	v_mfma_f32_16x16x32_bf16 v[2:5], v[176:179], v[208:211], v[2:5]
	v_mfma_f32_16x16x32_bf16 v[18:21], v[176:179], v[200:203], v[18:21]
	v_mfma_f32_16x16x32_bf16 v[34:37], v[176:179], v[192:195], v[34:37]
	v_mfma_f32_16x16x32_bf16 v[50:53], v[176:179], v[184:187], v[50:53]
	v_mfma_f32_16x16x32_bf16 v[58:61], v[172:175], v[188:191], v[58:61]
	v_mfma_f32_16x16x32_bf16 v[42:45], v[172:175], v[196:199], v[42:45]
	v_mfma_f32_16x16x32_bf16 v[26:29], v[172:175], v[204:207], v[26:29]
	v_mfma_f32_16x16x32_bf16 v[10:13], v[172:175], v[212:215], v[10:13]
	v_mfma_f32_16x16x32_bf16 v[2:5], v[180:183], v[212:215], v[2:5]
	v_mfma_f32_16x16x32_bf16 v[18:21], v[180:183], v[204:207], v[18:21]
	v_mfma_f32_16x16x32_bf16 v[34:37], v[180:183], v[196:199], v[34:37]
	v_mfma_f32_16x16x32_bf16 v[50:53], v[180:183], v[188:191], v[50:53]
	s_setprio 0
	s_barrier
	s_add_i32 s62, 0, 0x18000
	s_add_i32 s63, 0, 0x1c000
	v_add_u32_e32 v164, s62, v151
	v_add_u32_e32 v180, s63, v151
	ds_read_b128 v[146:149], v164
	ds_read_b128 v[156:159], v164 offset:1024
	ds_read_b128 v[160:163], v164 offset:2048
	ds_read_b128 v[164:167], v164 offset:3072
	ds_read_b128 v[168:171], v180
	ds_read_b128 v[172:175], v180 offset:1024
	ds_read_b128 v[176:179], v180 offset:2048
	ds_read_b128 v[180:183], v180 offset:3072
	s_add_u32 s46, s46, 0x80000
	s_addc_u32 s47, s47, 0
	s_mov_b32 m0, s49
	v_lshl_add_u64 v[226:227], s[46:47], 0, v[136:137]
	ds_read_b128 v[184:187], v155 offset:32768
	ds_read_b128 v[188:191], v155 offset:33792
	ds_read_b128 v[192:195], v155 offset:34816
	ds_read_b128 v[196:199], v155 offset:35840
	ds_read_b128 v[200:203], v155 offset:36864
	ds_read_b128 v[204:207], v155 offset:37888
	ds_read_b128 v[208:211], v155 offset:38912
	ds_read_b128 v[212:215], v155 offset:39936
	global_load_lds_dwordx4 v[226:227], off
	v_lshl_add_u64 v[226:227], s[46:47], 0, v[132:133]
	s_mov_b32 m0, s52
	s_nop 0
	global_load_lds_dwordx4 v[226:227], off
	s_waitcnt vmcnt(8)
	s_waitcnt lgkmcnt(0)
	s_barrier
	s_setprio 1
	s_waitcnt lgkmcnt(0)
	v_mfma_f32_16x16x32_bf16 v[126:129], v[146:149], v[184:187], v[126:129]
	v_mfma_f32_16x16x32_bf16 v[110:113], v[146:149], v[192:195], v[110:113]
	v_mfma_f32_16x16x32_bf16 v[94:97], v[146:149], v[200:203], v[94:97]
	v_mfma_f32_16x16x32_bf16 v[78:81], v[146:149], v[208:211], v[78:81]
	v_mfma_f32_16x16x32_bf16 v[70:73], v[160:163], v[208:211], v[70:73]
	v_mfma_f32_16x16x32_bf16 v[86:89], v[160:163], v[200:203], v[86:89]
	v_mfma_f32_16x16x32_bf16 v[102:105], v[160:163], v[192:195], v[102:105]
	v_mfma_f32_16x16x32_bf16 v[118:121], v[160:163], v[184:187], v[118:121]
	v_mfma_f32_16x16x32_bf16 v[126:129], v[156:159], v[188:191], v[126:129]
	v_mfma_f32_16x16x32_bf16 v[110:113], v[156:159], v[196:199], v[110:113]
	v_mfma_f32_16x16x32_bf16 v[94:97], v[156:159], v[204:207], v[94:97]
	v_mfma_f32_16x16x32_bf16 v[78:81], v[156:159], v[212:215], v[78:81]
	v_mfma_f32_16x16x32_bf16 v[70:73], v[164:167], v[212:215], v[70:73]
	v_mfma_f32_16x16x32_bf16 v[86:89], v[164:167], v[204:207], v[86:89]
	v_mfma_f32_16x16x32_bf16 v[102:105], v[164:167], v[196:199], v[102:105]
	v_mfma_f32_16x16x32_bf16 v[118:121], v[164:167], v[188:191], v[118:121]
	s_setprio 0
	s_setprio 1
	v_mfma_f32_16x16x32_bf16 v[122:125], v[168:171], v[184:187], v[122:125]
	v_mfma_f32_16x16x32_bf16 v[106:109], v[168:171], v[192:195], v[106:109]
	v_mfma_f32_16x16x32_bf16 v[90:93], v[168:171], v[200:203], v[90:93]
	v_mfma_f32_16x16x32_bf16 v[74:77], v[168:171], v[208:211], v[74:77]
	v_mfma_f32_16x16x32_bf16 v[66:69], v[176:179], v[208:211], v[66:69]
	v_mfma_f32_16x16x32_bf16 v[82:85], v[176:179], v[200:203], v[82:85]
	v_mfma_f32_16x16x32_bf16 v[98:101], v[176:179], v[192:195], v[98:101]
	v_mfma_f32_16x16x32_bf16 v[114:117], v[176:179], v[184:187], v[114:117]
	v_mfma_f32_16x16x32_bf16 v[122:125], v[172:175], v[188:191], v[122:125]
	v_mfma_f32_16x16x32_bf16 v[106:109], v[172:175], v[196:199], v[106:109]
	v_mfma_f32_16x16x32_bf16 v[90:93], v[172:175], v[204:207], v[90:93]
	v_mfma_f32_16x16x32_bf16 v[74:77], v[172:175], v[212:215], v[74:77]
	v_mfma_f32_16x16x32_bf16 v[66:69], v[180:183], v[212:215], v[66:69]
	v_mfma_f32_16x16x32_bf16 v[82:85], v[180:183], v[204:207], v[82:85]
	v_mfma_f32_16x16x32_bf16 v[98:101], v[180:183], v[196:199], v[98:101]
	v_mfma_f32_16x16x32_bf16 v[114:117], v[180:183], v[188:191], v[114:117]
	s_setprio 0
	s_barrier
	s_add_i32 s46, s62, s30
	v_lshl_add_u64 v[218:219], v[218:219], 0, s[8:9]
	s_mov_b32 m0, s46
	ds_read_b128 v[184:187], v155 offset:49152
	ds_read_b128 v[188:191], v155 offset:50176
	ds_read_b128 v[192:195], v155 offset:51200
	ds_read_b128 v[196:199], v155 offset:52224
	ds_read_b128 v[200:203], v155 offset:53248
	ds_read_b128 v[204:207], v155 offset:54272
	ds_read_b128 v[208:211], v155 offset:55296
	ds_read_b128 v[212:215], v155 offset:56320
	global_load_lds_dwordx4 v[218:219], off
	s_add_i32 m0, s46, 0x2000
	s_add_u32 s34, s34, 0x80080
	v_lshl_add_u64 v[218:219], v[220:221], 0, s[8:9]
	s_addc_u32 s35, s35, 0
	s_add_i32 s46, s63, s30
	global_load_lds_dwordx4 v[218:219], off
	v_lshl_add_u64 v[218:219], s[34:35], 0, v[134:135]
	s_mov_b32 m0, s46
	s_nop 0
	global_load_lds_dwordx4 v[218:219], off
	v_lshl_add_u64 v[218:219], s[34:35], 0, v[130:131]
	s_add_i32 m0, s46, 0x2000
	s_nop 0
	global_load_lds_dwordx4 v[218:219], off
	v_lshl_add_u64 v[218:219], v[222:223], 0, s[8:9]
	s_mov_b32 m0, s54
	s_nop 0
	global_load_lds_dwordx4 v[218:219], off
	v_lshl_add_u64 v[218:219], v[224:225], 0, s[8:9]
	s_mov_b32 m0, s55
	s_nop 0
	global_load_lds_dwordx4 v[218:219], off
	s_waitcnt vmcnt(8)
	s_waitcnt lgkmcnt(0)
	s_barrier
	s_setprio 1
	s_waitcnt lgkmcnt(0)
	v_mfma_f32_16x16x32_bf16 v[62:65], v[146:149], v[184:187], v[62:65]
	v_mfma_f32_16x16x32_bf16 v[46:49], v[146:149], v[192:195], v[46:49]
	v_mfma_f32_16x16x32_bf16 v[30:33], v[146:149], v[200:203], v[30:33]
	v_mfma_f32_16x16x32_bf16 v[14:17], v[146:149], v[208:211], v[14:17]
	v_mfma_f32_16x16x32_bf16 v[6:9], v[160:163], v[208:211], v[6:9]
	v_mfma_f32_16x16x32_bf16 v[22:25], v[160:163], v[200:203], v[22:25]
	v_mfma_f32_16x16x32_bf16 v[38:41], v[160:163], v[192:195], v[38:41]
	v_mfma_f32_16x16x32_bf16 v[54:57], v[160:163], v[184:187], v[54:57]
	v_mfma_f32_16x16x32_bf16 v[62:65], v[156:159], v[188:191], v[62:65]
	v_mfma_f32_16x16x32_bf16 v[46:49], v[156:159], v[196:199], v[46:49]
	v_mfma_f32_16x16x32_bf16 v[30:33], v[156:159], v[204:207], v[30:33]
	v_mfma_f32_16x16x32_bf16 v[14:17], v[156:159], v[212:215], v[14:17]
	v_mfma_f32_16x16x32_bf16 v[6:9], v[164:167], v[212:215], v[6:9]
	v_mfma_f32_16x16x32_bf16 v[22:25], v[164:167], v[204:207], v[22:25]
	v_mfma_f32_16x16x32_bf16 v[38:41], v[164:167], v[196:199], v[38:41]
	v_mfma_f32_16x16x32_bf16 v[54:57], v[164:167], v[188:191], v[54:57]
	s_setprio 0
	s_setprio 1
	v_mfma_f32_16x16x32_bf16 v[58:61], v[168:171], v[184:187], v[58:61]
	v_mfma_f32_16x16x32_bf16 v[42:45], v[168:171], v[192:195], v[42:45]
	v_mfma_f32_16x16x32_bf16 v[26:29], v[168:171], v[200:203], v[26:29]
	v_mfma_f32_16x16x32_bf16 v[10:13], v[168:171], v[208:211], v[10:13]
	v_mfma_f32_16x16x32_bf16 v[2:5], v[176:179], v[208:211], v[2:5]
	v_mfma_f32_16x16x32_bf16 v[18:21], v[176:179], v[200:203], v[18:21]
	v_mfma_f32_16x16x32_bf16 v[34:37], v[176:179], v[192:195], v[34:37]
	v_mfma_f32_16x16x32_bf16 v[50:53], v[176:179], v[184:187], v[50:53]
	v_mfma_f32_16x16x32_bf16 v[58:61], v[172:175], v[188:191], v[58:61]
	v_mfma_f32_16x16x32_bf16 v[42:45], v[172:175], v[196:199], v[42:45]
	v_mfma_f32_16x16x32_bf16 v[26:29], v[172:175], v[204:207], v[26:29]
	v_mfma_f32_16x16x32_bf16 v[10:13], v[172:175], v[212:215], v[10:13]
	v_mfma_f32_16x16x32_bf16 v[2:5], v[180:183], v[212:215], v[2:5]
	v_mfma_f32_16x16x32_bf16 v[18:21], v[180:183], v[204:207], v[18:21]
	v_mfma_f32_16x16x32_bf16 v[34:37], v[180:183], v[196:199], v[34:37]
	v_mfma_f32_16x16x32_bf16 v[50:53], v[180:183], v[188:191], v[50:53]
	s_setprio 0
	s_barrier
	s_add_i32 s69, s69, 2
	s_add_u32 s44, s44, 0x100
	s_addc_u32 s45, s45, 0
	s_add_u32 s61, s61, 0x100
	s_addc_u32 s68, s68, 0
	s_cmp_gt_u32 s69, 29
	s_cbranch_scc0 .LBB0_3309
	v_mov_b32_e32 v160, 0xbfb8aa3b
	s_and_b64 vcc, exec, s[24:25]
	s_cbranch_vccz .LBB0_3312
	s_barrier

.LBB0_3533:
	ds_read_b128 v[154:157], v151
	ds_read_b128 v[158:161], v151 offset:1024
	ds_read_b128 v[162:165], v151 offset:2048
	ds_read_b128 v[166:169], v151 offset:3072
	ds_read_b128 v[170:173], v152
	ds_read_b128 v[174:177], v152 offset:1024
	ds_read_b128 v[178:181], v152 offset:2048
	ds_read_b128 v[182:185], v152 offset:3072
	s_add_u32 s34, s44, 0xfff80080
	s_addc_u32 s35, s45, -1
	s_cmp_eq_u32 s68, 28
	s_cselect_b32 s47, s0, s35
	s_cselect_b32 s46, s1, s34
	s_cselect_b32 s35, s27, s61
	s_cselect_b32 s34, s37, s60
	v_lshl_add_u64 v[146:147], s[44:45], 0, v[138:139]
	s_add_i32 m0, s33, 0xc000
	ds_read_b128 v[186:189], v153
	ds_read_b128 v[190:193], v153 offset:1024
	ds_read_b128 v[194:197], v153 offset:2048
	ds_read_b128 v[198:201], v153 offset:3072
	ds_read_b128 v[202:205], v153 offset:4096
	ds_read_b128 v[206:209], v153 offset:5120
	ds_read_b128 v[210:213], v153 offset:6144
	ds_read_b128 v[218:221], v153 offset:7168
	global_load_lds_dwordx4 v[146:147], off
	v_lshl_add_u64 v[146:147], s[44:45], 0, v[140:141]
	s_add_i32 m0, s33, 0xe000
	s_nop 0
	global_load_lds_dwordx4 v[146:147], off
	s_waitcnt vmcnt(8)
	s_waitcnt lgkmcnt(0)
	s_barrier
	s_setprio 1
	s_waitcnt lgkmcnt(0)
	v_mfma_f32_16x16x32_bf16 v[126:129], v[154:157], v[186:189], v[126:129]
	v_mfma_f32_16x16x32_bf16 v[114:117], v[154:157], v[194:197], v[114:117]
	v_mfma_f32_16x16x32_bf16 v[98:101], v[154:157], v[202:205], v[98:101]
	v_mfma_f32_16x16x32_bf16 v[82:85], v[154:157], v[210:213], v[82:85]
	v_mfma_f32_16x16x32_bf16 v[74:77], v[162:165], v[210:213], v[74:77]
	v_mfma_f32_16x16x32_bf16 v[90:93], v[162:165], v[202:205], v[90:93]
	v_mfma_f32_16x16x32_bf16 v[106:109], v[162:165], v[194:197], v[106:109]
	v_mfma_f32_16x16x32_bf16 v[122:125], v[162:165], v[186:189], v[122:125]
	v_mfma_f32_16x16x32_bf16 v[126:129], v[158:161], v[190:193], v[126:129]
	v_mfma_f32_16x16x32_bf16 v[114:117], v[158:161], v[198:201], v[114:117]
	v_mfma_f32_16x16x32_bf16 v[98:101], v[158:161], v[206:209], v[98:101]
	v_mfma_f32_16x16x32_bf16 v[82:85], v[158:161], v[218:221], v[82:85]
	v_mfma_f32_16x16x32_bf16 v[74:77], v[166:169], v[218:221], v[74:77]
	v_mfma_f32_16x16x32_bf16 v[90:93], v[166:169], v[206:209], v[90:93]
	v_mfma_f32_16x16x32_bf16 v[106:109], v[166:169], v[198:201], v[106:109]
	v_mfma_f32_16x16x32_bf16 v[122:125], v[166:169], v[190:193], v[122:125]
	s_setprio 0
	s_setprio 1
	v_mfma_f32_16x16x32_bf16 v[118:121], v[170:173], v[186:189], v[118:121]
	v_mfma_f32_16x16x32_bf16 v[102:105], v[170:173], v[194:197], v[102:105]
	v_mfma_f32_16x16x32_bf16 v[86:89], v[170:173], v[202:205], v[86:89]
	v_mfma_f32_16x16x32_bf16 v[70:73], v[170:173], v[210:213], v[70:73]
	v_mfma_f32_16x16x32_bf16 v[66:69], v[178:181], v[210:213], v[66:69]
	v_mfma_f32_16x16x32_bf16 v[78:81], v[178:181], v[202:205], v[78:81]
	v_mfma_f32_16x16x32_bf16 v[94:97], v[178:181], v[194:197], v[94:97]
	v_mfma_f32_16x16x32_bf16 v[110:113], v[178:181], v[186:189], v[110:113]
	v_mfma_f32_16x16x32_bf16 v[118:121], v[174:177], v[190:193], v[118:121]
	v_mfma_f32_16x16x32_bf16 v[102:105], v[174:177], v[198:201], v[102:105]
	v_mfma_f32_16x16x32_bf16 v[86:89], v[174:177], v[206:209], v[86:89]
	v_mfma_f32_16x16x32_bf16 v[70:73], v[174:177], v[218:221], v[70:73]
	v_mfma_f32_16x16x32_bf16 v[66:69], v[182:185], v[218:221], v[66:69]
	v_mfma_f32_16x16x32_bf16 v[78:81], v[182:185], v[206:209], v[78:81]
	v_mfma_f32_16x16x32_bf16 v[94:97], v[182:185], v[198:201], v[94:97]
	v_mfma_f32_16x16x32_bf16 v[110:113], v[182:185], v[190:193], v[110:113]
	s_setprio 0
	s_barrier
	s_add_i32 s62, s56, s12
	v_lshl_add_u64 v[146:147], s[34:35], 0, v[134:135]
	s_mov_b32 m0, s62
	ds_read_b128 v[186:189], v153 offset:16384
	ds_read_b128 v[190:193], v153 offset:17408
	ds_read_b128 v[194:197], v153 offset:18432
	ds_read_b128 v[198:201], v153 offset:19456
	ds_read_b128 v[202:205], v153 offset:20480
	ds_read_b128 v[206:209], v153 offset:21504
	ds_read_b128 v[210:213], v153 offset:22528
	ds_read_b128 v[218:221], v153 offset:23552
	global_load_lds_dwordx4 v[146:147], off
	s_add_i32 m0, s62, 0x2000
	s_add_u32 s62, s34, 0x80000
	v_lshl_add_u64 v[214:215], s[34:35], 0, v[130:131]
	s_addc_u32 s63, s35, 0
	s_add_i32 s66, s57, s12
	global_load_lds_dwordx4 v[214:215], off
	v_lshl_add_u64 v[222:223], s[62:63], 0, v[134:135]
	s_mov_b32 m0, s66
	v_lshl_add_u64 v[224:225], s[46:47], 0, v[132:133]
	global_load_lds_dwordx4 v[222:223], off
	v_lshl_add_u64 v[222:223], s[62:63], 0, v[130:131]
	s_add_i32 m0, s66, 0x2000
	s_nop 0
	global_load_lds_dwordx4 v[222:223], off
	v_lshl_add_u64 v[222:223], s[46:47], 0, v[136:137]
	s_mov_b32 m0, s33
	s_nop 0
	global_load_lds_dwordx4 v[222:223], off
	s_mov_b32 m0, s43
	s_nop 0
	global_load_lds_dwordx4 v[224:225], off
	s_waitcnt vmcnt(8)
	s_waitcnt lgkmcnt(0)
	s_barrier
	s_setprio 1
	s_waitcnt lgkmcnt(0)
	v_mfma_f32_16x16x32_bf16 v[62:65], v[154:157], v[186:189], v[62:65]
	v_mfma_f32_16x16x32_bf16 v[50:53], v[154:157], v[194:197], v[50:53]
	v_mfma_f32_16x16x32_bf16 v[34:37], v[154:157], v[202:205], v[34:37]
	v_mfma_f32_16x16x32_bf16 v[18:21], v[154:157], v[210:213], v[18:21]
	v_mfma_f32_16x16x32_bf16 v[10:13], v[162:165], v[210:213], v[10:13]
	v_mfma_f32_16x16x32_bf16 v[26:29], v[162:165], v[202:205], v[26:29]
	v_mfma_f32_16x16x32_bf16 v[42:45], v[162:165], v[194:197], v[42:45]
	v_mfma_f32_16x16x32_bf16 v[58:61], v[162:165], v[186:189], v[58:61]
	v_mfma_f32_16x16x32_bf16 v[62:65], v[158:161], v[190:193], v[62:65]
	v_mfma_f32_16x16x32_bf16 v[50:53], v[158:161], v[198:201], v[50:53]
	v_mfma_f32_16x16x32_bf16 v[34:37], v[158:161], v[206:209], v[34:37]
	v_mfma_f32_16x16x32_bf16 v[18:21], v[158:161], v[218:221], v[18:21]
	v_mfma_f32_16x16x32_bf16 v[10:13], v[166:169], v[218:221], v[10:13]
	v_mfma_f32_16x16x32_bf16 v[26:29], v[166:169], v[206:209], v[26:29]
	v_mfma_f32_16x16x32_bf16 v[42:45], v[166:169], v[198:201], v[42:45]
	v_mfma_f32_16x16x32_bf16 v[58:61], v[166:169], v[190:193], v[58:61]
	s_setprio 0
	s_setprio 1
	v_mfma_f32_16x16x32_bf16 v[54:57], v[170:173], v[186:189], v[54:57]
	v_mfma_f32_16x16x32_bf16 v[38:41], v[170:173], v[194:197], v[38:41]
	v_mfma_f32_16x16x32_bf16 v[22:25], v[170:173], v[202:205], v[22:25]
	v_mfma_f32_16x16x32_bf16 v[6:9], v[170:173], v[210:213], v[6:9]
	v_mfma_f32_16x16x32_bf16 v[2:5], v[178:181], v[210:213], v[2:5]
	v_mfma_f32_16x16x32_bf16 v[14:17], v[178:181], v[202:205], v[14:17]
	v_mfma_f32_16x16x32_bf16 v[30:33], v[178:181], v[194:197], v[30:33]
	v_mfma_f32_16x16x32_bf16 v[46:49], v[178:181], v[186:189], v[46:49]
	v_mfma_f32_16x16x32_bf16 v[54:57], v[174:177], v[190:193], v[54:57]
	v_mfma_f32_16x16x32_bf16 v[38:41], v[174:177], v[198:201], v[38:41]
	v_mfma_f32_16x16x32_bf16 v[22:25], v[174:177], v[206:209], v[22:25]
	v_mfma_f32_16x16x32_bf16 v[6:9], v[174:177], v[218:221], v[6:9]
	v_mfma_f32_16x16x32_bf16 v[2:5], v[182:185], v[218:221], v[2:5]
	v_mfma_f32_16x16x32_bf16 v[14:17], v[182:185], v[206:209], v[14:17]
	v_mfma_f32_16x16x32_bf16 v[30:33], v[182:185], v[198:201], v[30:33]
	v_mfma_f32_16x16x32_bf16 v[46:49], v[182:185], v[190:193], v[46:49]
	s_setprio 0
	s_barrier
	s_add_i32 s62, 0, 0x18000
	s_add_i32 s63, 0, 0x1c000
	v_add_u32_e32 v166, s62, v149
	v_add_u32_e32 v182, s63, v149
	ds_read_b128 v[154:157], v166
	ds_read_b128 v[158:161], v166 offset:1024
	ds_read_b128 v[162:165], v166 offset:2048
	ds_read_b128 v[166:169], v166 offset:3072
	ds_read_b128 v[170:173], v182
	ds_read_b128 v[174:177], v182 offset:1024
	ds_read_b128 v[178:181], v182 offset:2048
	ds_read_b128 v[182:185], v182 offset:3072
	s_add_u32 s46, s46, 0x80000
	s_addc_u32 s47, s47, 0
	s_mov_b32 m0, s48
	v_lshl_add_u64 v[226:227], s[46:47], 0, v[136:137]
	ds_read_b128 v[186:189], v153 offset:32768
	ds_read_b128 v[190:193], v153 offset:33792
	ds_read_b128 v[194:197], v153 offset:34816
	ds_read_b128 v[198:201], v153 offset:35840
	ds_read_b128 v[202:205], v153 offset:36864
	ds_read_b128 v[206:209], v153 offset:37888
	ds_read_b128 v[210:213], v153 offset:38912
	ds_read_b128 v[218:221], v153 offset:39936
	global_load_lds_dwordx4 v[226:227], off
	v_lshl_add_u64 v[226:227], s[46:47], 0, v[132:133]
	s_mov_b32 m0, s49
	s_nop 0
	global_load_lds_dwordx4 v[226:227], off
	s_waitcnt vmcnt(8)
	s_waitcnt lgkmcnt(0)
	s_barrier
	s_setprio 1
	s_waitcnt lgkmcnt(0)
	v_mfma_f32_16x16x32_bf16 v[126:129], v[154:157], v[186:189], v[126:129]
	v_mfma_f32_16x16x32_bf16 v[114:117], v[154:157], v[194:197], v[114:117]
	v_mfma_f32_16x16x32_bf16 v[98:101], v[154:157], v[202:205], v[98:101]
	v_mfma_f32_16x16x32_bf16 v[82:85], v[154:157], v[210:213], v[82:85]
	v_mfma_f32_16x16x32_bf16 v[74:77], v[162:165], v[210:213], v[74:77]
	v_mfma_f32_16x16x32_bf16 v[90:93], v[162:165], v[202:205], v[90:93]
	v_mfma_f32_16x16x32_bf16 v[106:109], v[162:165], v[194:197], v[106:109]
	v_mfma_f32_16x16x32_bf16 v[122:125], v[162:165], v[186:189], v[122:125]
	v_mfma_f32_16x16x32_bf16 v[126:129], v[158:161], v[190:193], v[126:129]
	v_mfma_f32_16x16x32_bf16 v[114:117], v[158:161], v[198:201], v[114:117]
	v_mfma_f32_16x16x32_bf16 v[98:101], v[158:161], v[206:209], v[98:101]
	v_mfma_f32_16x16x32_bf16 v[82:85], v[158:161], v[218:221], v[82:85]
	v_mfma_f32_16x16x32_bf16 v[74:77], v[166:169], v[218:221], v[74:77]
	v_mfma_f32_16x16x32_bf16 v[90:93], v[166:169], v[206:209], v[90:93]
	v_mfma_f32_16x16x32_bf16 v[106:109], v[166:169], v[198:201], v[106:109]
	v_mfma_f32_16x16x32_bf16 v[122:125], v[166:169], v[190:193], v[122:125]
	s_setprio 0
	s_setprio 1
	v_mfma_f32_16x16x32_bf16 v[118:121], v[170:173], v[186:189], v[118:121]
	v_mfma_f32_16x16x32_bf16 v[102:105], v[170:173], v[194:197], v[102:105]
	v_mfma_f32_16x16x32_bf16 v[86:89], v[170:173], v[202:205], v[86:89]
	v_mfma_f32_16x16x32_bf16 v[70:73], v[170:173], v[210:213], v[70:73]
	v_mfma_f32_16x16x32_bf16 v[66:69], v[178:181], v[210:213], v[66:69]
	v_mfma_f32_16x16x32_bf16 v[78:81], v[178:181], v[202:205], v[78:81]
	v_mfma_f32_16x16x32_bf16 v[94:97], v[178:181], v[194:197], v[94:97]
	v_mfma_f32_16x16x32_bf16 v[110:113], v[178:181], v[186:189], v[110:113]
	v_mfma_f32_16x16x32_bf16 v[118:121], v[174:177], v[190:193], v[118:121]
	v_mfma_f32_16x16x32_bf16 v[102:105], v[174:177], v[198:201], v[102:105]
	v_mfma_f32_16x16x32_bf16 v[86:89], v[174:177], v[206:209], v[86:89]
	v_mfma_f32_16x16x32_bf16 v[70:73], v[174:177], v[218:221], v[70:73]
	v_mfma_f32_16x16x32_bf16 v[66:69], v[182:185], v[218:221], v[66:69]
	v_mfma_f32_16x16x32_bf16 v[78:81], v[182:185], v[206:209], v[78:81]
	v_mfma_f32_16x16x32_bf16 v[94:97], v[182:185], v[198:201], v[94:97]
	v_mfma_f32_16x16x32_bf16 v[110:113], v[182:185], v[190:193], v[110:113]
	s_setprio 0
	s_barrier
	s_add_i32 s46, s62, s12
	v_lshl_add_u64 v[146:147], v[146:147], 0, s[8:9]
	s_mov_b32 m0, s46
	ds_read_b128 v[186:189], v153 offset:49152
	ds_read_b128 v[190:193], v153 offset:50176
	ds_read_b128 v[194:197], v153 offset:51200
	ds_read_b128 v[198:201], v153 offset:52224
	ds_read_b128 v[202:205], v153 offset:53248
	ds_read_b128 v[206:209], v153 offset:54272
	ds_read_b128 v[210:213], v153 offset:55296
	ds_read_b128 v[218:221], v153 offset:56320
	global_load_lds_dwordx4 v[146:147], off
	s_add_i32 m0, s46, 0x2000
	s_add_u32 s34, s34, 0x80080
	v_lshl_add_u64 v[146:147], v[214:215], 0, s[8:9]
	s_addc_u32 s35, s35, 0
	s_add_i32 s46, s63, s12
	global_load_lds_dwordx4 v[146:147], off
	v_lshl_add_u64 v[146:147], s[34:35], 0, v[134:135]
	s_mov_b32 m0, s46
	s_nop 0
	global_load_lds_dwordx4 v[146:147], off
	v_lshl_add_u64 v[146:147], s[34:35], 0, v[130:131]
	s_add_i32 m0, s46, 0x2000
	s_nop 0
	global_load_lds_dwordx4 v[146:147], off
	v_lshl_add_u64 v[146:147], v[222:223], 0, s[8:9]
	s_mov_b32 m0, s53
	s_nop 0
	global_load_lds_dwordx4 v[146:147], off
	v_lshl_add_u64 v[146:147], v[224:225], 0, s[8:9]
	s_mov_b32 m0, s54
	s_nop 0
	global_load_lds_dwordx4 v[146:147], off
	s_waitcnt vmcnt(8)
	s_waitcnt lgkmcnt(0)
	s_barrier
	s_setprio 1
	s_waitcnt lgkmcnt(0)
	v_mfma_f32_16x16x32_bf16 v[62:65], v[154:157], v[186:189], v[62:65]
	v_mfma_f32_16x16x32_bf16 v[50:53], v[154:157], v[194:197], v[50:53]
	v_mfma_f32_16x16x32_bf16 v[34:37], v[154:157], v[202:205], v[34:37]
	v_mfma_f32_16x16x32_bf16 v[18:21], v[154:157], v[210:213], v[18:21]
	v_mfma_f32_16x16x32_bf16 v[10:13], v[162:165], v[210:213], v[10:13]
	v_mfma_f32_16x16x32_bf16 v[26:29], v[162:165], v[202:205], v[26:29]
	v_mfma_f32_16x16x32_bf16 v[42:45], v[162:165], v[194:197], v[42:45]
	v_mfma_f32_16x16x32_bf16 v[58:61], v[162:165], v[186:189], v[58:61]
	v_mfma_f32_16x16x32_bf16 v[62:65], v[158:161], v[190:193], v[62:65]
	v_mfma_f32_16x16x32_bf16 v[50:53], v[158:161], v[198:201], v[50:53]
	v_mfma_f32_16x16x32_bf16 v[34:37], v[158:161], v[206:209], v[34:37]
	v_mfma_f32_16x16x32_bf16 v[18:21], v[158:161], v[218:221], v[18:21]
	v_mfma_f32_16x16x32_bf16 v[10:13], v[166:169], v[218:221], v[10:13]
	v_mfma_f32_16x16x32_bf16 v[26:29], v[166:169], v[206:209], v[26:29]
	v_mfma_f32_16x16x32_bf16 v[42:45], v[166:169], v[198:201], v[42:45]
	v_mfma_f32_16x16x32_bf16 v[58:61], v[166:169], v[190:193], v[58:61]
	s_setprio 0
	s_setprio 1
	v_mfma_f32_16x16x32_bf16 v[54:57], v[170:173], v[186:189], v[54:57]
	v_mfma_f32_16x16x32_bf16 v[38:41], v[170:173], v[194:197], v[38:41]
	v_mfma_f32_16x16x32_bf16 v[22:25], v[170:173], v[202:205], v[22:25]
	v_mfma_f32_16x16x32_bf16 v[6:9], v[170:173], v[210:213], v[6:9]
	v_mfma_f32_16x16x32_bf16 v[2:5], v[178:181], v[210:213], v[2:5]
	v_mfma_f32_16x16x32_bf16 v[14:17], v[178:181], v[202:205], v[14:17]
	v_mfma_f32_16x16x32_bf16 v[30:33], v[178:181], v[194:197], v[30:33]
	v_mfma_f32_16x16x32_bf16 v[46:49], v[178:181], v[186:189], v[46:49]
	v_mfma_f32_16x16x32_bf16 v[54:57], v[174:177], v[190:193], v[54:57]
	v_mfma_f32_16x16x32_bf16 v[38:41], v[174:177], v[198:201], v[38:41]
	v_mfma_f32_16x16x32_bf16 v[22:25], v[174:177], v[206:209], v[22:25]
	v_mfma_f32_16x16x32_bf16 v[6:9], v[174:177], v[218:221], v[6:9]
	v_mfma_f32_16x16x32_bf16 v[2:5], v[182:185], v[218:221], v[2:5]
	v_mfma_f32_16x16x32_bf16 v[14:17], v[182:185], v[206:209], v[14:17]
	v_mfma_f32_16x16x32_bf16 v[30:33], v[182:185], v[198:201], v[30:33]
	v_mfma_f32_16x16x32_bf16 v[46:49], v[182:185], v[190:193], v[46:49]
	s_setprio 0
	s_barrier
	s_add_i32 s68, s68, 2
	s_add_u32 s44, s44, 0x100
	s_addc_u32 s45, s45, 0
	s_add_u32 s60, s60, 0x100
	s_addc_u32 s61, s61, 0
	s_cmp_gt_u32 s68, 29
	s_cbranch_scc0 .LBB0_3533
	s_and_b64 vcc, exec, s[24:25]
	s_cbranch_vccz .LBB0_3536
	s_barrier

.LBB0_3706:
	ds_read_b128 v[130:133], v174
	ds_read_b128 v[134:137], v174 offset:1024
	ds_read_b128 v[138:141], v174 offset:2048
	ds_read_b128 v[158:161], v174 offset:3072
	ds_read_b128 v[162:165], v175
	ds_read_b128 v[166:169], v175 offset:1024
	ds_read_b128 v[178:181], v175 offset:2048
	ds_read_b128 v[182:185], v175 offset:3072
	s_add_u32 s34, s42, 0xfff80080
	s_addc_u32 s35, s43, -1
	s_cmp_eq_u32 s60, 28
	s_cselect_b32 s45, s0, s35
	s_cselect_b32 s44, s1, s34
	s_cselect_b32 s35, s25, s59
	s_cselect_b32 s34, s27, s58
	v_lshl_add_u64 v[170:171], s[42:43], 0, v[150:151]
	s_add_i32 m0, s41, 0xc000
	ds_read_b128 v[186:189], v176
	ds_read_b128 v[190:193], v176 offset:1024
	ds_read_b128 v[194:197], v176 offset:2048
	ds_read_b128 v[198:201], v176 offset:3072
	ds_read_b128 v[202:205], v176 offset:4096
	ds_read_b128 v[206:209], v176 offset:5120
	ds_read_b128 v[210:213], v176 offset:6144
	ds_read_b128 v[218:221], v176 offset:7168
	global_load_lds_dwordx4 v[170:171], off
	v_lshl_add_u64 v[170:171], s[42:43], 0, v[152:153]
	s_add_i32 m0, s41, 0xe000
	s_nop 0
	global_load_lds_dwordx4 v[170:171], off
	s_waitcnt vmcnt(8)
	s_waitcnt lgkmcnt(0)
	s_barrier
	s_setprio 1
	s_waitcnt lgkmcnt(0)
	v_mfma_f32_16x16x32_bf16 v[126:129], v[130:133], v[186:189], v[126:129]
	v_mfma_f32_16x16x32_bf16 v[110:113], v[130:133], v[194:197], v[110:113]
	v_mfma_f32_16x16x32_bf16 v[94:97], v[130:133], v[202:205], v[94:97]
	v_mfma_f32_16x16x32_bf16 v[78:81], v[130:133], v[210:213], v[78:81]
	v_mfma_f32_16x16x32_bf16 v[74:77], v[138:141], v[210:213], v[74:77]
	v_mfma_f32_16x16x32_bf16 v[90:93], v[138:141], v[202:205], v[90:93]
	v_mfma_f32_16x16x32_bf16 v[106:109], v[138:141], v[194:197], v[106:109]
	v_mfma_f32_16x16x32_bf16 v[122:125], v[138:141], v[186:189], v[122:125]
	v_mfma_f32_16x16x32_bf16 v[126:129], v[134:137], v[190:193], v[126:129]
	v_mfma_f32_16x16x32_bf16 v[110:113], v[134:137], v[198:201], v[110:113]
	v_mfma_f32_16x16x32_bf16 v[94:97], v[134:137], v[206:209], v[94:97]
	v_mfma_f32_16x16x32_bf16 v[78:81], v[134:137], v[218:221], v[78:81]
	v_mfma_f32_16x16x32_bf16 v[74:77], v[158:161], v[218:221], v[74:77]
	v_mfma_f32_16x16x32_bf16 v[90:93], v[158:161], v[206:209], v[90:93]
	v_mfma_f32_16x16x32_bf16 v[106:109], v[158:161], v[198:201], v[106:109]
	v_mfma_f32_16x16x32_bf16 v[122:125], v[158:161], v[190:193], v[122:125]
	s_setprio 0
	s_setprio 1
	v_mfma_f32_16x16x32_bf16 v[118:121], v[162:165], v[186:189], v[118:121]
	v_mfma_f32_16x16x32_bf16 v[102:105], v[162:165], v[194:197], v[102:105]
	v_mfma_f32_16x16x32_bf16 v[86:89], v[162:165], v[202:205], v[86:89]
	v_mfma_f32_16x16x32_bf16 v[70:73], v[162:165], v[210:213], v[70:73]
	v_mfma_f32_16x16x32_bf16 v[66:69], v[178:181], v[210:213], v[66:69]
	v_mfma_f32_16x16x32_bf16 v[82:85], v[178:181], v[202:205], v[82:85]
	v_mfma_f32_16x16x32_bf16 v[98:101], v[178:181], v[194:197], v[98:101]
	v_mfma_f32_16x16x32_bf16 v[114:117], v[178:181], v[186:189], v[114:117]
	v_mfma_f32_16x16x32_bf16 v[118:121], v[166:169], v[190:193], v[118:121]
	v_mfma_f32_16x16x32_bf16 v[102:105], v[166:169], v[198:201], v[102:105]
	v_mfma_f32_16x16x32_bf16 v[86:89], v[166:169], v[206:209], v[86:89]
	v_mfma_f32_16x16x32_bf16 v[70:73], v[166:169], v[218:221], v[70:73]
	v_mfma_f32_16x16x32_bf16 v[66:69], v[182:185], v[218:221], v[66:69]
	v_mfma_f32_16x16x32_bf16 v[82:85], v[182:185], v[206:209], v[82:85]
	v_mfma_f32_16x16x32_bf16 v[98:101], v[182:185], v[198:201], v[98:101]
	v_mfma_f32_16x16x32_bf16 v[114:117], v[182:185], v[190:193], v[114:117]
	s_setprio 0
	s_barrier
	s_add_i32 s61, s54, s46
	v_lshl_add_u64 v[170:171], s[34:35], 0, v[144:145]
	s_mov_b32 m0, s61
	ds_read_b128 v[186:189], v176 offset:16384
	ds_read_b128 v[190:193], v176 offset:17408
	ds_read_b128 v[194:197], v176 offset:18432
	ds_read_b128 v[198:201], v176 offset:19456
	ds_read_b128 v[202:205], v176 offset:20480
	ds_read_b128 v[206:209], v176 offset:21504
	ds_read_b128 v[210:213], v176 offset:22528
	ds_read_b128 v[218:221], v176 offset:23552
	global_load_lds_dwordx4 v[170:171], off
	s_add_i32 m0, s61, 0x2000
	s_add_u32 s62, s34, 0x80000
	v_lshl_add_u64 v[214:215], s[34:35], 0, v[148:149]
	s_addc_u32 s63, s35, 0
	s_add_i32 s61, s55, s46
	global_load_lds_dwordx4 v[214:215], off
	v_lshl_add_u64 v[222:223], s[62:63], 0, v[144:145]
	s_mov_b32 m0, s61
	v_lshl_add_u64 v[224:225], s[44:45], 0, v[146:147]
	global_load_lds_dwordx4 v[222:223], off
	v_lshl_add_u64 v[222:223], s[62:63], 0, v[148:149]
	s_add_i32 m0, s61, 0x2000
	s_nop 0
	global_load_lds_dwordx4 v[222:223], off
	v_lshl_add_u64 v[222:223], s[44:45], 0, v[142:143]
	s_mov_b32 m0, s41
	s_nop 0
	global_load_lds_dwordx4 v[222:223], off
	s_mov_b32 m0, s47
	s_nop 0
	global_load_lds_dwordx4 v[224:225], off
	s_waitcnt vmcnt(8)
	s_waitcnt lgkmcnt(0)
	s_barrier
	s_setprio 1
	s_waitcnt lgkmcnt(0)
	v_mfma_f32_16x16x32_bf16 v[62:65], v[130:133], v[186:189], v[62:65]
	v_mfma_f32_16x16x32_bf16 v[50:53], v[130:133], v[194:197], v[50:53]
	v_mfma_f32_16x16x32_bf16 v[38:41], v[130:133], v[202:205], v[38:41]
	v_mfma_f32_16x16x32_bf16 v[14:17], v[130:133], v[210:213], v[14:17]
	v_mfma_f32_16x16x32_bf16 v[10:13], v[138:141], v[210:213], v[10:13]
	v_mfma_f32_16x16x32_bf16 v[34:37], v[138:141], v[202:205], v[34:37]
	v_mfma_f32_16x16x32_bf16 v[42:45], v[138:141], v[194:197], v[42:45]
	v_mfma_f32_16x16x32_bf16 v[58:61], v[138:141], v[186:189], v[58:61]
	v_mfma_f32_16x16x32_bf16 v[62:65], v[134:137], v[190:193], v[62:65]
	v_mfma_f32_16x16x32_bf16 v[50:53], v[134:137], v[198:201], v[50:53]
	v_mfma_f32_16x16x32_bf16 v[38:41], v[134:137], v[206:209], v[38:41]
	v_mfma_f32_16x16x32_bf16 v[14:17], v[134:137], v[218:221], v[14:17]
	v_mfma_f32_16x16x32_bf16 v[10:13], v[158:161], v[218:221], v[10:13]
	v_mfma_f32_16x16x32_bf16 v[34:37], v[158:161], v[206:209], v[34:37]
	v_mfma_f32_16x16x32_bf16 v[42:45], v[158:161], v[198:201], v[42:45]
	v_mfma_f32_16x16x32_bf16 v[58:61], v[158:161], v[190:193], v[58:61]
	s_setprio 0
	s_setprio 1
	v_mfma_f32_16x16x32_bf16 v[54:57], v[162:165], v[186:189], v[54:57]
	v_mfma_f32_16x16x32_bf16 v[30:33], v[162:165], v[194:197], v[30:33]
	v_mfma_f32_16x16x32_bf16 v[22:25], v[162:165], v[202:205], v[22:25]
	v_mfma_f32_16x16x32_bf16 v[6:9], v[162:165], v[210:213], v[6:9]
	v_mfma_f32_16x16x32_bf16 v[2:5], v[178:181], v[210:213], v[2:5]
	v_mfma_f32_16x16x32_bf16 v[18:21], v[178:181], v[202:205], v[18:21]
	v_mfma_f32_16x16x32_bf16 v[26:29], v[178:181], v[194:197], v[26:29]
	v_mfma_f32_16x16x32_bf16 v[46:49], v[178:181], v[186:189], v[46:49]
	v_mfma_f32_16x16x32_bf16 v[54:57], v[166:169], v[190:193], v[54:57]
	v_mfma_f32_16x16x32_bf16 v[30:33], v[166:169], v[198:201], v[30:33]
	v_mfma_f32_16x16x32_bf16 v[22:25], v[166:169], v[206:209], v[22:25]
	v_mfma_f32_16x16x32_bf16 v[6:9], v[166:169], v[218:221], v[6:9]
	v_mfma_f32_16x16x32_bf16 v[2:5], v[182:185], v[218:221], v[2:5]
	v_mfma_f32_16x16x32_bf16 v[18:21], v[182:185], v[206:209], v[18:21]
	v_mfma_f32_16x16x32_bf16 v[26:29], v[182:185], v[198:201], v[26:29]
	v_mfma_f32_16x16x32_bf16 v[46:49], v[182:185], v[190:193], v[46:49]
	s_setprio 0
	s_barrier
	s_add_i32 s61, 0, 0x18000
	s_add_i32 s62, 0, 0x1c000
	v_add_u32_e32 v158, s61, v172
	v_add_u32_e32 v177, s62, v172
	ds_read_b128 v[130:133], v158
	ds_read_b128 v[134:137], v158 offset:1024
	ds_read_b128 v[138:141], v158 offset:2048
	ds_read_b128 v[158:161], v158 offset:3072
	ds_read_b128 v[162:165], v177
	ds_read_b128 v[166:169], v177 offset:1024
	ds_read_b128 v[178:181], v177 offset:2048
	ds_read_b128 v[182:185], v177 offset:3072
	s_add_u32 s44, s44, 0x80000
	s_addc_u32 s45, s45, 0
	s_mov_b32 m0, s48
	v_lshl_add_u64 v[226:227], s[44:45], 0, v[142:143]
	ds_read_b128 v[186:189], v176 offset:32768
	ds_read_b128 v[190:193], v176 offset:33792
	ds_read_b128 v[194:197], v176 offset:34816
	ds_read_b128 v[198:201], v176 offset:35840
	ds_read_b128 v[202:205], v176 offset:36864
	ds_read_b128 v[206:209], v176 offset:37888
	ds_read_b128 v[210:213], v176 offset:38912
	ds_read_b128 v[218:221], v176 offset:39936
	global_load_lds_dwordx4 v[226:227], off
	v_lshl_add_u64 v[226:227], s[44:45], 0, v[146:147]
	s_mov_b32 m0, s49
	s_nop 0
	global_load_lds_dwordx4 v[226:227], off
	s_waitcnt vmcnt(8)
	s_waitcnt lgkmcnt(0)
	s_barrier
	s_setprio 1
	s_waitcnt lgkmcnt(0)
	v_mfma_f32_16x16x32_bf16 v[126:129], v[130:133], v[186:189], v[126:129]
	v_mfma_f32_16x16x32_bf16 v[110:113], v[130:133], v[194:197], v[110:113]
	v_mfma_f32_16x16x32_bf16 v[94:97], v[130:133], v[202:205], v[94:97]
	v_mfma_f32_16x16x32_bf16 v[78:81], v[130:133], v[210:213], v[78:81]
	v_mfma_f32_16x16x32_bf16 v[74:77], v[138:141], v[210:213], v[74:77]
	v_mfma_f32_16x16x32_bf16 v[90:93], v[138:141], v[202:205], v[90:93]
	v_mfma_f32_16x16x32_bf16 v[106:109], v[138:141], v[194:197], v[106:109]
	v_mfma_f32_16x16x32_bf16 v[122:125], v[138:141], v[186:189], v[122:125]
	v_mfma_f32_16x16x32_bf16 v[126:129], v[134:137], v[190:193], v[126:129]
	v_mfma_f32_16x16x32_bf16 v[110:113], v[134:137], v[198:201], v[110:113]
	v_mfma_f32_16x16x32_bf16 v[94:97], v[134:137], v[206:209], v[94:97]
	v_mfma_f32_16x16x32_bf16 v[78:81], v[134:137], v[218:221], v[78:81]
	v_mfma_f32_16x16x32_bf16 v[74:77], v[158:161], v[218:221], v[74:77]
	v_mfma_f32_16x16x32_bf16 v[90:93], v[158:161], v[206:209], v[90:93]
	v_mfma_f32_16x16x32_bf16 v[106:109], v[158:161], v[198:201], v[106:109]
	v_mfma_f32_16x16x32_bf16 v[122:125], v[158:161], v[190:193], v[122:125]
	s_setprio 0
	s_setprio 1
	v_mfma_f32_16x16x32_bf16 v[118:121], v[162:165], v[186:189], v[118:121]
	v_mfma_f32_16x16x32_bf16 v[102:105], v[162:165], v[194:197], v[102:105]
	v_mfma_f32_16x16x32_bf16 v[86:89], v[162:165], v[202:205], v[86:89]
	v_mfma_f32_16x16x32_bf16 v[70:73], v[162:165], v[210:213], v[70:73]
	v_mfma_f32_16x16x32_bf16 v[66:69], v[178:181], v[210:213], v[66:69]
	v_mfma_f32_16x16x32_bf16 v[82:85], v[178:181], v[202:205], v[82:85]
	v_mfma_f32_16x16x32_bf16 v[98:101], v[178:181], v[194:197], v[98:101]
	v_mfma_f32_16x16x32_bf16 v[114:117], v[178:181], v[186:189], v[114:117]
	v_mfma_f32_16x16x32_bf16 v[118:121], v[166:169], v[190:193], v[118:121]
	v_mfma_f32_16x16x32_bf16 v[102:105], v[166:169], v[198:201], v[102:105]
	v_mfma_f32_16x16x32_bf16 v[86:89], v[166:169], v[206:209], v[86:89]
	v_mfma_f32_16x16x32_bf16 v[70:73], v[166:169], v[218:221], v[70:73]
	v_mfma_f32_16x16x32_bf16 v[66:69], v[182:185], v[218:221], v[66:69]
	v_mfma_f32_16x16x32_bf16 v[82:85], v[182:185], v[206:209], v[82:85]
	v_mfma_f32_16x16x32_bf16 v[98:101], v[182:185], v[198:201], v[98:101]
	v_mfma_f32_16x16x32_bf16 v[114:117], v[182:185], v[190:193], v[114:117]
	s_setprio 0
	s_barrier
	s_add_i32 s44, s61, s46
	v_lshl_add_u64 v[170:171], v[170:171], 0, s[12:13]
	s_mov_b32 m0, s44
	ds_read_b128 v[186:189], v176 offset:49152
	ds_read_b128 v[190:193], v176 offset:50176
	ds_read_b128 v[194:197], v176 offset:51200
	ds_read_b128 v[198:201], v176 offset:52224
	ds_read_b128 v[202:205], v176 offset:53248
	ds_read_b128 v[206:209], v176 offset:54272
	ds_read_b128 v[210:213], v176 offset:55296
	ds_read_b128 v[218:221], v176 offset:56320
	global_load_lds_dwordx4 v[170:171], off
	s_add_i32 m0, s44, 0x2000
	s_add_u32 s34, s34, 0x80080
	v_lshl_add_u64 v[170:171], v[214:215], 0, s[12:13]
	s_addc_u32 s35, s35, 0
	s_add_i32 s44, s62, s46
	global_load_lds_dwordx4 v[170:171], off
	v_lshl_add_u64 v[170:171], s[34:35], 0, v[144:145]
	s_mov_b32 m0, s44
	s_nop 0
	global_load_lds_dwordx4 v[170:171], off
	v_lshl_add_u64 v[170:171], s[34:35], 0, v[148:149]
	s_add_i32 m0, s44, 0x2000
	s_nop 0
	global_load_lds_dwordx4 v[170:171], off
	v_lshl_add_u64 v[170:171], v[222:223], 0, s[12:13]
	s_mov_b32 m0, s51
	s_nop 0
	global_load_lds_dwordx4 v[170:171], off
	v_lshl_add_u64 v[170:171], v[224:225], 0, s[12:13]
	s_mov_b32 m0, s52
	s_nop 0
	global_load_lds_dwordx4 v[170:171], off
	s_waitcnt vmcnt(8)
	s_waitcnt lgkmcnt(0)
	s_barrier
	s_setprio 1
	s_waitcnt lgkmcnt(0)
	v_mfma_f32_16x16x32_bf16 v[62:65], v[130:133], v[186:189], v[62:65]
	v_mfma_f32_16x16x32_bf16 v[50:53], v[130:133], v[194:197], v[50:53]
	v_mfma_f32_16x16x32_bf16 v[38:41], v[130:133], v[202:205], v[38:41]
	v_mfma_f32_16x16x32_bf16 v[14:17], v[130:133], v[210:213], v[14:17]
	v_mfma_f32_16x16x32_bf16 v[10:13], v[138:141], v[210:213], v[10:13]
	v_mfma_f32_16x16x32_bf16 v[34:37], v[138:141], v[202:205], v[34:37]
	v_mfma_f32_16x16x32_bf16 v[42:45], v[138:141], v[194:197], v[42:45]
	v_mfma_f32_16x16x32_bf16 v[58:61], v[138:141], v[186:189], v[58:61]
	v_mfma_f32_16x16x32_bf16 v[62:65], v[134:137], v[190:193], v[62:65]
	v_mfma_f32_16x16x32_bf16 v[50:53], v[134:137], v[198:201], v[50:53]
	v_mfma_f32_16x16x32_bf16 v[38:41], v[134:137], v[206:209], v[38:41]
	v_mfma_f32_16x16x32_bf16 v[14:17], v[134:137], v[218:221], v[14:17]
	v_mfma_f32_16x16x32_bf16 v[10:13], v[158:161], v[218:221], v[10:13]
	v_mfma_f32_16x16x32_bf16 v[34:37], v[158:161], v[206:209], v[34:37]
	v_mfma_f32_16x16x32_bf16 v[42:45], v[158:161], v[198:201], v[42:45]
	v_mfma_f32_16x16x32_bf16 v[58:61], v[158:161], v[190:193], v[58:61]
	s_setprio 0
	s_setprio 1
	v_mfma_f32_16x16x32_bf16 v[54:57], v[162:165], v[186:189], v[54:57]
	v_mfma_f32_16x16x32_bf16 v[30:33], v[162:165], v[194:197], v[30:33]
	v_mfma_f32_16x16x32_bf16 v[22:25], v[162:165], v[202:205], v[22:25]
	v_mfma_f32_16x16x32_bf16 v[6:9], v[162:165], v[210:213], v[6:9]
	v_mfma_f32_16x16x32_bf16 v[2:5], v[178:181], v[210:213], v[2:5]
	v_mfma_f32_16x16x32_bf16 v[18:21], v[178:181], v[202:205], v[18:21]
	v_mfma_f32_16x16x32_bf16 v[26:29], v[178:181], v[194:197], v[26:29]
	v_mfma_f32_16x16x32_bf16 v[46:49], v[178:181], v[186:189], v[46:49]
	v_mfma_f32_16x16x32_bf16 v[54:57], v[166:169], v[190:193], v[54:57]
	v_mfma_f32_16x16x32_bf16 v[30:33], v[166:169], v[198:201], v[30:33]
	v_mfma_f32_16x16x32_bf16 v[22:25], v[166:169], v[206:209], v[22:25]
	v_mfma_f32_16x16x32_bf16 v[6:9], v[166:169], v[218:221], v[6:9]
	v_mfma_f32_16x16x32_bf16 v[2:5], v[182:185], v[218:221], v[2:5]
	v_mfma_f32_16x16x32_bf16 v[18:21], v[182:185], v[206:209], v[18:21]
	v_mfma_f32_16x16x32_bf16 v[26:29], v[182:185], v[198:201], v[26:29]
	v_mfma_f32_16x16x32_bf16 v[46:49], v[182:185], v[190:193], v[46:49]
	s_setprio 0
	s_barrier
	s_add_i32 s60, s60, 2
	s_add_u32 s42, s42, 0x100
	s_addc_u32 s43, s43, 0
	s_add_u32 s58, s58, 0x100
	s_addc_u32 s59, s59, 0
	s_cmp_gt_u32 s60, 29
	s_cbranch_scc0 .LBB0_3706
	s_and_b64 vcc, exec, s[14:15]
	s_cbranch_vccz .LBB0_3709
	s_barrier

.LBB0_3835:
	ds_read_b128 v[146:149], v153
	ds_read_b128 v[156:159], v153 offset:1024
	ds_read_b128 v[160:163], v153 offset:2048
	ds_read_b128 v[164:167], v153 offset:3072
	ds_read_b128 v[168:171], v154
	ds_read_b128 v[172:175], v154 offset:1024
	ds_read_b128 v[176:179], v154 offset:2048
	ds_read_b128 v[180:183], v154 offset:3072
	s_add_u32 s34, s38, 0xfff80080
	s_addc_u32 s35, s39, -1
	s_cmp_eq_u32 s57, 28
	s_cselect_b32 s41, s0, s35
	s_cselect_b32 s40, s1, s34
	s_cselect_b32 s35, s15, s56
	s_cselect_b32 s34, s17, s55
	v_lshl_add_u64 v[218:219], s[38:39], 0, v[138:139]
	s_add_i32 m0, s37, 0xc000
	ds_read_b128 v[184:187], v155
	ds_read_b128 v[188:191], v155 offset:1024
	ds_read_b128 v[192:195], v155 offset:2048
	ds_read_b128 v[196:199], v155 offset:3072
	ds_read_b128 v[200:203], v155 offset:4096
	ds_read_b128 v[204:207], v155 offset:5120
	ds_read_b128 v[208:211], v155 offset:6144
	ds_read_b128 v[212:215], v155 offset:7168
	global_load_lds_dwordx4 v[218:219], off
	v_lshl_add_u64 v[218:219], s[38:39], 0, v[140:141]
	s_add_i32 m0, s37, 0xe000
	s_nop 0
	global_load_lds_dwordx4 v[218:219], off
	s_waitcnt vmcnt(8)
	s_waitcnt lgkmcnt(0)
	s_barrier
	s_setprio 1
	s_waitcnt lgkmcnt(0)
	v_mfma_f32_16x16x32_bf16 v[126:129], v[146:149], v[184:187], v[126:129]
	v_mfma_f32_16x16x32_bf16 v[110:113], v[146:149], v[192:195], v[110:113]
	v_mfma_f32_16x16x32_bf16 v[94:97], v[146:149], v[200:203], v[94:97]
	v_mfma_f32_16x16x32_bf16 v[78:81], v[146:149], v[208:211], v[78:81]
	v_mfma_f32_16x16x32_bf16 v[70:73], v[160:163], v[208:211], v[70:73]
	v_mfma_f32_16x16x32_bf16 v[86:89], v[160:163], v[200:203], v[86:89]
	v_mfma_f32_16x16x32_bf16 v[102:105], v[160:163], v[192:195], v[102:105]
	v_mfma_f32_16x16x32_bf16 v[118:121], v[160:163], v[184:187], v[118:121]
	v_mfma_f32_16x16x32_bf16 v[126:129], v[156:159], v[188:191], v[126:129]
	v_mfma_f32_16x16x32_bf16 v[110:113], v[156:159], v[196:199], v[110:113]
	v_mfma_f32_16x16x32_bf16 v[94:97], v[156:159], v[204:207], v[94:97]
	v_mfma_f32_16x16x32_bf16 v[78:81], v[156:159], v[212:215], v[78:81]
	v_mfma_f32_16x16x32_bf16 v[70:73], v[164:167], v[212:215], v[70:73]
	v_mfma_f32_16x16x32_bf16 v[86:89], v[164:167], v[204:207], v[86:89]
	v_mfma_f32_16x16x32_bf16 v[102:105], v[164:167], v[196:199], v[102:105]
	v_mfma_f32_16x16x32_bf16 v[118:121], v[164:167], v[188:191], v[118:121]
	s_setprio 0
	s_setprio 1
	v_mfma_f32_16x16x32_bf16 v[122:125], v[168:171], v[184:187], v[122:125]
	v_mfma_f32_16x16x32_bf16 v[106:109], v[168:171], v[192:195], v[106:109]
	v_mfma_f32_16x16x32_bf16 v[90:93], v[168:171], v[200:203], v[90:93]
	v_mfma_f32_16x16x32_bf16 v[74:77], v[168:171], v[208:211], v[74:77]
	v_mfma_f32_16x16x32_bf16 v[66:69], v[176:179], v[208:211], v[66:69]
	v_mfma_f32_16x16x32_bf16 v[82:85], v[176:179], v[200:203], v[82:85]
	v_mfma_f32_16x16x32_bf16 v[98:101], v[176:179], v[192:195], v[98:101]
	v_mfma_f32_16x16x32_bf16 v[114:117], v[176:179], v[184:187], v[114:117]
	v_mfma_f32_16x16x32_bf16 v[122:125], v[172:175], v[188:191], v[122:125]
	v_mfma_f32_16x16x32_bf16 v[106:109], v[172:175], v[196:199], v[106:109]
	v_mfma_f32_16x16x32_bf16 v[90:93], v[172:175], v[204:207], v[90:93]
	v_mfma_f32_16x16x32_bf16 v[74:77], v[172:175], v[212:215], v[74:77]
	v_mfma_f32_16x16x32_bf16 v[66:69], v[180:183], v[212:215], v[66:69]
	v_mfma_f32_16x16x32_bf16 v[82:85], v[180:183], v[204:207], v[82:85]
	v_mfma_f32_16x16x32_bf16 v[98:101], v[180:183], v[196:199], v[98:101]
	v_mfma_f32_16x16x32_bf16 v[114:117], v[180:183], v[188:191], v[114:117]
	s_setprio 0
	s_barrier
	s_add_i32 s58, s51, s33
	v_lshl_add_u64 v[218:219], s[34:35], 0, v[134:135]
	s_mov_b32 m0, s58
	ds_read_b128 v[184:187], v155 offset:16384
	ds_read_b128 v[188:191], v155 offset:17408
	ds_read_b128 v[192:195], v155 offset:18432
	ds_read_b128 v[196:199], v155 offset:19456
	ds_read_b128 v[200:203], v155 offset:20480
	ds_read_b128 v[204:207], v155 offset:21504
	ds_read_b128 v[208:211], v155 offset:22528
	ds_read_b128 v[212:215], v155 offset:23552
	global_load_lds_dwordx4 v[218:219], off
	s_add_i32 m0, s58, 0x2000
	s_add_u32 s58, s34, 0x80000
	v_lshl_add_u64 v[220:221], s[34:35], 0, v[130:131]
	s_addc_u32 s59, s35, 0
	s_add_i32 s60, s52, s33
	global_load_lds_dwordx4 v[220:221], off
	v_lshl_add_u64 v[222:223], s[58:59], 0, v[134:135]
	s_mov_b32 m0, s60
	v_lshl_add_u64 v[224:225], s[40:41], 0, v[132:133]
	global_load_lds_dwordx4 v[222:223], off
	v_lshl_add_u64 v[222:223], s[58:59], 0, v[130:131]
	s_add_i32 m0, s60, 0x2000
	s_nop 0
	global_load_lds_dwordx4 v[222:223], off
	v_lshl_add_u64 v[222:223], s[40:41], 0, v[136:137]
	s_mov_b32 m0, s37
	s_nop 0
	global_load_lds_dwordx4 v[222:223], off
	s_mov_b32 m0, s44
	s_nop 0
	global_load_lds_dwordx4 v[224:225], off
	s_waitcnt vmcnt(8)
	s_waitcnt lgkmcnt(0)
	s_barrier
	s_setprio 1
	s_waitcnt lgkmcnt(0)
	v_mfma_f32_16x16x32_bf16 v[62:65], v[146:149], v[184:187], v[62:65]
	v_mfma_f32_16x16x32_bf16 v[46:49], v[146:149], v[192:195], v[46:49]
	v_mfma_f32_16x16x32_bf16 v[30:33], v[146:149], v[200:203], v[30:33]
	v_mfma_f32_16x16x32_bf16 v[14:17], v[146:149], v[208:211], v[14:17]
	v_mfma_f32_16x16x32_bf16 v[6:9], v[160:163], v[208:211], v[6:9]
	v_mfma_f32_16x16x32_bf16 v[22:25], v[160:163], v[200:203], v[22:25]
	v_mfma_f32_16x16x32_bf16 v[38:41], v[160:163], v[192:195], v[38:41]
	v_mfma_f32_16x16x32_bf16 v[54:57], v[160:163], v[184:187], v[54:57]
	v_mfma_f32_16x16x32_bf16 v[62:65], v[156:159], v[188:191], v[62:65]
	v_mfma_f32_16x16x32_bf16 v[46:49], v[156:159], v[196:199], v[46:49]
	v_mfma_f32_16x16x32_bf16 v[30:33], v[156:159], v[204:207], v[30:33]
	v_mfma_f32_16x16x32_bf16 v[14:17], v[156:159], v[212:215], v[14:17]
	v_mfma_f32_16x16x32_bf16 v[6:9], v[164:167], v[212:215], v[6:9]
	v_mfma_f32_16x16x32_bf16 v[22:25], v[164:167], v[204:207], v[22:25]
	v_mfma_f32_16x16x32_bf16 v[38:41], v[164:167], v[196:199], v[38:41]
	v_mfma_f32_16x16x32_bf16 v[54:57], v[164:167], v[188:191], v[54:57]
	s_setprio 0
	s_setprio 1
	v_mfma_f32_16x16x32_bf16 v[58:61], v[168:171], v[184:187], v[58:61]
	v_mfma_f32_16x16x32_bf16 v[42:45], v[168:171], v[192:195], v[42:45]
	v_mfma_f32_16x16x32_bf16 v[26:29], v[168:171], v[200:203], v[26:29]
	v_mfma_f32_16x16x32_bf16 v[10:13], v[168:171], v[208:211], v[10:13]
	v_mfma_f32_16x16x32_bf16 v[2:5], v[176:179], v[208:211], v[2:5]
	v_mfma_f32_16x16x32_bf16 v[18:21], v[176:179], v[200:203], v[18:21]
	v_mfma_f32_16x16x32_bf16 v[34:37], v[176:179], v[192:195], v[34:37]
	v_mfma_f32_16x16x32_bf16 v[50:53], v[176:179], v[184:187], v[50:53]
	v_mfma_f32_16x16x32_bf16 v[58:61], v[172:175], v[188:191], v[58:61]
	v_mfma_f32_16x16x32_bf16 v[42:45], v[172:175], v[196:199], v[42:45]
	v_mfma_f32_16x16x32_bf16 v[26:29], v[172:175], v[204:207], v[26:29]
	v_mfma_f32_16x16x32_bf16 v[10:13], v[172:175], v[212:215], v[10:13]
	v_mfma_f32_16x16x32_bf16 v[2:5], v[180:183], v[212:215], v[2:5]
	v_mfma_f32_16x16x32_bf16 v[18:21], v[180:183], v[204:207], v[18:21]
	v_mfma_f32_16x16x32_bf16 v[34:37], v[180:183], v[196:199], v[34:37]
	v_mfma_f32_16x16x32_bf16 v[50:53], v[180:183], v[188:191], v[50:53]
	s_setprio 0
	s_barrier
	s_add_i32 s58, 0, 0x18000
	s_add_i32 s59, 0, 0x1c000
	v_add_u32_e32 v164, s58, v151
	v_add_u32_e32 v180, s59, v151
	ds_read_b128 v[146:149], v164
	ds_read_b128 v[156:159], v164 offset:1024
	ds_read_b128 v[160:163], v164 offset:2048
	ds_read_b128 v[164:167], v164 offset:3072
	ds_read_b128 v[168:171], v180
	ds_read_b128 v[172:175], v180 offset:1024
	ds_read_b128 v[176:179], v180 offset:2048
	ds_read_b128 v[180:183], v180 offset:3072
	s_add_u32 s40, s40, 0x80000
	s_addc_u32 s41, s41, 0
	s_mov_b32 m0, s45
	v_lshl_add_u64 v[226:227], s[40:41], 0, v[136:137]
	ds_read_b128 v[184:187], v155 offset:32768
	ds_read_b128 v[188:191], v155 offset:33792
	ds_read_b128 v[192:195], v155 offset:34816
	ds_read_b128 v[196:199], v155 offset:35840
	ds_read_b128 v[200:203], v155 offset:36864
	ds_read_b128 v[204:207], v155 offset:37888
	ds_read_b128 v[208:211], v155 offset:38912
	ds_read_b128 v[212:215], v155 offset:39936
	global_load_lds_dwordx4 v[226:227], off
	v_lshl_add_u64 v[226:227], s[40:41], 0, v[132:133]
	s_mov_b32 m0, s46
	s_nop 0
	global_load_lds_dwordx4 v[226:227], off
	s_waitcnt vmcnt(8)
	s_waitcnt lgkmcnt(0)
	s_barrier
	s_setprio 1
	s_waitcnt lgkmcnt(0)
	v_mfma_f32_16x16x32_bf16 v[126:129], v[146:149], v[184:187], v[126:129]
	v_mfma_f32_16x16x32_bf16 v[110:113], v[146:149], v[192:195], v[110:113]
	v_mfma_f32_16x16x32_bf16 v[94:97], v[146:149], v[200:203], v[94:97]
	v_mfma_f32_16x16x32_bf16 v[78:81], v[146:149], v[208:211], v[78:81]
	v_mfma_f32_16x16x32_bf16 v[70:73], v[160:163], v[208:211], v[70:73]
	v_mfma_f32_16x16x32_bf16 v[86:89], v[160:163], v[200:203], v[86:89]
	v_mfma_f32_16x16x32_bf16 v[102:105], v[160:163], v[192:195], v[102:105]
	v_mfma_f32_16x16x32_bf16 v[118:121], v[160:163], v[184:187], v[118:121]
	v_mfma_f32_16x16x32_bf16 v[126:129], v[156:159], v[188:191], v[126:129]
	v_mfma_f32_16x16x32_bf16 v[110:113], v[156:159], v[196:199], v[110:113]
	v_mfma_f32_16x16x32_bf16 v[94:97], v[156:159], v[204:207], v[94:97]
	v_mfma_f32_16x16x32_bf16 v[78:81], v[156:159], v[212:215], v[78:81]
	v_mfma_f32_16x16x32_bf16 v[70:73], v[164:167], v[212:215], v[70:73]
	v_mfma_f32_16x16x32_bf16 v[86:89], v[164:167], v[204:207], v[86:89]
	v_mfma_f32_16x16x32_bf16 v[102:105], v[164:167], v[196:199], v[102:105]
	v_mfma_f32_16x16x32_bf16 v[118:121], v[164:167], v[188:191], v[118:121]
	s_setprio 0
	s_setprio 1
	v_mfma_f32_16x16x32_bf16 v[122:125], v[168:171], v[184:187], v[122:125]
	v_mfma_f32_16x16x32_bf16 v[106:109], v[168:171], v[192:195], v[106:109]
	v_mfma_f32_16x16x32_bf16 v[90:93], v[168:171], v[200:203], v[90:93]
	v_mfma_f32_16x16x32_bf16 v[74:77], v[168:171], v[208:211], v[74:77]
	v_mfma_f32_16x16x32_bf16 v[66:69], v[176:179], v[208:211], v[66:69]
	v_mfma_f32_16x16x32_bf16 v[82:85], v[176:179], v[200:203], v[82:85]
	v_mfma_f32_16x16x32_bf16 v[98:101], v[176:179], v[192:195], v[98:101]
	v_mfma_f32_16x16x32_bf16 v[114:117], v[176:179], v[184:187], v[114:117]
	v_mfma_f32_16x16x32_bf16 v[122:125], v[172:175], v[188:191], v[122:125]
	v_mfma_f32_16x16x32_bf16 v[106:109], v[172:175], v[196:199], v[106:109]
	v_mfma_f32_16x16x32_bf16 v[90:93], v[172:175], v[204:207], v[90:93]
	v_mfma_f32_16x16x32_bf16 v[74:77], v[172:175], v[212:215], v[74:77]
	v_mfma_f32_16x16x32_bf16 v[66:69], v[180:183], v[212:215], v[66:69]
	v_mfma_f32_16x16x32_bf16 v[82:85], v[180:183], v[204:207], v[82:85]
	v_mfma_f32_16x16x32_bf16 v[98:101], v[180:183], v[196:199], v[98:101]
	v_mfma_f32_16x16x32_bf16 v[114:117], v[180:183], v[188:191], v[114:117]
	s_setprio 0
	s_barrier
	s_add_i32 s40, s58, s33
	v_lshl_add_u64 v[218:219], v[218:219], 0, s[8:9]
	s_mov_b32 m0, s40
	ds_read_b128 v[184:187], v155 offset:49152
	ds_read_b128 v[188:191], v155 offset:50176
	ds_read_b128 v[192:195], v155 offset:51200
	ds_read_b128 v[196:199], v155 offset:52224
	ds_read_b128 v[200:203], v155 offset:53248
	ds_read_b128 v[204:207], v155 offset:54272
	ds_read_b128 v[208:211], v155 offset:55296
	ds_read_b128 v[212:215], v155 offset:56320
	global_load_lds_dwordx4 v[218:219], off
	s_add_i32 m0, s40, 0x2000
	s_add_u32 s34, s34, 0x80080
	v_lshl_add_u64 v[218:219], v[220:221], 0, s[8:9]
	s_addc_u32 s35, s35, 0
	s_add_i32 s40, s59, s33
	global_load_lds_dwordx4 v[218:219], off
	v_lshl_add_u64 v[218:219], s[34:35], 0, v[134:135]
	s_mov_b32 m0, s40
	s_nop 0
	global_load_lds_dwordx4 v[218:219], off
	v_lshl_add_u64 v[218:219], s[34:35], 0, v[130:131]
	s_add_i32 m0, s40, 0x2000
	s_nop 0
	global_load_lds_dwordx4 v[218:219], off
	v_lshl_add_u64 v[218:219], v[222:223], 0, s[8:9]
	s_mov_b32 m0, s48
	s_nop 0
	global_load_lds_dwordx4 v[218:219], off
	v_lshl_add_u64 v[218:219], v[224:225], 0, s[8:9]
	s_mov_b32 m0, s49
	s_nop 0
	global_load_lds_dwordx4 v[218:219], off
	s_waitcnt vmcnt(8)
	s_waitcnt lgkmcnt(0)
	s_barrier
	s_setprio 1
	s_waitcnt lgkmcnt(0)
	v_mfma_f32_16x16x32_bf16 v[62:65], v[146:149], v[184:187], v[62:65]
	v_mfma_f32_16x16x32_bf16 v[46:49], v[146:149], v[192:195], v[46:49]
	v_mfma_f32_16x16x32_bf16 v[30:33], v[146:149], v[200:203], v[30:33]
	v_mfma_f32_16x16x32_bf16 v[14:17], v[146:149], v[208:211], v[14:17]
	v_mfma_f32_16x16x32_bf16 v[6:9], v[160:163], v[208:211], v[6:9]
	v_mfma_f32_16x16x32_bf16 v[22:25], v[160:163], v[200:203], v[22:25]
	v_mfma_f32_16x16x32_bf16 v[38:41], v[160:163], v[192:195], v[38:41]
	v_mfma_f32_16x16x32_bf16 v[54:57], v[160:163], v[184:187], v[54:57]
	v_mfma_f32_16x16x32_bf16 v[62:65], v[156:159], v[188:191], v[62:65]
	v_mfma_f32_16x16x32_bf16 v[46:49], v[156:159], v[196:199], v[46:49]
	v_mfma_f32_16x16x32_bf16 v[30:33], v[156:159], v[204:207], v[30:33]
	v_mfma_f32_16x16x32_bf16 v[14:17], v[156:159], v[212:215], v[14:17]
	v_mfma_f32_16x16x32_bf16 v[6:9], v[164:167], v[212:215], v[6:9]
	v_mfma_f32_16x16x32_bf16 v[22:25], v[164:167], v[204:207], v[22:25]
	v_mfma_f32_16x16x32_bf16 v[38:41], v[164:167], v[196:199], v[38:41]
	v_mfma_f32_16x16x32_bf16 v[54:57], v[164:167], v[188:191], v[54:57]
	s_setprio 0
	s_setprio 1
	v_mfma_f32_16x16x32_bf16 v[58:61], v[168:171], v[184:187], v[58:61]
	v_mfma_f32_16x16x32_bf16 v[42:45], v[168:171], v[192:195], v[42:45]
	v_mfma_f32_16x16x32_bf16 v[26:29], v[168:171], v[200:203], v[26:29]
	v_mfma_f32_16x16x32_bf16 v[10:13], v[168:171], v[208:211], v[10:13]
	v_mfma_f32_16x16x32_bf16 v[2:5], v[176:179], v[208:211], v[2:5]
	v_mfma_f32_16x16x32_bf16 v[18:21], v[176:179], v[200:203], v[18:21]
	v_mfma_f32_16x16x32_bf16 v[34:37], v[176:179], v[192:195], v[34:37]
	v_mfma_f32_16x16x32_bf16 v[50:53], v[176:179], v[184:187], v[50:53]
	v_mfma_f32_16x16x32_bf16 v[58:61], v[172:175], v[188:191], v[58:61]
	v_mfma_f32_16x16x32_bf16 v[42:45], v[172:175], v[196:199], v[42:45]
	v_mfma_f32_16x16x32_bf16 v[26:29], v[172:175], v[204:207], v[26:29]
	v_mfma_f32_16x16x32_bf16 v[10:13], v[172:175], v[212:215], v[10:13]
	v_mfma_f32_16x16x32_bf16 v[2:5], v[180:183], v[212:215], v[2:5]
	v_mfma_f32_16x16x32_bf16 v[18:21], v[180:183], v[204:207], v[18:21]
	v_mfma_f32_16x16x32_bf16 v[34:37], v[180:183], v[196:199], v[34:37]
	v_mfma_f32_16x16x32_bf16 v[50:53], v[180:183], v[188:191], v[50:53]
	s_setprio 0
	s_barrier
	s_add_i32 s57, s57, 2
	s_add_u32 s38, s38, 0x100
	s_addc_u32 s39, s39, 0
	s_add_u32 s55, s55, 0x100
	s_addc_u32 s56, s56, 0
	s_cmp_gt_u32 s57, 29
	s_cbranch_scc0 .LBB0_3835
	v_mov_b32_e32 v160, 0xbfb8aa3b
	s_and_b64 vcc, exec, s[12:13]
	s_cbranch_vccz .LBB0_3838
	s_barrier

.LBB0_3930:
	ds_read_b128 v[144:147], v155
	ds_read_b128 v[148:151], v155 offset:1024
	ds_read_b128 v[158:161], v155 offset:2048
	ds_read_b128 v[162:165], v155 offset:3072
	ds_read_b128 v[166:169], v156
	ds_read_b128 v[170:173], v156 offset:1024
	ds_read_b128 v[174:177], v156 offset:2048
	ds_read_b128 v[178:181], v156 offset:3072
	s_add_u32 s20, s18, 0xffea0080
	s_addc_u32 s21, s19, -1
	s_cmpk_eq_i32 s45, 0x54
	s_cselect_b32 s23, s5, s21
	s_cselect_b32 s22, s4, s20
	s_cselect_b32 s21, s17, s1
	s_cselect_b32 s20, s16, s0
	v_lshl_add_u64 v[214:215], s[18:19], 0, v[136:137]
	s_add_i32 m0, s30, 0xc000
	ds_read_b128 v[182:185], v157
	ds_read_b128 v[186:189], v157 offset:1024
	ds_read_b128 v[190:193], v157 offset:2048
	ds_read_b128 v[194:197], v157 offset:3072
	ds_read_b128 v[198:201], v157 offset:4096
	ds_read_b128 v[202:205], v157 offset:5120
	ds_read_b128 v[206:209], v157 offset:6144
	ds_read_b128 v[210:213], v157 offset:7168
	global_load_lds_dwordx4 v[214:215], off
	v_lshl_add_u64 v[214:215], s[18:19], 0, v[138:139]
	s_add_i32 m0, s30, 0xe000
	s_nop 0
	global_load_lds_dwordx4 v[214:215], off
	s_waitcnt vmcnt(8)
	s_waitcnt lgkmcnt(0)
	s_barrier
	s_setprio 1
	s_waitcnt lgkmcnt(0)
	v_mfma_f32_16x16x32_bf16 v[124:127], v[144:147], v[182:185], v[124:127]
	v_mfma_f32_16x16x32_bf16 v[116:119], v[144:147], v[190:193], v[116:119]
	v_mfma_f32_16x16x32_bf16 v[92:95], v[144:147], v[198:201], v[92:95]
	v_mfma_f32_16x16x32_bf16 v[84:87], v[144:147], v[206:209], v[84:87]
	v_mfma_f32_16x16x32_bf16 v[80:83], v[158:161], v[206:209], v[80:83]
	v_mfma_f32_16x16x32_bf16 v[88:91], v[158:161], v[198:201], v[88:91]
	v_mfma_f32_16x16x32_bf16 v[112:115], v[158:161], v[190:193], v[112:115]
	v_mfma_f32_16x16x32_bf16 v[120:123], v[158:161], v[182:185], v[120:123]
	v_mfma_f32_16x16x32_bf16 v[124:127], v[148:151], v[186:189], v[124:127]
	v_mfma_f32_16x16x32_bf16 v[116:119], v[148:151], v[194:197], v[116:119]
	v_mfma_f32_16x16x32_bf16 v[92:95], v[148:151], v[202:205], v[92:95]
	v_mfma_f32_16x16x32_bf16 v[84:87], v[148:151], v[210:213], v[84:87]
	v_mfma_f32_16x16x32_bf16 v[80:83], v[162:165], v[210:213], v[80:83]
	v_mfma_f32_16x16x32_bf16 v[88:91], v[162:165], v[202:205], v[88:91]
	v_mfma_f32_16x16x32_bf16 v[112:115], v[162:165], v[194:197], v[112:115]
	v_mfma_f32_16x16x32_bf16 v[120:123], v[162:165], v[186:189], v[120:123]
	s_setprio 0
	s_setprio 1
	v_mfma_f32_16x16x32_bf16 v[108:111], v[166:169], v[182:185], v[108:111]
	v_mfma_f32_16x16x32_bf16 v[100:103], v[166:169], v[190:193], v[100:103]
	v_mfma_f32_16x16x32_bf16 v[76:79], v[166:169], v[198:201], v[76:79]
	v_mfma_f32_16x16x32_bf16 v[68:71], v[166:169], v[206:209], v[68:71]
	v_mfma_f32_16x16x32_bf16 v[64:67], v[174:177], v[206:209], v[64:67]
	v_mfma_f32_16x16x32_bf16 v[72:75], v[174:177], v[198:201], v[72:75]
	v_mfma_f32_16x16x32_bf16 v[96:99], v[174:177], v[190:193], v[96:99]
	v_mfma_f32_16x16x32_bf16 v[104:107], v[174:177], v[182:185], v[104:107]
	v_mfma_f32_16x16x32_bf16 v[108:111], v[170:173], v[186:189], v[108:111]
	v_mfma_f32_16x16x32_bf16 v[100:103], v[170:173], v[194:197], v[100:103]
	v_mfma_f32_16x16x32_bf16 v[76:79], v[170:173], v[202:205], v[76:79]
	v_mfma_f32_16x16x32_bf16 v[68:71], v[170:173], v[210:213], v[68:71]
	v_mfma_f32_16x16x32_bf16 v[64:67], v[178:181], v[210:213], v[64:67]
	v_mfma_f32_16x16x32_bf16 v[72:75], v[178:181], v[202:205], v[72:75]
	v_mfma_f32_16x16x32_bf16 v[96:99], v[178:181], v[194:197], v[96:99]
	v_mfma_f32_16x16x32_bf16 v[104:107], v[178:181], v[186:189], v[104:107]
	s_setprio 0
	s_barrier
	s_add_i32 s46, s39, s27
	v_lshl_add_u64 v[214:215], s[20:21], 0, v[130:131]
	s_mov_b32 m0, s46
	ds_read_b128 v[182:185], v157 offset:16384
	ds_read_b128 v[186:189], v157 offset:17408
	ds_read_b128 v[190:193], v157 offset:18432
	ds_read_b128 v[194:197], v157 offset:19456
	ds_read_b128 v[198:201], v157 offset:20480
	ds_read_b128 v[202:205], v157 offset:21504
	ds_read_b128 v[206:209], v157 offset:22528
	ds_read_b128 v[210:213], v157 offset:23552
	global_load_lds_dwordx4 v[214:215], off
	s_add_i32 m0, s46, 0x2000
	s_add_u32 s46, s20, 0x160000
	v_lshl_add_u64 v[216:217], s[20:21], 0, v[134:135]
	s_addc_u32 s47, s21, 0
	s_add_i32 s48, s40, s27
	global_load_lds_dwordx4 v[216:217], off
	v_lshl_add_u64 v[218:219], s[46:47], 0, v[130:131]
	s_mov_b32 m0, s48
	v_lshl_add_u64 v[220:221], s[22:23], 0, v[132:133]
	global_load_lds_dwordx4 v[218:219], off
	v_lshl_add_u64 v[218:219], s[46:47], 0, v[134:135]
	s_add_i32 m0, s48, 0x2000
	s_nop 0
	global_load_lds_dwordx4 v[218:219], off
	v_lshl_add_u64 v[218:219], s[22:23], 0, v[128:129]
	s_mov_b32 m0, s30
	s_nop 0
	global_load_lds_dwordx4 v[218:219], off
	s_mov_b32 m0, s31
	s_nop 0
	global_load_lds_dwordx4 v[220:221], off
	s_waitcnt vmcnt(8)
	s_waitcnt lgkmcnt(0)
	s_barrier
	s_setprio 1
	s_waitcnt lgkmcnt(0)
	v_mfma_f32_16x16x32_bf16 v[60:63], v[144:147], v[182:185], v[60:63]
	v_mfma_f32_16x16x32_bf16 v[52:55], v[144:147], v[190:193], v[52:55]
	v_mfma_f32_16x16x32_bf16 v[28:31], v[144:147], v[198:201], v[28:31]
	v_mfma_f32_16x16x32_bf16 v[20:23], v[144:147], v[206:209], v[20:23]
	v_mfma_f32_16x16x32_bf16 v[16:19], v[158:161], v[206:209], v[16:19]
	v_mfma_f32_16x16x32_bf16 v[24:27], v[158:161], v[198:201], v[24:27]
	v_mfma_f32_16x16x32_bf16 v[48:51], v[158:161], v[190:193], v[48:51]
	v_mfma_f32_16x16x32_bf16 v[56:59], v[158:161], v[182:185], v[56:59]
	v_mfma_f32_16x16x32_bf16 v[60:63], v[148:151], v[186:189], v[60:63]
	v_mfma_f32_16x16x32_bf16 v[52:55], v[148:151], v[194:197], v[52:55]
	v_mfma_f32_16x16x32_bf16 v[28:31], v[148:151], v[202:205], v[28:31]
	v_mfma_f32_16x16x32_bf16 v[20:23], v[148:151], v[210:213], v[20:23]
	v_mfma_f32_16x16x32_bf16 v[16:19], v[162:165], v[210:213], v[16:19]
	v_mfma_f32_16x16x32_bf16 v[24:27], v[162:165], v[202:205], v[24:27]
	v_mfma_f32_16x16x32_bf16 v[48:51], v[162:165], v[194:197], v[48:51]
	v_mfma_f32_16x16x32_bf16 v[56:59], v[162:165], v[186:189], v[56:59]
	s_setprio 0
	s_setprio 1
	v_mfma_f32_16x16x32_bf16 v[44:47], v[166:169], v[182:185], v[44:47]
	v_mfma_f32_16x16x32_bf16 v[36:39], v[166:169], v[190:193], v[36:39]
	v_mfma_f32_16x16x32_bf16 v[12:15], v[166:169], v[198:201], v[12:15]
	v_mfma_f32_16x16x32_bf16 v[4:7], v[166:169], v[206:209], v[4:7]
	v_mfma_f32_16x16x32_bf16 v[0:3], v[174:177], v[206:209], v[0:3]
	v_mfma_f32_16x16x32_bf16 v[8:11], v[174:177], v[198:201], v[8:11]
	v_mfma_f32_16x16x32_bf16 v[32:35], v[174:177], v[190:193], v[32:35]
	v_mfma_f32_16x16x32_bf16 v[40:43], v[174:177], v[182:185], v[40:43]
	v_mfma_f32_16x16x32_bf16 v[44:47], v[170:173], v[186:189], v[44:47]
	v_mfma_f32_16x16x32_bf16 v[36:39], v[170:173], v[194:197], v[36:39]
	v_mfma_f32_16x16x32_bf16 v[12:15], v[170:173], v[202:205], v[12:15]
	v_mfma_f32_16x16x32_bf16 v[4:7], v[170:173], v[210:213], v[4:7]
	v_mfma_f32_16x16x32_bf16 v[0:3], v[178:181], v[210:213], v[0:3]
	v_mfma_f32_16x16x32_bf16 v[8:11], v[178:181], v[202:205], v[8:11]
	v_mfma_f32_16x16x32_bf16 v[32:35], v[178:181], v[194:197], v[32:35]
	v_mfma_f32_16x16x32_bf16 v[40:43], v[178:181], v[186:189], v[40:43]
	s_setprio 0
	s_barrier
	s_add_i32 s46, 0, 0x18000
	s_add_i32 s47, 0, 0x1c000
	v_add_u32_e32 v162, s46, v153
	v_add_u32_e32 v178, s47, v153
	ds_read_b128 v[144:147], v162
	ds_read_b128 v[148:151], v162 offset:1024
	ds_read_b128 v[158:161], v162 offset:2048
	ds_read_b128 v[162:165], v162 offset:3072
	ds_read_b128 v[166:169], v178
	ds_read_b128 v[170:173], v178 offset:1024
	ds_read_b128 v[174:177], v178 offset:2048
	ds_read_b128 v[178:181], v178 offset:3072
	s_add_u32 s22, s22, 0x160000
	s_addc_u32 s23, s23, 0
	s_mov_b32 m0, s33
	v_lshl_add_u64 v[222:223], s[22:23], 0, v[128:129]
	ds_read_b128 v[182:185], v157 offset:32768
	ds_read_b128 v[186:189], v157 offset:33792
	ds_read_b128 v[190:193], v157 offset:34816
	ds_read_b128 v[194:197], v157 offset:35840
	ds_read_b128 v[198:201], v157 offset:36864
	ds_read_b128 v[202:205], v157 offset:37888
	ds_read_b128 v[206:209], v157 offset:38912
	ds_read_b128 v[210:213], v157 offset:39936
	global_load_lds_dwordx4 v[222:223], off
	v_lshl_add_u64 v[222:223], s[22:23], 0, v[132:133]
	s_mov_b32 m0, s34
	s_nop 0
	global_load_lds_dwordx4 v[222:223], off
	s_waitcnt vmcnt(8)
	s_waitcnt lgkmcnt(0)
	s_barrier
	s_setprio 1
	s_waitcnt lgkmcnt(0)
	v_mfma_f32_16x16x32_bf16 v[124:127], v[144:147], v[182:185], v[124:127]
	v_mfma_f32_16x16x32_bf16 v[116:119], v[144:147], v[190:193], v[116:119]
	v_mfma_f32_16x16x32_bf16 v[92:95], v[144:147], v[198:201], v[92:95]
	v_mfma_f32_16x16x32_bf16 v[84:87], v[144:147], v[206:209], v[84:87]
	v_mfma_f32_16x16x32_bf16 v[80:83], v[158:161], v[206:209], v[80:83]
	v_mfma_f32_16x16x32_bf16 v[88:91], v[158:161], v[198:201], v[88:91]
	v_mfma_f32_16x16x32_bf16 v[112:115], v[158:161], v[190:193], v[112:115]
	v_mfma_f32_16x16x32_bf16 v[120:123], v[158:161], v[182:185], v[120:123]
	v_mfma_f32_16x16x32_bf16 v[124:127], v[148:151], v[186:189], v[124:127]
	v_mfma_f32_16x16x32_bf16 v[116:119], v[148:151], v[194:197], v[116:119]
	v_mfma_f32_16x16x32_bf16 v[92:95], v[148:151], v[202:205], v[92:95]
	v_mfma_f32_16x16x32_bf16 v[84:87], v[148:151], v[210:213], v[84:87]
	v_mfma_f32_16x16x32_bf16 v[80:83], v[162:165], v[210:213], v[80:83]
	v_mfma_f32_16x16x32_bf16 v[88:91], v[162:165], v[202:205], v[88:91]
	v_mfma_f32_16x16x32_bf16 v[112:115], v[162:165], v[194:197], v[112:115]
	v_mfma_f32_16x16x32_bf16 v[120:123], v[162:165], v[186:189], v[120:123]
	s_setprio 0
	s_setprio 1
	v_mfma_f32_16x16x32_bf16 v[108:111], v[166:169], v[182:185], v[108:111]
	v_mfma_f32_16x16x32_bf16 v[100:103], v[166:169], v[190:193], v[100:103]
	v_mfma_f32_16x16x32_bf16 v[76:79], v[166:169], v[198:201], v[76:79]
	v_mfma_f32_16x16x32_bf16 v[68:71], v[166:169], v[206:209], v[68:71]
	v_mfma_f32_16x16x32_bf16 v[64:67], v[174:177], v[206:209], v[64:67]
	v_mfma_f32_16x16x32_bf16 v[72:75], v[174:177], v[198:201], v[72:75]
	v_mfma_f32_16x16x32_bf16 v[96:99], v[174:177], v[190:193], v[96:99]
	v_mfma_f32_16x16x32_bf16 v[104:107], v[174:177], v[182:185], v[104:107]
	v_mfma_f32_16x16x32_bf16 v[108:111], v[170:173], v[186:189], v[108:111]
	v_mfma_f32_16x16x32_bf16 v[100:103], v[170:173], v[194:197], v[100:103]
	v_mfma_f32_16x16x32_bf16 v[76:79], v[170:173], v[202:205], v[76:79]
	v_mfma_f32_16x16x32_bf16 v[68:71], v[170:173], v[210:213], v[68:71]
	v_mfma_f32_16x16x32_bf16 v[64:67], v[178:181], v[210:213], v[64:67]
	v_mfma_f32_16x16x32_bf16 v[72:75], v[178:181], v[202:205], v[72:75]
	v_mfma_f32_16x16x32_bf16 v[96:99], v[178:181], v[194:197], v[96:99]
	v_mfma_f32_16x16x32_bf16 v[104:107], v[178:181], v[186:189], v[104:107]
	s_setprio 0
	s_barrier
	s_add_i32 s22, s46, s27
	v_lshl_add_u64 v[214:215], v[214:215], 0, s[12:13]
	s_mov_b32 m0, s22
	ds_read_b128 v[182:185], v157 offset:49152
	ds_read_b128 v[186:189], v157 offset:50176
	ds_read_b128 v[190:193], v157 offset:51200
	ds_read_b128 v[194:197], v157 offset:52224
	ds_read_b128 v[198:201], v157 offset:53248
	ds_read_b128 v[202:205], v157 offset:54272
	ds_read_b128 v[206:209], v157 offset:55296
	ds_read_b128 v[210:213], v157 offset:56320
	global_load_lds_dwordx4 v[214:215], off
	s_add_i32 m0, s22, 0x2000
	s_add_u32 s20, s20, 0x160080
	v_lshl_add_u64 v[214:215], v[216:217], 0, s[12:13]
	s_addc_u32 s21, s21, 0
	s_add_i32 s22, s47, s27
	global_load_lds_dwordx4 v[214:215], off
	v_lshl_add_u64 v[214:215], s[20:21], 0, v[130:131]
	s_mov_b32 m0, s22
	s_nop 0
	global_load_lds_dwordx4 v[214:215], off
	v_lshl_add_u64 v[214:215], s[20:21], 0, v[134:135]
	s_add_i32 m0, s22, 0x2000
	s_nop 0
	global_load_lds_dwordx4 v[214:215], off
	v_lshl_add_u64 v[214:215], v[218:219], 0, s[12:13]
	s_mov_b32 m0, s36
	s_nop 0
	global_load_lds_dwordx4 v[214:215], off
	v_lshl_add_u64 v[214:215], v[220:221], 0, s[12:13]
	s_mov_b32 m0, s37
	s_nop 0
	global_load_lds_dwordx4 v[214:215], off
	s_waitcnt vmcnt(8)
	s_waitcnt lgkmcnt(0)
	s_barrier
	s_setprio 1
	s_waitcnt lgkmcnt(0)
	v_mfma_f32_16x16x32_bf16 v[60:63], v[144:147], v[182:185], v[60:63]
	v_mfma_f32_16x16x32_bf16 v[52:55], v[144:147], v[190:193], v[52:55]
	v_mfma_f32_16x16x32_bf16 v[28:31], v[144:147], v[198:201], v[28:31]
	v_mfma_f32_16x16x32_bf16 v[20:23], v[144:147], v[206:209], v[20:23]
	v_mfma_f32_16x16x32_bf16 v[16:19], v[158:161], v[206:209], v[16:19]
	v_mfma_f32_16x16x32_bf16 v[24:27], v[158:161], v[198:201], v[24:27]
	v_mfma_f32_16x16x32_bf16 v[48:51], v[158:161], v[190:193], v[48:51]
	v_mfma_f32_16x16x32_bf16 v[56:59], v[158:161], v[182:185], v[56:59]
	v_mfma_f32_16x16x32_bf16 v[60:63], v[148:151], v[186:189], v[60:63]
	v_mfma_f32_16x16x32_bf16 v[52:55], v[148:151], v[194:197], v[52:55]
	v_mfma_f32_16x16x32_bf16 v[28:31], v[148:151], v[202:205], v[28:31]
	v_mfma_f32_16x16x32_bf16 v[20:23], v[148:151], v[210:213], v[20:23]
	v_mfma_f32_16x16x32_bf16 v[16:19], v[162:165], v[210:213], v[16:19]
	v_mfma_f32_16x16x32_bf16 v[24:27], v[162:165], v[202:205], v[24:27]
	v_mfma_f32_16x16x32_bf16 v[48:51], v[162:165], v[194:197], v[48:51]
	v_mfma_f32_16x16x32_bf16 v[56:59], v[162:165], v[186:189], v[56:59]
	s_setprio 0
	s_setprio 1
	v_mfma_f32_16x16x32_bf16 v[44:47], v[166:169], v[182:185], v[44:47]
	v_mfma_f32_16x16x32_bf16 v[36:39], v[166:169], v[190:193], v[36:39]
	v_mfma_f32_16x16x32_bf16 v[12:15], v[166:169], v[198:201], v[12:15]
	v_mfma_f32_16x16x32_bf16 v[4:7], v[166:169], v[206:209], v[4:7]
	v_mfma_f32_16x16x32_bf16 v[0:3], v[174:177], v[206:209], v[0:3]
	v_mfma_f32_16x16x32_bf16 v[8:11], v[174:177], v[198:201], v[8:11]
	v_mfma_f32_16x16x32_bf16 v[32:35], v[174:177], v[190:193], v[32:35]
	v_mfma_f32_16x16x32_bf16 v[40:43], v[174:177], v[182:185], v[40:43]
	v_mfma_f32_16x16x32_bf16 v[44:47], v[170:173], v[186:189], v[44:47]
	v_mfma_f32_16x16x32_bf16 v[36:39], v[170:173], v[194:197], v[36:39]
	v_mfma_f32_16x16x32_bf16 v[12:15], v[170:173], v[202:205], v[12:15]
	v_mfma_f32_16x16x32_bf16 v[4:7], v[170:173], v[210:213], v[4:7]
	v_mfma_f32_16x16x32_bf16 v[0:3], v[178:181], v[210:213], v[0:3]
	v_mfma_f32_16x16x32_bf16 v[8:11], v[178:181], v[202:205], v[8:11]
	v_mfma_f32_16x16x32_bf16 v[32:35], v[178:181], v[194:197], v[32:35]
	v_mfma_f32_16x16x32_bf16 v[40:43], v[178:181], v[186:189], v[40:43]
	s_setprio 0
	s_barrier
	s_add_i32 s45, s45, 2
	s_add_u32 s18, s18, 0x100
	s_addc_u32 s19, s19, 0
	s_add_u32 s0, s0, 0x100
	s_addc_u32 s1, s1, 0
	s_cmpk_gt_u32 s45, 0x55
	s_cbranch_scc0 .LBB0_3930
	s_and_b64 vcc, exec, s[14:15]
	s_cbranch_vccz .LBB0_3933
	s_barrier
